# v27 plus GEMM K-loop back-edge rotated above the loop-back barrier in 11 loops (loop-edge strategy)
# speedup vs baseline: 1.0029x; 1.0029x over previous
.LBB0_212:
	s_or_b64 exec, exec, s[16:17]
	v_add_u32_e32 v175, s15, v3
	v_lshl_add_u64 v[6:7], s[76:77], 0, v[128:129]
	v_readfirstlane_b32 s11, v175
	v_add_u32_e32 v176, 0x2000, v175
	v_lshl_add_u64 v[8:9], v[6:7], 0, s[22:23]
	s_mov_b32 m0, s11
	s_mov_b64 s[16:17], 0x20080
	v_readfirstlane_b32 s11, v176
	v_add_u32_e32 v177, 0x8000, v161
	s_waitcnt vmcnt(0)
	s_barrier
	global_load_lds_dwordx4 v[8:9], off
	v_lshl_add_u64 v[8:9], v[6:7], 0, s[16:17]
	s_mov_b32 m0, s11
	v_lshl_add_u64 v[130:131], s[90:91], 0, v[128:129]
	v_readfirstlane_b32 s11, v177
	v_add_u32_e32 v178, 0xa000, v161
	global_load_lds_dwordx4 v[8:9], off
	v_lshl_add_u64 v[8:9], v[130:131], 0, s[22:23]
	s_mov_b32 m0, s11
	v_readfirstlane_b32 s11, v178
	v_add_u32_e32 v179, s36, v3
	global_load_lds_dwordx4 v[8:9], off
	v_lshl_add_u64 v[8:9], v[130:131], 0, s[16:17]
	s_mov_b32 m0, s11
	s_mov_b64 s[16:17], 0x40080
	v_readfirstlane_b32 s11, v179
	v_add_u32_e32 v181, 0x2000, v179
	global_load_lds_dwordx4 v[8:9], off
	v_lshl_add_u64 v[8:9], v[6:7], 0, s[16:17]
	s_mov_b32 m0, s11
	s_mov_b64 s[16:17], 0x60080
	v_readfirstlane_b32 s11, v181
	global_load_lds_dwordx4 v[8:9], off
	v_lshl_add_u64 v[6:7], v[6:7], 0, s[16:17]
	s_mov_b32 m0, s11
	v_and_b32_e32 v164, 15, v163
	global_load_lds_dwordx4 v[6:7], off
	v_bfe_u32 v136, v163, 4, 2
	v_lshlrev_b32_e32 v168, 2, v163
	v_lshlrev_b32_e32 v14, 8, v163
	v_ashrrev_i32_e32 v166, 6, v163
	v_lshlrev_b32_e32 v5, 4, v136
	v_lshlrev_b32_e32 v6, 6, v164
	v_and_b32_e32 v7, 32, v168
	v_lshlrev_b32_e32 v12, 6, v163
	s_movk_i32 s11, 0x3c0
	v_and_b32_e32 v14, 0xffff8000, v14
	v_lshlrev_b32_e32 v0, 11, v0
	v_and_b32_e32 v165, 3, v166
	s_waitcnt vmcnt(6)
	v_bitop3_b32 v6, v5, v7, v6 bitop3:0x36
	v_lshlrev_b32_e32 v167, 6, v4
	v_lshlrev_b32_e32 v4, 13, v4
	v_and_or_b32 v5, v12, s11, v5
	v_or3_b32 v0, v1, v14, v0
	v_lshlrev_b32_e32 v3, 12, v165
	v_add_u32_e32 v8, s35, v6
	v_add_u32_e32 v9, s14, v6
	v_add_u32_e32 v10, s15, v6
	v_add_u32_e32 v11, s36, v6
	v_add_u32_e32 v6, 16, v6
	v_xad_u32 v5, v5, v7, 16
	v_or_b32_e32 v7, 0x800, v4
	v_or_b32_e32 v12, 0x1000, v4
	v_or_b32_e32 v13, 0x1800, v4
	v_add_u32_e32 v132, v0, v2
	s_add_u32 s80, s12, s70
	v_mov_b32_e32 v0, 0
	v_mov_b32_e32 v133, v129
	s_addc_u32 s81, s13, s71
	s_mov_b32 s11, -2
	v_add_u32_e32 v186, v8, v3
	v_add_u32_e32 v172, v6, v4
	v_add_u32_e32 v171, v5, v7
	v_add_u32_e32 v170, v5, v12
	v_add_u32_e32 v169, v5, v13
	v_add_u32_e32 v185, 0xc000, v161
	v_add_u32_e32 v184, 0xe000, v161
	v_add_u32_e32 v180, v9, v3
	v_add_u32_e32 v174, v10, v3
	v_add_u32_e32 v173, v11, v3
	v_mov_b32_e32 v1, v0
	v_mov_b32_e32 v2, v0
	v_mov_b32_e32 v3, v0
	v_mov_b32_e32 v4, v0
	v_mov_b32_e32 v5, v0
	v_mov_b32_e32 v6, v0
	v_mov_b32_e32 v7, v0
	v_mov_b32_e32 v8, v0
	v_mov_b32_e32 v9, v0
	v_mov_b32_e32 v10, v0
	v_mov_b32_e32 v11, v0
	v_mov_b32_e32 v12, v0
	v_mov_b32_e32 v13, v0
	v_mov_b32_e32 v14, v0
	v_mov_b32_e32 v15, v0
	v_mov_b32_e32 v16, v0
	v_mov_b32_e32 v17, v0
	v_mov_b32_e32 v18, v0
	v_mov_b32_e32 v19, v0
	v_mov_b32_e32 v20, v0
	v_mov_b32_e32 v21, v0
	v_mov_b32_e32 v22, v0
	v_mov_b32_e32 v23, v0
	v_mov_b32_e32 v24, v0
	v_mov_b32_e32 v25, v0
	v_mov_b32_e32 v26, v0
	v_mov_b32_e32 v27, v0
	v_mov_b32_e32 v28, v0
	v_mov_b32_e32 v29, v0
	v_mov_b32_e32 v30, v0
	v_mov_b32_e32 v31, v0
	v_mov_b32_e32 v32, v0
	v_mov_b32_e32 v33, v0
	v_mov_b32_e32 v34, v0
	v_mov_b32_e32 v35, v0
	v_mov_b32_e32 v36, v0
	v_mov_b32_e32 v37, v0
	v_mov_b32_e32 v38, v0
	v_mov_b32_e32 v39, v0
	v_mov_b32_e32 v40, v0
	v_mov_b32_e32 v41, v0
	v_mov_b32_e32 v42, v0
	v_mov_b32_e32 v43, v0
	v_mov_b32_e32 v44, v0
	v_mov_b32_e32 v45, v0
	v_mov_b32_e32 v46, v0
	v_mov_b32_e32 v47, v0
	v_mov_b32_e32 v48, v0
	v_mov_b32_e32 v49, v0
	v_mov_b32_e32 v50, v0
	v_mov_b32_e32 v51, v0
	v_mov_b32_e32 v52, v0
	v_mov_b32_e32 v53, v0
	v_mov_b32_e32 v54, v0
	v_mov_b32_e32 v55, v0
	v_mov_b32_e32 v56, v0
	v_mov_b32_e32 v57, v0
	v_mov_b32_e32 v58, v0
	v_mov_b32_e32 v59, v0
	v_mov_b32_e32 v60, v0
	v_mov_b32_e32 v61, v0
	v_mov_b32_e32 v62, v0
	v_mov_b32_e32 v63, v0
	v_mov_b32_e32 v64, v0
	v_mov_b32_e32 v65, v0
	v_mov_b32_e32 v66, v0
	v_mov_b32_e32 v67, v0
	v_mov_b32_e32 v68, v0
	v_mov_b32_e32 v69, v0
	v_mov_b32_e32 v70, v0
	v_mov_b32_e32 v71, v0
	v_mov_b32_e32 v72, v0
	v_mov_b32_e32 v73, v0
	v_mov_b32_e32 v74, v0
	v_mov_b32_e32 v75, v0
	v_mov_b32_e32 v76, v0
	v_mov_b32_e32 v77, v0
	v_mov_b32_e32 v78, v0
	v_mov_b32_e32 v79, v0
	v_mov_b32_e32 v80, v0
	v_mov_b32_e32 v81, v0
	v_mov_b32_e32 v82, v0
	v_mov_b32_e32 v83, v0
	v_mov_b32_e32 v84, v0
	v_mov_b32_e32 v85, v0
	v_mov_b32_e32 v86, v0
	v_mov_b32_e32 v87, v0
	v_mov_b32_e32 v88, v0
	v_mov_b32_e32 v89, v0
	v_mov_b32_e32 v90, v0
	v_mov_b32_e32 v91, v0
	v_mov_b32_e32 v92, v0
	v_mov_b32_e32 v93, v0
	v_mov_b32_e32 v94, v0
	v_mov_b32_e32 v95, v0
	v_mov_b32_e32 v96, v0
	v_mov_b32_e32 v97, v0
	v_mov_b32_e32 v98, v0
	v_mov_b32_e32 v99, v0
	v_mov_b32_e32 v100, v0
	v_mov_b32_e32 v101, v0
	v_mov_b32_e32 v102, v0
	v_mov_b32_e32 v103, v0
	v_mov_b32_e32 v104, v0
	v_mov_b32_e32 v105, v0
	v_mov_b32_e32 v106, v0
	v_mov_b32_e32 v107, v0
	v_mov_b32_e32 v108, v0
	v_mov_b32_e32 v109, v0
	v_mov_b32_e32 v110, v0
	v_mov_b32_e32 v111, v0
	v_mov_b32_e32 v112, v0
	v_mov_b32_e32 v113, v0
	v_mov_b32_e32 v114, v0
	v_mov_b32_e32 v115, v0
	v_mov_b32_e32 v116, v0
	v_mov_b32_e32 v117, v0
	v_mov_b32_e32 v118, v0
	v_mov_b32_e32 v119, v0
	v_mov_b32_e32 v120, v0
	v_mov_b32_e32 v121, v0
	v_mov_b32_e32 v122, v0
	v_mov_b32_e32 v123, v0
	v_mov_b32_e32 v124, v0
	v_mov_b32_e32 v125, v0
	v_mov_b32_e32 v126, v0
	v_mov_b32_e32 v127, v0
.Lkh_213:
	s_barrier
.LBB0_213:
	ds_read_b128 v[138:141], v186
	ds_read_b128 v[146:149], v186 offset:1024
	ds_read_b128 v[150:153], v186 offset:2048
	ds_read_b128 v[154:157], v186 offset:3072
	v_lshl_add_u64 v[240:241], s[80:81], 0, v[132:133]
	v_readfirstlane_b32 s16, v185
	v_lshl_add_u64 v[220:221], v[240:241], 0, s[30:31]
	s_mov_b32 m0, s16
	v_readfirstlane_b32 s16, v184
	ds_read_b128 v[188:191], v172
	ds_read_b128 v[192:195], v172 offset:1024
	ds_read_b128 v[196:199], v171
	ds_read_b128 v[200:203], v171 offset:1024
	ds_read_b128 v[204:207], v170
	ds_read_b128 v[208:211], v170 offset:1024
	ds_read_b128 v[212:215], v169
	ds_read_b128 v[216:219], v169 offset:1024
	global_load_lds_dwordx4 v[220:221], off
	v_lshl_add_u64 v[220:221], v[240:241], 0, s[38:39]
	s_mov_b32 m0, s16
	s_nop 0
	global_load_lds_dwordx4 v[220:221], off
	s_waitcnt lgkmcnt(8)
	s_barrier
	s_waitcnt lgkmcnt(0)
	s_setprio 1
	s_waitcnt lgkmcnt(0)
	v_mfma_f32_16x16x32_bf16 v[124:127], v[188:191], v[138:141], v[124:127]
	v_mfma_f32_16x16x32_bf16 v[120:123], v[188:191], v[150:153], v[120:123]
	v_mfma_f32_16x16x32_bf16 v[116:119], v[196:199], v[138:141], v[116:119]
	v_mfma_f32_16x16x32_bf16 v[112:115], v[196:199], v[150:153], v[112:115]
	v_mfma_f32_16x16x32_bf16 v[108:111], v[204:207], v[138:141], v[108:111]
	v_mfma_f32_16x16x32_bf16 v[104:107], v[204:207], v[150:153], v[104:107]
	v_mfma_f32_16x16x32_bf16 v[100:103], v[212:215], v[138:141], v[100:103]
	v_mfma_f32_16x16x32_bf16 v[96:99], v[212:215], v[150:153], v[96:99]
	v_mfma_f32_16x16x32_bf16 v[124:127], v[192:195], v[146:149], v[124:127]
	v_mfma_f32_16x16x32_bf16 v[120:123], v[192:195], v[154:157], v[120:123]
	v_mfma_f32_16x16x32_bf16 v[116:119], v[200:203], v[146:149], v[116:119]
	v_mfma_f32_16x16x32_bf16 v[112:115], v[200:203], v[154:157], v[112:115]
	v_mfma_f32_16x16x32_bf16 v[108:111], v[208:211], v[146:149], v[108:111]
	v_mfma_f32_16x16x32_bf16 v[104:107], v[208:211], v[154:157], v[104:107]
	v_mfma_f32_16x16x32_bf16 v[100:103], v[216:219], v[146:149], v[100:103]
	v_mfma_f32_16x16x32_bf16 v[96:99], v[216:219], v[154:157], v[96:99]
	s_setprio 0
	s_barrier
	v_lshl_add_u64 v[242:243], s[76:77], 0, v[132:133]
	v_readfirstlane_b32 s16, v162
	v_add_u32_e32 v187, 0x2000, v162
	v_lshl_add_u64 v[236:237], v[242:243], 0, s[40:41]
	s_mov_b32 m0, s16
	v_readfirstlane_b32 s16, v187
	ds_read_b128 v[220:223], v180
	ds_read_b128 v[224:227], v180 offset:1024
	ds_read_b128 v[228:231], v180 offset:2048
	ds_read_b128 v[232:235], v180 offset:3072
	global_load_lds_dwordx4 v[236:237], off
	v_lshl_add_u64 v[236:237], v[242:243], 0, s[42:43]
	s_mov_b32 m0, s16
	s_nop 0
	global_load_lds_dwordx4 v[236:237], off
	s_barrier
	s_waitcnt lgkmcnt(0)
	s_setprio 1
	s_waitcnt lgkmcnt(0)
	v_mfma_f32_16x16x32_bf16 v[92:95], v[188:191], v[220:223], v[92:95]
	v_mfma_f32_16x16x32_bf16 v[88:91], v[188:191], v[228:231], v[88:91]
	v_mfma_f32_16x16x32_bf16 v[84:87], v[196:199], v[220:223], v[84:87]
	v_mfma_f32_16x16x32_bf16 v[80:83], v[196:199], v[228:231], v[80:83]
	v_mfma_f32_16x16x32_bf16 v[76:79], v[204:207], v[220:223], v[76:79]
	v_mfma_f32_16x16x32_bf16 v[72:75], v[204:207], v[228:231], v[72:75]
	v_mfma_f32_16x16x32_bf16 v[68:71], v[212:215], v[220:223], v[68:71]
	v_mfma_f32_16x16x32_bf16 v[64:67], v[212:215], v[228:231], v[64:67]
	v_mfma_f32_16x16x32_bf16 v[92:95], v[192:195], v[224:227], v[92:95]
	v_mfma_f32_16x16x32_bf16 v[88:91], v[192:195], v[232:235], v[88:91]
	v_mfma_f32_16x16x32_bf16 v[84:87], v[200:203], v[224:227], v[84:87]
	v_mfma_f32_16x16x32_bf16 v[80:83], v[200:203], v[232:235], v[80:83]
	v_mfma_f32_16x16x32_bf16 v[76:79], v[208:211], v[224:227], v[76:79]
	v_mfma_f32_16x16x32_bf16 v[72:75], v[208:211], v[232:235], v[72:75]
	v_mfma_f32_16x16x32_bf16 v[68:71], v[216:219], v[224:227], v[68:71]
	v_mfma_f32_16x16x32_bf16 v[64:67], v[216:219], v[232:235], v[64:67]
	s_setprio 0
	v_readfirstlane_b32 s16, v161
	v_lshl_add_u64 v[188:189], v[240:241], 0, s[44:45]
	s_mov_b32 m0, s16
	v_readfirstlane_b32 s16, v160
	s_barrier
	ds_read_b128 v[190:193], v172 offset:16384
	ds_read_b128 v[194:197], v172 offset:17408
	ds_read_b128 v[198:201], v171 offset:16384
	ds_read_b128 v[202:205], v171 offset:17408
	ds_read_b128 v[206:209], v170 offset:16384
	ds_read_b128 v[210:213], v170 offset:17408
	ds_read_b128 v[214:217], v169 offset:16384
	ds_read_b128 v[236:239], v169 offset:17408
	global_load_lds_dwordx4 v[188:189], off
	v_lshl_add_u64 v[188:189], v[240:241], 0, s[46:47]
	s_mov_b32 m0, s16
	s_nop 0
	global_load_lds_dwordx4 v[188:189], off
	s_barrier
	s_waitcnt lgkmcnt(0)
	s_setprio 1
	s_waitcnt lgkmcnt(0)
	v_mfma_f32_16x16x32_bf16 v[60:63], v[190:193], v[138:141], v[60:63]
	v_mfma_f32_16x16x32_bf16 v[56:59], v[190:193], v[150:153], v[56:59]
	v_mfma_f32_16x16x32_bf16 v[52:55], v[198:201], v[138:141], v[52:55]
	v_mfma_f32_16x16x32_bf16 v[48:51], v[198:201], v[150:153], v[48:51]
	v_mfma_f32_16x16x32_bf16 v[44:47], v[206:209], v[138:141], v[44:47]
	v_mfma_f32_16x16x32_bf16 v[40:43], v[206:209], v[150:153], v[40:43]
	v_mfma_f32_16x16x32_bf16 v[36:39], v[214:217], v[138:141], v[36:39]
	v_mfma_f32_16x16x32_bf16 v[32:35], v[214:217], v[150:153], v[32:35]
	v_mfma_f32_16x16x32_bf16 v[60:63], v[194:197], v[146:149], v[60:63]
	v_mfma_f32_16x16x32_bf16 v[56:59], v[194:197], v[154:157], v[56:59]
	v_mfma_f32_16x16x32_bf16 v[52:55], v[202:205], v[146:149], v[52:55]
	v_mfma_f32_16x16x32_bf16 v[48:51], v[202:205], v[154:157], v[48:51]
	v_mfma_f32_16x16x32_bf16 v[44:47], v[210:213], v[146:149], v[44:47]
	v_mfma_f32_16x16x32_bf16 v[40:43], v[210:213], v[154:157], v[40:43]
	v_mfma_f32_16x16x32_bf16 v[36:39], v[236:239], v[146:149], v[36:39]
	v_mfma_f32_16x16x32_bf16 v[32:35], v[236:239], v[154:157], v[32:35]
	s_setprio 0
	s_barrier
	v_readfirstlane_b32 s16, v137
	v_add_u32_e32 v188, 0x2000, v137
	v_lshl_add_u64 v[138:139], v[242:243], 0, s[48:49]
	s_mov_b32 m0, s16
	v_readfirstlane_b32 s16, v188
	global_load_lds_dwordx4 v[138:139], off
	v_lshl_add_u64 v[138:139], v[242:243], 0, s[50:51]
	s_mov_b32 m0, s16
	s_nop 0
	global_load_lds_dwordx4 v[138:139], off
	s_waitcnt vmcnt(6)
	s_barrier
	s_setprio 1
	v_mfma_f32_16x16x32_bf16 v[28:31], v[190:193], v[220:223], v[28:31]
	v_mfma_f32_16x16x32_bf16 v[24:27], v[190:193], v[228:231], v[24:27]
	v_mfma_f32_16x16x32_bf16 v[20:23], v[198:201], v[220:223], v[20:23]
	v_mfma_f32_16x16x32_bf16 v[16:19], v[198:201], v[228:231], v[16:19]
	v_mfma_f32_16x16x32_bf16 v[12:15], v[206:209], v[220:223], v[12:15]
	v_mfma_f32_16x16x32_bf16 v[8:11], v[206:209], v[228:231], v[8:11]
	v_mfma_f32_16x16x32_bf16 v[4:7], v[214:217], v[220:223], v[4:7]
	v_mfma_f32_16x16x32_bf16 v[0:3], v[214:217], v[228:231], v[0:3]
	v_mfma_f32_16x16x32_bf16 v[28:31], v[194:197], v[224:227], v[28:31]
	v_mfma_f32_16x16x32_bf16 v[24:27], v[194:197], v[232:235], v[24:27]
	v_mfma_f32_16x16x32_bf16 v[20:23], v[202:205], v[224:227], v[20:23]
	v_mfma_f32_16x16x32_bf16 v[16:19], v[202:205], v[232:235], v[16:19]
	v_mfma_f32_16x16x32_bf16 v[12:15], v[210:213], v[224:227], v[12:15]
	v_mfma_f32_16x16x32_bf16 v[8:11], v[210:213], v[232:235], v[8:11]
	v_mfma_f32_16x16x32_bf16 v[4:7], v[236:239], v[224:227], v[4:7]
	v_mfma_f32_16x16x32_bf16 v[0:3], v[236:239], v[232:235], v[0:3]
	s_setprio 0
	s_barrier
	ds_read_b128 v[138:141], v174
	ds_read_b128 v[146:149], v174 offset:1024
	ds_read_b128 v[150:153], v174 offset:2048
	ds_read_b128 v[154:157], v174 offset:3072
	v_readfirstlane_b32 s16, v135
	v_lshl_add_u64 v[222:223], v[240:241], 0, s[52:53]
	s_mov_b32 m0, s16
	v_readfirstlane_b32 s16, v134
	ds_read_b128 v[190:193], v172 offset:32768
	ds_read_b128 v[194:197], v172 offset:33792
	ds_read_b128 v[198:201], v171 offset:32768
	ds_read_b128 v[202:205], v171 offset:33792
	ds_read_b128 v[206:209], v170 offset:32768
	ds_read_b128 v[210:213], v170 offset:33792
	ds_read_b128 v[214:217], v169 offset:32768
	ds_read_b128 v[218:221], v169 offset:33792
	global_load_lds_dwordx4 v[222:223], off
	v_lshl_add_u64 v[222:223], v[240:241], 0, s[54:55]
	s_mov_b32 m0, s16
	s_nop 0
	global_load_lds_dwordx4 v[222:223], off
	s_waitcnt lgkmcnt(8)
	s_barrier
	s_waitcnt lgkmcnt(0)
	s_setprio 1
	s_waitcnt lgkmcnt(0)
	v_mfma_f32_16x16x32_bf16 v[124:127], v[190:193], v[138:141], v[124:127]
	v_mfma_f32_16x16x32_bf16 v[120:123], v[190:193], v[150:153], v[120:123]
	v_mfma_f32_16x16x32_bf16 v[116:119], v[198:201], v[138:141], v[116:119]
	v_mfma_f32_16x16x32_bf16 v[112:115], v[198:201], v[150:153], v[112:115]
	v_mfma_f32_16x16x32_bf16 v[108:111], v[206:209], v[138:141], v[108:111]
	v_mfma_f32_16x16x32_bf16 v[104:107], v[206:209], v[150:153], v[104:107]
	v_mfma_f32_16x16x32_bf16 v[100:103], v[214:217], v[138:141], v[100:103]
	v_mfma_f32_16x16x32_bf16 v[96:99], v[214:217], v[150:153], v[96:99]
	v_mfma_f32_16x16x32_bf16 v[124:127], v[194:197], v[146:149], v[124:127]
	v_mfma_f32_16x16x32_bf16 v[120:123], v[194:197], v[154:157], v[120:123]
	v_mfma_f32_16x16x32_bf16 v[116:119], v[202:205], v[146:149], v[116:119]
	v_mfma_f32_16x16x32_bf16 v[112:115], v[202:205], v[154:157], v[112:115]
	v_mfma_f32_16x16x32_bf16 v[108:111], v[210:213], v[146:149], v[108:111]
	v_mfma_f32_16x16x32_bf16 v[104:107], v[210:213], v[154:157], v[104:107]
	v_mfma_f32_16x16x32_bf16 v[100:103], v[218:221], v[146:149], v[100:103]
	v_mfma_f32_16x16x32_bf16 v[96:99], v[218:221], v[154:157], v[96:99]
	s_setprio 0
	s_barrier
	v_readfirstlane_b32 s16, v175
	v_lshl_add_u64 v[238:239], v[242:243], 0, s[56:57]
	s_mov_b32 m0, s16
	v_readfirstlane_b32 s16, v176
	ds_read_b128 v[222:225], v173
	ds_read_b128 v[226:229], v173 offset:1024
	ds_read_b128 v[230:233], v173 offset:2048
	ds_read_b128 v[234:237], v173 offset:3072
	global_load_lds_dwordx4 v[238:239], off
	v_lshl_add_u64 v[238:239], v[242:243], 0, s[58:59]
	s_mov_b32 m0, s16
	s_nop 0
	global_load_lds_dwordx4 v[238:239], off
	s_barrier
	s_waitcnt lgkmcnt(0)
	s_setprio 1
	s_waitcnt lgkmcnt(0)
	v_mfma_f32_16x16x32_bf16 v[92:95], v[190:193], v[222:225], v[92:95]
	v_mfma_f32_16x16x32_bf16 v[88:91], v[190:193], v[230:233], v[88:91]
	v_mfma_f32_16x16x32_bf16 v[84:87], v[198:201], v[222:225], v[84:87]
	v_mfma_f32_16x16x32_bf16 v[80:83], v[198:201], v[230:233], v[80:83]
	v_mfma_f32_16x16x32_bf16 v[76:79], v[206:209], v[222:225], v[76:79]
	v_mfma_f32_16x16x32_bf16 v[72:75], v[206:209], v[230:233], v[72:75]
	v_mfma_f32_16x16x32_bf16 v[68:71], v[214:217], v[222:225], v[68:71]
	v_mfma_f32_16x16x32_bf16 v[64:67], v[214:217], v[230:233], v[64:67]
	v_mfma_f32_16x16x32_bf16 v[92:95], v[194:197], v[226:229], v[92:95]
	v_mfma_f32_16x16x32_bf16 v[88:91], v[194:197], v[234:237], v[88:91]
	v_mfma_f32_16x16x32_bf16 v[84:87], v[202:205], v[226:229], v[84:87]
	v_mfma_f32_16x16x32_bf16 v[80:83], v[202:205], v[234:237], v[80:83]
	v_mfma_f32_16x16x32_bf16 v[76:79], v[210:213], v[226:229], v[76:79]
	v_mfma_f32_16x16x32_bf16 v[72:75], v[210:213], v[234:237], v[72:75]
	v_mfma_f32_16x16x32_bf16 v[68:71], v[218:221], v[226:229], v[68:71]
	v_mfma_f32_16x16x32_bf16 v[64:67], v[218:221], v[234:237], v[64:67]
	s_setprio 0
	v_readfirstlane_b32 s16, v177
	v_lshl_add_u64 v[238:239], v[240:241], 0, s[60:61]
	s_mov_b32 m0, s16
	v_readfirstlane_b32 s16, v178
	s_barrier
	ds_read_b128 v[190:193], v172 offset:49152
	ds_read_b128 v[194:197], v172 offset:50176
	ds_read_b128 v[198:201], v171 offset:49152
	ds_read_b128 v[202:205], v171 offset:50176
	ds_read_b128 v[206:209], v170 offset:49152
	ds_read_b128 v[210:213], v170 offset:50176
	ds_read_b128 v[214:217], v169 offset:49152
	ds_read_b128 v[218:221], v169 offset:50176
	global_load_lds_dwordx4 v[238:239], off
	v_lshl_add_u64 v[238:239], v[240:241], 0, s[62:63]
	s_mov_b32 m0, s16
	s_nop 0
	global_load_lds_dwordx4 v[238:239], off
	s_barrier
	s_waitcnt lgkmcnt(0)
	s_setprio 1
	s_waitcnt lgkmcnt(0)
	v_mfma_f32_16x16x32_bf16 v[60:63], v[190:193], v[138:141], v[60:63]
	v_mfma_f32_16x16x32_bf16 v[56:59], v[190:193], v[150:153], v[56:59]
	v_mfma_f32_16x16x32_bf16 v[52:55], v[198:201], v[138:141], v[52:55]
	v_mfma_f32_16x16x32_bf16 v[48:51], v[198:201], v[150:153], v[48:51]
	v_mfma_f32_16x16x32_bf16 v[44:47], v[206:209], v[138:141], v[44:47]
	v_mfma_f32_16x16x32_bf16 v[40:43], v[206:209], v[150:153], v[40:43]
	v_mfma_f32_16x16x32_bf16 v[36:39], v[214:217], v[138:141], v[36:39]
	v_mfma_f32_16x16x32_bf16 v[32:35], v[214:217], v[150:153], v[32:35]
	v_mfma_f32_16x16x32_bf16 v[60:63], v[194:197], v[146:149], v[60:63]
	v_mfma_f32_16x16x32_bf16 v[56:59], v[194:197], v[154:157], v[56:59]
	v_mfma_f32_16x16x32_bf16 v[52:55], v[202:205], v[146:149], v[52:55]
	v_mfma_f32_16x16x32_bf16 v[48:51], v[202:205], v[154:157], v[48:51]
	v_mfma_f32_16x16x32_bf16 v[44:47], v[210:213], v[146:149], v[44:47]
	v_mfma_f32_16x16x32_bf16 v[40:43], v[210:213], v[154:157], v[40:43]
	v_mfma_f32_16x16x32_bf16 v[36:39], v[218:221], v[146:149], v[36:39]
	v_mfma_f32_16x16x32_bf16 v[32:35], v[218:221], v[154:157], v[32:35]
	s_setprio 0
	s_barrier
	v_readfirstlane_b32 s16, v179
	v_lshl_add_u64 v[138:139], v[242:243], 0, s[64:65]
	s_mov_b32 m0, s16
	v_readfirstlane_b32 s16, v181
	global_load_lds_dwordx4 v[138:139], off
	v_lshl_add_u64 v[138:139], v[242:243], 0, s[66:67]
	s_mov_b32 m0, s16
	s_nop 0
	global_load_lds_dwordx4 v[138:139], off
	s_waitcnt vmcnt(6)
	s_barrier
	s_setprio 1
	v_mfma_f32_16x16x32_bf16 v[28:31], v[190:193], v[222:225], v[28:31]
	v_mfma_f32_16x16x32_bf16 v[24:27], v[190:193], v[230:233], v[24:27]
	v_mfma_f32_16x16x32_bf16 v[20:23], v[198:201], v[222:225], v[20:23]
	v_mfma_f32_16x16x32_bf16 v[16:19], v[198:201], v[230:233], v[16:19]
	v_mfma_f32_16x16x32_bf16 v[12:15], v[206:209], v[222:225], v[12:15]
	v_mfma_f32_16x16x32_bf16 v[8:11], v[206:209], v[230:233], v[8:11]
	v_mfma_f32_16x16x32_bf16 v[4:7], v[214:217], v[222:225], v[4:7]
	v_mfma_f32_16x16x32_bf16 v[0:3], v[214:217], v[230:233], v[0:3]
	v_mfma_f32_16x16x32_bf16 v[28:31], v[194:197], v[226:229], v[28:31]
	v_mfma_f32_16x16x32_bf16 v[24:27], v[194:197], v[234:237], v[24:27]
	v_mfma_f32_16x16x32_bf16 v[20:23], v[202:205], v[226:229], v[20:23]
	v_mfma_f32_16x16x32_bf16 v[16:19], v[202:205], v[234:237], v[16:19]
	v_mfma_f32_16x16x32_bf16 v[12:15], v[210:213], v[226:229], v[12:15]
	v_mfma_f32_16x16x32_bf16 v[8:11], v[210:213], v[234:237], v[8:11]
	v_mfma_f32_16x16x32_bf16 v[4:7], v[218:221], v[226:229], v[4:7]
	v_mfma_f32_16x16x32_bf16 v[0:3], v[218:221], v[234:237], v[0:3]
	s_setprio 0
	s_add_i32 s11, s11, 2
	s_add_u32 s80, s80, 0x100
	s_addc_u32 s81, s81, 0
	s_add_u32 s76, s76, 0x100
	s_addc_u32 s77, s77, 0
	s_cmp_lt_u32 s11, 12
	s_cbranch_scc1 .Lkh_213
	s_barrier
	s_mov_b64 s[16:17], 0x40780
	v_readfirstlane_b32 s11, v185
	v_lshl_add_u64 v[132:133], v[130:131], 0, s[16:17]
	s_mov_b32 m0, s11
	s_mov_b64 s[16:17], 0x60780
	v_readfirstlane_b32 s11, v184
	ds_read_b128 v[138:141], v186
	ds_read_b128 v[146:149], v186 offset:1024
	ds_read_b128 v[150:153], v186 offset:2048
	ds_read_b128 v[154:157], v186 offset:3072
	ds_read_b128 v[176:179], v172
	ds_read_b128 v[190:193], v172 offset:1024
	ds_read_b128 v[194:197], v171
	ds_read_b128 v[198:201], v171 offset:1024
	ds_read_b128 v[202:205], v170
	ds_read_b128 v[206:209], v170 offset:1024
	ds_read_b128 v[210:213], v169
	ds_read_b128 v[214:217], v169 offset:1024
	global_load_lds_dwordx4 v[132:133], off
	v_lshl_add_u64 v[130:131], v[130:131], 0, s[16:17]
	s_mov_b32 m0, s11
	s_nop 0
	global_load_lds_dwordx4 v[130:131], off
	s_barrier
	s_waitcnt lgkmcnt(0)
	s_setprio 1
	s_waitcnt lgkmcnt(0)
	v_mfma_f32_16x16x32_bf16 v[124:127], v[176:179], v[138:141], v[124:127]
	v_mfma_f32_16x16x32_bf16 v[120:123], v[176:179], v[150:153], v[120:123]
	v_mfma_f32_16x16x32_bf16 v[116:119], v[194:197], v[138:141], v[116:119]
	v_mfma_f32_16x16x32_bf16 v[112:115], v[194:197], v[150:153], v[112:115]
	v_mfma_f32_16x16x32_bf16 v[124:127], v[190:193], v[146:149], v[124:127]
	v_mfma_f32_16x16x32_bf16 v[120:123], v[190:193], v[154:157], v[120:123]
	v_mfma_f32_16x16x32_bf16 v[116:119], v[198:201], v[146:149], v[116:119]
	v_mfma_f32_16x16x32_bf16 v[112:115], v[198:201], v[154:157], v[112:115]
	v_mfma_f32_16x16x32_bf16 v[108:111], v[202:205], v[138:141], v[108:111]
	v_mfma_f32_16x16x32_bf16 v[104:107], v[202:205], v[150:153], v[104:107]
	v_mfma_f32_16x16x32_bf16 v[100:103], v[210:213], v[138:141], v[100:103]
	v_mfma_f32_16x16x32_bf16 v[96:99], v[210:213], v[150:153], v[96:99]
	v_mfma_f32_16x16x32_bf16 v[130:133], v[206:209], v[146:149], v[108:111]
	v_mfma_f32_16x16x32_bf16 v[218:221], v[206:209], v[154:157], v[104:107]
	v_mfma_f32_16x16x32_bf16 v[222:225], v[214:217], v[146:149], v[100:103]
	v_mfma_f32_16x16x32_bf16 v[226:229], v[214:217], v[154:157], v[96:99]
	s_setprio 0
	s_barrier
	s_nop 1
	ds_read_b128 v[96:99], v180
	ds_read_b128 v[100:103], v180 offset:1024
	ds_read_b128 v[104:107], v180 offset:2048
	ds_read_b128 v[108:111], v180 offset:3072
	s_barrier
	s_waitcnt lgkmcnt(0)
	s_setprio 1
	s_waitcnt lgkmcnt(0)
	v_mfma_f32_16x16x32_bf16 v[92:95], v[176:179], v[96:99], v[92:95]
	v_mfma_f32_16x16x32_bf16 v[88:91], v[176:179], v[104:107], v[88:91]
	v_mfma_f32_16x16x32_bf16 v[84:87], v[194:197], v[96:99], v[84:87]
	v_mfma_f32_16x16x32_bf16 v[80:83], v[194:197], v[104:107], v[80:83]
	v_mfma_f32_16x16x32_bf16 v[92:95], v[190:193], v[100:103], v[92:95]
	v_mfma_f32_16x16x32_bf16 v[88:91], v[190:193], v[108:111], v[88:91]
	v_mfma_f32_16x16x32_bf16 v[84:87], v[198:201], v[100:103], v[84:87]
	v_mfma_f32_16x16x32_bf16 v[80:83], v[198:201], v[108:111], v[80:83]
	v_mfma_f32_16x16x32_bf16 v[76:79], v[202:205], v[96:99], v[76:79]
	v_mfma_f32_16x16x32_bf16 v[72:75], v[202:205], v[104:107], v[72:75]
	v_mfma_f32_16x16x32_bf16 v[68:71], v[210:213], v[96:99], v[68:71]
	v_mfma_f32_16x16x32_bf16 v[64:67], v[210:213], v[104:107], v[64:67]
	v_mfma_f32_16x16x32_bf16 v[176:179], v[206:209], v[100:103], v[76:79]
	v_mfma_f32_16x16x32_bf16 v[190:193], v[206:209], v[108:111], v[72:75]
	v_mfma_f32_16x16x32_bf16 v[194:197], v[214:217], v[100:103], v[68:71]
	v_mfma_f32_16x16x32_bf16 v[198:201], v[214:217], v[108:111], v[64:67]
	s_setprio 0
	s_barrier
	s_nop 1
	ds_read_b128 v[64:67], v172 offset:16384
	ds_read_b128 v[68:71], v172 offset:17408
	ds_read_b128 v[72:75], v171 offset:16384
	ds_read_b128 v[76:79], v171 offset:17408
	ds_read_b128 v[202:205], v170 offset:16384
	ds_read_b128 v[206:209], v170 offset:17408
	ds_read_b128 v[210:213], v169 offset:16384
	ds_read_b128 v[214:217], v169 offset:17408
	s_waitcnt vmcnt(4)
	s_barrier
	s_waitcnt lgkmcnt(0)
	s_setprio 1
	s_waitcnt lgkmcnt(0)
	v_mfma_f32_16x16x32_bf16 v[60:63], v[64:67], v[138:141], v[60:63]
	v_mfma_f32_16x16x32_bf16 v[56:59], v[64:67], v[150:153], v[56:59]
	v_mfma_f32_16x16x32_bf16 v[52:55], v[72:75], v[138:141], v[52:55]
	v_mfma_f32_16x16x32_bf16 v[48:51], v[72:75], v[150:153], v[48:51]
	v_mfma_f32_16x16x32_bf16 v[60:63], v[68:71], v[146:149], v[60:63]
	v_mfma_f32_16x16x32_bf16 v[56:59], v[68:71], v[154:157], v[56:59]
	v_mfma_f32_16x16x32_bf16 v[52:55], v[76:79], v[146:149], v[52:55]
	v_mfma_f32_16x16x32_bf16 v[48:51], v[76:79], v[154:157], v[48:51]
	v_mfma_f32_16x16x32_bf16 v[44:47], v[202:205], v[138:141], v[44:47]
	v_mfma_f32_16x16x32_bf16 v[40:43], v[202:205], v[150:153], v[40:43]
	v_mfma_f32_16x16x32_bf16 v[36:39], v[210:213], v[138:141], v[36:39]
	v_mfma_f32_16x16x32_bf16 v[32:35], v[210:213], v[150:153], v[32:35]
	v_mfma_f32_16x16x32_bf16 v[230:233], v[206:209], v[146:149], v[44:47]
	v_mfma_f32_16x16x32_bf16 v[234:237], v[206:209], v[154:157], v[40:43]
	v_mfma_f32_16x16x32_bf16 v[138:141], v[214:217], v[146:149], v[36:39]
	v_mfma_f32_16x16x32_bf16 v[146:149], v[214:217], v[154:157], v[32:35]
	s_setprio 0
	s_setprio 1
	v_mfma_f32_16x16x32_bf16 v[28:31], v[64:67], v[96:99], v[28:31]
	v_mfma_f32_16x16x32_bf16 v[24:27], v[64:67], v[104:107], v[24:27]
	v_mfma_f32_16x16x32_bf16 v[20:23], v[72:75], v[96:99], v[20:23]
	v_mfma_f32_16x16x32_bf16 v[16:19], v[72:75], v[104:107], v[16:19]
	v_mfma_f32_16x16x32_bf16 v[28:31], v[68:71], v[100:103], v[28:31]
	v_mfma_f32_16x16x32_bf16 v[24:27], v[68:71], v[108:111], v[24:27]
	v_mfma_f32_16x16x32_bf16 v[20:23], v[76:79], v[100:103], v[20:23]
	v_mfma_f32_16x16x32_bf16 v[16:19], v[76:79], v[108:111], v[16:19]
	v_mfma_f32_16x16x32_bf16 v[12:15], v[202:205], v[96:99], v[12:15]
	v_mfma_f32_16x16x32_bf16 v[8:11], v[202:205], v[104:107], v[8:11]
	v_mfma_f32_16x16x32_bf16 v[4:7], v[210:213], v[96:99], v[4:7]
	v_mfma_f32_16x16x32_bf16 v[0:3], v[210:213], v[104:107], v[0:3]
	v_mfma_f32_16x16x32_bf16 v[150:153], v[206:209], v[100:103], v[12:15]
	v_mfma_f32_16x16x32_bf16 v[154:157], v[206:209], v[108:111], v[8:11]
	v_mfma_f32_16x16x32_bf16 v[202:205], v[214:217], v[100:103], v[4:7]
	v_mfma_f32_16x16x32_bf16 v[206:209], v[214:217], v[108:111], v[0:3]
	s_setprio 0
	s_barrier
	s_nop 1
	ds_read_b128 v[0:3], v174
	ds_read_b128 v[4:7], v174 offset:1024
	ds_read_b128 v[210:213], v174 offset:2048
	ds_read_b128 v[214:217], v174 offset:3072
	ds_read_b128 v[8:11], v172 offset:32768
	ds_read_b128 v[12:15], v172 offset:33792
	ds_read_b128 v[32:35], v171 offset:32768
	ds_read_b128 v[36:39], v171 offset:33792
	ds_read_b128 v[40:43], v170 offset:32768
	ds_read_b128 v[44:47], v170 offset:33792
	ds_read_b128 v[238:241], v169 offset:32768
	ds_read_b128 v[242:245], v169 offset:33792
	s_waitcnt vmcnt(2)
	s_barrier
	s_waitcnt lgkmcnt(0)
	s_setprio 1
	s_waitcnt lgkmcnt(0)
	v_mfma_f32_16x16x32_bf16 v[64:67], v[8:11], v[0:3], v[124:127]
	v_mfma_f32_16x16x32_bf16 v[104:107], v[12:15], v[4:7], v[64:67]
	v_mfma_f32_16x16x32_bf16 v[64:67], v[8:11], v[210:213], v[120:123]
	v_mfma_f32_16x16x32_bf16 v[108:111], v[12:15], v[214:217], v[64:67]
	v_mfma_f32_16x16x32_bf16 v[64:67], v[32:35], v[0:3], v[116:119]
	v_mfma_f32_16x16x32_bf16 v[96:99], v[36:39], v[4:7], v[64:67]
	v_mfma_f32_16x16x32_bf16 v[64:67], v[32:35], v[210:213], v[112:115]
	v_mfma_f32_16x16x32_bf16 v[100:103], v[36:39], v[214:217], v[64:67]
	v_mfma_f32_16x16x32_bf16 v[64:67], v[40:43], v[0:3], v[130:133]
	v_mfma_f32_16x16x32_bf16 v[72:75], v[44:47], v[4:7], v[64:67]
	v_mfma_f32_16x16x32_bf16 v[64:67], v[40:43], v[210:213], v[218:221]
	v_mfma_f32_16x16x32_bf16 v[76:79], v[44:47], v[214:217], v[64:67]
	v_mfma_f32_16x16x32_bf16 v[64:67], v[238:241], v[0:3], v[222:225]
	v_mfma_f32_16x16x32_bf16 v[68:71], v[238:241], v[210:213], v[226:229]
	v_mfma_f32_16x16x32_bf16 v[64:67], v[242:245], v[4:7], v[64:67]
	v_mfma_f32_16x16x32_bf16 v[68:71], v[242:245], v[214:217], v[68:71]
	s_setprio 0
	s_barrier
	ds_read_b128 v[130:133], v173
	ds_read_b128 v[218:221], v173 offset:1024
	ds_read_b128 v[222:225], v173 offset:2048
	ds_read_b128 v[226:229], v173 offset:3072
	s_waitcnt vmcnt(0)
	s_barrier
	s_waitcnt lgkmcnt(0)
	s_setprio 1
	s_waitcnt lgkmcnt(0)
	v_mfma_f32_16x16x32_bf16 v[92:95], v[8:11], v[130:133], v[92:95]
	v_mfma_f32_16x16x32_bf16 v[8:11], v[8:11], v[222:225], v[88:91]
	v_mfma_f32_16x16x32_bf16 v[124:127], v[12:15], v[226:229], v[8:11]
	v_mfma_f32_16x16x32_bf16 v[8:11], v[32:35], v[130:133], v[84:87]
	v_mfma_f32_16x16x32_bf16 v[112:115], v[36:39], v[218:221], v[8:11]
	v_mfma_f32_16x16x32_bf16 v[8:11], v[32:35], v[222:225], v[80:83]
	v_mfma_f32_16x16x32_bf16 v[116:119], v[36:39], v[226:229], v[8:11]
	v_mfma_f32_16x16x32_bf16 v[8:11], v[40:43], v[130:133], v[176:179]
	v_mfma_f32_16x16x32_bf16 v[88:91], v[44:47], v[218:221], v[8:11]
	v_mfma_f32_16x16x32_bf16 v[8:11], v[40:43], v[222:225], v[190:193]
	v_mfma_f32_16x16x32_bf16 v[120:123], v[12:15], v[218:221], v[92:95]
	v_mfma_f32_16x16x32_bf16 v[92:95], v[44:47], v[226:229], v[8:11]
	v_mfma_f32_16x16x32_bf16 v[8:11], v[238:241], v[130:133], v[194:197]
	v_mfma_f32_16x16x32_bf16 v[80:83], v[242:245], v[218:221], v[8:11]
	v_mfma_f32_16x16x32_bf16 v[8:11], v[238:241], v[222:225], v[198:201]
	v_mfma_f32_16x16x32_bf16 v[84:87], v[242:245], v[226:229], v[8:11]
	s_setprio 0
	s_barrier
	ds_read_b128 v[174:177], v172 offset:49152
	ds_read_b128 v[178:181], v172 offset:50176
	ds_read_b128 v[190:193], v171 offset:49152
	ds_read_b128 v[194:197], v171 offset:50176
	ds_read_b128 v[198:201], v170 offset:49152
	ds_read_b128 v[170:173], v170 offset:50176
	ds_read_b128 v[238:241], v169 offset:49152
	ds_read_b128 v[242:245], v169 offset:50176
	s_barrier
	s_waitcnt lgkmcnt(0)
	s_setprio 1
	s_waitcnt lgkmcnt(0)
	v_mfma_f32_16x16x32_bf16 v[8:11], v[174:177], v[0:3], v[60:63]
	v_mfma_f32_16x16x32_bf16 v[40:43], v[178:181], v[4:7], v[8:11]
	v_mfma_f32_16x16x32_bf16 v[8:11], v[174:177], v[210:213], v[56:59]
	v_mfma_f32_16x16x32_bf16 v[44:47], v[178:181], v[214:217], v[8:11]
	v_mfma_f32_16x16x32_bf16 v[8:11], v[190:193], v[0:3], v[52:55]
	v_mfma_f32_16x16x32_bf16 v[32:35], v[194:197], v[4:7], v[8:11]
	v_mfma_f32_16x16x32_bf16 v[8:11], v[190:193], v[210:213], v[48:51]
	v_mfma_f32_16x16x32_bf16 v[36:39], v[194:197], v[214:217], v[8:11]
	v_mfma_f32_16x16x32_bf16 v[8:11], v[198:201], v[0:3], v[230:233]
	v_mfma_f32_16x16x32_bf16 v[0:3], v[238:241], v[0:3], v[138:141]
	v_mfma_f32_16x16x32_bf16 v[8:11], v[170:173], v[4:7], v[8:11]
	v_mfma_f32_16x16x32_bf16 v[12:15], v[198:201], v[210:213], v[234:237]
	v_mfma_f32_16x16x32_bf16 v[0:3], v[242:245], v[4:7], v[0:3]
	v_mfma_f32_16x16x32_bf16 v[4:7], v[238:241], v[210:213], v[146:149]
	v_mfma_f32_16x16x32_bf16 v[12:15], v[170:173], v[214:217], v[12:15]
	v_mfma_f32_16x16x32_bf16 v[4:7], v[242:245], v[214:217], v[4:7]
	s_setprio 0
	s_setprio 1
	v_mfma_f32_16x16x32_bf16 v[16:19], v[190:193], v[222:225], v[16:19]
	v_mfma_f32_16x16x32_bf16 v[24:27], v[174:177], v[222:225], v[24:27]
	v_mfma_f32_16x16x32_bf16 v[52:55], v[194:197], v[226:229], v[16:19]
	v_mfma_f32_16x16x32_bf16 v[16:19], v[198:201], v[130:133], v[150:153]
	v_mfma_f32_16x16x32_bf16 v[28:31], v[174:177], v[130:133], v[28:31]
	v_mfma_f32_16x16x32_bf16 v[60:63], v[178:181], v[226:229], v[24:27]
	v_mfma_f32_16x16x32_bf16 v[20:23], v[190:193], v[130:133], v[20:23]
	v_mfma_f32_16x16x32_bf16 v[24:27], v[170:173], v[218:221], v[16:19]
	v_mfma_f32_16x16x32_bf16 v[16:19], v[198:201], v[222:225], v[154:157]
	v_mfma_f32_16x16x32_bf16 v[56:59], v[178:181], v[218:221], v[28:31]
	v_mfma_f32_16x16x32_bf16 v[48:51], v[194:197], v[218:221], v[20:23]
	v_mfma_f32_16x16x32_bf16 v[28:31], v[170:173], v[226:229], v[16:19]
	v_mfma_f32_16x16x32_bf16 v[16:19], v[238:241], v[130:133], v[202:205]
	v_mfma_f32_16x16x32_bf16 v[20:23], v[238:241], v[222:225], v[206:209]
	v_mfma_f32_16x16x32_bf16 v[16:19], v[242:245], v[218:221], v[16:19]
	v_mfma_f32_16x16x32_bf16 v[20:23], v[242:245], v[226:229], v[20:23]
	s_setprio 0
	v_cmp_gt_u32_e32 vcc, s88, v163
	s_barrier
	s_and_saveexec_b64 s[16:17], vcc
	s_cbranch_execz .LBB0_216
	s_barrier

.LBB0_228:
	s_or_b64 exec, exec, s[16:17]
	v_add_u32_e32 v175, s15, v3
	v_lshl_add_u64 v[6:7], s[90:91], 0, v[128:129]
	v_readfirstlane_b32 s11, v175
	v_add_u32_e32 v176, 0x2000, v175
	v_lshl_add_u64 v[8:9], v[6:7], 0, s[22:23]
	s_mov_b32 m0, s11
	s_mov_b64 s[16:17], 0x20080
	v_readfirstlane_b32 s11, v176
	v_add_u32_e32 v177, 0x8000, v161
	s_waitcnt vmcnt(0)
	s_barrier
	global_load_lds_dwordx4 v[8:9], off
	v_lshl_add_u64 v[8:9], v[6:7], 0, s[16:17]
	s_mov_b32 m0, s11
	v_lshl_add_u64 v[130:131], s[8:9], 0, v[128:129]
	v_readfirstlane_b32 s11, v177
	v_add_u32_e32 v178, 0xa000, v161
	global_load_lds_dwordx4 v[8:9], off
	v_lshl_add_u64 v[8:9], v[130:131], 0, s[22:23]
	s_mov_b32 m0, s11
	v_readfirstlane_b32 s11, v178
	v_add_u32_e32 v179, s36, v3
	global_load_lds_dwordx4 v[8:9], off
	v_lshl_add_u64 v[8:9], v[130:131], 0, s[16:17]
	s_mov_b32 m0, s11
	s_mov_b64 s[26:27], 0x40080
	v_readfirstlane_b32 s11, v179
	v_add_u32_e32 v181, 0x2000, v179
	global_load_lds_dwordx4 v[8:9], off
	v_lshl_add_u64 v[8:9], v[6:7], 0, s[26:27]
	s_mov_b32 m0, s11
	s_mov_b64 vcc, 0x60080
	v_readfirstlane_b32 s11, v181
	global_load_lds_dwordx4 v[8:9], off
	v_lshl_add_u64 v[6:7], v[6:7], 0, vcc
	s_mov_b32 m0, s11
	v_and_b32_e32 v162, 15, v165
	global_load_lds_dwordx4 v[6:7], off
	v_bfe_u32 v135, v165, 4, 2
	v_lshlrev_b32_e32 v167, 2, v165
	v_lshlrev_b32_e32 v14, 8, v165
	v_ashrrev_i32_e32 v166, 6, v165
	v_lshlrev_b32_e32 v5, 4, v135
	v_lshlrev_b32_e32 v6, 6, v162
	v_and_b32_e32 v7, 32, v167
	v_lshlrev_b32_e32 v12, 6, v165
	s_movk_i32 s11, 0x3c0
	v_and_b32_e32 v14, 0xffff8000, v14
	v_lshlrev_b32_e32 v0, 11, v0
	v_and_b32_e32 v164, 3, v166
	s_waitcnt vmcnt(6)
	v_bitop3_b32 v6, v5, v7, v6 bitop3:0x36
	v_lshlrev_b32_e32 v168, 6, v4
	v_lshlrev_b32_e32 v4, 13, v4
	v_and_or_b32 v5, v12, s11, v5
	v_or3_b32 v0, v1, v14, v0
	v_lshlrev_b32_e32 v3, 12, v164
	v_add_u32_e32 v8, s35, v6
	v_add_u32_e32 v9, s14, v6
	v_add_u32_e32 v10, s15, v6
	v_add_u32_e32 v11, s36, v6
	v_add_u32_e32 v6, 16, v6
	v_xad_u32 v5, v5, v7, 16
	v_or_b32_e32 v7, 0x800, v4
	v_or_b32_e32 v12, 0x1000, v4
	v_or_b32_e32 v13, 0x1800, v4
	v_add_u32_e32 v132, v0, v2
	s_add_u32 s80, s12, s70
	v_mov_b32_e32 v0, 0
	v_mov_b32_e32 v133, v129
	s_addc_u32 s81, s13, s71
	s_mov_b32 s11, -2
	v_add_u32_e32 v184, v8, v3
	v_add_u32_e32 v172, v6, v4
	v_add_u32_e32 v171, v5, v7
	v_add_u32_e32 v170, v5, v12
	v_add_u32_e32 v169, v5, v13
	v_add_u32_e32 v180, v9, v3
	v_add_u32_e32 v174, v10, v3
	v_add_u32_e32 v173, v11, v3
	v_mov_b32_e32 v1, v0
	v_mov_b32_e32 v2, v0
	v_mov_b32_e32 v3, v0
	v_mov_b32_e32 v4, v0
	v_mov_b32_e32 v5, v0
	v_mov_b32_e32 v6, v0
	v_mov_b32_e32 v7, v0
	v_mov_b32_e32 v8, v0
	v_mov_b32_e32 v9, v0
	v_mov_b32_e32 v10, v0
	v_mov_b32_e32 v11, v0
	v_mov_b32_e32 v12, v0
	v_mov_b32_e32 v13, v0
	v_mov_b32_e32 v14, v0
	v_mov_b32_e32 v15, v0
	v_mov_b32_e32 v16, v0
	v_mov_b32_e32 v17, v0
	v_mov_b32_e32 v18, v0
	v_mov_b32_e32 v19, v0
	v_mov_b32_e32 v20, v0
	v_mov_b32_e32 v21, v0
	v_mov_b32_e32 v22, v0
	v_mov_b32_e32 v23, v0
	v_mov_b32_e32 v24, v0
	v_mov_b32_e32 v25, v0
	v_mov_b32_e32 v26, v0
	v_mov_b32_e32 v27, v0
	v_mov_b32_e32 v28, v0
	v_mov_b32_e32 v29, v0
	v_mov_b32_e32 v30, v0
	v_mov_b32_e32 v31, v0
	v_mov_b32_e32 v32, v0
	v_mov_b32_e32 v33, v0
	v_mov_b32_e32 v34, v0
	v_mov_b32_e32 v35, v0
	v_mov_b32_e32 v36, v0
	v_mov_b32_e32 v37, v0
	v_mov_b32_e32 v38, v0
	v_mov_b32_e32 v39, v0
	v_mov_b32_e32 v40, v0
	v_mov_b32_e32 v41, v0
	v_mov_b32_e32 v42, v0
	v_mov_b32_e32 v43, v0
	v_mov_b32_e32 v44, v0
	v_mov_b32_e32 v45, v0
	v_mov_b32_e32 v46, v0
	v_mov_b32_e32 v47, v0
	v_mov_b32_e32 v48, v0
	v_mov_b32_e32 v49, v0
	v_mov_b32_e32 v50, v0
	v_mov_b32_e32 v51, v0
	v_mov_b32_e32 v52, v0
	v_mov_b32_e32 v53, v0
	v_mov_b32_e32 v54, v0
	v_mov_b32_e32 v55, v0
	v_mov_b32_e32 v56, v0
	v_mov_b32_e32 v57, v0
	v_mov_b32_e32 v58, v0
	v_mov_b32_e32 v59, v0
	v_mov_b32_e32 v60, v0
	v_mov_b32_e32 v61, v0
	v_mov_b32_e32 v62, v0
	v_mov_b32_e32 v63, v0
	v_mov_b32_e32 v64, v0
	v_mov_b32_e32 v65, v0
	v_mov_b32_e32 v66, v0
	v_mov_b32_e32 v67, v0
	v_mov_b32_e32 v68, v0
	v_mov_b32_e32 v69, v0
	v_mov_b32_e32 v70, v0
	v_mov_b32_e32 v71, v0
	v_mov_b32_e32 v72, v0
	v_mov_b32_e32 v73, v0
	v_mov_b32_e32 v74, v0
	v_mov_b32_e32 v75, v0
	v_mov_b32_e32 v76, v0
	v_mov_b32_e32 v77, v0
	v_mov_b32_e32 v78, v0
	v_mov_b32_e32 v79, v0
	v_mov_b32_e32 v80, v0
	v_mov_b32_e32 v81, v0
	v_mov_b32_e32 v82, v0
	v_mov_b32_e32 v83, v0
	v_mov_b32_e32 v84, v0
	v_mov_b32_e32 v85, v0
	v_mov_b32_e32 v86, v0
	v_mov_b32_e32 v87, v0
	v_mov_b32_e32 v88, v0
	v_mov_b32_e32 v89, v0
	v_mov_b32_e32 v90, v0
	v_mov_b32_e32 v91, v0
	v_mov_b32_e32 v92, v0
	v_mov_b32_e32 v93, v0
	v_mov_b32_e32 v94, v0
	v_mov_b32_e32 v95, v0
	v_mov_b32_e32 v96, v0
	v_mov_b32_e32 v97, v0
	v_mov_b32_e32 v98, v0
	v_mov_b32_e32 v99, v0
	v_mov_b32_e32 v100, v0
	v_mov_b32_e32 v101, v0
	v_mov_b32_e32 v102, v0
	v_mov_b32_e32 v103, v0
	v_mov_b32_e32 v104, v0
	v_mov_b32_e32 v105, v0
	v_mov_b32_e32 v106, v0
	v_mov_b32_e32 v107, v0
	v_mov_b32_e32 v108, v0
	v_mov_b32_e32 v109, v0
	v_mov_b32_e32 v110, v0
	v_mov_b32_e32 v111, v0
	v_mov_b32_e32 v112, v0
	v_mov_b32_e32 v113, v0
	v_mov_b32_e32 v114, v0
	v_mov_b32_e32 v115, v0
	v_mov_b32_e32 v116, v0
	v_mov_b32_e32 v117, v0
	v_mov_b32_e32 v118, v0
	v_mov_b32_e32 v119, v0
	v_mov_b32_e32 v120, v0
	v_mov_b32_e32 v121, v0
	v_mov_b32_e32 v122, v0
	v_mov_b32_e32 v123, v0
	v_mov_b32_e32 v124, v0
	v_mov_b32_e32 v125, v0
	v_mov_b32_e32 v126, v0
	v_mov_b32_e32 v127, v0
.Lkh_229:
	s_barrier
.LBB0_229:
	ds_read_b128 v[138:141], v184
	ds_read_b128 v[146:149], v184 offset:1024
	ds_read_b128 v[150:153], v184 offset:2048
	ds_read_b128 v[154:157], v184 offset:3072
	v_add_u32_e32 v187, 0xc000, v161
	v_lshl_add_u64 v[238:239], s[8:9], 0, v[132:133]
	v_readfirstlane_b32 s16, v187
	v_lshl_add_u64 v[188:189], v[238:239], 0, s[26:27]
	s_mov_b32 m0, s16
	ds_read_b128 v[190:193], v172
	ds_read_b128 v[194:197], v172 offset:1024
	ds_read_b128 v[198:201], v171
	ds_read_b128 v[202:205], v171 offset:1024
	ds_read_b128 v[206:209], v170
	ds_read_b128 v[210:213], v170 offset:1024
	ds_read_b128 v[214:217], v169
	ds_read_b128 v[218:221], v169 offset:1024
	global_load_lds_dwordx4 v[188:189], off
	v_add_u32_e32 v188, 0xe000, v161
	v_lshl_add_u64 v[222:223], v[238:239], 0, vcc
	v_readfirstlane_b32 s16, v188
	s_mov_b32 m0, s16
	s_nop 0
	global_load_lds_dwordx4 v[222:223], off
	s_waitcnt lgkmcnt(8)
	s_barrier
	s_waitcnt lgkmcnt(0)
	s_setprio 1
	s_waitcnt lgkmcnt(0)
	v_mfma_f32_16x16x32_bf16 v[124:127], v[190:193], v[138:141], v[124:127]
	v_mfma_f32_16x16x32_bf16 v[120:123], v[190:193], v[150:153], v[120:123]
	v_mfma_f32_16x16x32_bf16 v[116:119], v[198:201], v[138:141], v[116:119]
	v_mfma_f32_16x16x32_bf16 v[112:115], v[198:201], v[150:153], v[112:115]
	v_mfma_f32_16x16x32_bf16 v[108:111], v[206:209], v[138:141], v[108:111]
	v_mfma_f32_16x16x32_bf16 v[104:107], v[206:209], v[150:153], v[104:107]
	v_mfma_f32_16x16x32_bf16 v[100:103], v[214:217], v[138:141], v[100:103]
	v_mfma_f32_16x16x32_bf16 v[96:99], v[214:217], v[150:153], v[96:99]
	v_mfma_f32_16x16x32_bf16 v[124:127], v[194:197], v[146:149], v[124:127]
	v_mfma_f32_16x16x32_bf16 v[120:123], v[194:197], v[154:157], v[120:123]
	v_mfma_f32_16x16x32_bf16 v[116:119], v[202:205], v[146:149], v[116:119]
	v_mfma_f32_16x16x32_bf16 v[112:115], v[202:205], v[154:157], v[112:115]
	v_mfma_f32_16x16x32_bf16 v[108:111], v[210:213], v[146:149], v[108:111]
	v_mfma_f32_16x16x32_bf16 v[104:107], v[210:213], v[154:157], v[104:107]
	v_mfma_f32_16x16x32_bf16 v[100:103], v[218:221], v[146:149], v[100:103]
	v_mfma_f32_16x16x32_bf16 v[96:99], v[218:221], v[154:157], v[96:99]
	s_setprio 0
	s_barrier
	v_lshl_add_u64 v[240:241], s[80:81], 0, v[132:133]
	v_readfirstlane_b32 s16, v163
	v_add_u32_e32 v185, 0x2000, v163
	v_lshl_add_u64 v[242:243], v[240:241], 0, s[44:45]
	s_mov_b32 m0, s16
	v_readfirstlane_b32 s16, v185
	ds_read_b128 v[222:225], v180
	ds_read_b128 v[226:229], v180 offset:1024
	ds_read_b128 v[230:233], v180 offset:2048
	ds_read_b128 v[234:237], v180 offset:3072
	global_load_lds_dwordx4 v[242:243], off
	v_lshl_add_u64 v[242:243], v[240:241], 0, s[46:47]
	s_mov_b32 m0, s16
	s_nop 0
	global_load_lds_dwordx4 v[242:243], off
	s_barrier
	s_waitcnt lgkmcnt(0)
	s_setprio 1
	s_waitcnt lgkmcnt(0)
	v_mfma_f32_16x16x32_bf16 v[92:95], v[190:193], v[222:225], v[92:95]
	v_mfma_f32_16x16x32_bf16 v[88:91], v[190:193], v[230:233], v[88:91]
	v_mfma_f32_16x16x32_bf16 v[84:87], v[198:201], v[222:225], v[84:87]
	v_mfma_f32_16x16x32_bf16 v[80:83], v[198:201], v[230:233], v[80:83]
	v_mfma_f32_16x16x32_bf16 v[76:79], v[206:209], v[222:225], v[76:79]
	v_mfma_f32_16x16x32_bf16 v[72:75], v[206:209], v[230:233], v[72:75]
	v_mfma_f32_16x16x32_bf16 v[68:71], v[214:217], v[222:225], v[68:71]
	v_mfma_f32_16x16x32_bf16 v[64:67], v[214:217], v[230:233], v[64:67]
	v_mfma_f32_16x16x32_bf16 v[92:95], v[194:197], v[226:229], v[92:95]
	v_mfma_f32_16x16x32_bf16 v[88:91], v[194:197], v[234:237], v[88:91]
	v_mfma_f32_16x16x32_bf16 v[84:87], v[202:205], v[226:229], v[84:87]
	v_mfma_f32_16x16x32_bf16 v[80:83], v[202:205], v[234:237], v[80:83]
	v_mfma_f32_16x16x32_bf16 v[76:79], v[210:213], v[226:229], v[76:79]
	v_mfma_f32_16x16x32_bf16 v[72:75], v[210:213], v[234:237], v[72:75]
	v_mfma_f32_16x16x32_bf16 v[68:71], v[218:221], v[226:229], v[68:71]
	v_mfma_f32_16x16x32_bf16 v[64:67], v[218:221], v[234:237], v[64:67]
	s_setprio 0
	v_readfirstlane_b32 s16, v161
	v_lshl_add_u64 v[242:243], v[238:239], 0, s[40:41]
	s_mov_b32 m0, s16
	v_readfirstlane_b32 s16, v160
	s_barrier
	ds_read_b128 v[190:193], v172 offset:16384
	ds_read_b128 v[194:197], v172 offset:17408
	ds_read_b128 v[198:201], v171 offset:16384
	ds_read_b128 v[202:205], v171 offset:17408
	ds_read_b128 v[206:209], v170 offset:16384
	ds_read_b128 v[210:213], v170 offset:17408
	ds_read_b128 v[214:217], v169 offset:16384
	ds_read_b128 v[218:221], v169 offset:17408
	global_load_lds_dwordx4 v[242:243], off
	v_lshl_add_u64 v[242:243], v[238:239], 0, s[42:43]
	s_mov_b32 m0, s16
	s_nop 0
	global_load_lds_dwordx4 v[242:243], off
	s_barrier
	s_waitcnt lgkmcnt(0)
	s_setprio 1
	s_waitcnt lgkmcnt(0)
	v_mfma_f32_16x16x32_bf16 v[60:63], v[190:193], v[138:141], v[60:63]
	v_mfma_f32_16x16x32_bf16 v[56:59], v[190:193], v[150:153], v[56:59]
	v_mfma_f32_16x16x32_bf16 v[52:55], v[198:201], v[138:141], v[52:55]
	v_mfma_f32_16x16x32_bf16 v[48:51], v[198:201], v[150:153], v[48:51]
	v_mfma_f32_16x16x32_bf16 v[44:47], v[206:209], v[138:141], v[44:47]
	v_mfma_f32_16x16x32_bf16 v[40:43], v[206:209], v[150:153], v[40:43]
	v_mfma_f32_16x16x32_bf16 v[36:39], v[214:217], v[138:141], v[36:39]
	v_mfma_f32_16x16x32_bf16 v[32:35], v[214:217], v[150:153], v[32:35]
	v_mfma_f32_16x16x32_bf16 v[60:63], v[194:197], v[146:149], v[60:63]
	v_mfma_f32_16x16x32_bf16 v[56:59], v[194:197], v[154:157], v[56:59]
	v_mfma_f32_16x16x32_bf16 v[52:55], v[202:205], v[146:149], v[52:55]
	v_mfma_f32_16x16x32_bf16 v[48:51], v[202:205], v[154:157], v[48:51]
	v_mfma_f32_16x16x32_bf16 v[44:47], v[210:213], v[146:149], v[44:47]
	v_mfma_f32_16x16x32_bf16 v[40:43], v[210:213], v[154:157], v[40:43]
	v_mfma_f32_16x16x32_bf16 v[36:39], v[218:221], v[146:149], v[36:39]
	v_mfma_f32_16x16x32_bf16 v[32:35], v[218:221], v[154:157], v[32:35]
	s_setprio 0
	s_barrier
	v_readfirstlane_b32 s16, v137
	v_add_u32_e32 v186, 0x2000, v137
	v_lshl_add_u64 v[138:139], v[240:241], 0, s[52:53]
	s_mov_b32 m0, s16
	v_readfirstlane_b32 s16, v186
	global_load_lds_dwordx4 v[138:139], off
	v_lshl_add_u64 v[138:139], v[240:241], 0, s[54:55]
	s_mov_b32 m0, s16
	s_nop 0
	global_load_lds_dwordx4 v[138:139], off
	s_waitcnt vmcnt(6)
	s_barrier
	s_setprio 1
	v_mfma_f32_16x16x32_bf16 v[28:31], v[190:193], v[222:225], v[28:31]
	v_mfma_f32_16x16x32_bf16 v[24:27], v[190:193], v[230:233], v[24:27]
	v_mfma_f32_16x16x32_bf16 v[20:23], v[198:201], v[222:225], v[20:23]
	v_mfma_f32_16x16x32_bf16 v[16:19], v[198:201], v[230:233], v[16:19]
	v_mfma_f32_16x16x32_bf16 v[12:15], v[206:209], v[222:225], v[12:15]
	v_mfma_f32_16x16x32_bf16 v[8:11], v[206:209], v[230:233], v[8:11]
	v_mfma_f32_16x16x32_bf16 v[4:7], v[214:217], v[222:225], v[4:7]
	v_mfma_f32_16x16x32_bf16 v[0:3], v[214:217], v[230:233], v[0:3]
	v_mfma_f32_16x16x32_bf16 v[28:31], v[194:197], v[226:229], v[28:31]
	v_mfma_f32_16x16x32_bf16 v[24:27], v[194:197], v[234:237], v[24:27]
	v_mfma_f32_16x16x32_bf16 v[20:23], v[202:205], v[226:229], v[20:23]
	v_mfma_f32_16x16x32_bf16 v[16:19], v[202:205], v[234:237], v[16:19]
	v_mfma_f32_16x16x32_bf16 v[12:15], v[210:213], v[226:229], v[12:15]
	v_mfma_f32_16x16x32_bf16 v[8:11], v[210:213], v[234:237], v[8:11]
	v_mfma_f32_16x16x32_bf16 v[4:7], v[218:221], v[226:229], v[4:7]
	v_mfma_f32_16x16x32_bf16 v[0:3], v[218:221], v[234:237], v[0:3]
	s_setprio 0
	s_barrier
	ds_read_b128 v[138:141], v174
	ds_read_b128 v[146:149], v174 offset:1024
	ds_read_b128 v[150:153], v174 offset:2048
	ds_read_b128 v[154:157], v174 offset:3072
	v_readfirstlane_b32 s16, v136
	v_lshl_add_u64 v[222:223], v[238:239], 0, s[48:49]
	s_mov_b32 m0, s16
	v_readfirstlane_b32 s16, v134
	ds_read_b128 v[190:193], v172 offset:32768
	ds_read_b128 v[194:197], v172 offset:33792
	ds_read_b128 v[198:201], v171 offset:32768
	ds_read_b128 v[202:205], v171 offset:33792
	ds_read_b128 v[206:209], v170 offset:32768
	ds_read_b128 v[210:213], v170 offset:33792
	ds_read_b128 v[214:217], v169 offset:32768
	ds_read_b128 v[218:221], v169 offset:33792
	global_load_lds_dwordx4 v[222:223], off
	v_lshl_add_u64 v[222:223], v[238:239], 0, s[50:51]
	s_mov_b32 m0, s16
	s_nop 0
	global_load_lds_dwordx4 v[222:223], off
	s_waitcnt lgkmcnt(8)
	s_barrier
	s_waitcnt lgkmcnt(0)
	s_setprio 1
	s_waitcnt lgkmcnt(0)
	v_mfma_f32_16x16x32_bf16 v[124:127], v[190:193], v[138:141], v[124:127]
	v_mfma_f32_16x16x32_bf16 v[120:123], v[190:193], v[150:153], v[120:123]
	v_mfma_f32_16x16x32_bf16 v[116:119], v[198:201], v[138:141], v[116:119]
	v_mfma_f32_16x16x32_bf16 v[112:115], v[198:201], v[150:153], v[112:115]
	v_mfma_f32_16x16x32_bf16 v[108:111], v[206:209], v[138:141], v[108:111]
	v_mfma_f32_16x16x32_bf16 v[104:107], v[206:209], v[150:153], v[104:107]
	v_mfma_f32_16x16x32_bf16 v[100:103], v[214:217], v[138:141], v[100:103]
	v_mfma_f32_16x16x32_bf16 v[96:99], v[214:217], v[150:153], v[96:99]
	v_mfma_f32_16x16x32_bf16 v[124:127], v[194:197], v[146:149], v[124:127]
	v_mfma_f32_16x16x32_bf16 v[120:123], v[194:197], v[154:157], v[120:123]
	v_mfma_f32_16x16x32_bf16 v[116:119], v[202:205], v[146:149], v[116:119]
	v_mfma_f32_16x16x32_bf16 v[112:115], v[202:205], v[154:157], v[112:115]
	v_mfma_f32_16x16x32_bf16 v[108:111], v[210:213], v[146:149], v[108:111]
	v_mfma_f32_16x16x32_bf16 v[104:107], v[210:213], v[154:157], v[104:107]
	v_mfma_f32_16x16x32_bf16 v[100:103], v[218:221], v[146:149], v[100:103]
	v_mfma_f32_16x16x32_bf16 v[96:99], v[218:221], v[154:157], v[96:99]
	s_setprio 0
	s_barrier
	v_readfirstlane_b32 s16, v175
	v_lshl_add_u64 v[242:243], v[240:241], 0, s[60:61]
	s_mov_b32 m0, s16
	v_readfirstlane_b32 s16, v176
	ds_read_b128 v[222:225], v173
	ds_read_b128 v[226:229], v173 offset:1024
	ds_read_b128 v[230:233], v173 offset:2048
	ds_read_b128 v[234:237], v173 offset:3072
	global_load_lds_dwordx4 v[242:243], off
	v_lshl_add_u64 v[242:243], v[240:241], 0, s[62:63]
	s_mov_b32 m0, s16
	s_nop 0
	global_load_lds_dwordx4 v[242:243], off
	s_barrier
	s_waitcnt lgkmcnt(0)
	s_setprio 1
	s_waitcnt lgkmcnt(0)
	v_mfma_f32_16x16x32_bf16 v[92:95], v[190:193], v[222:225], v[92:95]
	v_mfma_f32_16x16x32_bf16 v[88:91], v[190:193], v[230:233], v[88:91]
	v_mfma_f32_16x16x32_bf16 v[84:87], v[198:201], v[222:225], v[84:87]
	v_mfma_f32_16x16x32_bf16 v[80:83], v[198:201], v[230:233], v[80:83]
	v_mfma_f32_16x16x32_bf16 v[76:79], v[206:209], v[222:225], v[76:79]
	v_mfma_f32_16x16x32_bf16 v[72:75], v[206:209], v[230:233], v[72:75]
	v_mfma_f32_16x16x32_bf16 v[68:71], v[214:217], v[222:225], v[68:71]
	v_mfma_f32_16x16x32_bf16 v[64:67], v[214:217], v[230:233], v[64:67]
	v_mfma_f32_16x16x32_bf16 v[92:95], v[194:197], v[226:229], v[92:95]
	v_mfma_f32_16x16x32_bf16 v[88:91], v[194:197], v[234:237], v[88:91]
	v_mfma_f32_16x16x32_bf16 v[84:87], v[202:205], v[226:229], v[84:87]
	v_mfma_f32_16x16x32_bf16 v[80:83], v[202:205], v[234:237], v[80:83]
	v_mfma_f32_16x16x32_bf16 v[76:79], v[210:213], v[226:229], v[76:79]
	v_mfma_f32_16x16x32_bf16 v[72:75], v[210:213], v[234:237], v[72:75]
	v_mfma_f32_16x16x32_bf16 v[68:71], v[218:221], v[226:229], v[68:71]
	v_mfma_f32_16x16x32_bf16 v[64:67], v[218:221], v[234:237], v[64:67]
	s_setprio 0
	v_readfirstlane_b32 s16, v177
	v_lshl_add_u64 v[242:243], v[238:239], 0, s[56:57]
	s_mov_b32 m0, s16
	v_readfirstlane_b32 s16, v178
	s_barrier
	ds_read_b128 v[190:193], v172 offset:49152
	ds_read_b128 v[194:197], v172 offset:50176
	ds_read_b128 v[198:201], v171 offset:49152
	ds_read_b128 v[202:205], v171 offset:50176
	ds_read_b128 v[206:209], v170 offset:49152
	ds_read_b128 v[210:213], v170 offset:50176
	ds_read_b128 v[214:217], v169 offset:49152
	ds_read_b128 v[218:221], v169 offset:50176
	global_load_lds_dwordx4 v[242:243], off
	v_lshl_add_u64 v[238:239], v[238:239], 0, s[58:59]
	s_mov_b32 m0, s16
	s_nop 0
	global_load_lds_dwordx4 v[238:239], off
	s_barrier
	s_waitcnt lgkmcnt(0)
	s_setprio 1
	s_waitcnt lgkmcnt(0)
	v_mfma_f32_16x16x32_bf16 v[60:63], v[190:193], v[138:141], v[60:63]
	v_mfma_f32_16x16x32_bf16 v[56:59], v[190:193], v[150:153], v[56:59]
	v_mfma_f32_16x16x32_bf16 v[52:55], v[198:201], v[138:141], v[52:55]
	v_mfma_f32_16x16x32_bf16 v[48:51], v[198:201], v[150:153], v[48:51]
	v_mfma_f32_16x16x32_bf16 v[44:47], v[206:209], v[138:141], v[44:47]
	v_mfma_f32_16x16x32_bf16 v[40:43], v[206:209], v[150:153], v[40:43]
	v_mfma_f32_16x16x32_bf16 v[36:39], v[214:217], v[138:141], v[36:39]
	v_mfma_f32_16x16x32_bf16 v[32:35], v[214:217], v[150:153], v[32:35]
	v_mfma_f32_16x16x32_bf16 v[60:63], v[194:197], v[146:149], v[60:63]
	v_mfma_f32_16x16x32_bf16 v[56:59], v[194:197], v[154:157], v[56:59]
	v_mfma_f32_16x16x32_bf16 v[52:55], v[202:205], v[146:149], v[52:55]
	v_mfma_f32_16x16x32_bf16 v[48:51], v[202:205], v[154:157], v[48:51]
	v_mfma_f32_16x16x32_bf16 v[44:47], v[210:213], v[146:149], v[44:47]
	v_mfma_f32_16x16x32_bf16 v[40:43], v[210:213], v[154:157], v[40:43]
	v_mfma_f32_16x16x32_bf16 v[36:39], v[218:221], v[146:149], v[36:39]
	v_mfma_f32_16x16x32_bf16 v[32:35], v[218:221], v[154:157], v[32:35]
	s_setprio 0
	s_barrier
	s_mov_b64 s[16:17], 0x366c280
	v_lshl_add_u64 v[138:139], v[240:241], 0, s[16:17]
	v_readfirstlane_b32 s16, v179
	s_mov_b32 m0, s16
	s_mov_b64 s[16:17], 0x368c280
	global_load_lds_dwordx4 v[138:139], off
	v_lshl_add_u64 v[138:139], v[240:241], 0, s[16:17]
	v_readfirstlane_b32 s16, v181
	s_mov_b32 m0, s16
	s_nop 0
	global_load_lds_dwordx4 v[138:139], off
	s_waitcnt vmcnt(6)
	s_barrier
	s_setprio 1
	v_mfma_f32_16x16x32_bf16 v[28:31], v[190:193], v[222:225], v[28:31]
	v_mfma_f32_16x16x32_bf16 v[24:27], v[190:193], v[230:233], v[24:27]
	v_mfma_f32_16x16x32_bf16 v[20:23], v[198:201], v[222:225], v[20:23]
	v_mfma_f32_16x16x32_bf16 v[16:19], v[198:201], v[230:233], v[16:19]
	v_mfma_f32_16x16x32_bf16 v[12:15], v[206:209], v[222:225], v[12:15]
	v_mfma_f32_16x16x32_bf16 v[8:11], v[206:209], v[230:233], v[8:11]
	v_mfma_f32_16x16x32_bf16 v[4:7], v[214:217], v[222:225], v[4:7]
	v_mfma_f32_16x16x32_bf16 v[0:3], v[214:217], v[230:233], v[0:3]
	v_mfma_f32_16x16x32_bf16 v[28:31], v[194:197], v[226:229], v[28:31]
	v_mfma_f32_16x16x32_bf16 v[24:27], v[194:197], v[234:237], v[24:27]
	v_mfma_f32_16x16x32_bf16 v[20:23], v[202:205], v[226:229], v[20:23]
	v_mfma_f32_16x16x32_bf16 v[16:19], v[202:205], v[234:237], v[16:19]
	v_mfma_f32_16x16x32_bf16 v[12:15], v[210:213], v[226:229], v[12:15]
	v_mfma_f32_16x16x32_bf16 v[8:11], v[210:213], v[234:237], v[8:11]
	v_mfma_f32_16x16x32_bf16 v[4:7], v[218:221], v[226:229], v[4:7]
	v_mfma_f32_16x16x32_bf16 v[0:3], v[218:221], v[234:237], v[0:3]
	s_setprio 0
	s_add_i32 s11, s11, 2
	s_add_u32 s80, s80, 0x100
	s_addc_u32 s81, s81, 0
	s_add_u32 s8, s8, 0x100
	s_addc_u32 s9, s9, 0
	s_cmp_lt_u32 s11, 12
	s_cbranch_scc1 .Lkh_229
	s_barrier
	s_mov_b64 s[8:9], 0x40780
	v_lshl_add_u64 v[132:133], v[130:131], 0, s[8:9]
	v_readfirstlane_b32 s8, v187
	s_mov_b32 m0, s8
	s_mov_b64 s[8:9], 0x60780
	v_lshl_add_u64 v[130:131], v[130:131], 0, s[8:9]
	v_readfirstlane_b32 s8, v188
	ds_read_b128 v[138:141], v184
	ds_read_b128 v[146:149], v184 offset:1024
	ds_read_b128 v[150:153], v184 offset:2048
	ds_read_b128 v[154:157], v184 offset:3072
	ds_read_b128 v[176:179], v172
	ds_read_b128 v[190:193], v172 offset:1024
	ds_read_b128 v[194:197], v171
	ds_read_b128 v[198:201], v171 offset:1024
	ds_read_b128 v[202:205], v170
	ds_read_b128 v[206:209], v170 offset:1024
	ds_read_b128 v[210:213], v169
	ds_read_b128 v[214:217], v169 offset:1024
	global_load_lds_dwordx4 v[132:133], off
	s_mov_b32 m0, s8
	s_nop 0
	global_load_lds_dwordx4 v[130:131], off
	s_barrier
	s_waitcnt lgkmcnt(0)
	s_setprio 1
	s_waitcnt lgkmcnt(0)
	v_mfma_f32_16x16x32_bf16 v[124:127], v[176:179], v[138:141], v[124:127]
	v_mfma_f32_16x16x32_bf16 v[120:123], v[176:179], v[150:153], v[120:123]
	v_mfma_f32_16x16x32_bf16 v[116:119], v[194:197], v[138:141], v[116:119]
	v_mfma_f32_16x16x32_bf16 v[112:115], v[194:197], v[150:153], v[112:115]
	v_mfma_f32_16x16x32_bf16 v[124:127], v[190:193], v[146:149], v[124:127]
	v_mfma_f32_16x16x32_bf16 v[120:123], v[190:193], v[154:157], v[120:123]
	v_mfma_f32_16x16x32_bf16 v[116:119], v[198:201], v[146:149], v[116:119]
	v_mfma_f32_16x16x32_bf16 v[112:115], v[198:201], v[154:157], v[112:115]
	v_mfma_f32_16x16x32_bf16 v[108:111], v[202:205], v[138:141], v[108:111]
	v_mfma_f32_16x16x32_bf16 v[104:107], v[202:205], v[150:153], v[104:107]
	v_mfma_f32_16x16x32_bf16 v[100:103], v[210:213], v[138:141], v[100:103]
	v_mfma_f32_16x16x32_bf16 v[96:99], v[210:213], v[150:153], v[96:99]
	v_mfma_f32_16x16x32_bf16 v[130:133], v[206:209], v[146:149], v[108:111]
	v_mfma_f32_16x16x32_bf16 v[218:221], v[206:209], v[154:157], v[104:107]
	v_mfma_f32_16x16x32_bf16 v[222:225], v[214:217], v[146:149], v[100:103]
	v_mfma_f32_16x16x32_bf16 v[226:229], v[214:217], v[154:157], v[96:99]
	s_setprio 0
	s_barrier
	s_nop 1
	ds_read_b128 v[96:99], v180
	ds_read_b128 v[100:103], v180 offset:1024
	ds_read_b128 v[104:107], v180 offset:2048
	ds_read_b128 v[108:111], v180 offset:3072
	s_barrier
	s_waitcnt lgkmcnt(0)
	s_setprio 1
	s_waitcnt lgkmcnt(0)
	v_mfma_f32_16x16x32_bf16 v[92:95], v[176:179], v[96:99], v[92:95]
	v_mfma_f32_16x16x32_bf16 v[88:91], v[176:179], v[104:107], v[88:91]
	v_mfma_f32_16x16x32_bf16 v[84:87], v[194:197], v[96:99], v[84:87]
	v_mfma_f32_16x16x32_bf16 v[80:83], v[194:197], v[104:107], v[80:83]
	v_mfma_f32_16x16x32_bf16 v[92:95], v[190:193], v[100:103], v[92:95]
	v_mfma_f32_16x16x32_bf16 v[88:91], v[190:193], v[108:111], v[88:91]
	v_mfma_f32_16x16x32_bf16 v[84:87], v[198:201], v[100:103], v[84:87]
	v_mfma_f32_16x16x32_bf16 v[80:83], v[198:201], v[108:111], v[80:83]
	v_mfma_f32_16x16x32_bf16 v[76:79], v[202:205], v[96:99], v[76:79]
	v_mfma_f32_16x16x32_bf16 v[72:75], v[202:205], v[104:107], v[72:75]
	v_mfma_f32_16x16x32_bf16 v[68:71], v[210:213], v[96:99], v[68:71]
	v_mfma_f32_16x16x32_bf16 v[64:67], v[210:213], v[104:107], v[64:67]
	v_mfma_f32_16x16x32_bf16 v[176:179], v[206:209], v[100:103], v[76:79]
	v_mfma_f32_16x16x32_bf16 v[188:191], v[206:209], v[108:111], v[72:75]
	v_mfma_f32_16x16x32_bf16 v[192:195], v[214:217], v[100:103], v[68:71]
	v_mfma_f32_16x16x32_bf16 v[196:199], v[214:217], v[108:111], v[64:67]
	s_setprio 0
	s_barrier
	s_nop 1
	ds_read_b128 v[64:67], v172 offset:16384
	ds_read_b128 v[68:71], v172 offset:17408
	ds_read_b128 v[72:75], v171 offset:16384
	ds_read_b128 v[76:79], v171 offset:17408
	ds_read_b128 v[200:203], v170 offset:16384
	ds_read_b128 v[204:207], v170 offset:17408
	ds_read_b128 v[208:211], v169 offset:16384
	ds_read_b128 v[212:215], v169 offset:17408
	s_waitcnt vmcnt(4)
	s_barrier
	s_waitcnt lgkmcnt(0)
	s_setprio 1
	s_waitcnt lgkmcnt(0)
	v_mfma_f32_16x16x32_bf16 v[60:63], v[64:67], v[138:141], v[60:63]
	v_mfma_f32_16x16x32_bf16 v[56:59], v[64:67], v[150:153], v[56:59]
	v_mfma_f32_16x16x32_bf16 v[52:55], v[72:75], v[138:141], v[52:55]
	v_mfma_f32_16x16x32_bf16 v[48:51], v[72:75], v[150:153], v[48:51]
	v_mfma_f32_16x16x32_bf16 v[60:63], v[68:71], v[146:149], v[60:63]
	v_mfma_f32_16x16x32_bf16 v[56:59], v[68:71], v[154:157], v[56:59]
	v_mfma_f32_16x16x32_bf16 v[52:55], v[76:79], v[146:149], v[52:55]
	v_mfma_f32_16x16x32_bf16 v[48:51], v[76:79], v[154:157], v[48:51]
	v_mfma_f32_16x16x32_bf16 v[44:47], v[200:203], v[138:141], v[44:47]
	v_mfma_f32_16x16x32_bf16 v[40:43], v[200:203], v[150:153], v[40:43]
	v_mfma_f32_16x16x32_bf16 v[36:39], v[208:211], v[138:141], v[36:39]
	v_mfma_f32_16x16x32_bf16 v[32:35], v[208:211], v[150:153], v[32:35]
	v_mfma_f32_16x16x32_bf16 v[230:233], v[204:207], v[146:149], v[44:47]
	v_mfma_f32_16x16x32_bf16 v[234:237], v[204:207], v[154:157], v[40:43]
	v_mfma_f32_16x16x32_bf16 v[138:141], v[212:215], v[146:149], v[36:39]
	v_mfma_f32_16x16x32_bf16 v[146:149], v[212:215], v[154:157], v[32:35]
	s_setprio 0
	s_setprio 1
	v_mfma_f32_16x16x32_bf16 v[28:31], v[64:67], v[96:99], v[28:31]
	v_mfma_f32_16x16x32_bf16 v[24:27], v[64:67], v[104:107], v[24:27]
	v_mfma_f32_16x16x32_bf16 v[20:23], v[72:75], v[96:99], v[20:23]
	v_mfma_f32_16x16x32_bf16 v[16:19], v[72:75], v[104:107], v[16:19]
	v_mfma_f32_16x16x32_bf16 v[28:31], v[68:71], v[100:103], v[28:31]
	v_mfma_f32_16x16x32_bf16 v[24:27], v[68:71], v[108:111], v[24:27]
	v_mfma_f32_16x16x32_bf16 v[20:23], v[76:79], v[100:103], v[20:23]
	v_mfma_f32_16x16x32_bf16 v[16:19], v[76:79], v[108:111], v[16:19]
	v_mfma_f32_16x16x32_bf16 v[12:15], v[200:203], v[96:99], v[12:15]
	v_mfma_f32_16x16x32_bf16 v[8:11], v[200:203], v[104:107], v[8:11]
	v_mfma_f32_16x16x32_bf16 v[4:7], v[208:211], v[96:99], v[4:7]
	v_mfma_f32_16x16x32_bf16 v[0:3], v[208:211], v[104:107], v[0:3]
	v_mfma_f32_16x16x32_bf16 v[150:153], v[204:207], v[100:103], v[12:15]
	v_mfma_f32_16x16x32_bf16 v[154:157], v[204:207], v[108:111], v[8:11]
	v_mfma_f32_16x16x32_bf16 v[200:203], v[212:215], v[100:103], v[4:7]
	v_mfma_f32_16x16x32_bf16 v[204:207], v[212:215], v[108:111], v[0:3]
	s_setprio 0
	s_barrier
	s_nop 1
	ds_read_b128 v[0:3], v174
	ds_read_b128 v[4:7], v174 offset:1024
	ds_read_b128 v[208:211], v174 offset:2048
	ds_read_b128 v[212:215], v174 offset:3072
	ds_read_b128 v[8:11], v172 offset:32768
	ds_read_b128 v[12:15], v172 offset:33792
	ds_read_b128 v[32:35], v171 offset:32768
	ds_read_b128 v[36:39], v171 offset:33792
	ds_read_b128 v[40:43], v170 offset:32768
	ds_read_b128 v[44:47], v170 offset:33792
	ds_read_b128 v[238:241], v169 offset:32768
	ds_read_b128 v[242:245], v169 offset:33792
	s_waitcnt vmcnt(2)
	s_barrier
	s_waitcnt lgkmcnt(0)
	s_setprio 1
	s_waitcnt lgkmcnt(0)
	v_mfma_f32_16x16x32_bf16 v[64:67], v[8:11], v[0:3], v[124:127]
	v_mfma_f32_16x16x32_bf16 v[104:107], v[12:15], v[4:7], v[64:67]
	v_mfma_f32_16x16x32_bf16 v[64:67], v[8:11], v[208:211], v[120:123]
	v_mfma_f32_16x16x32_bf16 v[108:111], v[12:15], v[212:215], v[64:67]
	v_mfma_f32_16x16x32_bf16 v[64:67], v[32:35], v[0:3], v[116:119]
	v_mfma_f32_16x16x32_bf16 v[96:99], v[36:39], v[4:7], v[64:67]
	v_mfma_f32_16x16x32_bf16 v[64:67], v[32:35], v[208:211], v[112:115]
	v_mfma_f32_16x16x32_bf16 v[100:103], v[36:39], v[212:215], v[64:67]
	v_mfma_f32_16x16x32_bf16 v[64:67], v[40:43], v[0:3], v[130:133]
	v_mfma_f32_16x16x32_bf16 v[72:75], v[44:47], v[4:7], v[64:67]
	v_mfma_f32_16x16x32_bf16 v[64:67], v[40:43], v[208:211], v[218:221]
	v_mfma_f32_16x16x32_bf16 v[76:79], v[44:47], v[212:215], v[64:67]
	v_mfma_f32_16x16x32_bf16 v[64:67], v[238:241], v[0:3], v[222:225]
	v_mfma_f32_16x16x32_bf16 v[68:71], v[238:241], v[208:211], v[226:229]
	v_mfma_f32_16x16x32_bf16 v[64:67], v[242:245], v[4:7], v[64:67]
	v_mfma_f32_16x16x32_bf16 v[68:71], v[242:245], v[212:215], v[68:71]
	s_setprio 0
	s_barrier
	ds_read_b128 v[130:133], v173
	ds_read_b128 v[216:219], v173 offset:1024
	ds_read_b128 v[220:223], v173 offset:2048
	ds_read_b128 v[224:227], v173 offset:3072
	s_waitcnt vmcnt(0)
	s_barrier
	s_waitcnt lgkmcnt(0)
	s_setprio 1
	s_waitcnt lgkmcnt(0)
	v_mfma_f32_16x16x32_bf16 v[92:95], v[8:11], v[130:133], v[92:95]
	v_mfma_f32_16x16x32_bf16 v[8:11], v[8:11], v[220:223], v[88:91]
	v_mfma_f32_16x16x32_bf16 v[124:127], v[12:15], v[224:227], v[8:11]
	v_mfma_f32_16x16x32_bf16 v[8:11], v[32:35], v[130:133], v[84:87]
	v_mfma_f32_16x16x32_bf16 v[112:115], v[36:39], v[216:219], v[8:11]
	v_mfma_f32_16x16x32_bf16 v[8:11], v[32:35], v[220:223], v[80:83]
	v_mfma_f32_16x16x32_bf16 v[116:119], v[36:39], v[224:227], v[8:11]
	v_mfma_f32_16x16x32_bf16 v[8:11], v[40:43], v[130:133], v[176:179]
	v_mfma_f32_16x16x32_bf16 v[88:91], v[44:47], v[216:219], v[8:11]
	v_mfma_f32_16x16x32_bf16 v[8:11], v[40:43], v[220:223], v[188:191]
	v_mfma_f32_16x16x32_bf16 v[120:123], v[12:15], v[216:219], v[92:95]
	v_mfma_f32_16x16x32_bf16 v[92:95], v[44:47], v[224:227], v[8:11]
	v_mfma_f32_16x16x32_bf16 v[8:11], v[238:241], v[130:133], v[192:195]
	v_mfma_f32_16x16x32_bf16 v[80:83], v[242:245], v[216:219], v[8:11]
	v_mfma_f32_16x16x32_bf16 v[8:11], v[238:241], v[220:223], v[196:199]
	v_mfma_f32_16x16x32_bf16 v[84:87], v[242:245], v[224:227], v[8:11]
	s_setprio 0
	s_barrier
	ds_read_b128 v[174:177], v172 offset:49152
	ds_read_b128 v[178:181], v172 offset:50176
	ds_read_b128 v[188:191], v171 offset:49152
	ds_read_b128 v[192:195], v171 offset:50176
	ds_read_b128 v[196:199], v170 offset:49152
	ds_read_b128 v[170:173], v170 offset:50176
	ds_read_b128 v[238:241], v169 offset:49152
	ds_read_b128 v[242:245], v169 offset:50176
	s_barrier
	s_waitcnt lgkmcnt(0)
	s_setprio 1
	s_waitcnt lgkmcnt(0)
	v_mfma_f32_16x16x32_bf16 v[8:11], v[174:177], v[0:3], v[60:63]
	v_mfma_f32_16x16x32_bf16 v[40:43], v[178:181], v[4:7], v[8:11]
	v_mfma_f32_16x16x32_bf16 v[8:11], v[174:177], v[208:211], v[56:59]
	v_mfma_f32_16x16x32_bf16 v[44:47], v[178:181], v[212:215], v[8:11]
	v_mfma_f32_16x16x32_bf16 v[8:11], v[188:191], v[0:3], v[52:55]
	v_mfma_f32_16x16x32_bf16 v[32:35], v[192:195], v[4:7], v[8:11]
	v_mfma_f32_16x16x32_bf16 v[8:11], v[188:191], v[208:211], v[48:51]
	v_mfma_f32_16x16x32_bf16 v[36:39], v[192:195], v[212:215], v[8:11]
	v_mfma_f32_16x16x32_bf16 v[8:11], v[196:199], v[0:3], v[230:233]
	v_mfma_f32_16x16x32_bf16 v[0:3], v[238:241], v[0:3], v[138:141]
	v_mfma_f32_16x16x32_bf16 v[8:11], v[170:173], v[4:7], v[8:11]
	v_mfma_f32_16x16x32_bf16 v[12:15], v[196:199], v[208:211], v[234:237]
	v_mfma_f32_16x16x32_bf16 v[0:3], v[242:245], v[4:7], v[0:3]
	v_mfma_f32_16x16x32_bf16 v[4:7], v[238:241], v[208:211], v[146:149]
	v_mfma_f32_16x16x32_bf16 v[12:15], v[170:173], v[212:215], v[12:15]
	v_mfma_f32_16x16x32_bf16 v[4:7], v[242:245], v[212:215], v[4:7]
	s_setprio 0
	s_setprio 1
	v_mfma_f32_16x16x32_bf16 v[16:19], v[188:191], v[220:223], v[16:19]
	v_mfma_f32_16x16x32_bf16 v[24:27], v[174:177], v[220:223], v[24:27]
	v_mfma_f32_16x16x32_bf16 v[52:55], v[192:195], v[224:227], v[16:19]
	v_mfma_f32_16x16x32_bf16 v[16:19], v[196:199], v[130:133], v[150:153]
	v_mfma_f32_16x16x32_bf16 v[28:31], v[174:177], v[130:133], v[28:31]
	v_mfma_f32_16x16x32_bf16 v[60:63], v[178:181], v[224:227], v[24:27]
	v_mfma_f32_16x16x32_bf16 v[20:23], v[188:191], v[130:133], v[20:23]
	v_mfma_f32_16x16x32_bf16 v[24:27], v[170:173], v[216:219], v[16:19]
	v_mfma_f32_16x16x32_bf16 v[16:19], v[196:199], v[220:223], v[154:157]
	v_mfma_f32_16x16x32_bf16 v[56:59], v[178:181], v[216:219], v[28:31]
	v_mfma_f32_16x16x32_bf16 v[48:51], v[192:195], v[216:219], v[20:23]
	v_mfma_f32_16x16x32_bf16 v[28:31], v[170:173], v[224:227], v[16:19]
	v_mfma_f32_16x16x32_bf16 v[16:19], v[238:241], v[130:133], v[200:203]
	v_mfma_f32_16x16x32_bf16 v[20:23], v[238:241], v[220:223], v[204:207]
	v_mfma_f32_16x16x32_bf16 v[16:19], v[242:245], v[216:219], v[16:19]
	v_mfma_f32_16x16x32_bf16 v[20:23], v[242:245], v[224:227], v[20:23]
	s_setprio 0
	v_cmp_gt_u32_e32 vcc, s88, v165
	s_barrier
	s_and_saveexec_b64 s[8:9], vcc
	s_cbranch_execz .LBB0_232
	s_barrier

.LBB0_240:
	s_or_b64 exec, exec, s[8:9]
	v_add_u32_e32 v179, s15, v3
	v_lshl_add_u64 v[6:7], s[68:69], 0, v[128:129]
	v_readfirstlane_b32 s8, v179
	v_add_u32_e32 v180, 0x2000, v179
	v_lshl_add_u64 v[8:9], v[6:7], 0, s[22:23]
	s_mov_b32 m0, s8
	s_mov_b64 s[16:17], 0x20080
	v_readfirstlane_b32 s8, v180
	v_add_u32_e32 v181, 0x8000, v168
	s_waitcnt vmcnt(0)
	s_barrier
	global_load_lds_dwordx4 v[8:9], off
	v_lshl_add_u64 v[8:9], v[6:7], 0, s[16:17]
	s_mov_b32 m0, s8
	v_lshl_add_u64 v[134:135], s[90:91], 0, v[128:129]
	v_readfirstlane_b32 s8, v181
	v_add_u32_e32 v184, 0xa000, v168
	global_load_lds_dwordx4 v[8:9], off
	v_lshl_add_u64 v[8:9], v[134:135], 0, s[22:23]
	s_mov_b32 m0, s8
	v_readfirstlane_b32 s8, v184
	global_load_lds_dwordx4 v[8:9], off
	v_lshl_add_u64 v[8:9], v[134:135], 0, s[16:17]
	s_mov_b32 m0, s8
	s_mov_b64 s[8:9], 0x40080
	v_add_u32_e32 v185, s36, v3
	global_load_lds_dwordx4 v[8:9], off
	v_lshl_add_u64 v[8:9], v[6:7], 0, s[8:9]
	v_readfirstlane_b32 s8, v185
	s_mov_b32 m0, s8
	s_mov_b64 s[8:9], 0x60080
	v_add_u32_e32 v187, 0x2000, v185
	v_lshl_add_u64 v[6:7], v[6:7], 0, s[8:9]
	v_readfirstlane_b32 s8, v187
	global_load_lds_dwordx4 v[8:9], off
	s_mov_b32 m0, s8
	v_and_b32_e32 v163, 15, v133
	global_load_lds_dwordx4 v[6:7], off
	v_bfe_u32 v162, v133, 4, 2
	v_lshlrev_b32_e32 v172, 2, v133
	v_lshlrev_b32_e32 v14, 8, v133
	v_ashrrev_i32_e32 v171, 6, v133
	v_lshlrev_b32_e32 v5, 4, v162
	v_lshlrev_b32_e32 v6, 6, v163
	v_and_b32_e32 v7, 32, v172
	v_lshlrev_b32_e32 v130, 6, v4
	v_lshlrev_b32_e32 v12, 6, v133
	s_movk_i32 s8, 0x3c0
	v_and_b32_e32 v14, 0xffff8000, v14
	v_lshlrev_b32_e32 v0, 11, v0
	v_and_b32_e32 v169, 3, v171
	s_waitcnt vmcnt(6)
	v_bitop3_b32 v6, v5, v7, v6 bitop3:0x36
	v_lshlrev_b32_e32 v4, 13, v4
	v_and_or_b32 v5, v12, s8, v5
	v_or_b32_e32 v132, 32, v130
	v_or3_b32 v0, v1, v14, v0
	v_lshlrev_b32_e32 v3, 12, v169
	v_add_u32_e32 v8, s35, v6
	v_add_u32_e32 v9, s14, v6
	v_add_u32_e32 v10, s15, v6
	v_add_u32_e32 v11, s36, v6
	v_add_u32_e32 v6, 16, v6
	v_xad_u32 v5, v5, v7, 16
	v_or_b32_e32 v7, 0x800, v4
	v_lshlrev_b32_e32 v12, 7, v132
	v_or_b32_e32 v13, 0x1800, v4
	v_add_u32_e32 v136, v0, v2
	s_add_u32 s8, s12, s70
	v_mov_b32_e32 v0, 0
	v_mov_b32_e32 v137, v129
	s_addc_u32 s9, s13, s71
	s_mov_b32 s11, -2
	v_add_u32_e32 v188, v8, v3
	v_add_u32_e32 v176, v6, v4
	v_add_u32_e32 v175, v5, v7
	v_add_u32_e32 v174, v5, v12
	v_add_u32_e32 v173, v5, v13
	v_add_u32_e32 v186, v9, v3
	v_add_u32_e32 v178, v10, v3
	v_add_u32_e32 v177, v11, v3
	s_mov_b64 s[80:81], s[68:69]
	v_mov_b32_e32 v1, v0
	v_mov_b32_e32 v2, v0
	v_mov_b32_e32 v3, v0
	v_mov_b32_e32 v4, v0
	v_mov_b32_e32 v5, v0
	v_mov_b32_e32 v6, v0
	v_mov_b32_e32 v7, v0
	v_mov_b32_e32 v8, v0
	v_mov_b32_e32 v9, v0
	v_mov_b32_e32 v10, v0
	v_mov_b32_e32 v11, v0
	v_mov_b32_e32 v12, v0
	v_mov_b32_e32 v13, v0
	v_mov_b32_e32 v14, v0
	v_mov_b32_e32 v15, v0
	v_mov_b32_e32 v16, v0
	v_mov_b32_e32 v17, v0
	v_mov_b32_e32 v18, v0
	v_mov_b32_e32 v19, v0
	v_mov_b32_e32 v20, v0
	v_mov_b32_e32 v21, v0
	v_mov_b32_e32 v22, v0
	v_mov_b32_e32 v23, v0
	v_mov_b32_e32 v24, v0
	v_mov_b32_e32 v25, v0
	v_mov_b32_e32 v26, v0
	v_mov_b32_e32 v27, v0
	v_mov_b32_e32 v28, v0
	v_mov_b32_e32 v29, v0
	v_mov_b32_e32 v30, v0
	v_mov_b32_e32 v31, v0
	v_mov_b32_e32 v32, v0
	v_mov_b32_e32 v33, v0
	v_mov_b32_e32 v34, v0
	v_mov_b32_e32 v35, v0
	v_mov_b32_e32 v36, v0
	v_mov_b32_e32 v37, v0
	v_mov_b32_e32 v38, v0
	v_mov_b32_e32 v39, v0
	v_mov_b32_e32 v40, v0
	v_mov_b32_e32 v41, v0
	v_mov_b32_e32 v42, v0
	v_mov_b32_e32 v43, v0
	v_mov_b32_e32 v44, v0
	v_mov_b32_e32 v45, v0
	v_mov_b32_e32 v46, v0
	v_mov_b32_e32 v47, v0
	v_mov_b32_e32 v48, v0
	v_mov_b32_e32 v49, v0
	v_mov_b32_e32 v50, v0
	v_mov_b32_e32 v51, v0
	v_mov_b32_e32 v52, v0
	v_mov_b32_e32 v53, v0
	v_mov_b32_e32 v54, v0
	v_mov_b32_e32 v55, v0
	v_mov_b32_e32 v56, v0
	v_mov_b32_e32 v57, v0
	v_mov_b32_e32 v58, v0
	v_mov_b32_e32 v59, v0
	v_mov_b32_e32 v60, v0
	v_mov_b32_e32 v61, v0
	v_mov_b32_e32 v62, v0
	v_mov_b32_e32 v63, v0
	v_mov_b32_e32 v64, v0
	v_mov_b32_e32 v65, v0
	v_mov_b32_e32 v66, v0
	v_mov_b32_e32 v67, v0
	v_mov_b32_e32 v68, v0
	v_mov_b32_e32 v69, v0
	v_mov_b32_e32 v70, v0
	v_mov_b32_e32 v71, v0
	v_mov_b32_e32 v72, v0
	v_mov_b32_e32 v73, v0
	v_mov_b32_e32 v74, v0
	v_mov_b32_e32 v75, v0
	v_mov_b32_e32 v76, v0
	v_mov_b32_e32 v77, v0
	v_mov_b32_e32 v78, v0
	v_mov_b32_e32 v79, v0
	v_mov_b32_e32 v80, v0
	v_mov_b32_e32 v81, v0
	v_mov_b32_e32 v82, v0
	v_mov_b32_e32 v83, v0
	v_mov_b32_e32 v84, v0
	v_mov_b32_e32 v85, v0
	v_mov_b32_e32 v86, v0
	v_mov_b32_e32 v87, v0
	v_mov_b32_e32 v88, v0
	v_mov_b32_e32 v89, v0
	v_mov_b32_e32 v90, v0
	v_mov_b32_e32 v91, v0
	v_mov_b32_e32 v92, v0
	v_mov_b32_e32 v93, v0
	v_mov_b32_e32 v94, v0
	v_mov_b32_e32 v95, v0
	v_mov_b32_e32 v96, v0
	v_mov_b32_e32 v97, v0
	v_mov_b32_e32 v98, v0
	v_mov_b32_e32 v99, v0
	v_mov_b32_e32 v100, v0
	v_mov_b32_e32 v101, v0
	v_mov_b32_e32 v102, v0
	v_mov_b32_e32 v103, v0
	v_mov_b32_e32 v104, v0
	v_mov_b32_e32 v105, v0
	v_mov_b32_e32 v106, v0
	v_mov_b32_e32 v107, v0
	v_mov_b32_e32 v108, v0
	v_mov_b32_e32 v109, v0
	v_mov_b32_e32 v110, v0
	v_mov_b32_e32 v111, v0
	v_mov_b32_e32 v112, v0
	v_mov_b32_e32 v113, v0
	v_mov_b32_e32 v114, v0
	v_mov_b32_e32 v115, v0
	v_mov_b32_e32 v116, v0
	v_mov_b32_e32 v117, v0
	v_mov_b32_e32 v118, v0
	v_mov_b32_e32 v119, v0
	v_mov_b32_e32 v120, v0
	v_mov_b32_e32 v121, v0
	v_mov_b32_e32 v122, v0
	v_mov_b32_e32 v123, v0
	v_mov_b32_e32 v124, v0
	v_mov_b32_e32 v125, v0
	v_mov_b32_e32 v126, v0
	v_mov_b32_e32 v127, v0
.Lkh_241:
	s_barrier
.LBB0_241:
	ds_read_b128 v[138:141], v188
	ds_read_b128 v[146:149], v188 offset:1024
	ds_read_b128 v[150:153], v188 offset:2048
	ds_read_b128 v[154:157], v188 offset:3072
	v_add_u32_e32 v191, 0xc000, v168
	v_lshl_add_u64 v[242:243], s[8:9], 0, v[136:137]
	v_readfirstlane_b32 s16, v191
	v_lshl_add_u64 v[192:193], v[242:243], 0, s[30:31]
	s_mov_b32 m0, s16
	ds_read_b128 v[194:197], v176
	ds_read_b128 v[198:201], v176 offset:1024
	ds_read_b128 v[202:205], v175
	ds_read_b128 v[206:209], v175 offset:1024
	ds_read_b128 v[210:213], v174
	ds_read_b128 v[214:217], v174 offset:1024
	ds_read_b128 v[218:221], v173
	ds_read_b128 v[222:225], v173 offset:1024
	global_load_lds_dwordx4 v[192:193], off
	v_add_u32_e32 v192, 0xe000, v168
	v_lshl_add_u64 v[226:227], v[242:243], 0, s[38:39]
	v_readfirstlane_b32 s16, v192
	s_mov_b32 m0, s16
	s_nop 0
	global_load_lds_dwordx4 v[226:227], off
	s_waitcnt lgkmcnt(8)
	s_barrier
	s_waitcnt lgkmcnt(0)
	s_setprio 1
	s_waitcnt lgkmcnt(0)
	v_mfma_f32_16x16x32_bf16 v[124:127], v[194:197], v[138:141], v[124:127]
	v_mfma_f32_16x16x32_bf16 v[120:123], v[194:197], v[150:153], v[120:123]
	v_mfma_f32_16x16x32_bf16 v[116:119], v[202:205], v[138:141], v[116:119]
	v_mfma_f32_16x16x32_bf16 v[112:115], v[202:205], v[150:153], v[112:115]
	v_mfma_f32_16x16x32_bf16 v[108:111], v[210:213], v[138:141], v[108:111]
	v_mfma_f32_16x16x32_bf16 v[104:107], v[210:213], v[150:153], v[104:107]
	v_mfma_f32_16x16x32_bf16 v[100:103], v[218:221], v[138:141], v[100:103]
	v_mfma_f32_16x16x32_bf16 v[96:99], v[218:221], v[150:153], v[96:99]
	v_mfma_f32_16x16x32_bf16 v[124:127], v[198:201], v[146:149], v[124:127]
	v_mfma_f32_16x16x32_bf16 v[120:123], v[198:201], v[154:157], v[120:123]
	v_mfma_f32_16x16x32_bf16 v[116:119], v[206:209], v[146:149], v[116:119]
	v_mfma_f32_16x16x32_bf16 v[112:115], v[206:209], v[154:157], v[112:115]
	v_mfma_f32_16x16x32_bf16 v[108:111], v[214:217], v[146:149], v[108:111]
	v_mfma_f32_16x16x32_bf16 v[104:107], v[214:217], v[154:157], v[104:107]
	v_mfma_f32_16x16x32_bf16 v[100:103], v[222:225], v[146:149], v[100:103]
	v_mfma_f32_16x16x32_bf16 v[96:99], v[222:225], v[154:157], v[96:99]
	s_setprio 0
	s_barrier
	v_lshl_add_u64 v[244:245], s[80:81], 0, v[136:137]
	v_readfirstlane_b32 s16, v170
	v_add_u32_e32 v189, 0x2000, v170
	v_lshl_add_u64 v[246:247], v[244:245], 0, s[40:41]
	s_mov_b32 m0, s16
	v_readfirstlane_b32 s16, v189
	ds_read_b128 v[226:229], v186
	ds_read_b128 v[230:233], v186 offset:1024
	ds_read_b128 v[234:237], v186 offset:2048
	ds_read_b128 v[238:241], v186 offset:3072
	global_load_lds_dwordx4 v[246:247], off
	v_lshl_add_u64 v[246:247], v[244:245], 0, s[42:43]
	s_mov_b32 m0, s16
	s_nop 0
	global_load_lds_dwordx4 v[246:247], off
	s_barrier
	s_waitcnt lgkmcnt(0)
	s_setprio 1
	s_waitcnt lgkmcnt(0)
	v_mfma_f32_16x16x32_bf16 v[92:95], v[194:197], v[226:229], v[92:95]
	v_mfma_f32_16x16x32_bf16 v[88:91], v[194:197], v[234:237], v[88:91]
	v_mfma_f32_16x16x32_bf16 v[84:87], v[202:205], v[226:229], v[84:87]
	v_mfma_f32_16x16x32_bf16 v[80:83], v[202:205], v[234:237], v[80:83]
	v_mfma_f32_16x16x32_bf16 v[76:79], v[210:213], v[226:229], v[76:79]
	v_mfma_f32_16x16x32_bf16 v[72:75], v[210:213], v[234:237], v[72:75]
	v_mfma_f32_16x16x32_bf16 v[68:71], v[218:221], v[226:229], v[68:71]
	v_mfma_f32_16x16x32_bf16 v[64:67], v[218:221], v[234:237], v[64:67]
	v_mfma_f32_16x16x32_bf16 v[92:95], v[198:201], v[230:233], v[92:95]
	v_mfma_f32_16x16x32_bf16 v[88:91], v[198:201], v[238:241], v[88:91]
	v_mfma_f32_16x16x32_bf16 v[84:87], v[206:209], v[230:233], v[84:87]
	v_mfma_f32_16x16x32_bf16 v[80:83], v[206:209], v[238:241], v[80:83]
	v_mfma_f32_16x16x32_bf16 v[76:79], v[214:217], v[230:233], v[76:79]
	v_mfma_f32_16x16x32_bf16 v[72:75], v[214:217], v[238:241], v[72:75]
	v_mfma_f32_16x16x32_bf16 v[68:71], v[222:225], v[230:233], v[68:71]
	v_mfma_f32_16x16x32_bf16 v[64:67], v[222:225], v[238:241], v[64:67]
	s_setprio 0
	v_readfirstlane_b32 s16, v168
	v_lshl_add_u64 v[246:247], v[242:243], 0, s[44:45]
	s_mov_b32 m0, s16
	v_readfirstlane_b32 s16, v167
	s_barrier
	ds_read_b128 v[194:197], v176 offset:16384
	ds_read_b128 v[198:201], v176 offset:17408
	ds_read_b128 v[202:205], v175 offset:16384
	ds_read_b128 v[206:209], v175 offset:17408
	ds_read_b128 v[210:213], v174 offset:16384
	ds_read_b128 v[214:217], v174 offset:17408
	ds_read_b128 v[218:221], v173 offset:16384
	ds_read_b128 v[222:225], v173 offset:17408
	global_load_lds_dwordx4 v[246:247], off
	v_lshl_add_u64 v[246:247], v[242:243], 0, s[46:47]
	s_mov_b32 m0, s16
	s_nop 0
	global_load_lds_dwordx4 v[246:247], off
	s_barrier
	s_waitcnt lgkmcnt(0)
	s_setprio 1
	s_waitcnt lgkmcnt(0)
	v_mfma_f32_16x16x32_bf16 v[60:63], v[194:197], v[138:141], v[60:63]
	v_mfma_f32_16x16x32_bf16 v[56:59], v[194:197], v[150:153], v[56:59]
	v_mfma_f32_16x16x32_bf16 v[52:55], v[202:205], v[138:141], v[52:55]
	v_mfma_f32_16x16x32_bf16 v[48:51], v[202:205], v[150:153], v[48:51]
	v_mfma_f32_16x16x32_bf16 v[44:47], v[210:213], v[138:141], v[44:47]
	v_mfma_f32_16x16x32_bf16 v[40:43], v[210:213], v[150:153], v[40:43]
	v_mfma_f32_16x16x32_bf16 v[36:39], v[218:221], v[138:141], v[36:39]
	v_mfma_f32_16x16x32_bf16 v[32:35], v[218:221], v[150:153], v[32:35]
	v_mfma_f32_16x16x32_bf16 v[60:63], v[198:201], v[146:149], v[60:63]
	v_mfma_f32_16x16x32_bf16 v[56:59], v[198:201], v[154:157], v[56:59]
	v_mfma_f32_16x16x32_bf16 v[52:55], v[206:209], v[146:149], v[52:55]
	v_mfma_f32_16x16x32_bf16 v[48:51], v[206:209], v[154:157], v[48:51]
	v_mfma_f32_16x16x32_bf16 v[44:47], v[214:217], v[146:149], v[44:47]
	v_mfma_f32_16x16x32_bf16 v[40:43], v[214:217], v[154:157], v[40:43]
	v_mfma_f32_16x16x32_bf16 v[36:39], v[222:225], v[146:149], v[36:39]
	v_mfma_f32_16x16x32_bf16 v[32:35], v[222:225], v[154:157], v[32:35]
	s_setprio 0
	s_barrier
	v_readfirstlane_b32 s16, v166
	v_add_u32_e32 v190, 0x2000, v166
	v_lshl_add_u64 v[138:139], v[244:245], 0, s[48:49]
	s_mov_b32 m0, s16
	v_readfirstlane_b32 s16, v190
	global_load_lds_dwordx4 v[138:139], off
	v_lshl_add_u64 v[138:139], v[244:245], 0, s[50:51]
	s_mov_b32 m0, s16
	s_nop 0
	global_load_lds_dwordx4 v[138:139], off
	s_waitcnt vmcnt(6)
	s_barrier
	s_setprio 1
	v_mfma_f32_16x16x32_bf16 v[28:31], v[194:197], v[226:229], v[28:31]
	v_mfma_f32_16x16x32_bf16 v[24:27], v[194:197], v[234:237], v[24:27]
	v_mfma_f32_16x16x32_bf16 v[20:23], v[202:205], v[226:229], v[20:23]
	v_mfma_f32_16x16x32_bf16 v[16:19], v[202:205], v[234:237], v[16:19]
	v_mfma_f32_16x16x32_bf16 v[12:15], v[210:213], v[226:229], v[12:15]
	v_mfma_f32_16x16x32_bf16 v[8:11], v[210:213], v[234:237], v[8:11]
	v_mfma_f32_16x16x32_bf16 v[4:7], v[218:221], v[226:229], v[4:7]
	v_mfma_f32_16x16x32_bf16 v[0:3], v[218:221], v[234:237], v[0:3]
	v_mfma_f32_16x16x32_bf16 v[28:31], v[198:201], v[230:233], v[28:31]
	v_mfma_f32_16x16x32_bf16 v[24:27], v[198:201], v[238:241], v[24:27]
	v_mfma_f32_16x16x32_bf16 v[20:23], v[206:209], v[230:233], v[20:23]
	v_mfma_f32_16x16x32_bf16 v[16:19], v[206:209], v[238:241], v[16:19]
	v_mfma_f32_16x16x32_bf16 v[12:15], v[214:217], v[230:233], v[12:15]
	v_mfma_f32_16x16x32_bf16 v[8:11], v[214:217], v[238:241], v[8:11]
	v_mfma_f32_16x16x32_bf16 v[4:7], v[222:225], v[230:233], v[4:7]
	v_mfma_f32_16x16x32_bf16 v[0:3], v[222:225], v[238:241], v[0:3]
	s_setprio 0
	s_barrier
	ds_read_b128 v[138:141], v178
	ds_read_b128 v[146:149], v178 offset:1024
	ds_read_b128 v[150:153], v178 offset:2048
	ds_read_b128 v[154:157], v178 offset:3072
	v_readfirstlane_b32 s16, v165
	v_lshl_add_u64 v[226:227], v[242:243], 0, s[52:53]
	s_mov_b32 m0, s16
	v_readfirstlane_b32 s16, v164
	ds_read_b128 v[194:197], v176 offset:32768
	ds_read_b128 v[198:201], v176 offset:33792
	ds_read_b128 v[202:205], v175 offset:32768
	ds_read_b128 v[206:209], v175 offset:33792
	ds_read_b128 v[210:213], v174 offset:32768
	ds_read_b128 v[214:217], v174 offset:33792
	ds_read_b128 v[218:221], v173 offset:32768
	ds_read_b128 v[222:225], v173 offset:33792
	global_load_lds_dwordx4 v[226:227], off
	v_lshl_add_u64 v[226:227], v[242:243], 0, s[54:55]
	s_mov_b32 m0, s16
	s_nop 0
	global_load_lds_dwordx4 v[226:227], off
	s_waitcnt lgkmcnt(8)
	s_barrier
	s_waitcnt lgkmcnt(0)
	s_setprio 1
	s_waitcnt lgkmcnt(0)
	v_mfma_f32_16x16x32_bf16 v[124:127], v[194:197], v[138:141], v[124:127]
	v_mfma_f32_16x16x32_bf16 v[120:123], v[194:197], v[150:153], v[120:123]
	v_mfma_f32_16x16x32_bf16 v[116:119], v[202:205], v[138:141], v[116:119]
	v_mfma_f32_16x16x32_bf16 v[112:115], v[202:205], v[150:153], v[112:115]
	v_mfma_f32_16x16x32_bf16 v[108:111], v[210:213], v[138:141], v[108:111]
	v_mfma_f32_16x16x32_bf16 v[104:107], v[210:213], v[150:153], v[104:107]
	v_mfma_f32_16x16x32_bf16 v[100:103], v[218:221], v[138:141], v[100:103]
	v_mfma_f32_16x16x32_bf16 v[96:99], v[218:221], v[150:153], v[96:99]
	v_mfma_f32_16x16x32_bf16 v[124:127], v[198:201], v[146:149], v[124:127]
	v_mfma_f32_16x16x32_bf16 v[120:123], v[198:201], v[154:157], v[120:123]
	v_mfma_f32_16x16x32_bf16 v[116:119], v[206:209], v[146:149], v[116:119]
	v_mfma_f32_16x16x32_bf16 v[112:115], v[206:209], v[154:157], v[112:115]
	v_mfma_f32_16x16x32_bf16 v[108:111], v[214:217], v[146:149], v[108:111]
	v_mfma_f32_16x16x32_bf16 v[104:107], v[214:217], v[154:157], v[104:107]
	v_mfma_f32_16x16x32_bf16 v[100:103], v[222:225], v[146:149], v[100:103]
	v_mfma_f32_16x16x32_bf16 v[96:99], v[222:225], v[154:157], v[96:99]
	s_setprio 0
	s_barrier
	v_readfirstlane_b32 s16, v179
	v_lshl_add_u64 v[246:247], v[244:245], 0, s[56:57]
	s_mov_b32 m0, s16
	v_readfirstlane_b32 s16, v180
	ds_read_b128 v[226:229], v177
	ds_read_b128 v[230:233], v177 offset:1024
	ds_read_b128 v[234:237], v177 offset:2048
	ds_read_b128 v[238:241], v177 offset:3072
	global_load_lds_dwordx4 v[246:247], off
	v_lshl_add_u64 v[246:247], v[244:245], 0, s[58:59]
	s_mov_b32 m0, s16
	s_nop 0
	global_load_lds_dwordx4 v[246:247], off
	s_barrier
	s_waitcnt lgkmcnt(0)
	s_setprio 1
	s_waitcnt lgkmcnt(0)
	v_mfma_f32_16x16x32_bf16 v[92:95], v[194:197], v[226:229], v[92:95]
	v_mfma_f32_16x16x32_bf16 v[88:91], v[194:197], v[234:237], v[88:91]
	v_mfma_f32_16x16x32_bf16 v[84:87], v[202:205], v[226:229], v[84:87]
	v_mfma_f32_16x16x32_bf16 v[80:83], v[202:205], v[234:237], v[80:83]
	v_mfma_f32_16x16x32_bf16 v[76:79], v[210:213], v[226:229], v[76:79]
	v_mfma_f32_16x16x32_bf16 v[72:75], v[210:213], v[234:237], v[72:75]
	v_mfma_f32_16x16x32_bf16 v[68:71], v[218:221], v[226:229], v[68:71]
	v_mfma_f32_16x16x32_bf16 v[64:67], v[218:221], v[234:237], v[64:67]
	v_mfma_f32_16x16x32_bf16 v[92:95], v[198:201], v[230:233], v[92:95]
	v_mfma_f32_16x16x32_bf16 v[88:91], v[198:201], v[238:241], v[88:91]
	v_mfma_f32_16x16x32_bf16 v[84:87], v[206:209], v[230:233], v[84:87]
	v_mfma_f32_16x16x32_bf16 v[80:83], v[206:209], v[238:241], v[80:83]
	v_mfma_f32_16x16x32_bf16 v[76:79], v[214:217], v[230:233], v[76:79]
	v_mfma_f32_16x16x32_bf16 v[72:75], v[214:217], v[238:241], v[72:75]
	v_mfma_f32_16x16x32_bf16 v[68:71], v[222:225], v[230:233], v[68:71]
	v_mfma_f32_16x16x32_bf16 v[64:67], v[222:225], v[238:241], v[64:67]
	s_setprio 0
	v_readfirstlane_b32 s16, v181
	v_lshl_add_u64 v[246:247], v[242:243], 0, s[60:61]
	s_mov_b32 m0, s16
	v_readfirstlane_b32 s16, v184
	s_barrier
	ds_read_b128 v[194:197], v176 offset:49152
	ds_read_b128 v[198:201], v176 offset:50176
	ds_read_b128 v[202:205], v175 offset:49152
	ds_read_b128 v[206:209], v175 offset:50176
	ds_read_b128 v[210:213], v174 offset:49152
	ds_read_b128 v[214:217], v174 offset:50176
	ds_read_b128 v[218:221], v173 offset:49152
	ds_read_b128 v[222:225], v173 offset:50176
	global_load_lds_dwordx4 v[246:247], off
	v_lshl_add_u64 v[242:243], v[242:243], 0, s[62:63]
	s_mov_b32 m0, s16
	s_nop 0
	global_load_lds_dwordx4 v[242:243], off
	s_barrier
	s_waitcnt lgkmcnt(0)
	s_setprio 1
	s_waitcnt lgkmcnt(0)
	v_mfma_f32_16x16x32_bf16 v[60:63], v[194:197], v[138:141], v[60:63]
	v_mfma_f32_16x16x32_bf16 v[56:59], v[194:197], v[150:153], v[56:59]
	v_mfma_f32_16x16x32_bf16 v[52:55], v[202:205], v[138:141], v[52:55]
	v_mfma_f32_16x16x32_bf16 v[48:51], v[202:205], v[150:153], v[48:51]
	v_mfma_f32_16x16x32_bf16 v[44:47], v[210:213], v[138:141], v[44:47]
	v_mfma_f32_16x16x32_bf16 v[40:43], v[210:213], v[150:153], v[40:43]
	v_mfma_f32_16x16x32_bf16 v[36:39], v[218:221], v[138:141], v[36:39]
	v_mfma_f32_16x16x32_bf16 v[32:35], v[218:221], v[150:153], v[32:35]
	v_mfma_f32_16x16x32_bf16 v[60:63], v[198:201], v[146:149], v[60:63]
	v_mfma_f32_16x16x32_bf16 v[56:59], v[198:201], v[154:157], v[56:59]
	v_mfma_f32_16x16x32_bf16 v[52:55], v[206:209], v[146:149], v[52:55]
	v_mfma_f32_16x16x32_bf16 v[48:51], v[206:209], v[154:157], v[48:51]
	v_mfma_f32_16x16x32_bf16 v[44:47], v[214:217], v[146:149], v[44:47]
	v_mfma_f32_16x16x32_bf16 v[40:43], v[214:217], v[154:157], v[40:43]
	v_mfma_f32_16x16x32_bf16 v[36:39], v[222:225], v[146:149], v[36:39]
	v_mfma_f32_16x16x32_bf16 v[32:35], v[222:225], v[154:157], v[32:35]
	s_setprio 0
	s_barrier
	v_readfirstlane_b32 s16, v185
	v_lshl_add_u64 v[138:139], v[244:245], 0, s[64:65]
	s_mov_b32 m0, s16
	v_readfirstlane_b32 s16, v187
	global_load_lds_dwordx4 v[138:139], off
	v_lshl_add_u64 v[138:139], v[244:245], 0, s[66:67]
	s_mov_b32 m0, s16
	s_nop 0
	global_load_lds_dwordx4 v[138:139], off
	s_waitcnt vmcnt(6)
	s_barrier
	s_setprio 1
	v_mfma_f32_16x16x32_bf16 v[28:31], v[194:197], v[226:229], v[28:31]
	v_mfma_f32_16x16x32_bf16 v[24:27], v[194:197], v[234:237], v[24:27]
	v_mfma_f32_16x16x32_bf16 v[20:23], v[202:205], v[226:229], v[20:23]
	v_mfma_f32_16x16x32_bf16 v[16:19], v[202:205], v[234:237], v[16:19]
	v_mfma_f32_16x16x32_bf16 v[12:15], v[210:213], v[226:229], v[12:15]
	v_mfma_f32_16x16x32_bf16 v[8:11], v[210:213], v[234:237], v[8:11]
	v_mfma_f32_16x16x32_bf16 v[4:7], v[218:221], v[226:229], v[4:7]
	v_mfma_f32_16x16x32_bf16 v[0:3], v[218:221], v[234:237], v[0:3]
	v_mfma_f32_16x16x32_bf16 v[28:31], v[198:201], v[230:233], v[28:31]
	v_mfma_f32_16x16x32_bf16 v[24:27], v[198:201], v[238:241], v[24:27]
	v_mfma_f32_16x16x32_bf16 v[20:23], v[206:209], v[230:233], v[20:23]
	v_mfma_f32_16x16x32_bf16 v[16:19], v[206:209], v[238:241], v[16:19]
	v_mfma_f32_16x16x32_bf16 v[12:15], v[214:217], v[230:233], v[12:15]
	v_mfma_f32_16x16x32_bf16 v[8:11], v[214:217], v[238:241], v[8:11]
	v_mfma_f32_16x16x32_bf16 v[4:7], v[222:225], v[230:233], v[4:7]
	v_mfma_f32_16x16x32_bf16 v[0:3], v[222:225], v[238:241], v[0:3]
	s_setprio 0
	s_add_i32 s11, s11, 2
	s_add_u32 s8, s8, 0x100
	s_addc_u32 s9, s9, 0
	s_add_u32 s80, s80, 0x100
	s_addc_u32 s81, s81, 0
	s_cmp_lt_u32 s11, 12
	s_cbranch_scc1 .Lkh_241
	s_barrier
	s_mov_b64 s[8:9], 0x40780
	v_lshl_add_u64 v[140:141], v[134:135], 0, s[8:9]
	v_readfirstlane_b32 s8, v191
	s_mov_b32 m0, s8
	s_mov_b64 s[8:9], 0x60780
	v_lshl_add_u64 v[134:135], v[134:135], 0, s[8:9]
	v_readfirstlane_b32 s8, v192
	ds_read_b128 v[136:139], v188
	ds_read_b128 v[146:149], v188 offset:1024
	ds_read_b128 v[150:153], v188 offset:2048
	ds_read_b128 v[154:157], v188 offset:3072
	ds_read_b128 v[194:197], v176
	ds_read_b128 v[198:201], v176 offset:1024
	ds_read_b128 v[202:205], v175
	ds_read_b128 v[206:209], v175 offset:1024
	ds_read_b128 v[210:213], v174
	ds_read_b128 v[214:217], v174 offset:1024
	ds_read_b128 v[218:221], v173
	ds_read_b128 v[222:225], v173 offset:1024
	global_load_lds_dwordx4 v[140:141], off
	s_mov_b32 m0, s8
	s_nop 0
	global_load_lds_dwordx4 v[134:135], off
	s_barrier
	s_waitcnt lgkmcnt(0)
	s_setprio 1
	s_waitcnt lgkmcnt(0)
	v_mfma_f32_16x16x32_bf16 v[124:127], v[194:197], v[136:139], v[124:127]
	v_mfma_f32_16x16x32_bf16 v[120:123], v[194:197], v[150:153], v[120:123]
	v_mfma_f32_16x16x32_bf16 v[116:119], v[202:205], v[136:139], v[116:119]
	v_mfma_f32_16x16x32_bf16 v[112:115], v[202:205], v[150:153], v[112:115]
	v_mfma_f32_16x16x32_bf16 v[124:127], v[198:201], v[146:149], v[124:127]
	v_mfma_f32_16x16x32_bf16 v[120:123], v[198:201], v[154:157], v[120:123]
	v_mfma_f32_16x16x32_bf16 v[116:119], v[206:209], v[146:149], v[116:119]
	v_mfma_f32_16x16x32_bf16 v[112:115], v[206:209], v[154:157], v[112:115]
	v_mfma_f32_16x16x32_bf16 v[108:111], v[210:213], v[136:139], v[108:111]
	v_mfma_f32_16x16x32_bf16 v[104:107], v[210:213], v[150:153], v[104:107]
	v_mfma_f32_16x16x32_bf16 v[100:103], v[218:221], v[136:139], v[100:103]
	v_mfma_f32_16x16x32_bf16 v[96:99], v[218:221], v[150:153], v[96:99]
	v_mfma_f32_16x16x32_bf16 v[226:229], v[214:217], v[146:149], v[108:111]
	v_mfma_f32_16x16x32_bf16 v[230:233], v[214:217], v[154:157], v[104:107]
	v_mfma_f32_16x16x32_bf16 v[234:237], v[222:225], v[146:149], v[100:103]
	v_mfma_f32_16x16x32_bf16 v[238:241], v[222:225], v[154:157], v[96:99]
	s_setprio 0
	s_barrier
	s_nop 1
	ds_read_b128 v[96:99], v186
	ds_read_b128 v[100:103], v186 offset:1024
	ds_read_b128 v[104:107], v186 offset:2048
	ds_read_b128 v[108:111], v186 offset:3072
	s_barrier
	s_waitcnt lgkmcnt(0)
	s_setprio 1
	s_waitcnt lgkmcnt(0)
	v_mfma_f32_16x16x32_bf16 v[92:95], v[194:197], v[96:99], v[92:95]
	v_mfma_f32_16x16x32_bf16 v[88:91], v[194:197], v[104:107], v[88:91]
	v_mfma_f32_16x16x32_bf16 v[84:87], v[202:205], v[96:99], v[84:87]
	v_mfma_f32_16x16x32_bf16 v[80:83], v[202:205], v[104:107], v[80:83]
	v_mfma_f32_16x16x32_bf16 v[92:95], v[198:201], v[100:103], v[92:95]
	v_mfma_f32_16x16x32_bf16 v[88:91], v[198:201], v[108:111], v[88:91]
	v_mfma_f32_16x16x32_bf16 v[84:87], v[206:209], v[100:103], v[84:87]
	v_mfma_f32_16x16x32_bf16 v[80:83], v[206:209], v[108:111], v[80:83]
	v_mfma_f32_16x16x32_bf16 v[76:79], v[210:213], v[96:99], v[76:79]
	v_mfma_f32_16x16x32_bf16 v[72:75], v[210:213], v[104:107], v[72:75]
	v_mfma_f32_16x16x32_bf16 v[68:71], v[218:221], v[96:99], v[68:71]
	v_mfma_f32_16x16x32_bf16 v[64:67], v[218:221], v[104:107], v[64:67]
	v_mfma_f32_16x16x32_bf16 v[184:187], v[214:217], v[100:103], v[76:79]
	v_mfma_f32_16x16x32_bf16 v[192:195], v[214:217], v[108:111], v[72:75]
	v_mfma_f32_16x16x32_bf16 v[196:199], v[222:225], v[100:103], v[68:71]
	v_mfma_f32_16x16x32_bf16 v[200:203], v[222:225], v[108:111], v[64:67]
	s_setprio 0
	s_barrier
	s_nop 1
	ds_read_b128 v[64:67], v176 offset:16384
	ds_read_b128 v[68:71], v176 offset:17408
	ds_read_b128 v[72:75], v175 offset:16384
	ds_read_b128 v[76:79], v175 offset:17408
	ds_read_b128 v[204:207], v174 offset:16384
	ds_read_b128 v[208:211], v174 offset:17408
	ds_read_b128 v[212:215], v173 offset:16384
	ds_read_b128 v[216:219], v173 offset:17408
	s_waitcnt vmcnt(4)
	s_barrier
	s_waitcnt lgkmcnt(0)
	s_setprio 1
	s_waitcnt lgkmcnt(0)
	v_mfma_f32_16x16x32_bf16 v[60:63], v[64:67], v[136:139], v[60:63]
	v_mfma_f32_16x16x32_bf16 v[56:59], v[64:67], v[150:153], v[56:59]
	v_mfma_f32_16x16x32_bf16 v[52:55], v[72:75], v[136:139], v[52:55]
	v_mfma_f32_16x16x32_bf16 v[48:51], v[72:75], v[150:153], v[48:51]
	v_mfma_f32_16x16x32_bf16 v[60:63], v[68:71], v[146:149], v[60:63]
	v_mfma_f32_16x16x32_bf16 v[56:59], v[68:71], v[154:157], v[56:59]
	v_mfma_f32_16x16x32_bf16 v[52:55], v[76:79], v[146:149], v[52:55]
	v_mfma_f32_16x16x32_bf16 v[48:51], v[76:79], v[154:157], v[48:51]
	v_mfma_f32_16x16x32_bf16 v[44:47], v[204:207], v[136:139], v[44:47]
	v_mfma_f32_16x16x32_bf16 v[40:43], v[204:207], v[150:153], v[40:43]
	v_mfma_f32_16x16x32_bf16 v[36:39], v[212:215], v[136:139], v[36:39]
	v_mfma_f32_16x16x32_bf16 v[32:35], v[212:215], v[150:153], v[32:35]
	v_mfma_f32_16x16x32_bf16 v[220:223], v[208:211], v[146:149], v[44:47]
	v_mfma_f32_16x16x32_bf16 v[242:245], v[208:211], v[154:157], v[40:43]
	v_mfma_f32_16x16x32_bf16 v[134:137], v[216:219], v[146:149], v[36:39]
	v_mfma_f32_16x16x32_bf16 v[138:141], v[216:219], v[154:157], v[32:35]
	s_setprio 0
	s_setprio 1
	v_mfma_f32_16x16x32_bf16 v[28:31], v[64:67], v[96:99], v[28:31]
	v_mfma_f32_16x16x32_bf16 v[24:27], v[64:67], v[104:107], v[24:27]
	v_mfma_f32_16x16x32_bf16 v[20:23], v[72:75], v[96:99], v[20:23]
	v_mfma_f32_16x16x32_bf16 v[16:19], v[72:75], v[104:107], v[16:19]
	v_mfma_f32_16x16x32_bf16 v[28:31], v[68:71], v[100:103], v[28:31]
	v_mfma_f32_16x16x32_bf16 v[24:27], v[68:71], v[108:111], v[24:27]
	v_mfma_f32_16x16x32_bf16 v[20:23], v[76:79], v[100:103], v[20:23]
	v_mfma_f32_16x16x32_bf16 v[16:19], v[76:79], v[108:111], v[16:19]
	v_mfma_f32_16x16x32_bf16 v[12:15], v[204:207], v[96:99], v[12:15]
	v_mfma_f32_16x16x32_bf16 v[8:11], v[204:207], v[104:107], v[8:11]
	v_mfma_f32_16x16x32_bf16 v[4:7], v[212:215], v[96:99], v[4:7]
	v_mfma_f32_16x16x32_bf16 v[0:3], v[212:215], v[104:107], v[0:3]
	v_mfma_f32_16x16x32_bf16 v[146:149], v[208:211], v[100:103], v[12:15]
	v_mfma_f32_16x16x32_bf16 v[150:153], v[208:211], v[108:111], v[8:11]
	v_mfma_f32_16x16x32_bf16 v[154:157], v[216:219], v[100:103], v[4:7]
	v_mfma_f32_16x16x32_bf16 v[204:207], v[216:219], v[108:111], v[0:3]
	s_setprio 0
	s_barrier
	s_nop 1
	ds_read_b128 v[0:3], v178
	ds_read_b128 v[4:7], v178 offset:1024
	ds_read_b128 v[208:211], v178 offset:2048
	ds_read_b128 v[178:181], v178 offset:3072
	ds_read_b128 v[8:11], v176 offset:32768
	ds_read_b128 v[12:15], v176 offset:33792
	ds_read_b128 v[32:35], v175 offset:32768
	ds_read_b128 v[36:39], v175 offset:33792
	ds_read_b128 v[40:43], v174 offset:32768
	ds_read_b128 v[44:47], v174 offset:33792
	ds_read_b128 v[212:215], v173 offset:32768
	ds_read_b128 v[216:219], v173 offset:33792
	s_waitcnt vmcnt(2)
	s_barrier
	s_waitcnt lgkmcnt(0)
	s_setprio 1
	s_waitcnt lgkmcnt(0)
	v_mfma_f32_16x16x32_bf16 v[64:67], v[8:11], v[0:3], v[124:127]
	v_mfma_f32_16x16x32_bf16 v[104:107], v[12:15], v[4:7], v[64:67]
	v_mfma_f32_16x16x32_bf16 v[64:67], v[8:11], v[208:211], v[120:123]
	v_mfma_f32_16x16x32_bf16 v[108:111], v[12:15], v[178:181], v[64:67]
	v_mfma_f32_16x16x32_bf16 v[64:67], v[32:35], v[0:3], v[116:119]
	v_mfma_f32_16x16x32_bf16 v[96:99], v[36:39], v[4:7], v[64:67]
	v_mfma_f32_16x16x32_bf16 v[64:67], v[32:35], v[208:211], v[112:115]
	v_mfma_f32_16x16x32_bf16 v[100:103], v[36:39], v[178:181], v[64:67]
	v_mfma_f32_16x16x32_bf16 v[64:67], v[40:43], v[0:3], v[226:229]
	v_mfma_f32_16x16x32_bf16 v[72:75], v[44:47], v[4:7], v[64:67]
	v_mfma_f32_16x16x32_bf16 v[64:67], v[40:43], v[208:211], v[230:233]
	v_mfma_f32_16x16x32_bf16 v[76:79], v[44:47], v[178:181], v[64:67]
	v_mfma_f32_16x16x32_bf16 v[64:67], v[212:215], v[0:3], v[234:237]
	v_mfma_f32_16x16x32_bf16 v[68:71], v[212:215], v[208:211], v[238:241]
	v_mfma_f32_16x16x32_bf16 v[64:67], v[216:219], v[4:7], v[64:67]
	v_mfma_f32_16x16x32_bf16 v[68:71], v[216:219], v[178:181], v[68:71]
	s_setprio 0
	s_barrier
	ds_read_b128 v[224:227], v177
	ds_read_b128 v[228:231], v177 offset:1024
	ds_read_b128 v[232:235], v177 offset:2048
	ds_read_b128 v[236:239], v177 offset:3072
	s_waitcnt vmcnt(0)
	s_barrier
	s_waitcnt lgkmcnt(0)
	s_setprio 1
	s_waitcnt lgkmcnt(0)
	v_mfma_f32_16x16x32_bf16 v[92:95], v[8:11], v[224:227], v[92:95]
	v_mfma_f32_16x16x32_bf16 v[8:11], v[8:11], v[232:235], v[88:91]
	v_mfma_f32_16x16x32_bf16 v[124:127], v[12:15], v[236:239], v[8:11]
	v_mfma_f32_16x16x32_bf16 v[8:11], v[32:35], v[224:227], v[84:87]
	v_mfma_f32_16x16x32_bf16 v[112:115], v[36:39], v[228:231], v[8:11]
	v_mfma_f32_16x16x32_bf16 v[8:11], v[32:35], v[232:235], v[80:83]
	v_mfma_f32_16x16x32_bf16 v[116:119], v[36:39], v[236:239], v[8:11]
	v_mfma_f32_16x16x32_bf16 v[8:11], v[40:43], v[224:227], v[184:187]
	v_mfma_f32_16x16x32_bf16 v[88:91], v[44:47], v[228:231], v[8:11]
	v_mfma_f32_16x16x32_bf16 v[8:11], v[40:43], v[232:235], v[192:195]
	v_mfma_f32_16x16x32_bf16 v[120:123], v[12:15], v[228:231], v[92:95]
	v_mfma_f32_16x16x32_bf16 v[92:95], v[44:47], v[236:239], v[8:11]
	v_mfma_f32_16x16x32_bf16 v[8:11], v[212:215], v[224:227], v[196:199]
	v_mfma_f32_16x16x32_bf16 v[80:83], v[216:219], v[228:231], v[8:11]
	v_mfma_f32_16x16x32_bf16 v[8:11], v[212:215], v[232:235], v[200:203]
	v_mfma_f32_16x16x32_bf16 v[84:87], v[216:219], v[236:239], v[8:11]
	s_setprio 0
	s_barrier
	ds_read_b128 v[184:187], v176 offset:49152
	ds_read_b128 v[192:195], v176 offset:50176
	ds_read_b128 v[196:199], v175 offset:49152
	ds_read_b128 v[200:203], v175 offset:50176
	ds_read_b128 v[212:215], v174 offset:49152
	ds_read_b128 v[174:177], v174 offset:50176
	ds_read_b128 v[216:219], v173 offset:49152
	ds_read_b128 v[246:249], v173 offset:50176
	s_barrier
	s_waitcnt lgkmcnt(0)
	s_setprio 1
	s_waitcnt lgkmcnt(0)
	v_mfma_f32_16x16x32_bf16 v[8:11], v[184:187], v[0:3], v[60:63]
	v_mfma_f32_16x16x32_bf16 v[40:43], v[192:195], v[4:7], v[8:11]
	v_mfma_f32_16x16x32_bf16 v[8:11], v[184:187], v[208:211], v[56:59]
	v_mfma_f32_16x16x32_bf16 v[44:47], v[192:195], v[178:181], v[8:11]
	v_mfma_f32_16x16x32_bf16 v[8:11], v[196:199], v[0:3], v[52:55]
	v_mfma_f32_16x16x32_bf16 v[32:35], v[200:203], v[4:7], v[8:11]
	v_mfma_f32_16x16x32_bf16 v[8:11], v[196:199], v[208:211], v[48:51]
	v_mfma_f32_16x16x32_bf16 v[36:39], v[200:203], v[178:181], v[8:11]
	v_mfma_f32_16x16x32_bf16 v[8:11], v[212:215], v[0:3], v[220:223]
	v_mfma_f32_16x16x32_bf16 v[0:3], v[216:219], v[0:3], v[134:137]
	v_mfma_f32_16x16x32_bf16 v[8:11], v[174:177], v[4:7], v[8:11]
	v_mfma_f32_16x16x32_bf16 v[12:15], v[212:215], v[208:211], v[242:245]
	v_mfma_f32_16x16x32_bf16 v[0:3], v[246:249], v[4:7], v[0:3]
	v_mfma_f32_16x16x32_bf16 v[4:7], v[216:219], v[208:211], v[138:141]
	v_mfma_f32_16x16x32_bf16 v[12:15], v[174:177], v[178:181], v[12:15]
	v_mfma_f32_16x16x32_bf16 v[4:7], v[246:249], v[178:181], v[4:7]
	s_setprio 0
	s_setprio 1
	v_mfma_f32_16x16x32_bf16 v[16:19], v[196:199], v[232:235], v[16:19]
	v_mfma_f32_16x16x32_bf16 v[24:27], v[184:187], v[232:235], v[24:27]
	v_mfma_f32_16x16x32_bf16 v[52:55], v[200:203], v[236:239], v[16:19]
	v_mfma_f32_16x16x32_bf16 v[16:19], v[212:215], v[224:227], v[146:149]
	v_mfma_f32_16x16x32_bf16 v[28:31], v[184:187], v[224:227], v[28:31]
	v_mfma_f32_16x16x32_bf16 v[60:63], v[192:195], v[236:239], v[24:27]
	v_mfma_f32_16x16x32_bf16 v[20:23], v[196:199], v[224:227], v[20:23]
	v_mfma_f32_16x16x32_bf16 v[24:27], v[174:177], v[228:231], v[16:19]
	v_mfma_f32_16x16x32_bf16 v[16:19], v[212:215], v[232:235], v[150:153]
	v_mfma_f32_16x16x32_bf16 v[56:59], v[192:195], v[228:231], v[28:31]
	v_mfma_f32_16x16x32_bf16 v[48:51], v[200:203], v[228:231], v[20:23]
	v_mfma_f32_16x16x32_bf16 v[28:31], v[174:177], v[236:239], v[16:19]
	v_mfma_f32_16x16x32_bf16 v[16:19], v[216:219], v[224:227], v[154:157]
	v_mfma_f32_16x16x32_bf16 v[20:23], v[216:219], v[232:235], v[204:207]
	v_mfma_f32_16x16x32_bf16 v[16:19], v[246:249], v[228:231], v[16:19]
	v_mfma_f32_16x16x32_bf16 v[20:23], v[246:249], v[236:239], v[20:23]
	s_setprio 0
	v_cmp_gt_u32_e32 vcc, s88, v133
	s_barrier
	s_and_saveexec_b64 s[8:9], vcc
	s_cbranch_execz .LBB0_244
	s_barrier

.LBB0_253:
	s_or_b64 exec, exec, s[8:9]
	v_add_u32_e32 v177, s15, v3
	v_lshl_add_u64 v[6:7], s[68:69], 0, v[128:129]
	v_readfirstlane_b32 s8, v177
	v_add_u32_e32 v178, 0x2000, v177
	v_lshl_add_u64 v[8:9], v[6:7], 0, s[22:23]
	s_mov_b32 m0, s8
	s_mov_b64 s[16:17], 0x20080
	v_readfirstlane_b32 s8, v178
	v_add_u32_e32 v179, 0x8000, v167
	s_waitcnt vmcnt(0)
	s_barrier
	global_load_lds_dwordx4 v[8:9], off
	v_lshl_add_u64 v[8:9], v[6:7], 0, s[16:17]
	s_mov_b32 m0, s8
	v_lshl_add_u64 v[130:131], s[90:91], 0, v[128:129]
	v_readfirstlane_b32 s8, v179
	v_add_u32_e32 v180, 0xa000, v167
	global_load_lds_dwordx4 v[8:9], off
	v_lshl_add_u64 v[8:9], v[130:131], 0, s[22:23]
	s_mov_b32 m0, s8
	v_readfirstlane_b32 s8, v180
	global_load_lds_dwordx4 v[8:9], off
	v_lshl_add_u64 v[8:9], v[130:131], 0, s[16:17]
	s_mov_b32 m0, s8
	s_mov_b64 s[8:9], 0x40080
	v_add_u32_e32 v181, s36, v3
	global_load_lds_dwordx4 v[8:9], off
	v_lshl_add_u64 v[8:9], v[6:7], 0, s[8:9]
	v_readfirstlane_b32 s8, v181
	s_mov_b32 m0, s8
	s_mov_b64 s[8:9], 0x60080
	v_add_u32_e32 v185, 0x2000, v181
	v_lshl_add_u64 v[6:7], v[6:7], 0, s[8:9]
	v_readfirstlane_b32 s8, v185
	global_load_lds_dwordx4 v[8:9], off
	s_mov_b32 m0, s8
	v_and_b32_e32 v136, 15, v169
	global_load_lds_dwordx4 v[6:7], off
	v_bfe_u32 v160, v169, 4, 2
	v_lshlrev_b32_e32 v170, 2, v169
	v_lshlrev_b32_e32 v14, 8, v169
	v_ashrrev_i32_e32 v164, 6, v169
	v_lshlrev_b32_e32 v5, 4, v160
	v_lshlrev_b32_e32 v6, 6, v136
	v_and_b32_e32 v7, 32, v170
	v_lshlrev_b32_e32 v12, 6, v169
	s_movk_i32 s8, 0x3c0
	v_and_b32_e32 v14, 0xffff8000, v14
	v_lshlrev_b32_e32 v0, 11, v0
	v_and_b32_e32 v137, 3, v164
	s_waitcnt vmcnt(6)
	v_bitop3_b32 v6, v5, v7, v6 bitop3:0x36
	v_lshlrev_b32_e32 v161, 6, v4
	v_lshlrev_b32_e32 v4, 13, v4
	v_and_or_b32 v5, v12, s8, v5
	v_or3_b32 v0, v1, v14, v0
	v_lshlrev_b32_e32 v3, 12, v137
	v_add_u32_e32 v8, s35, v6
	v_add_u32_e32 v9, s14, v6
	v_add_u32_e32 v10, s15, v6
	v_add_u32_e32 v11, s36, v6
	v_add_u32_e32 v6, 16, v6
	v_xad_u32 v5, v5, v7, 16
	v_or_b32_e32 v7, 0x800, v4
	v_or_b32_e32 v12, 0x1000, v4
	v_or_b32_e32 v13, 0x1800, v4
	v_add_u32_e32 v132, v0, v2
	s_add_u32 s8, s12, s70
	v_mov_b32_e32 v0, 0
	v_mov_b32_e32 v133, v129
	s_addc_u32 s9, s13, s71
	s_mov_b32 s11, -2
	v_add_u32_e32 v186, v8, v3
	v_add_u32_e32 v174, v6, v4
	v_add_u32_e32 v173, v5, v7
	v_add_u32_e32 v172, v5, v12
	v_add_u32_e32 v171, v5, v13
	v_add_u32_e32 v184, v9, v3
	v_add_u32_e32 v176, v10, v3
	v_add_u32_e32 v175, v11, v3
	v_mov_b32_e32 v1, v0
	v_mov_b32_e32 v2, v0
	v_mov_b32_e32 v3, v0
	v_mov_b32_e32 v4, v0
	v_mov_b32_e32 v5, v0
	v_mov_b32_e32 v6, v0
	v_mov_b32_e32 v7, v0
	v_mov_b32_e32 v8, v0
	v_mov_b32_e32 v9, v0
	v_mov_b32_e32 v10, v0
	v_mov_b32_e32 v11, v0
	v_mov_b32_e32 v12, v0
	v_mov_b32_e32 v13, v0
	v_mov_b32_e32 v14, v0
	v_mov_b32_e32 v15, v0
	v_mov_b32_e32 v16, v0
	v_mov_b32_e32 v17, v0
	v_mov_b32_e32 v18, v0
	v_mov_b32_e32 v19, v0
	v_mov_b32_e32 v20, v0
	v_mov_b32_e32 v21, v0
	v_mov_b32_e32 v22, v0
	v_mov_b32_e32 v23, v0
	v_mov_b32_e32 v24, v0
	v_mov_b32_e32 v25, v0
	v_mov_b32_e32 v26, v0
	v_mov_b32_e32 v27, v0
	v_mov_b32_e32 v28, v0
	v_mov_b32_e32 v29, v0
	v_mov_b32_e32 v30, v0
	v_mov_b32_e32 v31, v0
	v_mov_b32_e32 v32, v0
	v_mov_b32_e32 v33, v0
	v_mov_b32_e32 v34, v0
	v_mov_b32_e32 v35, v0
	v_mov_b32_e32 v36, v0
	v_mov_b32_e32 v37, v0
	v_mov_b32_e32 v38, v0
	v_mov_b32_e32 v39, v0
	v_mov_b32_e32 v40, v0
	v_mov_b32_e32 v41, v0
	v_mov_b32_e32 v42, v0
	v_mov_b32_e32 v43, v0
	v_mov_b32_e32 v44, v0
	v_mov_b32_e32 v45, v0
	v_mov_b32_e32 v46, v0
	v_mov_b32_e32 v47, v0
	v_mov_b32_e32 v48, v0
	v_mov_b32_e32 v49, v0
	v_mov_b32_e32 v50, v0
	v_mov_b32_e32 v51, v0
	v_mov_b32_e32 v52, v0
	v_mov_b32_e32 v53, v0
	v_mov_b32_e32 v54, v0
	v_mov_b32_e32 v55, v0
	v_mov_b32_e32 v56, v0
	v_mov_b32_e32 v57, v0
	v_mov_b32_e32 v58, v0
	v_mov_b32_e32 v59, v0
	v_mov_b32_e32 v60, v0
	v_mov_b32_e32 v61, v0
	v_mov_b32_e32 v62, v0
	v_mov_b32_e32 v63, v0
	v_mov_b32_e32 v64, v0
	v_mov_b32_e32 v65, v0
	v_mov_b32_e32 v66, v0
	v_mov_b32_e32 v67, v0
	v_mov_b32_e32 v68, v0
	v_mov_b32_e32 v69, v0
	v_mov_b32_e32 v70, v0
	v_mov_b32_e32 v71, v0
	v_mov_b32_e32 v72, v0
	v_mov_b32_e32 v73, v0
	v_mov_b32_e32 v74, v0
	v_mov_b32_e32 v75, v0
	v_mov_b32_e32 v76, v0
	v_mov_b32_e32 v77, v0
	v_mov_b32_e32 v78, v0
	v_mov_b32_e32 v79, v0
	v_mov_b32_e32 v80, v0
	v_mov_b32_e32 v81, v0
	v_mov_b32_e32 v82, v0
	v_mov_b32_e32 v83, v0
	v_mov_b32_e32 v84, v0
	v_mov_b32_e32 v85, v0
	v_mov_b32_e32 v86, v0
	v_mov_b32_e32 v87, v0
	v_mov_b32_e32 v88, v0
	v_mov_b32_e32 v89, v0
	v_mov_b32_e32 v90, v0
	v_mov_b32_e32 v91, v0
	v_mov_b32_e32 v92, v0
	v_mov_b32_e32 v93, v0
	v_mov_b32_e32 v94, v0
	v_mov_b32_e32 v95, v0
	v_mov_b32_e32 v96, v0
	v_mov_b32_e32 v97, v0
	v_mov_b32_e32 v98, v0
	v_mov_b32_e32 v99, v0
	v_mov_b32_e32 v100, v0
	v_mov_b32_e32 v101, v0
	v_mov_b32_e32 v102, v0
	v_mov_b32_e32 v103, v0
	v_mov_b32_e32 v104, v0
	v_mov_b32_e32 v105, v0
	v_mov_b32_e32 v106, v0
	v_mov_b32_e32 v107, v0
	v_mov_b32_e32 v108, v0
	v_mov_b32_e32 v109, v0
	v_mov_b32_e32 v110, v0
	v_mov_b32_e32 v111, v0
	v_mov_b32_e32 v112, v0
	v_mov_b32_e32 v113, v0
	v_mov_b32_e32 v114, v0
	v_mov_b32_e32 v115, v0
	v_mov_b32_e32 v116, v0
	v_mov_b32_e32 v117, v0
	v_mov_b32_e32 v118, v0
	v_mov_b32_e32 v119, v0
	v_mov_b32_e32 v120, v0
	v_mov_b32_e32 v121, v0
	v_mov_b32_e32 v122, v0
	v_mov_b32_e32 v123, v0
	v_mov_b32_e32 v124, v0
	v_mov_b32_e32 v125, v0
	v_mov_b32_e32 v126, v0
	v_mov_b32_e32 v127, v0
.Lkh_254:
	s_barrier
.LBB0_254:
	ds_read_b128 v[192:195], v186
	ds_read_b128 v[196:199], v186 offset:1024
	ds_read_b128 v[200:203], v186 offset:2048
	ds_read_b128 v[204:207], v186 offset:3072
	v_add_u32_e32 v189, 0xc000, v167
	v_lshl_add_u64 v[138:139], s[8:9], 0, v[132:133]
	v_readfirstlane_b32 s16, v189
	v_add_u32_e32 v190, 0xe000, v167
	v_lshl_add_u64 v[140:141], v[138:139], 0, s[30:31]
	s_mov_b32 m0, s16
	v_readfirstlane_b32 s16, v190
	ds_read_b128 v[208:211], v174
	ds_read_b128 v[212:215], v174 offset:1024
	ds_read_b128 v[216:219], v173
	ds_read_b128 v[220:223], v173 offset:1024
	ds_read_b128 v[224:227], v172
	ds_read_b128 v[228:231], v172 offset:1024
	ds_read_b128 v[232:235], v171
	ds_read_b128 v[236:239], v171 offset:1024
	global_load_lds_dwordx4 v[140:141], off
	v_lshl_add_u64 v[140:141], v[138:139], 0, s[38:39]
	s_mov_b32 m0, s16
	s_nop 0
	global_load_lds_dwordx4 v[140:141], off
	s_waitcnt lgkmcnt(8)
	s_barrier
	s_waitcnt lgkmcnt(0)
	s_setprio 1
	s_waitcnt lgkmcnt(0)
	v_mfma_f32_16x16x32_bf16 v[124:127], v[208:211], v[192:195], v[124:127]
	v_mfma_f32_16x16x32_bf16 v[120:123], v[208:211], v[200:203], v[120:123]
	v_mfma_f32_16x16x32_bf16 v[116:119], v[216:219], v[192:195], v[116:119]
	v_mfma_f32_16x16x32_bf16 v[112:115], v[216:219], v[200:203], v[112:115]
	v_mfma_f32_16x16x32_bf16 v[108:111], v[224:227], v[192:195], v[108:111]
	v_mfma_f32_16x16x32_bf16 v[104:107], v[224:227], v[200:203], v[104:107]
	v_mfma_f32_16x16x32_bf16 v[100:103], v[232:235], v[192:195], v[100:103]
	v_mfma_f32_16x16x32_bf16 v[96:99], v[232:235], v[200:203], v[96:99]
	v_mfma_f32_16x16x32_bf16 v[124:127], v[212:215], v[196:199], v[124:127]
	v_mfma_f32_16x16x32_bf16 v[120:123], v[212:215], v[204:207], v[120:123]
	v_mfma_f32_16x16x32_bf16 v[116:119], v[220:223], v[196:199], v[116:119]
	v_mfma_f32_16x16x32_bf16 v[112:115], v[220:223], v[204:207], v[112:115]
	v_mfma_f32_16x16x32_bf16 v[108:111], v[228:231], v[196:199], v[108:111]
	v_mfma_f32_16x16x32_bf16 v[104:107], v[228:231], v[204:207], v[104:107]
	v_mfma_f32_16x16x32_bf16 v[100:103], v[236:239], v[196:199], v[100:103]
	v_mfma_f32_16x16x32_bf16 v[96:99], v[236:239], v[204:207], v[96:99]
	s_setprio 0
	s_barrier
	v_lshl_add_u64 v[140:141], s[68:69], 0, v[132:133]
	v_readfirstlane_b32 s16, v168
	v_add_u32_e32 v187, 0x2000, v168
	v_lshl_add_u64 v[150:151], v[140:141], 0, s[40:41]
	s_mov_b32 m0, s16
	v_readfirstlane_b32 s16, v187
	ds_read_b128 v[240:243], v184
	ds_read_b128 v[244:247], v184 offset:1024
	ds_read_b128 v[248:251], v184 offset:2048
	ds_read_b128 v[146:149], v184 offset:3072
	global_load_lds_dwordx4 v[150:151], off
	v_lshl_add_u64 v[150:151], v[140:141], 0, s[42:43]
	s_mov_b32 m0, s16
	s_nop 0
	global_load_lds_dwordx4 v[150:151], off
	s_barrier
	s_waitcnt lgkmcnt(0)
	s_setprio 1
	s_waitcnt lgkmcnt(0)
	v_mfma_f32_16x16x32_bf16 v[92:95], v[208:211], v[240:243], v[92:95]
	v_mfma_f32_16x16x32_bf16 v[88:91], v[208:211], v[248:251], v[88:91]
	v_mfma_f32_16x16x32_bf16 v[84:87], v[216:219], v[240:243], v[84:87]
	v_mfma_f32_16x16x32_bf16 v[80:83], v[216:219], v[248:251], v[80:83]
	v_mfma_f32_16x16x32_bf16 v[76:79], v[224:227], v[240:243], v[76:79]
	v_mfma_f32_16x16x32_bf16 v[72:75], v[224:227], v[248:251], v[72:75]
	v_mfma_f32_16x16x32_bf16 v[68:71], v[232:235], v[240:243], v[68:71]
	v_mfma_f32_16x16x32_bf16 v[64:67], v[232:235], v[248:251], v[64:67]
	v_mfma_f32_16x16x32_bf16 v[92:95], v[212:215], v[244:247], v[92:95]
	v_mfma_f32_16x16x32_bf16 v[88:91], v[212:215], v[146:149], v[88:91]
	v_mfma_f32_16x16x32_bf16 v[84:87], v[220:223], v[244:247], v[84:87]
	v_mfma_f32_16x16x32_bf16 v[80:83], v[220:223], v[146:149], v[80:83]
	v_mfma_f32_16x16x32_bf16 v[76:79], v[228:231], v[244:247], v[76:79]
	v_mfma_f32_16x16x32_bf16 v[72:75], v[228:231], v[146:149], v[72:75]
	v_mfma_f32_16x16x32_bf16 v[68:71], v[236:239], v[244:247], v[68:71]
	v_mfma_f32_16x16x32_bf16 v[64:67], v[236:239], v[146:149], v[64:67]
	s_setprio 0
	v_readfirstlane_b32 s16, v167
	v_lshl_add_u64 v[150:151], v[138:139], 0, s[44:45]
	s_mov_b32 m0, s16
	v_readfirstlane_b32 s16, v166
	s_barrier
	ds_read_b128 v[208:211], v174 offset:16384
	ds_read_b128 v[212:215], v174 offset:17408
	ds_read_b128 v[216:219], v173 offset:16384
	ds_read_b128 v[220:223], v173 offset:17408
	ds_read_b128 v[224:227], v172 offset:16384
	ds_read_b128 v[228:231], v172 offset:17408
	ds_read_b128 v[232:235], v171 offset:16384
	ds_read_b128 v[236:239], v171 offset:17408
	global_load_lds_dwordx4 v[150:151], off
	v_lshl_add_u64 v[150:151], v[138:139], 0, s[46:47]
	s_mov_b32 m0, s16
	s_nop 0
	global_load_lds_dwordx4 v[150:151], off
	s_barrier
	s_waitcnt lgkmcnt(0)
	s_setprio 1
	s_waitcnt lgkmcnt(0)
	v_mfma_f32_16x16x32_bf16 v[60:63], v[208:211], v[192:195], v[60:63]
	v_mfma_f32_16x16x32_bf16 v[56:59], v[208:211], v[200:203], v[56:59]
	v_mfma_f32_16x16x32_bf16 v[52:55], v[216:219], v[192:195], v[52:55]
	v_mfma_f32_16x16x32_bf16 v[48:51], v[216:219], v[200:203], v[48:51]
	v_mfma_f32_16x16x32_bf16 v[44:47], v[224:227], v[192:195], v[44:47]
	v_mfma_f32_16x16x32_bf16 v[40:43], v[224:227], v[200:203], v[40:43]
	v_mfma_f32_16x16x32_bf16 v[36:39], v[232:235], v[192:195], v[36:39]
	v_mfma_f32_16x16x32_bf16 v[32:35], v[232:235], v[200:203], v[32:35]
	v_mfma_f32_16x16x32_bf16 v[60:63], v[212:215], v[196:199], v[60:63]
	v_mfma_f32_16x16x32_bf16 v[56:59], v[212:215], v[204:207], v[56:59]
	v_mfma_f32_16x16x32_bf16 v[52:55], v[220:223], v[196:199], v[52:55]
	v_mfma_f32_16x16x32_bf16 v[48:51], v[220:223], v[204:207], v[48:51]
	v_mfma_f32_16x16x32_bf16 v[44:47], v[228:231], v[196:199], v[44:47]
	v_mfma_f32_16x16x32_bf16 v[40:43], v[228:231], v[204:207], v[40:43]
	v_mfma_f32_16x16x32_bf16 v[36:39], v[236:239], v[196:199], v[36:39]
	v_mfma_f32_16x16x32_bf16 v[32:35], v[236:239], v[204:207], v[32:35]
	s_setprio 0
	s_barrier
	v_readfirstlane_b32 s16, v165
	v_add_u32_e32 v188, 0x2000, v165
	v_lshl_add_u64 v[150:151], v[140:141], 0, s[48:49]
	s_mov_b32 m0, s16
	v_readfirstlane_b32 s16, v188
	global_load_lds_dwordx4 v[150:151], off
	v_lshl_add_u64 v[150:151], v[140:141], 0, s[50:51]
	s_mov_b32 m0, s16
	s_nop 0
	global_load_lds_dwordx4 v[150:151], off
	s_waitcnt vmcnt(6)
	s_barrier
	s_setprio 1
	v_mfma_f32_16x16x32_bf16 v[28:31], v[208:211], v[240:243], v[28:31]
	v_mfma_f32_16x16x32_bf16 v[24:27], v[208:211], v[248:251], v[24:27]
	v_mfma_f32_16x16x32_bf16 v[20:23], v[216:219], v[240:243], v[20:23]
	v_mfma_f32_16x16x32_bf16 v[16:19], v[216:219], v[248:251], v[16:19]
	v_mfma_f32_16x16x32_bf16 v[12:15], v[224:227], v[240:243], v[12:15]
	v_mfma_f32_16x16x32_bf16 v[8:11], v[224:227], v[248:251], v[8:11]
	v_mfma_f32_16x16x32_bf16 v[4:7], v[232:235], v[240:243], v[4:7]
	v_mfma_f32_16x16x32_bf16 v[0:3], v[232:235], v[248:251], v[0:3]
	v_mfma_f32_16x16x32_bf16 v[28:31], v[212:215], v[244:247], v[28:31]
	v_mfma_f32_16x16x32_bf16 v[24:27], v[212:215], v[146:149], v[24:27]
	v_mfma_f32_16x16x32_bf16 v[20:23], v[220:223], v[244:247], v[20:23]
	v_mfma_f32_16x16x32_bf16 v[16:19], v[220:223], v[146:149], v[16:19]
	v_mfma_f32_16x16x32_bf16 v[12:15], v[228:231], v[244:247], v[12:15]
	v_mfma_f32_16x16x32_bf16 v[8:11], v[228:231], v[146:149], v[8:11]
	v_mfma_f32_16x16x32_bf16 v[4:7], v[236:239], v[244:247], v[4:7]
	v_mfma_f32_16x16x32_bf16 v[0:3], v[236:239], v[146:149], v[0:3]
	s_setprio 0
	s_barrier
	ds_read_b128 v[146:149], v176
	ds_read_b128 v[192:195], v176 offset:1024
	ds_read_b128 v[196:199], v176 offset:2048
	ds_read_b128 v[200:203], v176 offset:3072
	v_readfirstlane_b32 s16, v163
	v_lshl_add_u64 v[150:151], v[138:139], 0, s[52:53]
	s_mov_b32 m0, s16
	v_readfirstlane_b32 s16, v162
	ds_read_b128 v[204:207], v174 offset:32768
	ds_read_b128 v[208:211], v174 offset:33792
	ds_read_b128 v[212:215], v173 offset:32768
	ds_read_b128 v[216:219], v173 offset:33792
	ds_read_b128 v[220:223], v172 offset:32768
	ds_read_b128 v[224:227], v172 offset:33792
	ds_read_b128 v[228:231], v171 offset:32768
	ds_read_b128 v[232:235], v171 offset:33792
	global_load_lds_dwordx4 v[150:151], off
	v_lshl_add_u64 v[150:151], v[138:139], 0, s[54:55]
	s_mov_b32 m0, s16
	s_nop 0
	global_load_lds_dwordx4 v[150:151], off
	s_waitcnt lgkmcnt(8)
	s_barrier
	s_waitcnt lgkmcnt(0)
	s_setprio 1
	s_waitcnt lgkmcnt(0)
	v_mfma_f32_16x16x32_bf16 v[124:127], v[204:207], v[146:149], v[124:127]
	v_mfma_f32_16x16x32_bf16 v[120:123], v[204:207], v[196:199], v[120:123]
	v_mfma_f32_16x16x32_bf16 v[116:119], v[212:215], v[146:149], v[116:119]
	v_mfma_f32_16x16x32_bf16 v[112:115], v[212:215], v[196:199], v[112:115]
	v_mfma_f32_16x16x32_bf16 v[108:111], v[220:223], v[146:149], v[108:111]
	v_mfma_f32_16x16x32_bf16 v[104:107], v[220:223], v[196:199], v[104:107]
	v_mfma_f32_16x16x32_bf16 v[100:103], v[228:231], v[146:149], v[100:103]
	v_mfma_f32_16x16x32_bf16 v[96:99], v[228:231], v[196:199], v[96:99]
	v_mfma_f32_16x16x32_bf16 v[124:127], v[208:211], v[192:195], v[124:127]
	v_mfma_f32_16x16x32_bf16 v[120:123], v[208:211], v[200:203], v[120:123]
	v_mfma_f32_16x16x32_bf16 v[116:119], v[216:219], v[192:195], v[116:119]
	v_mfma_f32_16x16x32_bf16 v[112:115], v[216:219], v[200:203], v[112:115]
	v_mfma_f32_16x16x32_bf16 v[108:111], v[224:227], v[192:195], v[108:111]
	v_mfma_f32_16x16x32_bf16 v[104:107], v[224:227], v[200:203], v[104:107]
	v_mfma_f32_16x16x32_bf16 v[100:103], v[232:235], v[192:195], v[100:103]
	v_mfma_f32_16x16x32_bf16 v[96:99], v[232:235], v[200:203], v[96:99]
	s_setprio 0
	s_barrier
	v_readfirstlane_b32 s16, v177
	v_lshl_add_u64 v[150:151], v[140:141], 0, s[56:57]
	s_mov_b32 m0, s16
	v_readfirstlane_b32 s16, v178
	ds_read_b128 v[236:239], v175
	ds_read_b128 v[240:243], v175 offset:1024
	ds_read_b128 v[244:247], v175 offset:2048
	ds_read_b128 v[248:251], v175 offset:3072
	global_load_lds_dwordx4 v[150:151], off
	v_lshl_add_u64 v[150:151], v[140:141], 0, s[58:59]
	s_mov_b32 m0, s16
	s_nop 0
	global_load_lds_dwordx4 v[150:151], off
	s_barrier
	s_waitcnt lgkmcnt(0)
	s_setprio 1
	s_waitcnt lgkmcnt(0)
	v_mfma_f32_16x16x32_bf16 v[92:95], v[204:207], v[236:239], v[92:95]
	v_mfma_f32_16x16x32_bf16 v[88:91], v[204:207], v[244:247], v[88:91]
	v_mfma_f32_16x16x32_bf16 v[84:87], v[212:215], v[236:239], v[84:87]
	v_mfma_f32_16x16x32_bf16 v[80:83], v[212:215], v[244:247], v[80:83]
	v_mfma_f32_16x16x32_bf16 v[76:79], v[220:223], v[236:239], v[76:79]
	v_mfma_f32_16x16x32_bf16 v[72:75], v[220:223], v[244:247], v[72:75]
	v_mfma_f32_16x16x32_bf16 v[68:71], v[228:231], v[236:239], v[68:71]
	v_mfma_f32_16x16x32_bf16 v[64:67], v[228:231], v[244:247], v[64:67]
	v_mfma_f32_16x16x32_bf16 v[92:95], v[208:211], v[240:243], v[92:95]
	v_mfma_f32_16x16x32_bf16 v[88:91], v[208:211], v[248:251], v[88:91]
	v_mfma_f32_16x16x32_bf16 v[84:87], v[216:219], v[240:243], v[84:87]
	v_mfma_f32_16x16x32_bf16 v[80:83], v[216:219], v[248:251], v[80:83]
	v_mfma_f32_16x16x32_bf16 v[76:79], v[224:227], v[240:243], v[76:79]
	v_mfma_f32_16x16x32_bf16 v[72:75], v[224:227], v[248:251], v[72:75]
	v_mfma_f32_16x16x32_bf16 v[68:71], v[232:235], v[240:243], v[68:71]
	v_mfma_f32_16x16x32_bf16 v[64:67], v[232:235], v[248:251], v[64:67]
	s_setprio 0
	v_readfirstlane_b32 s16, v179
	v_lshl_add_u64 v[150:151], v[138:139], 0, s[60:61]
	s_mov_b32 m0, s16
	v_readfirstlane_b32 s16, v180
	s_barrier
	ds_read_b128 v[204:207], v174 offset:49152
	ds_read_b128 v[208:211], v174 offset:50176
	ds_read_b128 v[212:215], v173 offset:49152
	ds_read_b128 v[216:219], v173 offset:50176
	ds_read_b128 v[220:223], v172 offset:49152
	ds_read_b128 v[224:227], v172 offset:50176
	ds_read_b128 v[228:231], v171 offset:49152
	ds_read_b128 v[232:235], v171 offset:50176
	global_load_lds_dwordx4 v[150:151], off
	v_lshl_add_u64 v[138:139], v[138:139], 0, s[62:63]
	s_mov_b32 m0, s16
	s_nop 0
	global_load_lds_dwordx4 v[138:139], off
	s_barrier
	s_waitcnt lgkmcnt(0)
	s_setprio 1
	s_waitcnt lgkmcnt(0)
	v_mfma_f32_16x16x32_bf16 v[60:63], v[204:207], v[146:149], v[60:63]
	v_mfma_f32_16x16x32_bf16 v[56:59], v[204:207], v[196:199], v[56:59]
	v_mfma_f32_16x16x32_bf16 v[52:55], v[212:215], v[146:149], v[52:55]
	v_mfma_f32_16x16x32_bf16 v[48:51], v[212:215], v[196:199], v[48:51]
	v_mfma_f32_16x16x32_bf16 v[44:47], v[220:223], v[146:149], v[44:47]
	v_mfma_f32_16x16x32_bf16 v[40:43], v[220:223], v[196:199], v[40:43]
	v_mfma_f32_16x16x32_bf16 v[36:39], v[228:231], v[146:149], v[36:39]
	v_mfma_f32_16x16x32_bf16 v[32:35], v[228:231], v[196:199], v[32:35]
	v_mfma_f32_16x16x32_bf16 v[60:63], v[208:211], v[192:195], v[60:63]
	v_mfma_f32_16x16x32_bf16 v[56:59], v[208:211], v[200:203], v[56:59]
	v_mfma_f32_16x16x32_bf16 v[52:55], v[216:219], v[192:195], v[52:55]
	v_mfma_f32_16x16x32_bf16 v[48:51], v[216:219], v[200:203], v[48:51]
	v_mfma_f32_16x16x32_bf16 v[44:47], v[224:227], v[192:195], v[44:47]
	v_mfma_f32_16x16x32_bf16 v[40:43], v[224:227], v[200:203], v[40:43]
	v_mfma_f32_16x16x32_bf16 v[36:39], v[232:235], v[192:195], v[36:39]
	v_mfma_f32_16x16x32_bf16 v[32:35], v[232:235], v[200:203], v[32:35]
	s_setprio 0
	s_barrier
	v_readfirstlane_b32 s16, v181
	v_lshl_add_u64 v[138:139], v[140:141], 0, s[64:65]
	s_mov_b32 m0, s16
	v_readfirstlane_b32 s16, v185
	global_load_lds_dwordx4 v[138:139], off
	v_lshl_add_u64 v[138:139], v[140:141], 0, s[66:67]
	s_mov_b32 m0, s16
	s_nop 0
	global_load_lds_dwordx4 v[138:139], off
	s_waitcnt vmcnt(6)
	s_barrier
	s_setprio 1
	v_mfma_f32_16x16x32_bf16 v[28:31], v[204:207], v[236:239], v[28:31]
	v_mfma_f32_16x16x32_bf16 v[24:27], v[204:207], v[244:247], v[24:27]
	v_mfma_f32_16x16x32_bf16 v[20:23], v[212:215], v[236:239], v[20:23]
	v_mfma_f32_16x16x32_bf16 v[16:19], v[212:215], v[244:247], v[16:19]
	v_mfma_f32_16x16x32_bf16 v[12:15], v[220:223], v[236:239], v[12:15]
	v_mfma_f32_16x16x32_bf16 v[8:11], v[220:223], v[244:247], v[8:11]
	v_mfma_f32_16x16x32_bf16 v[4:7], v[228:231], v[236:239], v[4:7]
	v_mfma_f32_16x16x32_bf16 v[0:3], v[228:231], v[244:247], v[0:3]
	v_mfma_f32_16x16x32_bf16 v[28:31], v[208:211], v[240:243], v[28:31]
	v_mfma_f32_16x16x32_bf16 v[24:27], v[208:211], v[248:251], v[24:27]
	v_mfma_f32_16x16x32_bf16 v[20:23], v[216:219], v[240:243], v[20:23]
	v_mfma_f32_16x16x32_bf16 v[16:19], v[216:219], v[248:251], v[16:19]
	v_mfma_f32_16x16x32_bf16 v[12:15], v[224:227], v[240:243], v[12:15]
	v_mfma_f32_16x16x32_bf16 v[8:11], v[224:227], v[248:251], v[8:11]
	v_mfma_f32_16x16x32_bf16 v[4:7], v[232:235], v[240:243], v[4:7]
	v_mfma_f32_16x16x32_bf16 v[0:3], v[232:235], v[248:251], v[0:3]
	s_setprio 0
	s_add_i32 s11, s11, 2
	s_add_u32 s8, s8, 0x100
	s_addc_u32 s9, s9, 0
	s_add_u32 s68, s68, 0x100
	s_addc_u32 s69, s69, 0
	s_cmp_lt_u32 s11, 12
	s_cbranch_scc1 .Lkh_254
	s_barrier
	s_mov_b64 s[8:9], 0x40780
	v_lshl_add_u64 v[132:133], v[130:131], 0, s[8:9]
	v_readfirstlane_b32 s8, v189
	s_mov_b32 m0, s8
	s_mov_b64 s[8:9], 0x60780
	v_lshl_add_u64 v[130:131], v[130:131], 0, s[8:9]
	v_readfirstlane_b32 s8, v190
	ds_read_b128 v[146:149], v186
	ds_read_b128 v[178:181], v186 offset:1024
	ds_read_b128 v[192:195], v186 offset:2048
	ds_read_b128 v[196:199], v186 offset:3072
	ds_read_b128 v[200:203], v174
	ds_read_b128 v[204:207], v174 offset:1024
	ds_read_b128 v[208:211], v173
	ds_read_b128 v[212:215], v173 offset:1024
	ds_read_b128 v[216:219], v172
	ds_read_b128 v[220:223], v172 offset:1024
	ds_read_b128 v[224:227], v171
	ds_read_b128 v[228:231], v171 offset:1024
	global_load_lds_dwordx4 v[132:133], off
	s_mov_b32 m0, s8
	s_nop 0
	global_load_lds_dwordx4 v[130:131], off
	s_barrier
	s_waitcnt lgkmcnt(0)
	s_setprio 1
	s_waitcnt lgkmcnt(0)
	v_mfma_f32_16x16x32_bf16 v[124:127], v[200:203], v[146:149], v[124:127]
	v_mfma_f32_16x16x32_bf16 v[120:123], v[200:203], v[192:195], v[120:123]
	v_mfma_f32_16x16x32_bf16 v[116:119], v[208:211], v[146:149], v[116:119]
	v_mfma_f32_16x16x32_bf16 v[112:115], v[208:211], v[192:195], v[112:115]
	v_mfma_f32_16x16x32_bf16 v[124:127], v[204:207], v[178:181], v[124:127]
	v_mfma_f32_16x16x32_bf16 v[120:123], v[204:207], v[196:199], v[120:123]
	v_mfma_f32_16x16x32_bf16 v[116:119], v[212:215], v[178:181], v[116:119]
	v_mfma_f32_16x16x32_bf16 v[112:115], v[212:215], v[196:199], v[112:115]
	v_mfma_f32_16x16x32_bf16 v[108:111], v[216:219], v[146:149], v[108:111]
	v_mfma_f32_16x16x32_bf16 v[104:107], v[216:219], v[192:195], v[104:107]
	v_mfma_f32_16x16x32_bf16 v[100:103], v[224:227], v[146:149], v[100:103]
	v_mfma_f32_16x16x32_bf16 v[96:99], v[224:227], v[192:195], v[96:99]
	v_mfma_f32_16x16x32_bf16 v[130:133], v[220:223], v[178:181], v[108:111]
	v_mfma_f32_16x16x32_bf16 v[232:235], v[220:223], v[196:199], v[104:107]
	v_mfma_f32_16x16x32_bf16 v[236:239], v[228:231], v[178:181], v[100:103]
	v_mfma_f32_16x16x32_bf16 v[240:243], v[228:231], v[196:199], v[96:99]
	s_setprio 0
	s_barrier
	s_nop 1
	ds_read_b128 v[96:99], v184
	ds_read_b128 v[100:103], v184 offset:1024
	ds_read_b128 v[104:107], v184 offset:2048
	ds_read_b128 v[108:111], v184 offset:3072
	s_barrier
	s_waitcnt lgkmcnt(0)
	s_setprio 1
	s_waitcnt lgkmcnt(0)
	v_mfma_f32_16x16x32_bf16 v[92:95], v[200:203], v[96:99], v[92:95]
	v_mfma_f32_16x16x32_bf16 v[88:91], v[200:203], v[104:107], v[88:91]
	v_mfma_f32_16x16x32_bf16 v[84:87], v[208:211], v[96:99], v[84:87]
	v_mfma_f32_16x16x32_bf16 v[80:83], v[208:211], v[104:107], v[80:83]
	v_mfma_f32_16x16x32_bf16 v[92:95], v[204:207], v[100:103], v[92:95]
	v_mfma_f32_16x16x32_bf16 v[88:91], v[204:207], v[108:111], v[88:91]
	v_mfma_f32_16x16x32_bf16 v[84:87], v[212:215], v[100:103], v[84:87]
	v_mfma_f32_16x16x32_bf16 v[80:83], v[212:215], v[108:111], v[80:83]
	v_mfma_f32_16x16x32_bf16 v[76:79], v[216:219], v[96:99], v[76:79]
	v_mfma_f32_16x16x32_bf16 v[72:75], v[216:219], v[104:107], v[72:75]
	v_mfma_f32_16x16x32_bf16 v[68:71], v[224:227], v[96:99], v[68:71]
	v_mfma_f32_16x16x32_bf16 v[64:67], v[224:227], v[104:107], v[64:67]
	v_mfma_f32_16x16x32_bf16 v[200:203], v[220:223], v[100:103], v[76:79]
	v_mfma_f32_16x16x32_bf16 v[204:207], v[220:223], v[108:111], v[72:75]
	v_mfma_f32_16x16x32_bf16 v[208:211], v[228:231], v[100:103], v[68:71]
	v_mfma_f32_16x16x32_bf16 v[212:215], v[228:231], v[108:111], v[64:67]
	s_setprio 0
	s_barrier
	s_nop 1
	ds_read_b128 v[64:67], v174 offset:16384
	ds_read_b128 v[68:71], v174 offset:17408
	ds_read_b128 v[72:75], v173 offset:16384
	ds_read_b128 v[76:79], v173 offset:17408
	ds_read_b128 v[216:219], v172 offset:16384
	ds_read_b128 v[220:223], v172 offset:17408
	ds_read_b128 v[224:227], v171 offset:16384
	ds_read_b128 v[228:231], v171 offset:17408
	s_waitcnt vmcnt(4)
	s_barrier
	s_waitcnt lgkmcnt(0)
	s_setprio 1
	s_waitcnt lgkmcnt(0)
	v_mfma_f32_16x16x32_bf16 v[60:63], v[64:67], v[146:149], v[60:63]
	v_mfma_f32_16x16x32_bf16 v[56:59], v[64:67], v[192:195], v[56:59]
	v_mfma_f32_16x16x32_bf16 v[52:55], v[72:75], v[146:149], v[52:55]
	v_mfma_f32_16x16x32_bf16 v[48:51], v[72:75], v[192:195], v[48:51]
	v_mfma_f32_16x16x32_bf16 v[60:63], v[68:71], v[178:181], v[60:63]
	v_mfma_f32_16x16x32_bf16 v[56:59], v[68:71], v[196:199], v[56:59]
	v_mfma_f32_16x16x32_bf16 v[52:55], v[76:79], v[178:181], v[52:55]
	v_mfma_f32_16x16x32_bf16 v[48:51], v[76:79], v[196:199], v[48:51]
	v_mfma_f32_16x16x32_bf16 v[44:47], v[216:219], v[146:149], v[44:47]
	v_mfma_f32_16x16x32_bf16 v[40:43], v[216:219], v[192:195], v[40:43]
	v_mfma_f32_16x16x32_bf16 v[36:39], v[224:227], v[146:149], v[36:39]
	v_mfma_f32_16x16x32_bf16 v[32:35], v[224:227], v[192:195], v[32:35]
	v_mfma_f32_16x16x32_bf16 v[244:247], v[220:223], v[178:181], v[44:47]
	v_mfma_f32_16x16x32_bf16 v[248:251], v[220:223], v[196:199], v[40:43]
	v_mfma_f32_16x16x32_bf16 v[146:149], v[228:231], v[178:181], v[36:39]
	v_mfma_f32_16x16x32_bf16 v[178:181], v[228:231], v[196:199], v[32:35]
	s_setprio 0
	s_setprio 1
	v_mfma_f32_16x16x32_bf16 v[28:31], v[64:67], v[96:99], v[28:31]
	v_mfma_f32_16x16x32_bf16 v[24:27], v[64:67], v[104:107], v[24:27]
	v_mfma_f32_16x16x32_bf16 v[20:23], v[72:75], v[96:99], v[20:23]
	v_mfma_f32_16x16x32_bf16 v[16:19], v[72:75], v[104:107], v[16:19]
	v_mfma_f32_16x16x32_bf16 v[28:31], v[68:71], v[100:103], v[28:31]
	v_mfma_f32_16x16x32_bf16 v[24:27], v[68:71], v[108:111], v[24:27]
	v_mfma_f32_16x16x32_bf16 v[20:23], v[76:79], v[100:103], v[20:23]
	v_mfma_f32_16x16x32_bf16 v[16:19], v[76:79], v[108:111], v[16:19]
	v_mfma_f32_16x16x32_bf16 v[12:15], v[216:219], v[96:99], v[12:15]
	v_mfma_f32_16x16x32_bf16 v[8:11], v[216:219], v[104:107], v[8:11]
	v_mfma_f32_16x16x32_bf16 v[4:7], v[224:227], v[96:99], v[4:7]
	v_mfma_f32_16x16x32_bf16 v[0:3], v[224:227], v[104:107], v[0:3]
	v_mfma_f32_16x16x32_bf16 v[190:193], v[220:223], v[100:103], v[12:15]
	v_mfma_f32_16x16x32_bf16 v[194:197], v[220:223], v[108:111], v[8:11]
	v_mfma_f32_16x16x32_bf16 v[216:219], v[228:231], v[100:103], v[4:7]
	v_mfma_f32_16x16x32_bf16 v[220:223], v[228:231], v[108:111], v[0:3]
	s_setprio 0
	s_barrier
	s_nop 1
	ds_read_b128 v[0:3], v176
	ds_read_b128 v[4:7], v176 offset:1024
	ds_read_b128 v[224:227], v176 offset:2048
	ds_read_b128 v[228:231], v176 offset:3072
	ds_read_b128 v[8:11], v174 offset:32768
	ds_read_b128 v[12:15], v174 offset:33792
	ds_read_b128 v[32:35], v173 offset:32768
	ds_read_b128 v[36:39], v173 offset:33792
	ds_read_b128 v[40:43], v172 offset:32768
	ds_read_b128 v[44:47], v172 offset:33792
	ds_read_b128 v[150:153], v171 offset:32768
	ds_read_b128 v[154:157], v171 offset:33792
	s_waitcnt vmcnt(2)
	s_barrier
	s_waitcnt lgkmcnt(0)
	s_setprio 1
	s_waitcnt lgkmcnt(0)
	v_mfma_f32_16x16x32_bf16 v[64:67], v[8:11], v[0:3], v[124:127]
	v_mfma_f32_16x16x32_bf16 v[104:107], v[12:15], v[4:7], v[64:67]
	v_mfma_f32_16x16x32_bf16 v[64:67], v[8:11], v[224:227], v[120:123]
	v_mfma_f32_16x16x32_bf16 v[108:111], v[12:15], v[228:231], v[64:67]
	v_mfma_f32_16x16x32_bf16 v[64:67], v[32:35], v[0:3], v[116:119]
	v_mfma_f32_16x16x32_bf16 v[96:99], v[36:39], v[4:7], v[64:67]
	v_mfma_f32_16x16x32_bf16 v[64:67], v[32:35], v[224:227], v[112:115]
	v_mfma_f32_16x16x32_bf16 v[100:103], v[36:39], v[228:231], v[64:67]
	v_mfma_f32_16x16x32_bf16 v[64:67], v[40:43], v[0:3], v[130:133]
	v_mfma_f32_16x16x32_bf16 v[72:75], v[44:47], v[4:7], v[64:67]
	v_mfma_f32_16x16x32_bf16 v[64:67], v[40:43], v[224:227], v[232:235]
	v_mfma_f32_16x16x32_bf16 v[76:79], v[44:47], v[228:231], v[64:67]
	v_mfma_f32_16x16x32_bf16 v[64:67], v[150:153], v[0:3], v[236:239]
	v_mfma_f32_16x16x32_bf16 v[68:71], v[150:153], v[224:227], v[240:243]
	v_mfma_f32_16x16x32_bf16 v[64:67], v[154:157], v[4:7], v[64:67]
	v_mfma_f32_16x16x32_bf16 v[68:71], v[154:157], v[228:231], v[68:71]
	s_setprio 0
	s_barrier
	ds_read_b128 v[130:133], v175
	ds_read_b128 v[232:235], v175 offset:1024
	ds_read_b128 v[236:239], v175 offset:2048
	ds_read_b128 v[240:243], v175 offset:3072
	s_waitcnt vmcnt(0)
	s_barrier
	s_waitcnt lgkmcnt(0)
	s_setprio 1
	s_waitcnt lgkmcnt(0)
	v_mfma_f32_16x16x32_bf16 v[92:95], v[8:11], v[130:133], v[92:95]
	v_mfma_f32_16x16x32_bf16 v[8:11], v[8:11], v[236:239], v[88:91]
	v_mfma_f32_16x16x32_bf16 v[124:127], v[12:15], v[240:243], v[8:11]
	v_mfma_f32_16x16x32_bf16 v[8:11], v[32:35], v[130:133], v[84:87]
	v_mfma_f32_16x16x32_bf16 v[112:115], v[36:39], v[232:235], v[8:11]
	v_mfma_f32_16x16x32_bf16 v[8:11], v[32:35], v[236:239], v[80:83]
	v_mfma_f32_16x16x32_bf16 v[116:119], v[36:39], v[240:243], v[8:11]
	v_mfma_f32_16x16x32_bf16 v[8:11], v[40:43], v[130:133], v[200:203]
	v_mfma_f32_16x16x32_bf16 v[88:91], v[44:47], v[232:235], v[8:11]
	v_mfma_f32_16x16x32_bf16 v[8:11], v[40:43], v[236:239], v[204:207]
	v_mfma_f32_16x16x32_bf16 v[120:123], v[12:15], v[232:235], v[92:95]
	v_mfma_f32_16x16x32_bf16 v[92:95], v[44:47], v[240:243], v[8:11]
	v_mfma_f32_16x16x32_bf16 v[8:11], v[150:153], v[130:133], v[208:211]
	v_mfma_f32_16x16x32_bf16 v[80:83], v[154:157], v[232:235], v[8:11]
	v_mfma_f32_16x16x32_bf16 v[8:11], v[150:153], v[236:239], v[212:215]
	v_mfma_f32_16x16x32_bf16 v[84:87], v[154:157], v[240:243], v[8:11]
	s_setprio 0
	s_barrier
	ds_read_b128 v[150:153], v174 offset:49152
	ds_read_b128 v[154:157], v174 offset:50176
	ds_read_b128 v[174:177], v173 offset:49152
	ds_read_b128 v[198:201], v173 offset:50176
	ds_read_b128 v[202:205], v172 offset:49152
	ds_read_b128 v[206:209], v172 offset:50176
	ds_read_b128 v[210:213], v171 offset:49152
	ds_read_b128 v[138:141], v171 offset:50176
	s_barrier
	s_waitcnt lgkmcnt(0)
	s_setprio 1
	s_waitcnt lgkmcnt(0)
	v_mfma_f32_16x16x32_bf16 v[8:11], v[150:153], v[0:3], v[60:63]
	v_mfma_f32_16x16x32_bf16 v[40:43], v[154:157], v[4:7], v[8:11]
	v_mfma_f32_16x16x32_bf16 v[8:11], v[150:153], v[224:227], v[56:59]
	v_mfma_f32_16x16x32_bf16 v[44:47], v[154:157], v[228:231], v[8:11]
	v_mfma_f32_16x16x32_bf16 v[8:11], v[174:177], v[0:3], v[52:55]
	v_mfma_f32_16x16x32_bf16 v[32:35], v[198:201], v[4:7], v[8:11]
	v_mfma_f32_16x16x32_bf16 v[8:11], v[174:177], v[224:227], v[48:51]
	v_mfma_f32_16x16x32_bf16 v[36:39], v[198:201], v[228:231], v[8:11]
	v_mfma_f32_16x16x32_bf16 v[8:11], v[202:205], v[0:3], v[244:247]
	v_mfma_f32_16x16x32_bf16 v[0:3], v[210:213], v[0:3], v[146:149]
	v_mfma_f32_16x16x32_bf16 v[8:11], v[206:209], v[4:7], v[8:11]
	v_mfma_f32_16x16x32_bf16 v[12:15], v[202:205], v[224:227], v[248:251]
	v_mfma_f32_16x16x32_bf16 v[0:3], v[138:141], v[4:7], v[0:3]
	v_mfma_f32_16x16x32_bf16 v[4:7], v[210:213], v[224:227], v[178:181]
	v_mfma_f32_16x16x32_bf16 v[12:15], v[206:209], v[228:231], v[12:15]
	v_mfma_f32_16x16x32_bf16 v[4:7], v[138:141], v[228:231], v[4:7]
	s_setprio 0
	s_setprio 1
	v_mfma_f32_16x16x32_bf16 v[16:19], v[174:177], v[236:239], v[16:19]
	v_mfma_f32_16x16x32_bf16 v[24:27], v[150:153], v[236:239], v[24:27]
	v_mfma_f32_16x16x32_bf16 v[52:55], v[198:201], v[240:243], v[16:19]
	v_mfma_f32_16x16x32_bf16 v[16:19], v[202:205], v[130:133], v[190:193]
	v_mfma_f32_16x16x32_bf16 v[28:31], v[150:153], v[130:133], v[28:31]
	v_mfma_f32_16x16x32_bf16 v[60:63], v[154:157], v[240:243], v[24:27]
	v_mfma_f32_16x16x32_bf16 v[20:23], v[174:177], v[130:133], v[20:23]
	v_mfma_f32_16x16x32_bf16 v[24:27], v[206:209], v[232:235], v[16:19]
	v_mfma_f32_16x16x32_bf16 v[16:19], v[202:205], v[236:239], v[194:197]
	v_mfma_f32_16x16x32_bf16 v[56:59], v[154:157], v[232:235], v[28:31]
	v_mfma_f32_16x16x32_bf16 v[48:51], v[198:201], v[232:235], v[20:23]
	v_mfma_f32_16x16x32_bf16 v[28:31], v[206:209], v[240:243], v[16:19]
	v_mfma_f32_16x16x32_bf16 v[16:19], v[210:213], v[130:133], v[216:219]
	v_mfma_f32_16x16x32_bf16 v[20:23], v[210:213], v[236:239], v[220:223]
	v_mfma_f32_16x16x32_bf16 v[16:19], v[138:141], v[232:235], v[16:19]
	v_mfma_f32_16x16x32_bf16 v[20:23], v[138:141], v[240:243], v[20:23]
	s_setprio 0
	v_cmp_gt_u32_e32 vcc, s92, v169
	s_barrier
	s_and_saveexec_b64 s[8:9], vcc
	s_cbranch_execz .LBB0_257
	s_barrier

.LBB0_641:
	s_or_b64 exec, exec, s[10:11]
	v_add_u32_e32 v175, s15, v6
	v_add_u32_e32 v176, 0x2000, v175
	v_readfirstlane_b32 s10, v175
	v_lshl_add_u64 v[8:9], v[0:1], 0, s[22:23]
	s_mov_b32 m0, s10
	s_mov_b64 s[70:71], 0x40080
	v_readfirstlane_b32 s10, v176
	v_add_u32_e32 v177, 0x8000, v168
	s_waitcnt vmcnt(0)
	s_barrier
	global_load_lds_dwordx4 v[8:9], off
	v_lshl_add_u64 v[8:9], v[0:1], 0, s[70:71]
	s_mov_b32 m0, s10
	v_readfirstlane_b32 s10, v177
	v_add_u32_e32 v178, 0xa000, v168
	global_load_lds_dwordx4 v[8:9], off
	v_lshl_add_u64 v[8:9], v[130:131], 0, s[22:23]
	s_mov_b32 m0, s10
	v_readfirstlane_b32 s10, v178
	global_load_lds_dwordx4 v[8:9], off
	v_lshl_add_u64 v[8:9], v[130:131], 0, s[70:71]
	s_mov_b32 m0, s10
	s_mov_b64 s[10:11], 0x80080
	v_add_u32_e32 v179, s36, v6
	global_load_lds_dwordx4 v[8:9], off
	v_lshl_add_u64 v[8:9], v[0:1], 0, s[10:11]
	v_readfirstlane_b32 s10, v179
	s_mov_b32 m0, s10
	s_mov_b64 s[10:11], 0xc0080
	v_add_u32_e32 v181, 0x2000, v179
	v_lshl_add_u64 v[0:1], v[0:1], 0, s[10:11]
	v_readfirstlane_b32 s10, v181
	global_load_lds_dwordx4 v[8:9], off
	s_mov_b32 m0, s10
	v_bfe_u32 v133, v132, 4, 2
	global_load_lds_dwordx4 v[0:1], off
	v_and_b32_e32 v134, 15, v132
	v_lshlrev_b32_e32 v137, 2, v132
	v_lshlrev_b32_e32 v0, 4, v133
	v_lshlrev_b32_e32 v6, 6, v134
	v_and_b32_e32 v7, 32, v137
	v_lshlrev_b32_e32 v12, 6, v132
	v_bitop3_b32 v6, v0, v7, v6 bitop3:0x36
	v_and_or_b32 v0, v12, s83, v0
	v_xad_u32 v7, v0, v7, 16
	v_lshlrev_b32_e32 v0, 9, v132
	v_ashrrev_i32_e32 v136, 6, v132
	v_and_b32_e32 v0, 0xffff0000, v0
	v_lshlrev_b32_e32 v2, 12, v2
	s_add_u32 s70, s8, s26
	v_and_b32_e32 v135, 3, v136
	s_waitcnt vmcnt(6)
	v_lshlrev_b32_e32 v160, 6, v5
	v_lshlrev_b32_e32 v5, 13, v5
	v_or3_b32 v0, v3, v0, v2
	s_addc_u32 s71, s9, 0
	v_lshlrev_b32_e32 v1, 12, v135
	v_add_u32_e32 v8, s35, v6
	v_add_u32_e32 v9, s14, v6
	v_add_u32_e32 v10, s15, v6
	v_add_u32_e32 v11, s36, v6
	v_add_u32_e32 v6, 16, v6
	v_or_b32_e32 v12, 0x800, v5
	v_or_b32_e32 v13, 0x1000, v5
	v_or_b32_e32 v14, 0x1800, v5
	v_add_u32_e32 v128, v0, v4
	s_add_u32 s72, s8, s72
	v_mov_b32_e32 v0, 0
	s_addc_u32 s73, s9, s73
	s_mov_b32 s10, -2
	v_add_u32_e32 v184, v8, v1
	v_add_u32_e32 v164, v6, v5
	v_add_u32_e32 v163, v7, v12
	v_add_u32_e32 v162, v7, v13
	v_add_u32_e32 v161, v7, v14
	v_add_u32_e32 v180, v9, v1
	v_add_u32_e32 v170, v10, v1
	v_add_u32_e32 v165, v11, v1
	v_mov_b32_e32 v1, v0
	v_mov_b32_e32 v2, v0
	v_mov_b32_e32 v3, v0
	v_mov_b32_e32 v4, v0
	v_mov_b32_e32 v5, v0
	v_mov_b32_e32 v6, v0
	v_mov_b32_e32 v7, v0
	v_mov_b32_e32 v8, v0
	v_mov_b32_e32 v9, v0
	v_mov_b32_e32 v10, v0
	v_mov_b32_e32 v11, v0
	v_mov_b32_e32 v12, v0
	v_mov_b32_e32 v13, v0
	v_mov_b32_e32 v14, v0
	v_mov_b32_e32 v15, v0
	v_mov_b32_e32 v16, v0
	v_mov_b32_e32 v17, v0
	v_mov_b32_e32 v18, v0
	v_mov_b32_e32 v19, v0
	v_mov_b32_e32 v20, v0
	v_mov_b32_e32 v21, v0
	v_mov_b32_e32 v22, v0
	v_mov_b32_e32 v23, v0
	v_mov_b32_e32 v24, v0
	v_mov_b32_e32 v25, v0
	v_mov_b32_e32 v26, v0
	v_mov_b32_e32 v27, v0
	v_mov_b32_e32 v28, v0
	v_mov_b32_e32 v29, v0
	v_mov_b32_e32 v30, v0
	v_mov_b32_e32 v31, v0
	v_mov_b32_e32 v32, v0
	v_mov_b32_e32 v33, v0
	v_mov_b32_e32 v34, v0
	v_mov_b32_e32 v35, v0
	v_mov_b32_e32 v36, v0
	v_mov_b32_e32 v37, v0
	v_mov_b32_e32 v38, v0
	v_mov_b32_e32 v39, v0
	v_mov_b32_e32 v40, v0
	v_mov_b32_e32 v41, v0
	v_mov_b32_e32 v42, v0
	v_mov_b32_e32 v43, v0
	v_mov_b32_e32 v44, v0
	v_mov_b32_e32 v45, v0
	v_mov_b32_e32 v46, v0
	v_mov_b32_e32 v47, v0
	v_mov_b32_e32 v48, v0
	v_mov_b32_e32 v49, v0
	v_mov_b32_e32 v50, v0
	v_mov_b32_e32 v51, v0
	v_mov_b32_e32 v52, v0
	v_mov_b32_e32 v53, v0
	v_mov_b32_e32 v54, v0
	v_mov_b32_e32 v55, v0
	v_mov_b32_e32 v56, v0
	v_mov_b32_e32 v57, v0
	v_mov_b32_e32 v58, v0
	v_mov_b32_e32 v59, v0
	v_mov_b32_e32 v60, v0
	v_mov_b32_e32 v61, v0
	v_mov_b32_e32 v62, v0
	v_mov_b32_e32 v63, v0
	v_mov_b32_e32 v64, v0
	v_mov_b32_e32 v65, v0
	v_mov_b32_e32 v66, v0
	v_mov_b32_e32 v67, v0
	v_mov_b32_e32 v68, v0
	v_mov_b32_e32 v69, v0
	v_mov_b32_e32 v70, v0
	v_mov_b32_e32 v71, v0
	v_mov_b32_e32 v72, v0
	v_mov_b32_e32 v73, v0
	v_mov_b32_e32 v74, v0
	v_mov_b32_e32 v75, v0
	v_mov_b32_e32 v76, v0
	v_mov_b32_e32 v77, v0
	v_mov_b32_e32 v78, v0
	v_mov_b32_e32 v79, v0
	v_mov_b32_e32 v80, v0
	v_mov_b32_e32 v81, v0
	v_mov_b32_e32 v82, v0
	v_mov_b32_e32 v83, v0
	v_mov_b32_e32 v84, v0
	v_mov_b32_e32 v85, v0
	v_mov_b32_e32 v86, v0
	v_mov_b32_e32 v87, v0
	v_mov_b32_e32 v88, v0
	v_mov_b32_e32 v89, v0
	v_mov_b32_e32 v90, v0
	v_mov_b32_e32 v91, v0
	v_mov_b32_e32 v92, v0
	v_mov_b32_e32 v93, v0
	v_mov_b32_e32 v94, v0
	v_mov_b32_e32 v95, v0
	v_mov_b32_e32 v96, v0
	v_mov_b32_e32 v97, v0
	v_mov_b32_e32 v98, v0
	v_mov_b32_e32 v99, v0
	v_mov_b32_e32 v100, v0
	v_mov_b32_e32 v101, v0
	v_mov_b32_e32 v102, v0
	v_mov_b32_e32 v103, v0
	v_mov_b32_e32 v104, v0
	v_mov_b32_e32 v105, v0
	v_mov_b32_e32 v106, v0
	v_mov_b32_e32 v107, v0
	v_mov_b32_e32 v108, v0
	v_mov_b32_e32 v109, v0
	v_mov_b32_e32 v110, v0
	v_mov_b32_e32 v111, v0
	v_mov_b32_e32 v112, v0
	v_mov_b32_e32 v113, v0
	v_mov_b32_e32 v114, v0
	v_mov_b32_e32 v115, v0
	v_mov_b32_e32 v116, v0
	v_mov_b32_e32 v117, v0
	v_mov_b32_e32 v118, v0
	v_mov_b32_e32 v119, v0
	v_mov_b32_e32 v120, v0
	v_mov_b32_e32 v121, v0
	v_mov_b32_e32 v122, v0
	v_mov_b32_e32 v123, v0
	v_mov_b32_e32 v124, v0
	v_mov_b32_e32 v125, v0
	v_mov_b32_e32 v126, v0
	v_mov_b32_e32 v127, v0
.Lkh_642:
	s_barrier
.LBB0_642:
	ds_read_b128 v[138:141], v184
	ds_read_b128 v[146:149], v184 offset:1024
	ds_read_b128 v[150:153], v184 offset:2048
	ds_read_b128 v[154:157], v184 offset:3072
	v_add_u32_e32 v185, 0xc000, v168
	v_lshl_add_u64 v[236:237], s[72:73], 0, v[128:129]
	s_mov_b64 s[26:27], 0x276ac180
	v_readfirstlane_b32 s11, v185
	v_lshl_add_u64 v[186:187], v[236:237], 0, s[26:27]
	s_mov_b32 m0, s11
	ds_read_b128 v[188:191], v164
	ds_read_b128 v[192:195], v164 offset:1024
	ds_read_b128 v[196:199], v163
	ds_read_b128 v[200:203], v163 offset:1024
	ds_read_b128 v[204:207], v162
	ds_read_b128 v[208:211], v162 offset:1024
	ds_read_b128 v[212:215], v161
	ds_read_b128 v[216:219], v161 offset:1024
	global_load_lds_dwordx4 v[186:187], off
	v_add_u32_e32 v186, 0xe000, v168
	s_mov_b64 s[26:27], 0x276ec180
	v_readfirstlane_b32 s11, v186
	v_lshl_add_u64 v[220:221], v[236:237], 0, s[26:27]
	s_mov_b32 m0, s11
	s_nop 0
	global_load_lds_dwordx4 v[220:221], off
	s_waitcnt lgkmcnt(8)
	s_barrier
	s_waitcnt lgkmcnt(0)
	s_setprio 1
	s_waitcnt lgkmcnt(0)
	v_mfma_f32_16x16x32_bf16 v[124:127], v[188:191], v[138:141], v[124:127]
	v_mfma_f32_16x16x32_bf16 v[120:123], v[188:191], v[150:153], v[120:123]
	v_mfma_f32_16x16x32_bf16 v[116:119], v[196:199], v[138:141], v[116:119]
	v_mfma_f32_16x16x32_bf16 v[112:115], v[196:199], v[150:153], v[112:115]
	v_mfma_f32_16x16x32_bf16 v[108:111], v[204:207], v[138:141], v[108:111]
	v_mfma_f32_16x16x32_bf16 v[104:107], v[204:207], v[150:153], v[104:107]
	v_mfma_f32_16x16x32_bf16 v[100:103], v[212:215], v[138:141], v[100:103]
	v_mfma_f32_16x16x32_bf16 v[96:99], v[212:215], v[150:153], v[96:99]
	v_mfma_f32_16x16x32_bf16 v[124:127], v[192:195], v[146:149], v[124:127]
	v_mfma_f32_16x16x32_bf16 v[120:123], v[192:195], v[154:157], v[120:123]
	v_mfma_f32_16x16x32_bf16 v[116:119], v[200:203], v[146:149], v[116:119]
	v_mfma_f32_16x16x32_bf16 v[112:115], v[200:203], v[154:157], v[112:115]
	v_mfma_f32_16x16x32_bf16 v[108:111], v[208:211], v[146:149], v[108:111]
	v_mfma_f32_16x16x32_bf16 v[104:107], v[208:211], v[154:157], v[104:107]
	v_mfma_f32_16x16x32_bf16 v[100:103], v[216:219], v[146:149], v[100:103]
	v_mfma_f32_16x16x32_bf16 v[96:99], v[216:219], v[154:157], v[96:99]
	s_setprio 0
	s_barrier
	v_lshl_add_u64 v[238:239], s[70:71], 0, v[128:129]
	s_mov_b64 s[26:27], 0xc00100
	v_readfirstlane_b32 s11, v166
	v_lshl_add_u64 v[240:241], v[238:239], 0, s[26:27]
	s_mov_b32 m0, s11
	s_mov_b64 s[26:27], 0xc40100
	v_readfirstlane_b32 s11, v167
	ds_read_b128 v[220:223], v180
	ds_read_b128 v[224:227], v180 offset:1024
	ds_read_b128 v[228:231], v180 offset:2048
	ds_read_b128 v[232:235], v180 offset:3072
	global_load_lds_dwordx4 v[240:241], off
	v_lshl_add_u64 v[240:241], v[238:239], 0, s[26:27]
	s_mov_b32 m0, s11
	s_nop 0
	global_load_lds_dwordx4 v[240:241], off
	s_barrier
	s_waitcnt lgkmcnt(0)
	s_setprio 1
	s_waitcnt lgkmcnt(0)
	v_mfma_f32_16x16x32_bf16 v[92:95], v[188:191], v[220:223], v[92:95]
	v_mfma_f32_16x16x32_bf16 v[88:91], v[188:191], v[228:231], v[88:91]
	v_mfma_f32_16x16x32_bf16 v[84:87], v[196:199], v[220:223], v[84:87]
	v_mfma_f32_16x16x32_bf16 v[80:83], v[196:199], v[228:231], v[80:83]
	v_mfma_f32_16x16x32_bf16 v[76:79], v[204:207], v[220:223], v[76:79]
	v_mfma_f32_16x16x32_bf16 v[72:75], v[204:207], v[228:231], v[72:75]
	v_mfma_f32_16x16x32_bf16 v[68:71], v[212:215], v[220:223], v[68:71]
	v_mfma_f32_16x16x32_bf16 v[64:67], v[212:215], v[228:231], v[64:67]
	v_mfma_f32_16x16x32_bf16 v[92:95], v[192:195], v[224:227], v[92:95]
	v_mfma_f32_16x16x32_bf16 v[88:91], v[192:195], v[232:235], v[88:91]
	v_mfma_f32_16x16x32_bf16 v[84:87], v[200:203], v[224:227], v[84:87]
	v_mfma_f32_16x16x32_bf16 v[80:83], v[200:203], v[232:235], v[80:83]
	v_mfma_f32_16x16x32_bf16 v[76:79], v[208:211], v[224:227], v[76:79]
	v_mfma_f32_16x16x32_bf16 v[72:75], v[208:211], v[232:235], v[72:75]
	v_mfma_f32_16x16x32_bf16 v[68:71], v[216:219], v[224:227], v[68:71]
	v_mfma_f32_16x16x32_bf16 v[64:67], v[216:219], v[232:235], v[64:67]
	s_setprio 0
	s_mov_b64 s[26:27], 0x2762c200
	v_readfirstlane_b32 s11, v168
	v_lshl_add_u64 v[240:241], v[236:237], 0, s[26:27]
	s_mov_b32 m0, s11
	s_mov_b64 s[26:27], 0x2766c200
	v_readfirstlane_b32 s11, v169
	s_barrier
	ds_read_b128 v[188:191], v164 offset:16384
	ds_read_b128 v[192:195], v164 offset:17408
	ds_read_b128 v[196:199], v163 offset:16384
	ds_read_b128 v[200:203], v163 offset:17408
	ds_read_b128 v[204:207], v162 offset:16384
	ds_read_b128 v[208:211], v162 offset:17408
	ds_read_b128 v[212:215], v161 offset:16384
	ds_read_b128 v[216:219], v161 offset:17408
	global_load_lds_dwordx4 v[240:241], off
	v_lshl_add_u64 v[240:241], v[236:237], 0, s[26:27]
	s_mov_b32 m0, s11
	s_nop 0
	global_load_lds_dwordx4 v[240:241], off
	s_barrier
	s_waitcnt lgkmcnt(0)
	s_setprio 1
	s_waitcnt lgkmcnt(0)
	v_mfma_f32_16x16x32_bf16 v[60:63], v[188:191], v[138:141], v[60:63]
	v_mfma_f32_16x16x32_bf16 v[56:59], v[188:191], v[150:153], v[56:59]
	v_mfma_f32_16x16x32_bf16 v[52:55], v[196:199], v[138:141], v[52:55]
	v_mfma_f32_16x16x32_bf16 v[48:51], v[196:199], v[150:153], v[48:51]
	v_mfma_f32_16x16x32_bf16 v[44:47], v[204:207], v[138:141], v[44:47]
	v_mfma_f32_16x16x32_bf16 v[40:43], v[204:207], v[150:153], v[40:43]
	v_mfma_f32_16x16x32_bf16 v[36:39], v[212:215], v[138:141], v[36:39]
	v_mfma_f32_16x16x32_bf16 v[32:35], v[212:215], v[150:153], v[32:35]
	v_mfma_f32_16x16x32_bf16 v[60:63], v[192:195], v[146:149], v[60:63]
	v_mfma_f32_16x16x32_bf16 v[56:59], v[192:195], v[154:157], v[56:59]
	v_mfma_f32_16x16x32_bf16 v[52:55], v[200:203], v[146:149], v[52:55]
	v_mfma_f32_16x16x32_bf16 v[48:51], v[200:203], v[154:157], v[48:51]
	v_mfma_f32_16x16x32_bf16 v[44:47], v[208:211], v[146:149], v[44:47]
	v_mfma_f32_16x16x32_bf16 v[40:43], v[208:211], v[154:157], v[40:43]
	v_mfma_f32_16x16x32_bf16 v[36:39], v[216:219], v[146:149], v[36:39]
	v_mfma_f32_16x16x32_bf16 v[32:35], v[216:219], v[154:157], v[32:35]
	s_setprio 0
	s_barrier
	s_mov_b64 s[26:27], 0xc80100
	v_readfirstlane_b32 s11, v171
	v_lshl_add_u64 v[138:139], v[238:239], 0, s[26:27]
	s_mov_b32 m0, s11
	s_mov_b64 s[26:27], 0xcc0100
	v_readfirstlane_b32 s11, v172
	global_load_lds_dwordx4 v[138:139], off
	v_lshl_add_u64 v[138:139], v[238:239], 0, s[26:27]
	s_mov_b32 m0, s11
	s_nop 0
	global_load_lds_dwordx4 v[138:139], off
	s_waitcnt vmcnt(6)
	s_barrier
	s_setprio 1
	v_mfma_f32_16x16x32_bf16 v[28:31], v[188:191], v[220:223], v[28:31]
	v_mfma_f32_16x16x32_bf16 v[24:27], v[188:191], v[228:231], v[24:27]
	v_mfma_f32_16x16x32_bf16 v[20:23], v[196:199], v[220:223], v[20:23]
	v_mfma_f32_16x16x32_bf16 v[16:19], v[196:199], v[228:231], v[16:19]
	v_mfma_f32_16x16x32_bf16 v[12:15], v[204:207], v[220:223], v[12:15]
	v_mfma_f32_16x16x32_bf16 v[8:11], v[204:207], v[228:231], v[8:11]
	v_mfma_f32_16x16x32_bf16 v[4:7], v[212:215], v[220:223], v[4:7]
	v_mfma_f32_16x16x32_bf16 v[0:3], v[212:215], v[228:231], v[0:3]
	v_mfma_f32_16x16x32_bf16 v[28:31], v[192:195], v[224:227], v[28:31]
	v_mfma_f32_16x16x32_bf16 v[24:27], v[192:195], v[232:235], v[24:27]
	v_mfma_f32_16x16x32_bf16 v[20:23], v[200:203], v[224:227], v[20:23]
	v_mfma_f32_16x16x32_bf16 v[16:19], v[200:203], v[232:235], v[16:19]
	v_mfma_f32_16x16x32_bf16 v[12:15], v[208:211], v[224:227], v[12:15]
	v_mfma_f32_16x16x32_bf16 v[8:11], v[208:211], v[232:235], v[8:11]
	v_mfma_f32_16x16x32_bf16 v[4:7], v[216:219], v[224:227], v[4:7]
	v_mfma_f32_16x16x32_bf16 v[0:3], v[216:219], v[232:235], v[0:3]
	s_setprio 0
	s_barrier
	ds_read_b128 v[138:141], v170
	ds_read_b128 v[146:149], v170 offset:1024
	ds_read_b128 v[150:153], v170 offset:2048
	ds_read_b128 v[154:157], v170 offset:3072
	s_mov_b64 s[26:27], 0x276ac200
	v_readfirstlane_b32 s11, v173
	v_lshl_add_u64 v[220:221], v[236:237], 0, s[26:27]
	s_mov_b32 m0, s11
	s_mov_b64 s[26:27], 0x276ec200
	v_readfirstlane_b32 s11, v174
	ds_read_b128 v[188:191], v164 offset:32768
	ds_read_b128 v[192:195], v164 offset:33792
	ds_read_b128 v[196:199], v163 offset:32768
	ds_read_b128 v[200:203], v163 offset:33792
	ds_read_b128 v[204:207], v162 offset:32768
	ds_read_b128 v[208:211], v162 offset:33792
	ds_read_b128 v[212:215], v161 offset:32768
	ds_read_b128 v[216:219], v161 offset:33792
	global_load_lds_dwordx4 v[220:221], off
	v_lshl_add_u64 v[220:221], v[236:237], 0, s[26:27]
	s_mov_b32 m0, s11
	s_nop 0
	global_load_lds_dwordx4 v[220:221], off
	s_waitcnt lgkmcnt(8)
	s_barrier
	s_waitcnt lgkmcnt(0)
	s_setprio 1
	s_waitcnt lgkmcnt(0)
	v_mfma_f32_16x16x32_bf16 v[124:127], v[188:191], v[138:141], v[124:127]
	v_mfma_f32_16x16x32_bf16 v[120:123], v[188:191], v[150:153], v[120:123]
	v_mfma_f32_16x16x32_bf16 v[116:119], v[196:199], v[138:141], v[116:119]
	v_mfma_f32_16x16x32_bf16 v[112:115], v[196:199], v[150:153], v[112:115]
	v_mfma_f32_16x16x32_bf16 v[108:111], v[204:207], v[138:141], v[108:111]
	v_mfma_f32_16x16x32_bf16 v[104:107], v[204:207], v[150:153], v[104:107]
	v_mfma_f32_16x16x32_bf16 v[100:103], v[212:215], v[138:141], v[100:103]
	v_mfma_f32_16x16x32_bf16 v[96:99], v[212:215], v[150:153], v[96:99]
	v_mfma_f32_16x16x32_bf16 v[124:127], v[192:195], v[146:149], v[124:127]
	v_mfma_f32_16x16x32_bf16 v[120:123], v[192:195], v[154:157], v[120:123]
	v_mfma_f32_16x16x32_bf16 v[116:119], v[200:203], v[146:149], v[116:119]
	v_mfma_f32_16x16x32_bf16 v[112:115], v[200:203], v[154:157], v[112:115]
	v_mfma_f32_16x16x32_bf16 v[108:111], v[208:211], v[146:149], v[108:111]
	v_mfma_f32_16x16x32_bf16 v[104:107], v[208:211], v[154:157], v[104:107]
	v_mfma_f32_16x16x32_bf16 v[100:103], v[216:219], v[146:149], v[100:103]
	v_mfma_f32_16x16x32_bf16 v[96:99], v[216:219], v[154:157], v[96:99]
	s_setprio 0
	s_barrier
	s_mov_b64 s[26:27], 0xc00180
	v_readfirstlane_b32 s11, v175
	v_lshl_add_u64 v[240:241], v[238:239], 0, s[26:27]
	s_mov_b32 m0, s11
	s_mov_b64 s[26:27], 0xc40180
	v_readfirstlane_b32 s11, v176
	ds_read_b128 v[220:223], v165
	ds_read_b128 v[224:227], v165 offset:1024
	ds_read_b128 v[228:231], v165 offset:2048
	ds_read_b128 v[232:235], v165 offset:3072
	global_load_lds_dwordx4 v[240:241], off
	v_lshl_add_u64 v[240:241], v[238:239], 0, s[26:27]
	s_mov_b32 m0, s11
	s_nop 0
	global_load_lds_dwordx4 v[240:241], off
	s_barrier
	s_waitcnt lgkmcnt(0)
	s_setprio 1
	s_waitcnt lgkmcnt(0)
	v_mfma_f32_16x16x32_bf16 v[92:95], v[188:191], v[220:223], v[92:95]
	v_mfma_f32_16x16x32_bf16 v[88:91], v[188:191], v[228:231], v[88:91]
	v_mfma_f32_16x16x32_bf16 v[84:87], v[196:199], v[220:223], v[84:87]
	v_mfma_f32_16x16x32_bf16 v[80:83], v[196:199], v[228:231], v[80:83]
	v_mfma_f32_16x16x32_bf16 v[76:79], v[204:207], v[220:223], v[76:79]
	v_mfma_f32_16x16x32_bf16 v[72:75], v[204:207], v[228:231], v[72:75]
	v_mfma_f32_16x16x32_bf16 v[68:71], v[212:215], v[220:223], v[68:71]
	v_mfma_f32_16x16x32_bf16 v[64:67], v[212:215], v[228:231], v[64:67]
	v_mfma_f32_16x16x32_bf16 v[92:95], v[192:195], v[224:227], v[92:95]
	v_mfma_f32_16x16x32_bf16 v[88:91], v[192:195], v[232:235], v[88:91]
	v_mfma_f32_16x16x32_bf16 v[84:87], v[200:203], v[224:227], v[84:87]
	v_mfma_f32_16x16x32_bf16 v[80:83], v[200:203], v[232:235], v[80:83]
	v_mfma_f32_16x16x32_bf16 v[76:79], v[208:211], v[224:227], v[76:79]
	v_mfma_f32_16x16x32_bf16 v[72:75], v[208:211], v[232:235], v[72:75]
	v_mfma_f32_16x16x32_bf16 v[68:71], v[216:219], v[224:227], v[68:71]
	v_mfma_f32_16x16x32_bf16 v[64:67], v[216:219], v[232:235], v[64:67]
	s_setprio 0
	s_mov_b64 s[26:27], 0x2762c280
	v_readfirstlane_b32 s11, v177
	v_lshl_add_u64 v[240:241], v[236:237], 0, s[26:27]
	s_mov_b32 m0, s11
	s_mov_b64 s[26:27], 0x2766c280
	v_readfirstlane_b32 s11, v178
	s_barrier
	ds_read_b128 v[188:191], v164 offset:49152
	ds_read_b128 v[192:195], v164 offset:50176
	ds_read_b128 v[196:199], v163 offset:49152
	ds_read_b128 v[200:203], v163 offset:50176
	ds_read_b128 v[204:207], v162 offset:49152
	ds_read_b128 v[208:211], v162 offset:50176
	ds_read_b128 v[212:215], v161 offset:49152
	ds_read_b128 v[216:219], v161 offset:50176
	global_load_lds_dwordx4 v[240:241], off
	v_lshl_add_u64 v[236:237], v[236:237], 0, s[26:27]
	s_mov_b32 m0, s11
	s_nop 0
	global_load_lds_dwordx4 v[236:237], off
	s_barrier
	s_waitcnt lgkmcnt(0)
	s_setprio 1
	s_waitcnt lgkmcnt(0)
	v_mfma_f32_16x16x32_bf16 v[60:63], v[188:191], v[138:141], v[60:63]
	v_mfma_f32_16x16x32_bf16 v[56:59], v[188:191], v[150:153], v[56:59]
	v_mfma_f32_16x16x32_bf16 v[52:55], v[196:199], v[138:141], v[52:55]
	v_mfma_f32_16x16x32_bf16 v[48:51], v[196:199], v[150:153], v[48:51]
	v_mfma_f32_16x16x32_bf16 v[44:47], v[204:207], v[138:141], v[44:47]
	v_mfma_f32_16x16x32_bf16 v[40:43], v[204:207], v[150:153], v[40:43]
	v_mfma_f32_16x16x32_bf16 v[36:39], v[212:215], v[138:141], v[36:39]
	v_mfma_f32_16x16x32_bf16 v[32:35], v[212:215], v[150:153], v[32:35]
	v_mfma_f32_16x16x32_bf16 v[60:63], v[192:195], v[146:149], v[60:63]
	v_mfma_f32_16x16x32_bf16 v[56:59], v[192:195], v[154:157], v[56:59]
	v_mfma_f32_16x16x32_bf16 v[52:55], v[200:203], v[146:149], v[52:55]
	v_mfma_f32_16x16x32_bf16 v[48:51], v[200:203], v[154:157], v[48:51]
	v_mfma_f32_16x16x32_bf16 v[44:47], v[208:211], v[146:149], v[44:47]
	v_mfma_f32_16x16x32_bf16 v[40:43], v[208:211], v[154:157], v[40:43]
	v_mfma_f32_16x16x32_bf16 v[36:39], v[216:219], v[146:149], v[36:39]
	v_mfma_f32_16x16x32_bf16 v[32:35], v[216:219], v[154:157], v[32:35]
	s_setprio 0
	s_barrier
	s_mov_b64 s[26:27], 0xc80180
	v_readfirstlane_b32 s11, v179
	v_lshl_add_u64 v[138:139], v[238:239], 0, s[26:27]
	s_mov_b32 m0, s11
	s_mov_b64 s[26:27], 0xcc0180
	v_readfirstlane_b32 s11, v181
	global_load_lds_dwordx4 v[138:139], off
	v_lshl_add_u64 v[138:139], v[238:239], 0, s[26:27]
	s_mov_b32 m0, s11
	s_nop 0
	global_load_lds_dwordx4 v[138:139], off
	s_waitcnt vmcnt(6)
	s_barrier
	s_setprio 1
	v_mfma_f32_16x16x32_bf16 v[28:31], v[188:191], v[220:223], v[28:31]
	v_mfma_f32_16x16x32_bf16 v[24:27], v[188:191], v[228:231], v[24:27]
	v_mfma_f32_16x16x32_bf16 v[20:23], v[196:199], v[220:223], v[20:23]
	v_mfma_f32_16x16x32_bf16 v[16:19], v[196:199], v[228:231], v[16:19]
	v_mfma_f32_16x16x32_bf16 v[12:15], v[204:207], v[220:223], v[12:15]
	v_mfma_f32_16x16x32_bf16 v[8:11], v[204:207], v[228:231], v[8:11]
	v_mfma_f32_16x16x32_bf16 v[4:7], v[212:215], v[220:223], v[4:7]
	v_mfma_f32_16x16x32_bf16 v[0:3], v[212:215], v[228:231], v[0:3]
	v_mfma_f32_16x16x32_bf16 v[28:31], v[192:195], v[224:227], v[28:31]
	v_mfma_f32_16x16x32_bf16 v[24:27], v[192:195], v[232:235], v[24:27]
	v_mfma_f32_16x16x32_bf16 v[20:23], v[200:203], v[224:227], v[20:23]
	v_mfma_f32_16x16x32_bf16 v[16:19], v[200:203], v[232:235], v[16:19]
	v_mfma_f32_16x16x32_bf16 v[12:15], v[208:211], v[224:227], v[12:15]
	v_mfma_f32_16x16x32_bf16 v[8:11], v[208:211], v[232:235], v[8:11]
	v_mfma_f32_16x16x32_bf16 v[4:7], v[216:219], v[224:227], v[4:7]
	v_mfma_f32_16x16x32_bf16 v[0:3], v[216:219], v[232:235], v[0:3]
	s_setprio 0
	s_add_i32 s10, s10, 2
	s_add_u32 s70, s70, 0x100
	s_addc_u32 s71, s71, 0
	s_add_u32 s72, s72, 0x100
	s_addc_u32 s73, s73, 0
	s_cmp_lt_u32 s10, 28
	s_cbranch_scc1 .Lkh_642
	s_barrier
	s_mov_b64 s[10:11], 0x80f80
	v_lshl_add_u64 v[208:209], v[130:131], 0, s[10:11]
	v_readfirstlane_b32 s10, v185
	s_mov_b32 m0, s10
	s_mov_b64 s[10:11], 0xc0f80
	v_lshl_add_u64 v[130:131], v[130:131], 0, s[10:11]
	v_readfirstlane_b32 s10, v186
	ds_read_b128 v[138:141], v184
	ds_read_b128 v[146:149], v184 offset:1024
	ds_read_b128 v[150:153], v184 offset:2048
	ds_read_b128 v[154:157], v184 offset:3072
	ds_read_b128 v[166:169], v164
	ds_read_b128 v[172:175], v164 offset:1024
	ds_read_b128 v[176:179], v163
	ds_read_b128 v[188:191], v163 offset:1024
	ds_read_b128 v[192:195], v162
	ds_read_b128 v[196:199], v162 offset:1024
	ds_read_b128 v[200:203], v161
	ds_read_b128 v[204:207], v161 offset:1024
	global_load_lds_dwordx4 v[208:209], off
	s_mov_b32 m0, s10
	s_nop 0
	global_load_lds_dwordx4 v[130:131], off
	s_barrier
	s_waitcnt lgkmcnt(0)
	s_setprio 1
	s_waitcnt lgkmcnt(0)
	v_mfma_f32_16x16x32_bf16 v[124:127], v[166:169], v[138:141], v[124:127]
	v_mfma_f32_16x16x32_bf16 v[120:123], v[166:169], v[150:153], v[120:123]
	v_mfma_f32_16x16x32_bf16 v[116:119], v[176:179], v[138:141], v[116:119]
	v_mfma_f32_16x16x32_bf16 v[112:115], v[176:179], v[150:153], v[112:115]
	v_mfma_f32_16x16x32_bf16 v[124:127], v[172:175], v[146:149], v[124:127]
	v_mfma_f32_16x16x32_bf16 v[120:123], v[172:175], v[154:157], v[120:123]
	v_mfma_f32_16x16x32_bf16 v[116:119], v[188:191], v[146:149], v[116:119]
	v_mfma_f32_16x16x32_bf16 v[112:115], v[188:191], v[154:157], v[112:115]
	v_mfma_f32_16x16x32_bf16 v[108:111], v[192:195], v[138:141], v[108:111]
	v_mfma_f32_16x16x32_bf16 v[104:107], v[192:195], v[150:153], v[104:107]
	v_mfma_f32_16x16x32_bf16 v[100:103], v[200:203], v[138:141], v[100:103]
	v_mfma_f32_16x16x32_bf16 v[96:99], v[200:203], v[150:153], v[96:99]
	v_mfma_f32_16x16x32_bf16 v[184:187], v[196:199], v[146:149], v[108:111]
	v_mfma_f32_16x16x32_bf16 v[208:211], v[196:199], v[154:157], v[104:107]
	v_mfma_f32_16x16x32_bf16 v[212:215], v[204:207], v[146:149], v[100:103]
	v_mfma_f32_16x16x32_bf16 v[216:219], v[204:207], v[154:157], v[96:99]
	s_setprio 0
	s_barrier
	s_nop 1
	ds_read_b128 v[96:99], v180
	ds_read_b128 v[100:103], v180 offset:1024
	ds_read_b128 v[104:107], v180 offset:2048
	ds_read_b128 v[108:111], v180 offset:3072
	s_barrier
	s_waitcnt lgkmcnt(0)
	s_setprio 1
	s_waitcnt lgkmcnt(0)
	v_mfma_f32_16x16x32_bf16 v[92:95], v[166:169], v[96:99], v[92:95]
	v_mfma_f32_16x16x32_bf16 v[88:91], v[166:169], v[104:107], v[88:91]
	v_mfma_f32_16x16x32_bf16 v[84:87], v[176:179], v[96:99], v[84:87]
	v_mfma_f32_16x16x32_bf16 v[80:83], v[176:179], v[104:107], v[80:83]
	v_mfma_f32_16x16x32_bf16 v[92:95], v[172:175], v[100:103], v[92:95]
	v_mfma_f32_16x16x32_bf16 v[88:91], v[172:175], v[108:111], v[88:91]
	v_mfma_f32_16x16x32_bf16 v[84:87], v[188:191], v[100:103], v[84:87]
	v_mfma_f32_16x16x32_bf16 v[80:83], v[188:191], v[108:111], v[80:83]
	v_mfma_f32_16x16x32_bf16 v[76:79], v[192:195], v[96:99], v[76:79]
	v_mfma_f32_16x16x32_bf16 v[72:75], v[192:195], v[104:107], v[72:75]
	v_mfma_f32_16x16x32_bf16 v[68:71], v[200:203], v[96:99], v[68:71]
	v_mfma_f32_16x16x32_bf16 v[64:67], v[200:203], v[104:107], v[64:67]
	v_mfma_f32_16x16x32_bf16 v[166:169], v[196:199], v[100:103], v[76:79]
	v_mfma_f32_16x16x32_bf16 v[172:175], v[196:199], v[108:111], v[72:75]
	v_mfma_f32_16x16x32_bf16 v[176:179], v[204:207], v[100:103], v[68:71]
	v_mfma_f32_16x16x32_bf16 v[188:191], v[204:207], v[108:111], v[64:67]
	s_setprio 0
	s_barrier
	s_nop 1
	ds_read_b128 v[64:67], v164 offset:16384
	ds_read_b128 v[68:71], v164 offset:17408
	ds_read_b128 v[72:75], v163 offset:16384
	ds_read_b128 v[76:79], v163 offset:17408
	ds_read_b128 v[192:195], v162 offset:16384
	ds_read_b128 v[196:199], v162 offset:17408
	ds_read_b128 v[200:203], v161 offset:16384
	ds_read_b128 v[204:207], v161 offset:17408
	s_waitcnt vmcnt(4)
	s_barrier
	s_waitcnt lgkmcnt(0)
	s_setprio 1
	s_waitcnt lgkmcnt(0)
	v_mfma_f32_16x16x32_bf16 v[60:63], v[64:67], v[138:141], v[60:63]
	v_mfma_f32_16x16x32_bf16 v[56:59], v[64:67], v[150:153], v[56:59]
	v_mfma_f32_16x16x32_bf16 v[52:55], v[72:75], v[138:141], v[52:55]
	v_mfma_f32_16x16x32_bf16 v[48:51], v[72:75], v[150:153], v[48:51]
	v_mfma_f32_16x16x32_bf16 v[60:63], v[68:71], v[146:149], v[60:63]
	v_mfma_f32_16x16x32_bf16 v[56:59], v[68:71], v[154:157], v[56:59]
	v_mfma_f32_16x16x32_bf16 v[52:55], v[76:79], v[146:149], v[52:55]
	v_mfma_f32_16x16x32_bf16 v[48:51], v[76:79], v[154:157], v[48:51]
	v_mfma_f32_16x16x32_bf16 v[44:47], v[192:195], v[138:141], v[44:47]
	v_mfma_f32_16x16x32_bf16 v[40:43], v[192:195], v[150:153], v[40:43]
	v_mfma_f32_16x16x32_bf16 v[36:39], v[200:203], v[138:141], v[36:39]
	v_mfma_f32_16x16x32_bf16 v[32:35], v[200:203], v[150:153], v[32:35]
	v_mfma_f32_16x16x32_bf16 v[220:223], v[196:199], v[146:149], v[44:47]
	v_mfma_f32_16x16x32_bf16 v[224:227], v[196:199], v[154:157], v[40:43]
	v_mfma_f32_16x16x32_bf16 v[138:141], v[204:207], v[146:149], v[36:39]
	v_mfma_f32_16x16x32_bf16 v[146:149], v[204:207], v[154:157], v[32:35]
	s_setprio 0
	s_setprio 1
	v_mfma_f32_16x16x32_bf16 v[28:31], v[64:67], v[96:99], v[28:31]
	v_mfma_f32_16x16x32_bf16 v[24:27], v[64:67], v[104:107], v[24:27]
	v_mfma_f32_16x16x32_bf16 v[20:23], v[72:75], v[96:99], v[20:23]
	v_mfma_f32_16x16x32_bf16 v[16:19], v[72:75], v[104:107], v[16:19]
	v_mfma_f32_16x16x32_bf16 v[28:31], v[68:71], v[100:103], v[28:31]
	v_mfma_f32_16x16x32_bf16 v[24:27], v[68:71], v[108:111], v[24:27]
	v_mfma_f32_16x16x32_bf16 v[20:23], v[76:79], v[100:103], v[20:23]
	v_mfma_f32_16x16x32_bf16 v[16:19], v[76:79], v[108:111], v[16:19]
	v_mfma_f32_16x16x32_bf16 v[12:15], v[192:195], v[96:99], v[12:15]
	v_mfma_f32_16x16x32_bf16 v[8:11], v[192:195], v[104:107], v[8:11]
	v_mfma_f32_16x16x32_bf16 v[4:7], v[200:203], v[96:99], v[4:7]
	v_mfma_f32_16x16x32_bf16 v[0:3], v[200:203], v[104:107], v[0:3]
	v_mfma_f32_16x16x32_bf16 v[150:153], v[196:199], v[100:103], v[12:15]
	v_mfma_f32_16x16x32_bf16 v[154:157], v[196:199], v[108:111], v[8:11]
	v_mfma_f32_16x16x32_bf16 v[192:195], v[204:207], v[100:103], v[4:7]
	v_mfma_f32_16x16x32_bf16 v[196:199], v[204:207], v[108:111], v[0:3]
	s_setprio 0
	s_barrier
	s_nop 1
	ds_read_b128 v[0:3], v170
	ds_read_b128 v[4:7], v170 offset:1024
	ds_read_b128 v[200:203], v170 offset:2048
	ds_read_b128 v[204:207], v170 offset:3072
	ds_read_b128 v[8:11], v164 offset:32768
	ds_read_b128 v[12:15], v164 offset:33792
	ds_read_b128 v[32:35], v163 offset:32768
	ds_read_b128 v[36:39], v163 offset:33792
	ds_read_b128 v[40:43], v162 offset:32768
	ds_read_b128 v[44:47], v162 offset:33792
	ds_read_b128 v[228:231], v161 offset:32768
	ds_read_b128 v[232:235], v161 offset:33792
	s_waitcnt vmcnt(2)
	s_barrier
	s_waitcnt lgkmcnt(0)
	s_setprio 1
	s_waitcnt lgkmcnt(0)
	v_mfma_f32_16x16x32_bf16 v[64:67], v[8:11], v[0:3], v[124:127]
	v_mfma_f32_16x16x32_bf16 v[104:107], v[12:15], v[4:7], v[64:67]
	v_mfma_f32_16x16x32_bf16 v[64:67], v[8:11], v[200:203], v[120:123]
	v_mfma_f32_16x16x32_bf16 v[108:111], v[12:15], v[204:207], v[64:67]
	v_mfma_f32_16x16x32_bf16 v[64:67], v[32:35], v[0:3], v[116:119]
	v_mfma_f32_16x16x32_bf16 v[96:99], v[36:39], v[4:7], v[64:67]
	v_mfma_f32_16x16x32_bf16 v[64:67], v[32:35], v[200:203], v[112:115]
	v_mfma_f32_16x16x32_bf16 v[100:103], v[36:39], v[204:207], v[64:67]
	v_mfma_f32_16x16x32_bf16 v[64:67], v[40:43], v[0:3], v[184:187]
	v_mfma_f32_16x16x32_bf16 v[72:75], v[44:47], v[4:7], v[64:67]
	v_mfma_f32_16x16x32_bf16 v[64:67], v[40:43], v[200:203], v[208:211]
	v_mfma_f32_16x16x32_bf16 v[76:79], v[44:47], v[204:207], v[64:67]
	v_mfma_f32_16x16x32_bf16 v[64:67], v[228:231], v[0:3], v[212:215]
	v_mfma_f32_16x16x32_bf16 v[68:71], v[228:231], v[200:203], v[216:219]
	v_mfma_f32_16x16x32_bf16 v[64:67], v[232:235], v[4:7], v[64:67]
	v_mfma_f32_16x16x32_bf16 v[68:71], v[232:235], v[204:207], v[68:71]
	s_setprio 0
	s_barrier
	ds_read_b128 v[184:187], v165
	ds_read_b128 v[208:211], v165 offset:1024
	ds_read_b128 v[212:215], v165 offset:2048
	ds_read_b128 v[216:219], v165 offset:3072
	s_waitcnt vmcnt(0)
	s_barrier
	s_waitcnt lgkmcnt(0)
	s_setprio 1
	s_waitcnt lgkmcnt(0)
	v_mfma_f32_16x16x32_bf16 v[92:95], v[8:11], v[184:187], v[92:95]
	v_mfma_f32_16x16x32_bf16 v[8:11], v[8:11], v[212:215], v[88:91]
	v_mfma_f32_16x16x32_bf16 v[124:127], v[12:15], v[216:219], v[8:11]
	v_mfma_f32_16x16x32_bf16 v[8:11], v[32:35], v[184:187], v[84:87]
	v_mfma_f32_16x16x32_bf16 v[112:115], v[36:39], v[208:211], v[8:11]
	v_mfma_f32_16x16x32_bf16 v[8:11], v[32:35], v[212:215], v[80:83]
	v_mfma_f32_16x16x32_bf16 v[116:119], v[36:39], v[216:219], v[8:11]
	v_mfma_f32_16x16x32_bf16 v[8:11], v[40:43], v[184:187], v[166:169]
	v_mfma_f32_16x16x32_bf16 v[88:91], v[44:47], v[208:211], v[8:11]
	v_mfma_f32_16x16x32_bf16 v[8:11], v[40:43], v[212:215], v[172:175]
	v_mfma_f32_16x16x32_bf16 v[120:123], v[12:15], v[208:211], v[92:95]
	v_mfma_f32_16x16x32_bf16 v[92:95], v[44:47], v[216:219], v[8:11]
	v_mfma_f32_16x16x32_bf16 v[8:11], v[228:231], v[184:187], v[176:179]
	v_mfma_f32_16x16x32_bf16 v[80:83], v[232:235], v[208:211], v[8:11]
	v_mfma_f32_16x16x32_bf16 v[8:11], v[228:231], v[212:215], v[188:191]
	v_mfma_f32_16x16x32_bf16 v[84:87], v[232:235], v[216:219], v[8:11]
	s_setprio 0
	s_barrier
	ds_read_b128 v[166:169], v164 offset:49152
	ds_read_b128 v[170:173], v164 offset:50176
	ds_read_b128 v[174:177], v163 offset:49152
	ds_read_b128 v[178:181], v163 offset:50176
	ds_read_b128 v[188:191], v162 offset:49152
	ds_read_b128 v[162:165], v162 offset:50176
	ds_read_b128 v[228:231], v161 offset:49152
	ds_read_b128 v[232:235], v161 offset:50176
	s_barrier
	s_waitcnt lgkmcnt(0)
	s_setprio 1
	s_waitcnt lgkmcnt(0)
	v_mfma_f32_16x16x32_bf16 v[8:11], v[166:169], v[0:3], v[60:63]
	v_mfma_f32_16x16x32_bf16 v[40:43], v[170:173], v[4:7], v[8:11]
	v_mfma_f32_16x16x32_bf16 v[8:11], v[166:169], v[200:203], v[56:59]
	v_mfma_f32_16x16x32_bf16 v[44:47], v[170:173], v[204:207], v[8:11]
	v_mfma_f32_16x16x32_bf16 v[8:11], v[174:177], v[0:3], v[52:55]
	v_mfma_f32_16x16x32_bf16 v[32:35], v[178:181], v[4:7], v[8:11]
	v_mfma_f32_16x16x32_bf16 v[8:11], v[174:177], v[200:203], v[48:51]
	v_mfma_f32_16x16x32_bf16 v[36:39], v[178:181], v[204:207], v[8:11]
	v_mfma_f32_16x16x32_bf16 v[8:11], v[188:191], v[0:3], v[220:223]
	v_mfma_f32_16x16x32_bf16 v[0:3], v[228:231], v[0:3], v[138:141]
	v_mfma_f32_16x16x32_bf16 v[8:11], v[162:165], v[4:7], v[8:11]
	v_mfma_f32_16x16x32_bf16 v[12:15], v[188:191], v[200:203], v[224:227]
	v_mfma_f32_16x16x32_bf16 v[0:3], v[232:235], v[4:7], v[0:3]
	v_mfma_f32_16x16x32_bf16 v[4:7], v[228:231], v[200:203], v[146:149]
	v_mfma_f32_16x16x32_bf16 v[12:15], v[162:165], v[204:207], v[12:15]
	v_mfma_f32_16x16x32_bf16 v[4:7], v[232:235], v[204:207], v[4:7]
	s_setprio 0
	s_setprio 1
	v_mfma_f32_16x16x32_bf16 v[16:19], v[174:177], v[212:215], v[16:19]
	v_mfma_f32_16x16x32_bf16 v[24:27], v[166:169], v[212:215], v[24:27]
	v_mfma_f32_16x16x32_bf16 v[52:55], v[178:181], v[216:219], v[16:19]
	v_mfma_f32_16x16x32_bf16 v[16:19], v[188:191], v[184:187], v[150:153]
	v_mfma_f32_16x16x32_bf16 v[28:31], v[166:169], v[184:187], v[28:31]
	v_mfma_f32_16x16x32_bf16 v[60:63], v[170:173], v[216:219], v[24:27]
	v_mfma_f32_16x16x32_bf16 v[20:23], v[174:177], v[184:187], v[20:23]
	v_mfma_f32_16x16x32_bf16 v[24:27], v[162:165], v[208:211], v[16:19]
	v_mfma_f32_16x16x32_bf16 v[16:19], v[188:191], v[212:215], v[154:157]
	v_mfma_f32_16x16x32_bf16 v[56:59], v[170:173], v[208:211], v[28:31]
	v_mfma_f32_16x16x32_bf16 v[48:51], v[178:181], v[208:211], v[20:23]
	v_mfma_f32_16x16x32_bf16 v[28:31], v[162:165], v[216:219], v[16:19]
	v_mfma_f32_16x16x32_bf16 v[16:19], v[228:231], v[184:187], v[192:195]
	v_mfma_f32_16x16x32_bf16 v[20:23], v[228:231], v[212:215], v[196:199]
	v_mfma_f32_16x16x32_bf16 v[16:19], v[232:235], v[208:211], v[16:19]
	v_mfma_f32_16x16x32_bf16 v[20:23], v[232:235], v[216:219], v[20:23]
	s_setprio 0
	v_cmp_gt_u32_e32 vcc, s92, v132
	s_barrier
	s_and_saveexec_b64 s[10:11], vcc
	s_cbranch_execz .LBB0_638
	s_barrier
	s_branch .LBB0_638

.LBB0_812:
	s_or_b64 exec, exec, s[18:19]
	v_add_u32_e32 v175, s15, v3
	v_lshl_add_u64 v[6:7], s[16:17], 0, v[128:129]
	v_readfirstlane_b32 s16, v175
	v_add_u32_e32 v176, 0x2000, v175
	v_lshl_add_u64 v[8:9], v[6:7], 0, s[22:23]
	s_mov_b32 m0, s16
	s_mov_b64 s[18:19], 0x20080
	v_readfirstlane_b32 s16, v176
	v_add_u32_e32 v177, 0x8000, v161
	s_waitcnt vmcnt(0)
	s_barrier
	global_load_lds_dwordx4 v[8:9], off
	v_lshl_add_u64 v[8:9], v[6:7], 0, s[18:19]
	s_mov_b32 m0, s16
	v_lshl_add_u64 v[130:131], s[10:11], 0, v[128:129]
	v_readfirstlane_b32 s10, v177
	v_add_u32_e32 v178, 0xa000, v161
	global_load_lds_dwordx4 v[8:9], off
	v_lshl_add_u64 v[8:9], v[130:131], 0, s[22:23]
	s_mov_b32 m0, s10
	v_readfirstlane_b32 s10, v178
	global_load_lds_dwordx4 v[8:9], off
	v_lshl_add_u64 v[8:9], v[130:131], 0, s[18:19]
	s_mov_b32 m0, s10
	s_mov_b64 s[10:11], 0x40080
	v_add_u32_e32 v179, s36, v3
	global_load_lds_dwordx4 v[8:9], off
	v_lshl_add_u64 v[8:9], v[6:7], 0, s[10:11]
	v_readfirstlane_b32 s10, v179
	s_mov_b32 m0, s10
	s_mov_b64 s[10:11], 0x60080
	v_add_u32_e32 v181, 0x2000, v179
	v_lshl_add_u64 v[6:7], v[6:7], 0, s[10:11]
	v_readfirstlane_b32 s10, v181
	global_load_lds_dwordx4 v[8:9], off
	s_mov_b32 m0, s10
	v_and_b32_e32 v163, 15, v166
	global_load_lds_dwordx4 v[6:7], off
	v_bfe_u32 v136, v166, 4, 2
	v_lshlrev_b32_e32 v167, 2, v166
	v_lshlrev_b32_e32 v14, 8, v166
	v_ashrrev_i32_e32 v165, 6, v166
	v_lshlrev_b32_e32 v5, 4, v136
	v_lshlrev_b32_e32 v6, 6, v163
	v_and_b32_e32 v7, 32, v167
	v_lshlrev_b32_e32 v12, 6, v166
	v_and_b32_e32 v14, 0xffff8000, v14
	v_lshlrev_b32_e32 v0, 11, v0
	s_add_u32 s68, s12, s68
	v_and_b32_e32 v164, 3, v165
	s_waitcnt vmcnt(6)
	v_bitop3_b32 v6, v5, v7, v6 bitop3:0x36
	v_lshlrev_b32_e32 v168, 6, v4
	v_lshlrev_b32_e32 v4, 13, v4
	v_and_or_b32 v5, v12, s83, v5
	v_or3_b32 v0, v1, v14, v0
	s_addc_u32 s69, s13, s69
	v_lshlrev_b32_e32 v3, 12, v164
	v_add_u32_e32 v8, s35, v6
	v_add_u32_e32 v9, s14, v6
	v_add_u32_e32 v10, s15, v6
	v_add_u32_e32 v11, s36, v6
	v_add_u32_e32 v6, 16, v6
	v_xad_u32 v5, v5, v7, 16
	v_or_b32_e32 v7, 0x800, v4
	v_or_b32_e32 v12, 0x1000, v4
	v_or_b32_e32 v13, 0x1800, v4
	v_add_u32_e32 v132, v0, v2
	s_add_u32 s70, s12, s26
	v_mov_b32_e32 v0, 0
	v_mov_b32_e32 v133, v129
	s_addc_u32 s71, s13, 0
	s_mov_b32 s10, -2
	v_add_u32_e32 v184, v8, v3
	v_add_u32_e32 v172, v6, v4
	v_add_u32_e32 v171, v5, v7
	v_add_u32_e32 v170, v5, v12
	v_add_u32_e32 v169, v5, v13
	v_add_u32_e32 v180, v9, v3
	v_add_u32_e32 v174, v10, v3
	v_add_u32_e32 v173, v11, v3
	v_mov_b32_e32 v1, v0
	v_mov_b32_e32 v2, v0
	v_mov_b32_e32 v3, v0
	v_mov_b32_e32 v4, v0
	v_mov_b32_e32 v5, v0
	v_mov_b32_e32 v6, v0
	v_mov_b32_e32 v7, v0
	v_mov_b32_e32 v8, v0
	v_mov_b32_e32 v9, v0
	v_mov_b32_e32 v10, v0
	v_mov_b32_e32 v11, v0
	v_mov_b32_e32 v12, v0
	v_mov_b32_e32 v13, v0
	v_mov_b32_e32 v14, v0
	v_mov_b32_e32 v15, v0
	v_mov_b32_e32 v16, v0
	v_mov_b32_e32 v17, v0
	v_mov_b32_e32 v18, v0
	v_mov_b32_e32 v19, v0
	v_mov_b32_e32 v20, v0
	v_mov_b32_e32 v21, v0
	v_mov_b32_e32 v22, v0
	v_mov_b32_e32 v23, v0
	v_mov_b32_e32 v24, v0
	v_mov_b32_e32 v25, v0
	v_mov_b32_e32 v26, v0
	v_mov_b32_e32 v27, v0
	v_mov_b32_e32 v28, v0
	v_mov_b32_e32 v29, v0
	v_mov_b32_e32 v30, v0
	v_mov_b32_e32 v31, v0
	v_mov_b32_e32 v32, v0
	v_mov_b32_e32 v33, v0
	v_mov_b32_e32 v34, v0
	v_mov_b32_e32 v35, v0
	v_mov_b32_e32 v36, v0
	v_mov_b32_e32 v37, v0
	v_mov_b32_e32 v38, v0
	v_mov_b32_e32 v39, v0
	v_mov_b32_e32 v40, v0
	v_mov_b32_e32 v41, v0
	v_mov_b32_e32 v42, v0
	v_mov_b32_e32 v43, v0
	v_mov_b32_e32 v44, v0
	v_mov_b32_e32 v45, v0
	v_mov_b32_e32 v46, v0
	v_mov_b32_e32 v47, v0
	v_mov_b32_e32 v48, v0
	v_mov_b32_e32 v49, v0
	v_mov_b32_e32 v50, v0
	v_mov_b32_e32 v51, v0
	v_mov_b32_e32 v52, v0
	v_mov_b32_e32 v53, v0
	v_mov_b32_e32 v54, v0
	v_mov_b32_e32 v55, v0
	v_mov_b32_e32 v56, v0
	v_mov_b32_e32 v57, v0
	v_mov_b32_e32 v58, v0
	v_mov_b32_e32 v59, v0
	v_mov_b32_e32 v60, v0
	v_mov_b32_e32 v61, v0
	v_mov_b32_e32 v62, v0
	v_mov_b32_e32 v63, v0
	v_mov_b32_e32 v64, v0
	v_mov_b32_e32 v65, v0
	v_mov_b32_e32 v66, v0
	v_mov_b32_e32 v67, v0
	v_mov_b32_e32 v68, v0
	v_mov_b32_e32 v69, v0
	v_mov_b32_e32 v70, v0
	v_mov_b32_e32 v71, v0
	v_mov_b32_e32 v72, v0
	v_mov_b32_e32 v73, v0
	v_mov_b32_e32 v74, v0
	v_mov_b32_e32 v75, v0
	v_mov_b32_e32 v76, v0
	v_mov_b32_e32 v77, v0
	v_mov_b32_e32 v78, v0
	v_mov_b32_e32 v79, v0
	v_mov_b32_e32 v80, v0
	v_mov_b32_e32 v81, v0
	v_mov_b32_e32 v82, v0
	v_mov_b32_e32 v83, v0
	v_mov_b32_e32 v84, v0
	v_mov_b32_e32 v85, v0
	v_mov_b32_e32 v86, v0
	v_mov_b32_e32 v87, v0
	v_mov_b32_e32 v88, v0
	v_mov_b32_e32 v89, v0
	v_mov_b32_e32 v90, v0
	v_mov_b32_e32 v91, v0
	v_mov_b32_e32 v92, v0
	v_mov_b32_e32 v93, v0
	v_mov_b32_e32 v94, v0
	v_mov_b32_e32 v95, v0
	v_mov_b32_e32 v96, v0
	v_mov_b32_e32 v97, v0
	v_mov_b32_e32 v98, v0
	v_mov_b32_e32 v99, v0
	v_mov_b32_e32 v100, v0
	v_mov_b32_e32 v101, v0
	v_mov_b32_e32 v102, v0
	v_mov_b32_e32 v103, v0
	v_mov_b32_e32 v104, v0
	v_mov_b32_e32 v105, v0
	v_mov_b32_e32 v106, v0
	v_mov_b32_e32 v107, v0
	v_mov_b32_e32 v108, v0
	v_mov_b32_e32 v109, v0
	v_mov_b32_e32 v110, v0
	v_mov_b32_e32 v111, v0
	v_mov_b32_e32 v112, v0
	v_mov_b32_e32 v113, v0
	v_mov_b32_e32 v114, v0
	v_mov_b32_e32 v115, v0
	v_mov_b32_e32 v116, v0
	v_mov_b32_e32 v117, v0
	v_mov_b32_e32 v118, v0
	v_mov_b32_e32 v119, v0
	v_mov_b32_e32 v120, v0
	v_mov_b32_e32 v121, v0
	v_mov_b32_e32 v122, v0
	v_mov_b32_e32 v123, v0
	v_mov_b32_e32 v124, v0
	v_mov_b32_e32 v125, v0
	v_mov_b32_e32 v126, v0
	v_mov_b32_e32 v127, v0
.Lkh_813:
	s_barrier
.LBB0_813:
	ds_read_b128 v[138:141], v184
	ds_read_b128 v[146:149], v184 offset:1024
	ds_read_b128 v[150:153], v184 offset:2048
	ds_read_b128 v[154:157], v184 offset:3072
	v_add_u32_e32 v187, 0xc000, v161
	v_lshl_add_u64 v[238:239], s[68:69], 0, v[132:133]
	v_readfirstlane_b32 s11, v187
	v_lshl_add_u64 v[188:189], v[238:239], 0, s[30:31]
	s_mov_b32 m0, s11
	ds_read_b128 v[190:193], v172
	ds_read_b128 v[194:197], v172 offset:1024
	ds_read_b128 v[198:201], v171
	ds_read_b128 v[202:205], v171 offset:1024
	ds_read_b128 v[206:209], v170
	ds_read_b128 v[210:213], v170 offset:1024
	ds_read_b128 v[214:217], v169
	ds_read_b128 v[218:221], v169 offset:1024
	global_load_lds_dwordx4 v[188:189], off
	v_add_u32_e32 v188, 0xe000, v161
	v_lshl_add_u64 v[222:223], v[238:239], 0, s[38:39]
	v_readfirstlane_b32 s11, v188
	s_mov_b32 m0, s11
	s_nop 0
	global_load_lds_dwordx4 v[222:223], off
	s_waitcnt lgkmcnt(8)
	s_barrier
	s_waitcnt lgkmcnt(0)
	s_setprio 1
	s_waitcnt lgkmcnt(0)
	v_mfma_f32_16x16x32_bf16 v[124:127], v[190:193], v[138:141], v[124:127]
	v_mfma_f32_16x16x32_bf16 v[120:123], v[190:193], v[150:153], v[120:123]
	v_mfma_f32_16x16x32_bf16 v[116:119], v[198:201], v[138:141], v[116:119]
	v_mfma_f32_16x16x32_bf16 v[112:115], v[198:201], v[150:153], v[112:115]
	v_mfma_f32_16x16x32_bf16 v[108:111], v[206:209], v[138:141], v[108:111]
	v_mfma_f32_16x16x32_bf16 v[104:107], v[206:209], v[150:153], v[104:107]
	v_mfma_f32_16x16x32_bf16 v[100:103], v[214:217], v[138:141], v[100:103]
	v_mfma_f32_16x16x32_bf16 v[96:99], v[214:217], v[150:153], v[96:99]
	v_mfma_f32_16x16x32_bf16 v[124:127], v[194:197], v[146:149], v[124:127]
	v_mfma_f32_16x16x32_bf16 v[120:123], v[194:197], v[154:157], v[120:123]
	v_mfma_f32_16x16x32_bf16 v[116:119], v[202:205], v[146:149], v[116:119]
	v_mfma_f32_16x16x32_bf16 v[112:115], v[202:205], v[154:157], v[112:115]
	v_mfma_f32_16x16x32_bf16 v[108:111], v[210:213], v[146:149], v[108:111]
	v_mfma_f32_16x16x32_bf16 v[104:107], v[210:213], v[154:157], v[104:107]
	v_mfma_f32_16x16x32_bf16 v[100:103], v[218:221], v[146:149], v[100:103]
	v_mfma_f32_16x16x32_bf16 v[96:99], v[218:221], v[154:157], v[96:99]
	s_setprio 0
	s_barrier
	v_lshl_add_u64 v[240:241], s[70:71], 0, v[132:133]
	s_mov_b64 s[16:17], 0x1500100
	v_readfirstlane_b32 s11, v162
	v_add_u32_e32 v185, 0x2000, v162
	v_lshl_add_u64 v[242:243], v[240:241], 0, s[16:17]
	s_mov_b32 m0, s11
	s_mov_b64 s[16:17], 0x1520100
	v_readfirstlane_b32 s11, v185
	ds_read_b128 v[222:225], v180
	ds_read_b128 v[226:229], v180 offset:1024
	ds_read_b128 v[230:233], v180 offset:2048
	ds_read_b128 v[234:237], v180 offset:3072
	global_load_lds_dwordx4 v[242:243], off
	v_lshl_add_u64 v[242:243], v[240:241], 0, s[16:17]
	s_mov_b32 m0, s11
	s_nop 0
	global_load_lds_dwordx4 v[242:243], off
	s_barrier
	s_waitcnt lgkmcnt(0)
	s_setprio 1
	s_waitcnt lgkmcnt(0)
	v_mfma_f32_16x16x32_bf16 v[92:95], v[190:193], v[222:225], v[92:95]
	v_mfma_f32_16x16x32_bf16 v[88:91], v[190:193], v[230:233], v[88:91]
	v_mfma_f32_16x16x32_bf16 v[84:87], v[198:201], v[222:225], v[84:87]
	v_mfma_f32_16x16x32_bf16 v[80:83], v[198:201], v[230:233], v[80:83]
	v_mfma_f32_16x16x32_bf16 v[76:79], v[206:209], v[222:225], v[76:79]
	v_mfma_f32_16x16x32_bf16 v[72:75], v[206:209], v[230:233], v[72:75]
	v_mfma_f32_16x16x32_bf16 v[68:71], v[214:217], v[222:225], v[68:71]
	v_mfma_f32_16x16x32_bf16 v[64:67], v[214:217], v[230:233], v[64:67]
	v_mfma_f32_16x16x32_bf16 v[92:95], v[194:197], v[226:229], v[92:95]
	v_mfma_f32_16x16x32_bf16 v[88:91], v[194:197], v[234:237], v[88:91]
	v_mfma_f32_16x16x32_bf16 v[84:87], v[202:205], v[226:229], v[84:87]
	v_mfma_f32_16x16x32_bf16 v[80:83], v[202:205], v[234:237], v[80:83]
	v_mfma_f32_16x16x32_bf16 v[76:79], v[210:213], v[226:229], v[76:79]
	v_mfma_f32_16x16x32_bf16 v[72:75], v[210:213], v[234:237], v[72:75]
	v_mfma_f32_16x16x32_bf16 v[68:71], v[218:221], v[226:229], v[68:71]
	v_mfma_f32_16x16x32_bf16 v[64:67], v[218:221], v[234:237], v[64:67]
	s_setprio 0
	v_readfirstlane_b32 s11, v161
	v_lshl_add_u64 v[242:243], v[238:239], 0, s[44:45]
	s_mov_b32 m0, s11
	v_readfirstlane_b32 s11, v160
	s_barrier
	ds_read_b128 v[190:193], v172 offset:16384
	ds_read_b128 v[194:197], v172 offset:17408
	ds_read_b128 v[198:201], v171 offset:16384
	ds_read_b128 v[202:205], v171 offset:17408
	ds_read_b128 v[206:209], v170 offset:16384
	ds_read_b128 v[210:213], v170 offset:17408
	ds_read_b128 v[214:217], v169 offset:16384
	ds_read_b128 v[218:221], v169 offset:17408
	global_load_lds_dwordx4 v[242:243], off
	v_lshl_add_u64 v[242:243], v[238:239], 0, s[46:47]
	s_mov_b32 m0, s11
	s_nop 0
	global_load_lds_dwordx4 v[242:243], off
	s_barrier
	s_waitcnt lgkmcnt(0)
	s_setprio 1
	s_waitcnt lgkmcnt(0)
	v_mfma_f32_16x16x32_bf16 v[60:63], v[190:193], v[138:141], v[60:63]
	v_mfma_f32_16x16x32_bf16 v[56:59], v[190:193], v[150:153], v[56:59]
	v_mfma_f32_16x16x32_bf16 v[52:55], v[198:201], v[138:141], v[52:55]
	v_mfma_f32_16x16x32_bf16 v[48:51], v[198:201], v[150:153], v[48:51]
	v_mfma_f32_16x16x32_bf16 v[44:47], v[206:209], v[138:141], v[44:47]
	v_mfma_f32_16x16x32_bf16 v[40:43], v[206:209], v[150:153], v[40:43]
	v_mfma_f32_16x16x32_bf16 v[36:39], v[214:217], v[138:141], v[36:39]
	v_mfma_f32_16x16x32_bf16 v[32:35], v[214:217], v[150:153], v[32:35]
	v_mfma_f32_16x16x32_bf16 v[60:63], v[194:197], v[146:149], v[60:63]
	v_mfma_f32_16x16x32_bf16 v[56:59], v[194:197], v[154:157], v[56:59]
	v_mfma_f32_16x16x32_bf16 v[52:55], v[202:205], v[146:149], v[52:55]
	v_mfma_f32_16x16x32_bf16 v[48:51], v[202:205], v[154:157], v[48:51]
	v_mfma_f32_16x16x32_bf16 v[44:47], v[210:213], v[146:149], v[44:47]
	v_mfma_f32_16x16x32_bf16 v[40:43], v[210:213], v[154:157], v[40:43]
	v_mfma_f32_16x16x32_bf16 v[36:39], v[218:221], v[146:149], v[36:39]
	v_mfma_f32_16x16x32_bf16 v[32:35], v[218:221], v[154:157], v[32:35]
	s_setprio 0
	s_barrier
	s_mov_b64 s[16:17], 0x1540100
	v_readfirstlane_b32 s11, v137
	v_add_u32_e32 v186, 0x2000, v137
	v_lshl_add_u64 v[138:139], v[240:241], 0, s[16:17]
	s_mov_b32 m0, s11
	s_mov_b64 s[16:17], 0x1560100
	v_readfirstlane_b32 s11, v186
	global_load_lds_dwordx4 v[138:139], off
	v_lshl_add_u64 v[138:139], v[240:241], 0, s[16:17]
	s_mov_b32 m0, s11
	s_nop 0
	global_load_lds_dwordx4 v[138:139], off
	s_waitcnt vmcnt(6)
	s_barrier
	s_setprio 1
	v_mfma_f32_16x16x32_bf16 v[28:31], v[190:193], v[222:225], v[28:31]
	v_mfma_f32_16x16x32_bf16 v[24:27], v[190:193], v[230:233], v[24:27]
	v_mfma_f32_16x16x32_bf16 v[20:23], v[198:201], v[222:225], v[20:23]
	v_mfma_f32_16x16x32_bf16 v[16:19], v[198:201], v[230:233], v[16:19]
	v_mfma_f32_16x16x32_bf16 v[12:15], v[206:209], v[222:225], v[12:15]
	v_mfma_f32_16x16x32_bf16 v[8:11], v[206:209], v[230:233], v[8:11]
	v_mfma_f32_16x16x32_bf16 v[4:7], v[214:217], v[222:225], v[4:7]
	v_mfma_f32_16x16x32_bf16 v[0:3], v[214:217], v[230:233], v[0:3]
	v_mfma_f32_16x16x32_bf16 v[28:31], v[194:197], v[226:229], v[28:31]
	v_mfma_f32_16x16x32_bf16 v[24:27], v[194:197], v[234:237], v[24:27]
	v_mfma_f32_16x16x32_bf16 v[20:23], v[202:205], v[226:229], v[20:23]
	v_mfma_f32_16x16x32_bf16 v[16:19], v[202:205], v[234:237], v[16:19]
	v_mfma_f32_16x16x32_bf16 v[12:15], v[210:213], v[226:229], v[12:15]
	v_mfma_f32_16x16x32_bf16 v[8:11], v[210:213], v[234:237], v[8:11]
	v_mfma_f32_16x16x32_bf16 v[4:7], v[218:221], v[226:229], v[4:7]
	v_mfma_f32_16x16x32_bf16 v[0:3], v[218:221], v[234:237], v[0:3]
	s_setprio 0
	s_barrier
	ds_read_b128 v[138:141], v174
	ds_read_b128 v[146:149], v174 offset:1024
	ds_read_b128 v[150:153], v174 offset:2048
	ds_read_b128 v[154:157], v174 offset:3072
	v_readfirstlane_b32 s11, v135
	v_lshl_add_u64 v[222:223], v[238:239], 0, s[52:53]
	s_mov_b32 m0, s11
	v_readfirstlane_b32 s11, v134
	ds_read_b128 v[190:193], v172 offset:32768
	ds_read_b128 v[194:197], v172 offset:33792
	ds_read_b128 v[198:201], v171 offset:32768
	ds_read_b128 v[202:205], v171 offset:33792
	ds_read_b128 v[206:209], v170 offset:32768
	ds_read_b128 v[210:213], v170 offset:33792
	ds_read_b128 v[214:217], v169 offset:32768
	ds_read_b128 v[218:221], v169 offset:33792
	global_load_lds_dwordx4 v[222:223], off
	v_lshl_add_u64 v[222:223], v[238:239], 0, s[54:55]
	s_mov_b32 m0, s11
	s_nop 0
	global_load_lds_dwordx4 v[222:223], off
	s_waitcnt lgkmcnt(8)
	s_barrier
	s_waitcnt lgkmcnt(0)
	s_setprio 1
	s_waitcnt lgkmcnt(0)
	v_mfma_f32_16x16x32_bf16 v[124:127], v[190:193], v[138:141], v[124:127]
	v_mfma_f32_16x16x32_bf16 v[120:123], v[190:193], v[150:153], v[120:123]
	v_mfma_f32_16x16x32_bf16 v[116:119], v[198:201], v[138:141], v[116:119]
	v_mfma_f32_16x16x32_bf16 v[112:115], v[198:201], v[150:153], v[112:115]
	v_mfma_f32_16x16x32_bf16 v[108:111], v[206:209], v[138:141], v[108:111]
	v_mfma_f32_16x16x32_bf16 v[104:107], v[206:209], v[150:153], v[104:107]
	v_mfma_f32_16x16x32_bf16 v[100:103], v[214:217], v[138:141], v[100:103]
	v_mfma_f32_16x16x32_bf16 v[96:99], v[214:217], v[150:153], v[96:99]
	v_mfma_f32_16x16x32_bf16 v[124:127], v[194:197], v[146:149], v[124:127]
	v_mfma_f32_16x16x32_bf16 v[120:123], v[194:197], v[154:157], v[120:123]
	v_mfma_f32_16x16x32_bf16 v[116:119], v[202:205], v[146:149], v[116:119]
	v_mfma_f32_16x16x32_bf16 v[112:115], v[202:205], v[154:157], v[112:115]
	v_mfma_f32_16x16x32_bf16 v[108:111], v[210:213], v[146:149], v[108:111]
	v_mfma_f32_16x16x32_bf16 v[104:107], v[210:213], v[154:157], v[104:107]
	v_mfma_f32_16x16x32_bf16 v[100:103], v[218:221], v[146:149], v[100:103]
	v_mfma_f32_16x16x32_bf16 v[96:99], v[218:221], v[154:157], v[96:99]
	s_setprio 0
	s_barrier
	s_mov_b64 s[16:17], 0x1500180
	v_readfirstlane_b32 s11, v175
	v_lshl_add_u64 v[242:243], v[240:241], 0, s[16:17]
	s_mov_b32 m0, s11
	s_mov_b64 s[16:17], 0x1520180
	v_readfirstlane_b32 s11, v176
	ds_read_b128 v[222:225], v173
	ds_read_b128 v[226:229], v173 offset:1024
	ds_read_b128 v[230:233], v173 offset:2048
	ds_read_b128 v[234:237], v173 offset:3072
	global_load_lds_dwordx4 v[242:243], off
	v_lshl_add_u64 v[242:243], v[240:241], 0, s[16:17]
	s_mov_b32 m0, s11
	s_nop 0
	global_load_lds_dwordx4 v[242:243], off
	s_barrier
	s_waitcnt lgkmcnt(0)
	s_setprio 1
	s_waitcnt lgkmcnt(0)
	v_mfma_f32_16x16x32_bf16 v[92:95], v[190:193], v[222:225], v[92:95]
	v_mfma_f32_16x16x32_bf16 v[88:91], v[190:193], v[230:233], v[88:91]
	v_mfma_f32_16x16x32_bf16 v[84:87], v[198:201], v[222:225], v[84:87]
	v_mfma_f32_16x16x32_bf16 v[80:83], v[198:201], v[230:233], v[80:83]
	v_mfma_f32_16x16x32_bf16 v[76:79], v[206:209], v[222:225], v[76:79]
	v_mfma_f32_16x16x32_bf16 v[72:75], v[206:209], v[230:233], v[72:75]
	v_mfma_f32_16x16x32_bf16 v[68:71], v[214:217], v[222:225], v[68:71]
	v_mfma_f32_16x16x32_bf16 v[64:67], v[214:217], v[230:233], v[64:67]
	v_mfma_f32_16x16x32_bf16 v[92:95], v[194:197], v[226:229], v[92:95]
	v_mfma_f32_16x16x32_bf16 v[88:91], v[194:197], v[234:237], v[88:91]
	v_mfma_f32_16x16x32_bf16 v[84:87], v[202:205], v[226:229], v[84:87]
	v_mfma_f32_16x16x32_bf16 v[80:83], v[202:205], v[234:237], v[80:83]
	v_mfma_f32_16x16x32_bf16 v[76:79], v[210:213], v[226:229], v[76:79]
	v_mfma_f32_16x16x32_bf16 v[72:75], v[210:213], v[234:237], v[72:75]
	v_mfma_f32_16x16x32_bf16 v[68:71], v[218:221], v[226:229], v[68:71]
	v_mfma_f32_16x16x32_bf16 v[64:67], v[218:221], v[234:237], v[64:67]
	s_setprio 0
	v_readfirstlane_b32 s11, v177
	v_lshl_add_u64 v[242:243], v[238:239], 0, s[60:61]
	s_mov_b32 m0, s11
	v_readfirstlane_b32 s11, v178
	s_barrier
	ds_read_b128 v[190:193], v172 offset:49152
	ds_read_b128 v[194:197], v172 offset:50176
	ds_read_b128 v[198:201], v171 offset:49152
	ds_read_b128 v[202:205], v171 offset:50176
	ds_read_b128 v[206:209], v170 offset:49152
	ds_read_b128 v[210:213], v170 offset:50176
	ds_read_b128 v[214:217], v169 offset:49152
	ds_read_b128 v[218:221], v169 offset:50176
	global_load_lds_dwordx4 v[242:243], off
	v_lshl_add_u64 v[238:239], v[238:239], 0, s[62:63]
	s_mov_b32 m0, s11
	s_nop 0
	global_load_lds_dwordx4 v[238:239], off
	s_barrier
	s_waitcnt lgkmcnt(0)
	s_setprio 1
	s_waitcnt lgkmcnt(0)
	v_mfma_f32_16x16x32_bf16 v[60:63], v[190:193], v[138:141], v[60:63]
	v_mfma_f32_16x16x32_bf16 v[56:59], v[190:193], v[150:153], v[56:59]
	v_mfma_f32_16x16x32_bf16 v[52:55], v[198:201], v[138:141], v[52:55]
	v_mfma_f32_16x16x32_bf16 v[48:51], v[198:201], v[150:153], v[48:51]
	v_mfma_f32_16x16x32_bf16 v[44:47], v[206:209], v[138:141], v[44:47]
	v_mfma_f32_16x16x32_bf16 v[40:43], v[206:209], v[150:153], v[40:43]
	v_mfma_f32_16x16x32_bf16 v[36:39], v[214:217], v[138:141], v[36:39]
	v_mfma_f32_16x16x32_bf16 v[32:35], v[214:217], v[150:153], v[32:35]
	v_mfma_f32_16x16x32_bf16 v[60:63], v[194:197], v[146:149], v[60:63]
	v_mfma_f32_16x16x32_bf16 v[56:59], v[194:197], v[154:157], v[56:59]
	v_mfma_f32_16x16x32_bf16 v[52:55], v[202:205], v[146:149], v[52:55]
	v_mfma_f32_16x16x32_bf16 v[48:51], v[202:205], v[154:157], v[48:51]
	v_mfma_f32_16x16x32_bf16 v[44:47], v[210:213], v[146:149], v[44:47]
	v_mfma_f32_16x16x32_bf16 v[40:43], v[210:213], v[154:157], v[40:43]
	v_mfma_f32_16x16x32_bf16 v[36:39], v[218:221], v[146:149], v[36:39]
	v_mfma_f32_16x16x32_bf16 v[32:35], v[218:221], v[154:157], v[32:35]
	s_setprio 0
	s_barrier
	s_mov_b64 s[16:17], 0x1540180
	v_readfirstlane_b32 s11, v179
	v_lshl_add_u64 v[138:139], v[240:241], 0, s[16:17]
	s_mov_b32 m0, s11
	s_mov_b64 s[16:17], 0x1560180
	v_readfirstlane_b32 s11, v181
	global_load_lds_dwordx4 v[138:139], off
	v_lshl_add_u64 v[138:139], v[240:241], 0, s[16:17]
	s_mov_b32 m0, s11
	s_nop 0
	global_load_lds_dwordx4 v[138:139], off
	s_waitcnt vmcnt(6)
	s_barrier
	s_setprio 1
	v_mfma_f32_16x16x32_bf16 v[28:31], v[190:193], v[222:225], v[28:31]
	v_mfma_f32_16x16x32_bf16 v[24:27], v[190:193], v[230:233], v[24:27]
	v_mfma_f32_16x16x32_bf16 v[20:23], v[198:201], v[222:225], v[20:23]
	v_mfma_f32_16x16x32_bf16 v[16:19], v[198:201], v[230:233], v[16:19]
	v_mfma_f32_16x16x32_bf16 v[12:15], v[206:209], v[222:225], v[12:15]
	v_mfma_f32_16x16x32_bf16 v[8:11], v[206:209], v[230:233], v[8:11]
	v_mfma_f32_16x16x32_bf16 v[4:7], v[214:217], v[222:225], v[4:7]
	v_mfma_f32_16x16x32_bf16 v[0:3], v[214:217], v[230:233], v[0:3]
	v_mfma_f32_16x16x32_bf16 v[28:31], v[194:197], v[226:229], v[28:31]
	v_mfma_f32_16x16x32_bf16 v[24:27], v[194:197], v[234:237], v[24:27]
	v_mfma_f32_16x16x32_bf16 v[20:23], v[202:205], v[226:229], v[20:23]
	v_mfma_f32_16x16x32_bf16 v[16:19], v[202:205], v[234:237], v[16:19]
	v_mfma_f32_16x16x32_bf16 v[12:15], v[210:213], v[226:229], v[12:15]
	v_mfma_f32_16x16x32_bf16 v[8:11], v[210:213], v[234:237], v[8:11]
	v_mfma_f32_16x16x32_bf16 v[4:7], v[218:221], v[226:229], v[4:7]
	v_mfma_f32_16x16x32_bf16 v[0:3], v[218:221], v[234:237], v[0:3]
	s_setprio 0
	s_add_i32 s10, s10, 2
	s_add_u32 s68, s68, 0x100
	s_addc_u32 s69, s69, 0
	s_add_u32 s70, s70, 0x100
	s_addc_u32 s71, s71, 0
	s_cmp_lt_u32 s10, 12
	s_cbranch_scc1 .Lkh_813
	s_barrier
	s_mov_b64 s[10:11], 0x40780
	v_lshl_add_u64 v[132:133], v[130:131], 0, s[10:11]
	v_readfirstlane_b32 s10, v187
	s_mov_b32 m0, s10
	s_mov_b64 s[10:11], 0x60780
	v_lshl_add_u64 v[130:131], v[130:131], 0, s[10:11]
	v_readfirstlane_b32 s10, v188
	ds_read_b128 v[138:141], v184
	ds_read_b128 v[146:149], v184 offset:1024
	ds_read_b128 v[150:153], v184 offset:2048
	ds_read_b128 v[154:157], v184 offset:3072
	ds_read_b128 v[176:179], v172
	ds_read_b128 v[190:193], v172 offset:1024
	ds_read_b128 v[194:197], v171
	ds_read_b128 v[198:201], v171 offset:1024
	ds_read_b128 v[202:205], v170
	ds_read_b128 v[206:209], v170 offset:1024
	ds_read_b128 v[210:213], v169
	ds_read_b128 v[214:217], v169 offset:1024
	global_load_lds_dwordx4 v[132:133], off
	s_mov_b32 m0, s10
	s_nop 0
	global_load_lds_dwordx4 v[130:131], off
	s_barrier
	s_waitcnt lgkmcnt(0)
	s_setprio 1
	s_waitcnt lgkmcnt(0)
	v_mfma_f32_16x16x32_bf16 v[124:127], v[176:179], v[138:141], v[124:127]
	v_mfma_f32_16x16x32_bf16 v[120:123], v[176:179], v[150:153], v[120:123]
	v_mfma_f32_16x16x32_bf16 v[116:119], v[194:197], v[138:141], v[116:119]
	v_mfma_f32_16x16x32_bf16 v[112:115], v[194:197], v[150:153], v[112:115]
	v_mfma_f32_16x16x32_bf16 v[124:127], v[190:193], v[146:149], v[124:127]
	v_mfma_f32_16x16x32_bf16 v[120:123], v[190:193], v[154:157], v[120:123]
	v_mfma_f32_16x16x32_bf16 v[116:119], v[198:201], v[146:149], v[116:119]
	v_mfma_f32_16x16x32_bf16 v[112:115], v[198:201], v[154:157], v[112:115]
	v_mfma_f32_16x16x32_bf16 v[108:111], v[202:205], v[138:141], v[108:111]
	v_mfma_f32_16x16x32_bf16 v[104:107], v[202:205], v[150:153], v[104:107]
	v_mfma_f32_16x16x32_bf16 v[100:103], v[210:213], v[138:141], v[100:103]
	v_mfma_f32_16x16x32_bf16 v[96:99], v[210:213], v[150:153], v[96:99]
	v_mfma_f32_16x16x32_bf16 v[130:133], v[206:209], v[146:149], v[108:111]
	v_mfma_f32_16x16x32_bf16 v[218:221], v[206:209], v[154:157], v[104:107]
	v_mfma_f32_16x16x32_bf16 v[222:225], v[214:217], v[146:149], v[100:103]
	v_mfma_f32_16x16x32_bf16 v[226:229], v[214:217], v[154:157], v[96:99]
	s_setprio 0
	s_barrier
	s_nop 1
	ds_read_b128 v[96:99], v180
	ds_read_b128 v[100:103], v180 offset:1024
	ds_read_b128 v[104:107], v180 offset:2048
	ds_read_b128 v[108:111], v180 offset:3072
	s_barrier
	s_waitcnt lgkmcnt(0)
	s_setprio 1
	s_waitcnt lgkmcnt(0)
	v_mfma_f32_16x16x32_bf16 v[92:95], v[176:179], v[96:99], v[92:95]
	v_mfma_f32_16x16x32_bf16 v[88:91], v[176:179], v[104:107], v[88:91]
	v_mfma_f32_16x16x32_bf16 v[84:87], v[194:197], v[96:99], v[84:87]
	v_mfma_f32_16x16x32_bf16 v[80:83], v[194:197], v[104:107], v[80:83]
	v_mfma_f32_16x16x32_bf16 v[92:95], v[190:193], v[100:103], v[92:95]
	v_mfma_f32_16x16x32_bf16 v[88:91], v[190:193], v[108:111], v[88:91]
	v_mfma_f32_16x16x32_bf16 v[84:87], v[198:201], v[100:103], v[84:87]
	v_mfma_f32_16x16x32_bf16 v[80:83], v[198:201], v[108:111], v[80:83]
	v_mfma_f32_16x16x32_bf16 v[76:79], v[202:205], v[96:99], v[76:79]
	v_mfma_f32_16x16x32_bf16 v[72:75], v[202:205], v[104:107], v[72:75]
	v_mfma_f32_16x16x32_bf16 v[68:71], v[210:213], v[96:99], v[68:71]
	v_mfma_f32_16x16x32_bf16 v[64:67], v[210:213], v[104:107], v[64:67]
	v_mfma_f32_16x16x32_bf16 v[176:179], v[206:209], v[100:103], v[76:79]
	v_mfma_f32_16x16x32_bf16 v[188:191], v[206:209], v[108:111], v[72:75]
	v_mfma_f32_16x16x32_bf16 v[192:195], v[214:217], v[100:103], v[68:71]
	v_mfma_f32_16x16x32_bf16 v[196:199], v[214:217], v[108:111], v[64:67]
	s_setprio 0
	s_barrier
	s_nop 1
	ds_read_b128 v[64:67], v172 offset:16384
	ds_read_b128 v[68:71], v172 offset:17408
	ds_read_b128 v[72:75], v171 offset:16384
	ds_read_b128 v[76:79], v171 offset:17408
	ds_read_b128 v[200:203], v170 offset:16384
	ds_read_b128 v[204:207], v170 offset:17408
	ds_read_b128 v[208:211], v169 offset:16384
	ds_read_b128 v[212:215], v169 offset:17408
	s_waitcnt vmcnt(4)
	s_barrier
	s_waitcnt lgkmcnt(0)
	s_setprio 1
	s_waitcnt lgkmcnt(0)
	v_mfma_f32_16x16x32_bf16 v[60:63], v[64:67], v[138:141], v[60:63]
	v_mfma_f32_16x16x32_bf16 v[56:59], v[64:67], v[150:153], v[56:59]
	v_mfma_f32_16x16x32_bf16 v[52:55], v[72:75], v[138:141], v[52:55]
	v_mfma_f32_16x16x32_bf16 v[48:51], v[72:75], v[150:153], v[48:51]
	v_mfma_f32_16x16x32_bf16 v[60:63], v[68:71], v[146:149], v[60:63]
	v_mfma_f32_16x16x32_bf16 v[56:59], v[68:71], v[154:157], v[56:59]
	v_mfma_f32_16x16x32_bf16 v[52:55], v[76:79], v[146:149], v[52:55]
	v_mfma_f32_16x16x32_bf16 v[48:51], v[76:79], v[154:157], v[48:51]
	v_mfma_f32_16x16x32_bf16 v[44:47], v[200:203], v[138:141], v[44:47]
	v_mfma_f32_16x16x32_bf16 v[40:43], v[200:203], v[150:153], v[40:43]
	v_mfma_f32_16x16x32_bf16 v[36:39], v[208:211], v[138:141], v[36:39]
	v_mfma_f32_16x16x32_bf16 v[32:35], v[208:211], v[150:153], v[32:35]
	v_mfma_f32_16x16x32_bf16 v[230:233], v[204:207], v[146:149], v[44:47]
	v_mfma_f32_16x16x32_bf16 v[234:237], v[204:207], v[154:157], v[40:43]
	v_mfma_f32_16x16x32_bf16 v[138:141], v[212:215], v[146:149], v[36:39]
	v_mfma_f32_16x16x32_bf16 v[146:149], v[212:215], v[154:157], v[32:35]
	s_setprio 0
	s_setprio 1
	v_mfma_f32_16x16x32_bf16 v[28:31], v[64:67], v[96:99], v[28:31]
	v_mfma_f32_16x16x32_bf16 v[24:27], v[64:67], v[104:107], v[24:27]
	v_mfma_f32_16x16x32_bf16 v[20:23], v[72:75], v[96:99], v[20:23]
	v_mfma_f32_16x16x32_bf16 v[16:19], v[72:75], v[104:107], v[16:19]
	v_mfma_f32_16x16x32_bf16 v[28:31], v[68:71], v[100:103], v[28:31]
	v_mfma_f32_16x16x32_bf16 v[24:27], v[68:71], v[108:111], v[24:27]
	v_mfma_f32_16x16x32_bf16 v[20:23], v[76:79], v[100:103], v[20:23]
	v_mfma_f32_16x16x32_bf16 v[16:19], v[76:79], v[108:111], v[16:19]
	v_mfma_f32_16x16x32_bf16 v[12:15], v[200:203], v[96:99], v[12:15]
	v_mfma_f32_16x16x32_bf16 v[8:11], v[200:203], v[104:107], v[8:11]
	v_mfma_f32_16x16x32_bf16 v[4:7], v[208:211], v[96:99], v[4:7]
	v_mfma_f32_16x16x32_bf16 v[0:3], v[208:211], v[104:107], v[0:3]
	v_mfma_f32_16x16x32_bf16 v[150:153], v[204:207], v[100:103], v[12:15]
	v_mfma_f32_16x16x32_bf16 v[154:157], v[204:207], v[108:111], v[8:11]
	v_mfma_f32_16x16x32_bf16 v[200:203], v[212:215], v[100:103], v[4:7]
	v_mfma_f32_16x16x32_bf16 v[204:207], v[212:215], v[108:111], v[0:3]
	s_setprio 0
	s_barrier
	s_nop 1
	ds_read_b128 v[0:3], v174
	ds_read_b128 v[4:7], v174 offset:1024
	ds_read_b128 v[208:211], v174 offset:2048
	ds_read_b128 v[212:215], v174 offset:3072
	ds_read_b128 v[8:11], v172 offset:32768
	ds_read_b128 v[12:15], v172 offset:33792
	ds_read_b128 v[32:35], v171 offset:32768
	ds_read_b128 v[36:39], v171 offset:33792
	ds_read_b128 v[40:43], v170 offset:32768
	ds_read_b128 v[44:47], v170 offset:33792
	ds_read_b128 v[238:241], v169 offset:32768
	ds_read_b128 v[242:245], v169 offset:33792
	s_waitcnt vmcnt(2)
	s_barrier
	s_waitcnt lgkmcnt(0)
	s_setprio 1
	s_waitcnt lgkmcnt(0)
	v_mfma_f32_16x16x32_bf16 v[64:67], v[8:11], v[0:3], v[124:127]
	v_mfma_f32_16x16x32_bf16 v[104:107], v[12:15], v[4:7], v[64:67]
	v_mfma_f32_16x16x32_bf16 v[64:67], v[8:11], v[208:211], v[120:123]
	v_mfma_f32_16x16x32_bf16 v[108:111], v[12:15], v[212:215], v[64:67]
	v_mfma_f32_16x16x32_bf16 v[64:67], v[32:35], v[0:3], v[116:119]
	v_mfma_f32_16x16x32_bf16 v[96:99], v[36:39], v[4:7], v[64:67]
	v_mfma_f32_16x16x32_bf16 v[64:67], v[32:35], v[208:211], v[112:115]
	v_mfma_f32_16x16x32_bf16 v[100:103], v[36:39], v[212:215], v[64:67]
	v_mfma_f32_16x16x32_bf16 v[64:67], v[40:43], v[0:3], v[130:133]
	v_mfma_f32_16x16x32_bf16 v[72:75], v[44:47], v[4:7], v[64:67]
	v_mfma_f32_16x16x32_bf16 v[64:67], v[40:43], v[208:211], v[218:221]
	v_mfma_f32_16x16x32_bf16 v[76:79], v[44:47], v[212:215], v[64:67]
	v_mfma_f32_16x16x32_bf16 v[64:67], v[238:241], v[0:3], v[222:225]
	v_mfma_f32_16x16x32_bf16 v[68:71], v[238:241], v[208:211], v[226:229]
	v_mfma_f32_16x16x32_bf16 v[64:67], v[242:245], v[4:7], v[64:67]
	v_mfma_f32_16x16x32_bf16 v[68:71], v[242:245], v[212:215], v[68:71]
	s_setprio 0
	s_barrier
	ds_read_b128 v[130:133], v173
	ds_read_b128 v[216:219], v173 offset:1024
	ds_read_b128 v[220:223], v173 offset:2048
	ds_read_b128 v[224:227], v173 offset:3072
	s_waitcnt vmcnt(0)
	s_barrier
	s_waitcnt lgkmcnt(0)
	s_setprio 1
	s_waitcnt lgkmcnt(0)
	v_mfma_f32_16x16x32_bf16 v[92:95], v[8:11], v[130:133], v[92:95]
	v_mfma_f32_16x16x32_bf16 v[8:11], v[8:11], v[220:223], v[88:91]
	v_mfma_f32_16x16x32_bf16 v[124:127], v[12:15], v[224:227], v[8:11]
	v_mfma_f32_16x16x32_bf16 v[8:11], v[32:35], v[130:133], v[84:87]
	v_mfma_f32_16x16x32_bf16 v[112:115], v[36:39], v[216:219], v[8:11]
	v_mfma_f32_16x16x32_bf16 v[8:11], v[32:35], v[220:223], v[80:83]
	v_mfma_f32_16x16x32_bf16 v[116:119], v[36:39], v[224:227], v[8:11]
	v_mfma_f32_16x16x32_bf16 v[8:11], v[40:43], v[130:133], v[176:179]
	v_mfma_f32_16x16x32_bf16 v[88:91], v[44:47], v[216:219], v[8:11]
	v_mfma_f32_16x16x32_bf16 v[8:11], v[40:43], v[220:223], v[188:191]
	v_mfma_f32_16x16x32_bf16 v[120:123], v[12:15], v[216:219], v[92:95]
	v_mfma_f32_16x16x32_bf16 v[92:95], v[44:47], v[224:227], v[8:11]
	v_mfma_f32_16x16x32_bf16 v[8:11], v[238:241], v[130:133], v[192:195]
	v_mfma_f32_16x16x32_bf16 v[80:83], v[242:245], v[216:219], v[8:11]
	v_mfma_f32_16x16x32_bf16 v[8:11], v[238:241], v[220:223], v[196:199]
	v_mfma_f32_16x16x32_bf16 v[84:87], v[242:245], v[224:227], v[8:11]
	s_setprio 0
	s_barrier
	ds_read_b128 v[174:177], v172 offset:49152
	ds_read_b128 v[178:181], v172 offset:50176
	ds_read_b128 v[188:191], v171 offset:49152
	ds_read_b128 v[192:195], v171 offset:50176
	ds_read_b128 v[196:199], v170 offset:49152
	ds_read_b128 v[170:173], v170 offset:50176
	ds_read_b128 v[238:241], v169 offset:49152
	ds_read_b128 v[242:245], v169 offset:50176
	s_barrier
	s_waitcnt lgkmcnt(0)
	s_setprio 1
	s_waitcnt lgkmcnt(0)
	v_mfma_f32_16x16x32_bf16 v[8:11], v[174:177], v[0:3], v[60:63]
	v_mfma_f32_16x16x32_bf16 v[40:43], v[178:181], v[4:7], v[8:11]
	v_mfma_f32_16x16x32_bf16 v[8:11], v[174:177], v[208:211], v[56:59]
	v_mfma_f32_16x16x32_bf16 v[44:47], v[178:181], v[212:215], v[8:11]
	v_mfma_f32_16x16x32_bf16 v[8:11], v[188:191], v[0:3], v[52:55]
	v_mfma_f32_16x16x32_bf16 v[32:35], v[192:195], v[4:7], v[8:11]
	v_mfma_f32_16x16x32_bf16 v[8:11], v[188:191], v[208:211], v[48:51]
	v_mfma_f32_16x16x32_bf16 v[36:39], v[192:195], v[212:215], v[8:11]
	v_mfma_f32_16x16x32_bf16 v[8:11], v[196:199], v[0:3], v[230:233]
	v_mfma_f32_16x16x32_bf16 v[0:3], v[238:241], v[0:3], v[138:141]
	v_mfma_f32_16x16x32_bf16 v[8:11], v[170:173], v[4:7], v[8:11]
	v_mfma_f32_16x16x32_bf16 v[12:15], v[196:199], v[208:211], v[234:237]
	v_mfma_f32_16x16x32_bf16 v[0:3], v[242:245], v[4:7], v[0:3]
	v_mfma_f32_16x16x32_bf16 v[4:7], v[238:241], v[208:211], v[146:149]
	v_mfma_f32_16x16x32_bf16 v[12:15], v[170:173], v[212:215], v[12:15]
	v_mfma_f32_16x16x32_bf16 v[4:7], v[242:245], v[212:215], v[4:7]
	s_setprio 0
	s_setprio 1
	v_mfma_f32_16x16x32_bf16 v[16:19], v[188:191], v[220:223], v[16:19]
	v_mfma_f32_16x16x32_bf16 v[24:27], v[174:177], v[220:223], v[24:27]
	v_mfma_f32_16x16x32_bf16 v[52:55], v[192:195], v[224:227], v[16:19]
	v_mfma_f32_16x16x32_bf16 v[16:19], v[196:199], v[130:133], v[150:153]
	v_mfma_f32_16x16x32_bf16 v[28:31], v[174:177], v[130:133], v[28:31]
	v_mfma_f32_16x16x32_bf16 v[60:63], v[178:181], v[224:227], v[24:27]
	v_mfma_f32_16x16x32_bf16 v[20:23], v[188:191], v[130:133], v[20:23]
	v_mfma_f32_16x16x32_bf16 v[24:27], v[170:173], v[216:219], v[16:19]
	v_mfma_f32_16x16x32_bf16 v[16:19], v[196:199], v[220:223], v[154:157]
	v_mfma_f32_16x16x32_bf16 v[56:59], v[178:181], v[216:219], v[28:31]
	v_mfma_f32_16x16x32_bf16 v[48:51], v[192:195], v[216:219], v[20:23]
	v_mfma_f32_16x16x32_bf16 v[28:31], v[170:173], v[224:227], v[16:19]
	v_mfma_f32_16x16x32_bf16 v[16:19], v[238:241], v[130:133], v[200:203]
	v_mfma_f32_16x16x32_bf16 v[20:23], v[238:241], v[220:223], v[204:207]
	v_mfma_f32_16x16x32_bf16 v[16:19], v[242:245], v[216:219], v[16:19]
	v_mfma_f32_16x16x32_bf16 v[20:23], v[242:245], v[224:227], v[20:23]
	s_setprio 0
	v_cmp_gt_u32_e32 vcc, s92, v166
	s_barrier
	s_and_saveexec_b64 s[10:11], vcc
	s_cbranch_execz .LBB0_816
	s_barrier

.LBB0_905:
	s_or_b64 exec, exec, s[10:11]
	v_add_u32_e32 v175, s15, v6
	v_add_u32_e32 v176, 0x2000, v175
	v_readfirstlane_b32 s10, v175
	v_lshl_add_u64 v[8:9], v[0:1], 0, s[22:23]
	s_mov_b32 m0, s10
	s_mov_b64 s[70:71], 0x80080
	v_readfirstlane_b32 s10, v176
	v_add_u32_e32 v177, 0x8000, v168
	s_waitcnt vmcnt(0)
	s_barrier
	global_load_lds_dwordx4 v[8:9], off
	v_lshl_add_u64 v[8:9], v[0:1], 0, s[70:71]
	s_mov_b32 m0, s10
	v_readfirstlane_b32 s10, v177
	v_add_u32_e32 v178, 0xa000, v168
	global_load_lds_dwordx4 v[8:9], off
	v_lshl_add_u64 v[8:9], v[130:131], 0, s[22:23]
	s_mov_b32 m0, s10
	v_readfirstlane_b32 s10, v178
	global_load_lds_dwordx4 v[8:9], off
	v_lshl_add_u64 v[8:9], v[130:131], 0, s[70:71]
	s_mov_b32 m0, s10
	s_mov_b64 s[10:11], 0x100080
	v_add_u32_e32 v179, s36, v6
	global_load_lds_dwordx4 v[8:9], off
	v_lshl_add_u64 v[8:9], v[0:1], 0, s[10:11]
	v_readfirstlane_b32 s10, v179
	s_mov_b32 m0, s10
	s_mov_b64 s[10:11], 0x180080
	v_add_u32_e32 v181, 0x2000, v179
	v_lshl_add_u64 v[0:1], v[0:1], 0, s[10:11]
	v_readfirstlane_b32 s10, v181
	global_load_lds_dwordx4 v[8:9], off
	s_mov_b32 m0, s10
	v_bfe_u32 v133, v132, 4, 2
	global_load_lds_dwordx4 v[0:1], off
	v_and_b32_e32 v134, 15, v132
	v_lshlrev_b32_e32 v137, 2, v132
	v_lshlrev_b32_e32 v0, 4, v133
	v_lshlrev_b32_e32 v6, 6, v134
	v_and_b32_e32 v7, 32, v137
	v_lshlrev_b32_e32 v12, 6, v132
	v_bitop3_b32 v6, v0, v7, v6 bitop3:0x36
	v_and_or_b32 v0, v12, s83, v0
	v_xad_u32 v7, v0, v7, 16
	v_lshlrev_b32_e32 v0, 10, v132
	v_ashrrev_i32_e32 v136, 6, v132
	v_and_b32_e32 v0, 0xfffe0000, v0
	v_lshlrev_b32_e32 v2, 13, v2
	s_add_u32 s10, s8, s26
	v_and_b32_e32 v135, 3, v136
	s_waitcnt vmcnt(6)
	v_lshlrev_b32_e32 v160, 6, v5
	v_lshlrev_b32_e32 v5, 13, v5
	v_or3_b32 v0, v3, v0, v2
	s_addc_u32 s11, s9, 0
	v_lshlrev_b32_e32 v1, 12, v135
	v_add_u32_e32 v8, s35, v6
	v_add_u32_e32 v9, s14, v6
	v_add_u32_e32 v10, s15, v6
	v_add_u32_e32 v11, s36, v6
	v_add_u32_e32 v6, 16, v6
	v_or_b32_e32 v12, 0x800, v5
	v_or_b32_e32 v13, 0x1000, v5
	v_or_b32_e32 v14, 0x1800, v5
	v_add_u32_e32 v128, v0, v4
	s_add_u32 s68, s8, s68
	v_mov_b32_e32 v0, 0
	s_addc_u32 s69, s9, s69
	s_mov_b32 s34, -2
	v_add_u32_e32 v184, v8, v1
	v_add_u32_e32 v164, v6, v5
	v_add_u32_e32 v163, v7, v12
	v_add_u32_e32 v162, v7, v13
	v_add_u32_e32 v161, v7, v14
	v_add_u32_e32 v180, v9, v1
	v_add_u32_e32 v170, v10, v1
	v_add_u32_e32 v165, v11, v1
	v_mov_b32_e32 v1, v0
	v_mov_b32_e32 v2, v0
	v_mov_b32_e32 v3, v0
	v_mov_b32_e32 v4, v0
	v_mov_b32_e32 v5, v0
	v_mov_b32_e32 v6, v0
	v_mov_b32_e32 v7, v0
	v_mov_b32_e32 v8, v0
	v_mov_b32_e32 v9, v0
	v_mov_b32_e32 v10, v0
	v_mov_b32_e32 v11, v0
	v_mov_b32_e32 v12, v0
	v_mov_b32_e32 v13, v0
	v_mov_b32_e32 v14, v0
	v_mov_b32_e32 v15, v0
	v_mov_b32_e32 v16, v0
	v_mov_b32_e32 v17, v0
	v_mov_b32_e32 v18, v0
	v_mov_b32_e32 v19, v0
	v_mov_b32_e32 v20, v0
	v_mov_b32_e32 v21, v0
	v_mov_b32_e32 v22, v0
	v_mov_b32_e32 v23, v0
	v_mov_b32_e32 v24, v0
	v_mov_b32_e32 v25, v0
	v_mov_b32_e32 v26, v0
	v_mov_b32_e32 v27, v0
	v_mov_b32_e32 v28, v0
	v_mov_b32_e32 v29, v0
	v_mov_b32_e32 v30, v0
	v_mov_b32_e32 v31, v0
	v_mov_b32_e32 v32, v0
	v_mov_b32_e32 v33, v0
	v_mov_b32_e32 v34, v0
	v_mov_b32_e32 v35, v0
	v_mov_b32_e32 v36, v0
	v_mov_b32_e32 v37, v0
	v_mov_b32_e32 v38, v0
	v_mov_b32_e32 v39, v0
	v_mov_b32_e32 v40, v0
	v_mov_b32_e32 v41, v0
	v_mov_b32_e32 v42, v0
	v_mov_b32_e32 v43, v0
	v_mov_b32_e32 v44, v0
	v_mov_b32_e32 v45, v0
	v_mov_b32_e32 v46, v0
	v_mov_b32_e32 v47, v0
	v_mov_b32_e32 v48, v0
	v_mov_b32_e32 v49, v0
	v_mov_b32_e32 v50, v0
	v_mov_b32_e32 v51, v0
	v_mov_b32_e32 v52, v0
	v_mov_b32_e32 v53, v0
	v_mov_b32_e32 v54, v0
	v_mov_b32_e32 v55, v0
	v_mov_b32_e32 v56, v0
	v_mov_b32_e32 v57, v0
	v_mov_b32_e32 v58, v0
	v_mov_b32_e32 v59, v0
	v_mov_b32_e32 v60, v0
	v_mov_b32_e32 v61, v0
	v_mov_b32_e32 v62, v0
	v_mov_b32_e32 v63, v0
	v_mov_b32_e32 v64, v0
	v_mov_b32_e32 v65, v0
	v_mov_b32_e32 v66, v0
	v_mov_b32_e32 v67, v0
	v_mov_b32_e32 v68, v0
	v_mov_b32_e32 v69, v0
	v_mov_b32_e32 v70, v0
	v_mov_b32_e32 v71, v0
	v_mov_b32_e32 v72, v0
	v_mov_b32_e32 v73, v0
	v_mov_b32_e32 v74, v0
	v_mov_b32_e32 v75, v0
	v_mov_b32_e32 v76, v0
	v_mov_b32_e32 v77, v0
	v_mov_b32_e32 v78, v0
	v_mov_b32_e32 v79, v0
	v_mov_b32_e32 v80, v0
	v_mov_b32_e32 v81, v0
	v_mov_b32_e32 v82, v0
	v_mov_b32_e32 v83, v0
	v_mov_b32_e32 v84, v0
	v_mov_b32_e32 v85, v0
	v_mov_b32_e32 v86, v0
	v_mov_b32_e32 v87, v0
	v_mov_b32_e32 v88, v0
	v_mov_b32_e32 v89, v0
	v_mov_b32_e32 v90, v0
	v_mov_b32_e32 v91, v0
	v_mov_b32_e32 v92, v0
	v_mov_b32_e32 v93, v0
	v_mov_b32_e32 v94, v0
	v_mov_b32_e32 v95, v0
	v_mov_b32_e32 v96, v0
	v_mov_b32_e32 v97, v0
	v_mov_b32_e32 v98, v0
	v_mov_b32_e32 v99, v0
	v_mov_b32_e32 v100, v0
	v_mov_b32_e32 v101, v0
	v_mov_b32_e32 v102, v0
	v_mov_b32_e32 v103, v0
	v_mov_b32_e32 v104, v0
	v_mov_b32_e32 v105, v0
	v_mov_b32_e32 v106, v0
	v_mov_b32_e32 v107, v0
	v_mov_b32_e32 v108, v0
	v_mov_b32_e32 v109, v0
	v_mov_b32_e32 v110, v0
	v_mov_b32_e32 v111, v0
	v_mov_b32_e32 v112, v0
	v_mov_b32_e32 v113, v0
	v_mov_b32_e32 v114, v0
	v_mov_b32_e32 v115, v0
	v_mov_b32_e32 v116, v0
	v_mov_b32_e32 v117, v0
	v_mov_b32_e32 v118, v0
	v_mov_b32_e32 v119, v0
	v_mov_b32_e32 v120, v0
	v_mov_b32_e32 v121, v0
	v_mov_b32_e32 v122, v0
	v_mov_b32_e32 v123, v0
	v_mov_b32_e32 v124, v0
	v_mov_b32_e32 v125, v0
	v_mov_b32_e32 v126, v0
	v_mov_b32_e32 v127, v0
.Lkh_906:
	s_barrier
.LBB0_906:
	ds_read_b128 v[138:141], v184
	ds_read_b128 v[146:149], v184 offset:1024
	ds_read_b128 v[150:153], v184 offset:2048
	ds_read_b128 v[154:157], v184 offset:3072
	v_lshl_add_u64 v[236:237], s[68:69], 0, v[128:129]
	s_mov_b64 s[26:27], 0x572c180
	v_add_u32_e32 v185, 0xc000, v168
	v_lshl_add_u64 v[186:187], v[236:237], 0, s[26:27]
	v_readfirstlane_b32 s26, v185
	s_mov_b32 m0, s26
	ds_read_b128 v[188:191], v164
	ds_read_b128 v[192:195], v164 offset:1024
	ds_read_b128 v[196:199], v163
	ds_read_b128 v[200:203], v163 offset:1024
	ds_read_b128 v[204:207], v162
	ds_read_b128 v[208:211], v162 offset:1024
	ds_read_b128 v[212:215], v161
	ds_read_b128 v[216:219], v161 offset:1024
	global_load_lds_dwordx4 v[186:187], off
	s_mov_b64 s[26:27], 0x57ac180
	v_add_u32_e32 v186, 0xe000, v168
	v_lshl_add_u64 v[220:221], v[236:237], 0, s[26:27]
	v_readfirstlane_b32 s26, v186
	s_mov_b32 m0, s26
	s_nop 0
	global_load_lds_dwordx4 v[220:221], off
	s_waitcnt lgkmcnt(8)
	s_barrier
	s_waitcnt lgkmcnt(0)
	s_setprio 1
	s_waitcnt lgkmcnt(0)
	v_mfma_f32_16x16x32_bf16 v[124:127], v[188:191], v[138:141], v[124:127]
	v_mfma_f32_16x16x32_bf16 v[120:123], v[188:191], v[150:153], v[120:123]
	v_mfma_f32_16x16x32_bf16 v[116:119], v[196:199], v[138:141], v[116:119]
	v_mfma_f32_16x16x32_bf16 v[112:115], v[196:199], v[150:153], v[112:115]
	v_mfma_f32_16x16x32_bf16 v[108:111], v[204:207], v[138:141], v[108:111]
	v_mfma_f32_16x16x32_bf16 v[104:107], v[204:207], v[150:153], v[104:107]
	v_mfma_f32_16x16x32_bf16 v[100:103], v[212:215], v[138:141], v[100:103]
	v_mfma_f32_16x16x32_bf16 v[96:99], v[212:215], v[150:153], v[96:99]
	v_mfma_f32_16x16x32_bf16 v[124:127], v[192:195], v[146:149], v[124:127]
	v_mfma_f32_16x16x32_bf16 v[120:123], v[192:195], v[154:157], v[120:123]
	v_mfma_f32_16x16x32_bf16 v[116:119], v[200:203], v[146:149], v[116:119]
	v_mfma_f32_16x16x32_bf16 v[112:115], v[200:203], v[154:157], v[112:115]
	v_mfma_f32_16x16x32_bf16 v[108:111], v[208:211], v[146:149], v[108:111]
	v_mfma_f32_16x16x32_bf16 v[104:107], v[208:211], v[154:157], v[104:107]
	v_mfma_f32_16x16x32_bf16 v[100:103], v[216:219], v[146:149], v[100:103]
	v_mfma_f32_16x16x32_bf16 v[96:99], v[216:219], v[154:157], v[96:99]
	s_setprio 0
	s_barrier
	v_lshl_add_u64 v[238:239], s[10:11], 0, v[128:129]
	s_mov_b64 s[26:27], 0x2500100
	v_lshl_add_u64 v[240:241], v[238:239], 0, s[26:27]
	v_readfirstlane_b32 s26, v166
	s_mov_b32 m0, s26
	s_mov_b64 s[26:27], 0x2580100
	ds_read_b128 v[220:223], v180
	ds_read_b128 v[224:227], v180 offset:1024
	ds_read_b128 v[228:231], v180 offset:2048
	ds_read_b128 v[232:235], v180 offset:3072
	global_load_lds_dwordx4 v[240:241], off
	v_lshl_add_u64 v[240:241], v[238:239], 0, s[26:27]
	v_readfirstlane_b32 s26, v167
	s_mov_b32 m0, s26
	s_nop 0
	global_load_lds_dwordx4 v[240:241], off
	s_barrier
	s_waitcnt lgkmcnt(0)
	s_setprio 1
	s_waitcnt lgkmcnt(0)
	v_mfma_f32_16x16x32_bf16 v[92:95], v[188:191], v[220:223], v[92:95]
	v_mfma_f32_16x16x32_bf16 v[88:91], v[188:191], v[228:231], v[88:91]
	v_mfma_f32_16x16x32_bf16 v[84:87], v[196:199], v[220:223], v[84:87]
	v_mfma_f32_16x16x32_bf16 v[80:83], v[196:199], v[228:231], v[80:83]
	v_mfma_f32_16x16x32_bf16 v[76:79], v[204:207], v[220:223], v[76:79]
	v_mfma_f32_16x16x32_bf16 v[72:75], v[204:207], v[228:231], v[72:75]
	v_mfma_f32_16x16x32_bf16 v[68:71], v[212:215], v[220:223], v[68:71]
	v_mfma_f32_16x16x32_bf16 v[64:67], v[212:215], v[228:231], v[64:67]
	v_mfma_f32_16x16x32_bf16 v[92:95], v[192:195], v[224:227], v[92:95]
	v_mfma_f32_16x16x32_bf16 v[88:91], v[192:195], v[232:235], v[88:91]
	v_mfma_f32_16x16x32_bf16 v[84:87], v[200:203], v[224:227], v[84:87]
	v_mfma_f32_16x16x32_bf16 v[80:83], v[200:203], v[232:235], v[80:83]
	v_mfma_f32_16x16x32_bf16 v[76:79], v[208:211], v[224:227], v[76:79]
	v_mfma_f32_16x16x32_bf16 v[72:75], v[208:211], v[232:235], v[72:75]
	v_mfma_f32_16x16x32_bf16 v[68:71], v[216:219], v[224:227], v[68:71]
	v_mfma_f32_16x16x32_bf16 v[64:67], v[216:219], v[232:235], v[64:67]
	s_setprio 0
	s_mov_b64 s[26:27], 0x562c200
	v_lshl_add_u64 v[240:241], v[236:237], 0, s[26:27]
	v_readfirstlane_b32 s26, v168
	s_mov_b32 m0, s26
	s_mov_b64 s[26:27], 0x56ac200
	s_barrier
	ds_read_b128 v[188:191], v164 offset:16384
	ds_read_b128 v[192:195], v164 offset:17408
	ds_read_b128 v[196:199], v163 offset:16384
	ds_read_b128 v[200:203], v163 offset:17408
	ds_read_b128 v[204:207], v162 offset:16384
	ds_read_b128 v[208:211], v162 offset:17408
	ds_read_b128 v[212:215], v161 offset:16384
	ds_read_b128 v[216:219], v161 offset:17408
	global_load_lds_dwordx4 v[240:241], off
	v_lshl_add_u64 v[240:241], v[236:237], 0, s[26:27]
	v_readfirstlane_b32 s26, v169
	s_mov_b32 m0, s26
	s_nop 0
	global_load_lds_dwordx4 v[240:241], off
	s_barrier
	s_waitcnt lgkmcnt(0)
	s_setprio 1
	s_waitcnt lgkmcnt(0)
	v_mfma_f32_16x16x32_bf16 v[60:63], v[188:191], v[138:141], v[60:63]
	v_mfma_f32_16x16x32_bf16 v[56:59], v[188:191], v[150:153], v[56:59]
	v_mfma_f32_16x16x32_bf16 v[52:55], v[196:199], v[138:141], v[52:55]
	v_mfma_f32_16x16x32_bf16 v[48:51], v[196:199], v[150:153], v[48:51]
	v_mfma_f32_16x16x32_bf16 v[44:47], v[204:207], v[138:141], v[44:47]
	v_mfma_f32_16x16x32_bf16 v[40:43], v[204:207], v[150:153], v[40:43]
	v_mfma_f32_16x16x32_bf16 v[36:39], v[212:215], v[138:141], v[36:39]
	v_mfma_f32_16x16x32_bf16 v[32:35], v[212:215], v[150:153], v[32:35]
	v_mfma_f32_16x16x32_bf16 v[60:63], v[192:195], v[146:149], v[60:63]
	v_mfma_f32_16x16x32_bf16 v[56:59], v[192:195], v[154:157], v[56:59]
	v_mfma_f32_16x16x32_bf16 v[52:55], v[200:203], v[146:149], v[52:55]
	v_mfma_f32_16x16x32_bf16 v[48:51], v[200:203], v[154:157], v[48:51]
	v_mfma_f32_16x16x32_bf16 v[44:47], v[208:211], v[146:149], v[44:47]
	v_mfma_f32_16x16x32_bf16 v[40:43], v[208:211], v[154:157], v[40:43]
	v_mfma_f32_16x16x32_bf16 v[36:39], v[216:219], v[146:149], v[36:39]
	v_mfma_f32_16x16x32_bf16 v[32:35], v[216:219], v[154:157], v[32:35]
	s_setprio 0
	s_barrier
	s_mov_b64 s[26:27], 0x2600100
	v_lshl_add_u64 v[138:139], v[238:239], 0, s[26:27]
	v_readfirstlane_b32 s26, v171
	s_mov_b32 m0, s26
	s_mov_b64 s[26:27], 0x2680100
	global_load_lds_dwordx4 v[138:139], off
	v_lshl_add_u64 v[138:139], v[238:239], 0, s[26:27]
	v_readfirstlane_b32 s26, v172
	s_mov_b32 m0, s26
	s_nop 0
	global_load_lds_dwordx4 v[138:139], off
	s_waitcnt vmcnt(6)
	s_barrier
	s_setprio 1
	v_mfma_f32_16x16x32_bf16 v[28:31], v[188:191], v[220:223], v[28:31]
	v_mfma_f32_16x16x32_bf16 v[24:27], v[188:191], v[228:231], v[24:27]
	v_mfma_f32_16x16x32_bf16 v[20:23], v[196:199], v[220:223], v[20:23]
	v_mfma_f32_16x16x32_bf16 v[16:19], v[196:199], v[228:231], v[16:19]
	v_mfma_f32_16x16x32_bf16 v[12:15], v[204:207], v[220:223], v[12:15]
	v_mfma_f32_16x16x32_bf16 v[8:11], v[204:207], v[228:231], v[8:11]
	v_mfma_f32_16x16x32_bf16 v[4:7], v[212:215], v[220:223], v[4:7]
	v_mfma_f32_16x16x32_bf16 v[0:3], v[212:215], v[228:231], v[0:3]
	v_mfma_f32_16x16x32_bf16 v[28:31], v[192:195], v[224:227], v[28:31]
	v_mfma_f32_16x16x32_bf16 v[24:27], v[192:195], v[232:235], v[24:27]
	v_mfma_f32_16x16x32_bf16 v[20:23], v[200:203], v[224:227], v[20:23]
	v_mfma_f32_16x16x32_bf16 v[16:19], v[200:203], v[232:235], v[16:19]
	v_mfma_f32_16x16x32_bf16 v[12:15], v[208:211], v[224:227], v[12:15]
	v_mfma_f32_16x16x32_bf16 v[8:11], v[208:211], v[232:235], v[8:11]
	v_mfma_f32_16x16x32_bf16 v[4:7], v[216:219], v[224:227], v[4:7]
	v_mfma_f32_16x16x32_bf16 v[0:3], v[216:219], v[232:235], v[0:3]
	s_setprio 0
	s_barrier
	ds_read_b128 v[138:141], v170
	ds_read_b128 v[146:149], v170 offset:1024
	ds_read_b128 v[150:153], v170 offset:2048
	ds_read_b128 v[154:157], v170 offset:3072
	s_mov_b64 s[26:27], 0x572c200
	v_lshl_add_u64 v[220:221], v[236:237], 0, s[26:27]
	v_readfirstlane_b32 s26, v173
	s_mov_b32 m0, s26
	s_mov_b64 s[26:27], 0x57ac200
	ds_read_b128 v[188:191], v164 offset:32768
	ds_read_b128 v[192:195], v164 offset:33792
	ds_read_b128 v[196:199], v163 offset:32768
	ds_read_b128 v[200:203], v163 offset:33792
	ds_read_b128 v[204:207], v162 offset:32768
	ds_read_b128 v[208:211], v162 offset:33792
	ds_read_b128 v[212:215], v161 offset:32768
	ds_read_b128 v[216:219], v161 offset:33792
	global_load_lds_dwordx4 v[220:221], off
	v_lshl_add_u64 v[220:221], v[236:237], 0, s[26:27]
	v_readfirstlane_b32 s26, v174
	s_mov_b32 m0, s26
	s_nop 0
	global_load_lds_dwordx4 v[220:221], off
	s_waitcnt lgkmcnt(8)
	s_barrier
	s_waitcnt lgkmcnt(0)
	s_setprio 1
	s_waitcnt lgkmcnt(0)
	v_mfma_f32_16x16x32_bf16 v[124:127], v[188:191], v[138:141], v[124:127]
	v_mfma_f32_16x16x32_bf16 v[120:123], v[188:191], v[150:153], v[120:123]
	v_mfma_f32_16x16x32_bf16 v[116:119], v[196:199], v[138:141], v[116:119]
	v_mfma_f32_16x16x32_bf16 v[112:115], v[196:199], v[150:153], v[112:115]
	v_mfma_f32_16x16x32_bf16 v[108:111], v[204:207], v[138:141], v[108:111]
	v_mfma_f32_16x16x32_bf16 v[104:107], v[204:207], v[150:153], v[104:107]
	v_mfma_f32_16x16x32_bf16 v[100:103], v[212:215], v[138:141], v[100:103]
	v_mfma_f32_16x16x32_bf16 v[96:99], v[212:215], v[150:153], v[96:99]
	v_mfma_f32_16x16x32_bf16 v[124:127], v[192:195], v[146:149], v[124:127]
	v_mfma_f32_16x16x32_bf16 v[120:123], v[192:195], v[154:157], v[120:123]
	v_mfma_f32_16x16x32_bf16 v[116:119], v[200:203], v[146:149], v[116:119]
	v_mfma_f32_16x16x32_bf16 v[112:115], v[200:203], v[154:157], v[112:115]
	v_mfma_f32_16x16x32_bf16 v[108:111], v[208:211], v[146:149], v[108:111]
	v_mfma_f32_16x16x32_bf16 v[104:107], v[208:211], v[154:157], v[104:107]
	v_mfma_f32_16x16x32_bf16 v[100:103], v[216:219], v[146:149], v[100:103]
	v_mfma_f32_16x16x32_bf16 v[96:99], v[216:219], v[154:157], v[96:99]
	s_setprio 0
	s_barrier
	s_mov_b64 s[26:27], 0x2500180
	v_lshl_add_u64 v[240:241], v[238:239], 0, s[26:27]
	v_readfirstlane_b32 s26, v175
	s_mov_b32 m0, s26
	s_mov_b64 s[26:27], 0x2580180
	ds_read_b128 v[220:223], v165
	ds_read_b128 v[224:227], v165 offset:1024
	ds_read_b128 v[228:231], v165 offset:2048
	ds_read_b128 v[232:235], v165 offset:3072
	global_load_lds_dwordx4 v[240:241], off
	v_lshl_add_u64 v[240:241], v[238:239], 0, s[26:27]
	v_readfirstlane_b32 s26, v176
	s_mov_b32 m0, s26
	s_nop 0
	global_load_lds_dwordx4 v[240:241], off
	s_barrier
	s_waitcnt lgkmcnt(0)
	s_setprio 1
	s_waitcnt lgkmcnt(0)
	v_mfma_f32_16x16x32_bf16 v[92:95], v[188:191], v[220:223], v[92:95]
	v_mfma_f32_16x16x32_bf16 v[88:91], v[188:191], v[228:231], v[88:91]
	v_mfma_f32_16x16x32_bf16 v[84:87], v[196:199], v[220:223], v[84:87]
	v_mfma_f32_16x16x32_bf16 v[80:83], v[196:199], v[228:231], v[80:83]
	v_mfma_f32_16x16x32_bf16 v[76:79], v[204:207], v[220:223], v[76:79]
	v_mfma_f32_16x16x32_bf16 v[72:75], v[204:207], v[228:231], v[72:75]
	v_mfma_f32_16x16x32_bf16 v[68:71], v[212:215], v[220:223], v[68:71]
	v_mfma_f32_16x16x32_bf16 v[64:67], v[212:215], v[228:231], v[64:67]
	v_mfma_f32_16x16x32_bf16 v[92:95], v[192:195], v[224:227], v[92:95]
	v_mfma_f32_16x16x32_bf16 v[88:91], v[192:195], v[232:235], v[88:91]
	v_mfma_f32_16x16x32_bf16 v[84:87], v[200:203], v[224:227], v[84:87]
	v_mfma_f32_16x16x32_bf16 v[80:83], v[200:203], v[232:235], v[80:83]
	v_mfma_f32_16x16x32_bf16 v[76:79], v[208:211], v[224:227], v[76:79]
	v_mfma_f32_16x16x32_bf16 v[72:75], v[208:211], v[232:235], v[72:75]
	v_mfma_f32_16x16x32_bf16 v[68:71], v[216:219], v[224:227], v[68:71]
	v_mfma_f32_16x16x32_bf16 v[64:67], v[216:219], v[232:235], v[64:67]
	s_setprio 0
	s_mov_b64 s[26:27], 0x562c280
	v_lshl_add_u64 v[240:241], v[236:237], 0, s[26:27]
	v_readfirstlane_b32 s26, v177
	s_mov_b32 m0, s26
	s_mov_b64 s[26:27], 0x56ac280
	v_lshl_add_u64 v[236:237], v[236:237], 0, s[26:27]
	v_readfirstlane_b32 s26, v178
	s_barrier
	ds_read_b128 v[188:191], v164 offset:49152
	ds_read_b128 v[192:195], v164 offset:50176
	ds_read_b128 v[196:199], v163 offset:49152
	ds_read_b128 v[200:203], v163 offset:50176
	ds_read_b128 v[204:207], v162 offset:49152
	ds_read_b128 v[208:211], v162 offset:50176
	ds_read_b128 v[212:215], v161 offset:49152
	ds_read_b128 v[216:219], v161 offset:50176
	global_load_lds_dwordx4 v[240:241], off
	s_mov_b32 m0, s26
	s_nop 0
	global_load_lds_dwordx4 v[236:237], off
	s_barrier
	s_waitcnt lgkmcnt(0)
	s_setprio 1
	s_waitcnt lgkmcnt(0)
	v_mfma_f32_16x16x32_bf16 v[60:63], v[188:191], v[138:141], v[60:63]
	v_mfma_f32_16x16x32_bf16 v[56:59], v[188:191], v[150:153], v[56:59]
	v_mfma_f32_16x16x32_bf16 v[52:55], v[196:199], v[138:141], v[52:55]
	v_mfma_f32_16x16x32_bf16 v[48:51], v[196:199], v[150:153], v[48:51]
	v_mfma_f32_16x16x32_bf16 v[44:47], v[204:207], v[138:141], v[44:47]
	v_mfma_f32_16x16x32_bf16 v[40:43], v[204:207], v[150:153], v[40:43]
	v_mfma_f32_16x16x32_bf16 v[36:39], v[212:215], v[138:141], v[36:39]
	v_mfma_f32_16x16x32_bf16 v[32:35], v[212:215], v[150:153], v[32:35]
	v_mfma_f32_16x16x32_bf16 v[60:63], v[192:195], v[146:149], v[60:63]
	v_mfma_f32_16x16x32_bf16 v[56:59], v[192:195], v[154:157], v[56:59]
	v_mfma_f32_16x16x32_bf16 v[52:55], v[200:203], v[146:149], v[52:55]
	v_mfma_f32_16x16x32_bf16 v[48:51], v[200:203], v[154:157], v[48:51]
	v_mfma_f32_16x16x32_bf16 v[44:47], v[208:211], v[146:149], v[44:47]
	v_mfma_f32_16x16x32_bf16 v[40:43], v[208:211], v[154:157], v[40:43]
	v_mfma_f32_16x16x32_bf16 v[36:39], v[216:219], v[146:149], v[36:39]
	v_mfma_f32_16x16x32_bf16 v[32:35], v[216:219], v[154:157], v[32:35]
	s_setprio 0
	s_barrier
	s_mov_b64 s[26:27], 0x2600180
	v_lshl_add_u64 v[138:139], v[238:239], 0, s[26:27]
	v_readfirstlane_b32 s26, v179
	s_mov_b32 m0, s26
	s_mov_b64 s[26:27], 0x2680180
	global_load_lds_dwordx4 v[138:139], off
	v_lshl_add_u64 v[138:139], v[238:239], 0, s[26:27]
	v_readfirstlane_b32 s26, v181
	s_mov_b32 m0, s26
	s_nop 0
	global_load_lds_dwordx4 v[138:139], off
	s_waitcnt vmcnt(6)
	s_barrier
	s_setprio 1
	v_mfma_f32_16x16x32_bf16 v[28:31], v[188:191], v[220:223], v[28:31]
	v_mfma_f32_16x16x32_bf16 v[24:27], v[188:191], v[228:231], v[24:27]
	v_mfma_f32_16x16x32_bf16 v[20:23], v[196:199], v[220:223], v[20:23]
	v_mfma_f32_16x16x32_bf16 v[16:19], v[196:199], v[228:231], v[16:19]
	v_mfma_f32_16x16x32_bf16 v[12:15], v[204:207], v[220:223], v[12:15]
	v_mfma_f32_16x16x32_bf16 v[8:11], v[204:207], v[228:231], v[8:11]
	v_mfma_f32_16x16x32_bf16 v[4:7], v[212:215], v[220:223], v[4:7]
	v_mfma_f32_16x16x32_bf16 v[0:3], v[212:215], v[228:231], v[0:3]
	v_mfma_f32_16x16x32_bf16 v[28:31], v[192:195], v[224:227], v[28:31]
	v_mfma_f32_16x16x32_bf16 v[24:27], v[192:195], v[232:235], v[24:27]
	v_mfma_f32_16x16x32_bf16 v[20:23], v[200:203], v[224:227], v[20:23]
	v_mfma_f32_16x16x32_bf16 v[16:19], v[200:203], v[232:235], v[16:19]
	v_mfma_f32_16x16x32_bf16 v[12:15], v[208:211], v[224:227], v[12:15]
	v_mfma_f32_16x16x32_bf16 v[8:11], v[208:211], v[232:235], v[8:11]
	v_mfma_f32_16x16x32_bf16 v[4:7], v[216:219], v[224:227], v[4:7]
	v_mfma_f32_16x16x32_bf16 v[0:3], v[216:219], v[232:235], v[0:3]
	s_setprio 0
	s_add_i32 s34, s34, 2
	s_add_u32 s10, s10, 0x100
	s_addc_u32 s11, s11, 0
	s_add_u32 s68, s68, 0x100
	s_addc_u32 s69, s69, 0
	s_cmp_lt_u32 s34, 60
	s_cbranch_scc1 .Lkh_906
	s_barrier
	s_mov_b64 s[10:11], 0x101f80
	v_lshl_add_u64 v[208:209], v[130:131], 0, s[10:11]
	v_readfirstlane_b32 s10, v185
	s_mov_b32 m0, s10
	s_mov_b64 s[10:11], 0x181f80
	v_lshl_add_u64 v[130:131], v[130:131], 0, s[10:11]
	v_readfirstlane_b32 s10, v186
	ds_read_b128 v[138:141], v184
	ds_read_b128 v[146:149], v184 offset:1024
	ds_read_b128 v[150:153], v184 offset:2048
	ds_read_b128 v[154:157], v184 offset:3072
	ds_read_b128 v[166:169], v164
	ds_read_b128 v[172:175], v164 offset:1024
	ds_read_b128 v[176:179], v163
	ds_read_b128 v[188:191], v163 offset:1024
	ds_read_b128 v[192:195], v162
	ds_read_b128 v[196:199], v162 offset:1024
	ds_read_b128 v[200:203], v161
	ds_read_b128 v[204:207], v161 offset:1024
	global_load_lds_dwordx4 v[208:209], off
	s_mov_b32 m0, s10
	s_nop 0
	global_load_lds_dwordx4 v[130:131], off
	s_barrier
	s_waitcnt lgkmcnt(0)
	s_setprio 1
	s_waitcnt lgkmcnt(0)
	v_mfma_f32_16x16x32_bf16 v[124:127], v[166:169], v[138:141], v[124:127]
	v_mfma_f32_16x16x32_bf16 v[120:123], v[166:169], v[150:153], v[120:123]
	v_mfma_f32_16x16x32_bf16 v[116:119], v[176:179], v[138:141], v[116:119]
	v_mfma_f32_16x16x32_bf16 v[112:115], v[176:179], v[150:153], v[112:115]
	v_mfma_f32_16x16x32_bf16 v[124:127], v[172:175], v[146:149], v[124:127]
	v_mfma_f32_16x16x32_bf16 v[120:123], v[172:175], v[154:157], v[120:123]
	v_mfma_f32_16x16x32_bf16 v[116:119], v[188:191], v[146:149], v[116:119]
	v_mfma_f32_16x16x32_bf16 v[112:115], v[188:191], v[154:157], v[112:115]
	v_mfma_f32_16x16x32_bf16 v[108:111], v[192:195], v[138:141], v[108:111]
	v_mfma_f32_16x16x32_bf16 v[104:107], v[192:195], v[150:153], v[104:107]
	v_mfma_f32_16x16x32_bf16 v[100:103], v[200:203], v[138:141], v[100:103]
	v_mfma_f32_16x16x32_bf16 v[96:99], v[200:203], v[150:153], v[96:99]
	v_mfma_f32_16x16x32_bf16 v[184:187], v[196:199], v[146:149], v[108:111]
	v_mfma_f32_16x16x32_bf16 v[208:211], v[196:199], v[154:157], v[104:107]
	v_mfma_f32_16x16x32_bf16 v[212:215], v[204:207], v[146:149], v[100:103]
	v_mfma_f32_16x16x32_bf16 v[216:219], v[204:207], v[154:157], v[96:99]
	s_setprio 0
	s_barrier
	s_nop 1
	ds_read_b128 v[96:99], v180
	ds_read_b128 v[100:103], v180 offset:1024
	ds_read_b128 v[104:107], v180 offset:2048
	ds_read_b128 v[108:111], v180 offset:3072
	s_barrier
	s_waitcnt lgkmcnt(0)
	s_setprio 1
	s_waitcnt lgkmcnt(0)
	v_mfma_f32_16x16x32_bf16 v[92:95], v[166:169], v[96:99], v[92:95]
	v_mfma_f32_16x16x32_bf16 v[88:91], v[166:169], v[104:107], v[88:91]
	v_mfma_f32_16x16x32_bf16 v[84:87], v[176:179], v[96:99], v[84:87]
	v_mfma_f32_16x16x32_bf16 v[80:83], v[176:179], v[104:107], v[80:83]
	v_mfma_f32_16x16x32_bf16 v[92:95], v[172:175], v[100:103], v[92:95]
	v_mfma_f32_16x16x32_bf16 v[88:91], v[172:175], v[108:111], v[88:91]
	v_mfma_f32_16x16x32_bf16 v[84:87], v[188:191], v[100:103], v[84:87]
	v_mfma_f32_16x16x32_bf16 v[80:83], v[188:191], v[108:111], v[80:83]
	v_mfma_f32_16x16x32_bf16 v[76:79], v[192:195], v[96:99], v[76:79]
	v_mfma_f32_16x16x32_bf16 v[72:75], v[192:195], v[104:107], v[72:75]
	v_mfma_f32_16x16x32_bf16 v[68:71], v[200:203], v[96:99], v[68:71]
	v_mfma_f32_16x16x32_bf16 v[64:67], v[200:203], v[104:107], v[64:67]
	v_mfma_f32_16x16x32_bf16 v[166:169], v[196:199], v[100:103], v[76:79]
	v_mfma_f32_16x16x32_bf16 v[172:175], v[196:199], v[108:111], v[72:75]
	v_mfma_f32_16x16x32_bf16 v[176:179], v[204:207], v[100:103], v[68:71]
	v_mfma_f32_16x16x32_bf16 v[188:191], v[204:207], v[108:111], v[64:67]
	s_setprio 0
	s_barrier
	s_nop 1
	ds_read_b128 v[64:67], v164 offset:16384
	ds_read_b128 v[68:71], v164 offset:17408
	ds_read_b128 v[72:75], v163 offset:16384
	ds_read_b128 v[76:79], v163 offset:17408
	ds_read_b128 v[192:195], v162 offset:16384
	ds_read_b128 v[196:199], v162 offset:17408
	ds_read_b128 v[200:203], v161 offset:16384
	ds_read_b128 v[204:207], v161 offset:17408
	s_waitcnt vmcnt(4)
	s_barrier
	s_waitcnt lgkmcnt(0)
	s_setprio 1
	s_waitcnt lgkmcnt(0)
	v_mfma_f32_16x16x32_bf16 v[60:63], v[64:67], v[138:141], v[60:63]
	v_mfma_f32_16x16x32_bf16 v[56:59], v[64:67], v[150:153], v[56:59]
	v_mfma_f32_16x16x32_bf16 v[52:55], v[72:75], v[138:141], v[52:55]
	v_mfma_f32_16x16x32_bf16 v[48:51], v[72:75], v[150:153], v[48:51]
	v_mfma_f32_16x16x32_bf16 v[60:63], v[68:71], v[146:149], v[60:63]
	v_mfma_f32_16x16x32_bf16 v[56:59], v[68:71], v[154:157], v[56:59]
	v_mfma_f32_16x16x32_bf16 v[52:55], v[76:79], v[146:149], v[52:55]
	v_mfma_f32_16x16x32_bf16 v[48:51], v[76:79], v[154:157], v[48:51]
	v_mfma_f32_16x16x32_bf16 v[44:47], v[192:195], v[138:141], v[44:47]
	v_mfma_f32_16x16x32_bf16 v[40:43], v[192:195], v[150:153], v[40:43]
	v_mfma_f32_16x16x32_bf16 v[36:39], v[200:203], v[138:141], v[36:39]
	v_mfma_f32_16x16x32_bf16 v[32:35], v[200:203], v[150:153], v[32:35]
	v_mfma_f32_16x16x32_bf16 v[220:223], v[196:199], v[146:149], v[44:47]
	v_mfma_f32_16x16x32_bf16 v[224:227], v[196:199], v[154:157], v[40:43]
	v_mfma_f32_16x16x32_bf16 v[138:141], v[204:207], v[146:149], v[36:39]
	v_mfma_f32_16x16x32_bf16 v[146:149], v[204:207], v[154:157], v[32:35]
	s_setprio 0
	s_setprio 1
	v_mfma_f32_16x16x32_bf16 v[28:31], v[64:67], v[96:99], v[28:31]
	v_mfma_f32_16x16x32_bf16 v[24:27], v[64:67], v[104:107], v[24:27]
	v_mfma_f32_16x16x32_bf16 v[20:23], v[72:75], v[96:99], v[20:23]
	v_mfma_f32_16x16x32_bf16 v[16:19], v[72:75], v[104:107], v[16:19]
	v_mfma_f32_16x16x32_bf16 v[28:31], v[68:71], v[100:103], v[28:31]
	v_mfma_f32_16x16x32_bf16 v[24:27], v[68:71], v[108:111], v[24:27]
	v_mfma_f32_16x16x32_bf16 v[20:23], v[76:79], v[100:103], v[20:23]
	v_mfma_f32_16x16x32_bf16 v[16:19], v[76:79], v[108:111], v[16:19]
	v_mfma_f32_16x16x32_bf16 v[12:15], v[192:195], v[96:99], v[12:15]
	v_mfma_f32_16x16x32_bf16 v[8:11], v[192:195], v[104:107], v[8:11]
	v_mfma_f32_16x16x32_bf16 v[4:7], v[200:203], v[96:99], v[4:7]
	v_mfma_f32_16x16x32_bf16 v[0:3], v[200:203], v[104:107], v[0:3]
	v_mfma_f32_16x16x32_bf16 v[150:153], v[196:199], v[100:103], v[12:15]
	v_mfma_f32_16x16x32_bf16 v[154:157], v[196:199], v[108:111], v[8:11]
	v_mfma_f32_16x16x32_bf16 v[192:195], v[204:207], v[100:103], v[4:7]
	v_mfma_f32_16x16x32_bf16 v[196:199], v[204:207], v[108:111], v[0:3]
	s_setprio 0
	s_barrier
	s_nop 1
	ds_read_b128 v[0:3], v170
	ds_read_b128 v[4:7], v170 offset:1024
	ds_read_b128 v[200:203], v170 offset:2048
	ds_read_b128 v[204:207], v170 offset:3072
	ds_read_b128 v[8:11], v164 offset:32768
	ds_read_b128 v[12:15], v164 offset:33792
	ds_read_b128 v[32:35], v163 offset:32768
	ds_read_b128 v[36:39], v163 offset:33792
	ds_read_b128 v[40:43], v162 offset:32768
	ds_read_b128 v[44:47], v162 offset:33792
	ds_read_b128 v[228:231], v161 offset:32768
	ds_read_b128 v[232:235], v161 offset:33792
	s_waitcnt vmcnt(2)
	s_barrier
	s_waitcnt lgkmcnt(0)
	s_setprio 1
	s_waitcnt lgkmcnt(0)
	v_mfma_f32_16x16x32_bf16 v[64:67], v[8:11], v[0:3], v[124:127]
	v_mfma_f32_16x16x32_bf16 v[104:107], v[12:15], v[4:7], v[64:67]
	v_mfma_f32_16x16x32_bf16 v[64:67], v[8:11], v[200:203], v[120:123]
	v_mfma_f32_16x16x32_bf16 v[108:111], v[12:15], v[204:207], v[64:67]
	v_mfma_f32_16x16x32_bf16 v[64:67], v[32:35], v[0:3], v[116:119]
	v_mfma_f32_16x16x32_bf16 v[96:99], v[36:39], v[4:7], v[64:67]
	v_mfma_f32_16x16x32_bf16 v[64:67], v[32:35], v[200:203], v[112:115]
	v_mfma_f32_16x16x32_bf16 v[100:103], v[36:39], v[204:207], v[64:67]
	v_mfma_f32_16x16x32_bf16 v[64:67], v[40:43], v[0:3], v[184:187]
	v_mfma_f32_16x16x32_bf16 v[72:75], v[44:47], v[4:7], v[64:67]
	v_mfma_f32_16x16x32_bf16 v[64:67], v[40:43], v[200:203], v[208:211]
	v_mfma_f32_16x16x32_bf16 v[76:79], v[44:47], v[204:207], v[64:67]
	v_mfma_f32_16x16x32_bf16 v[64:67], v[228:231], v[0:3], v[212:215]
	v_mfma_f32_16x16x32_bf16 v[68:71], v[228:231], v[200:203], v[216:219]
	v_mfma_f32_16x16x32_bf16 v[64:67], v[232:235], v[4:7], v[64:67]
	v_mfma_f32_16x16x32_bf16 v[68:71], v[232:235], v[204:207], v[68:71]
	s_setprio 0
	s_barrier
	ds_read_b128 v[184:187], v165
	ds_read_b128 v[208:211], v165 offset:1024
	ds_read_b128 v[212:215], v165 offset:2048
	ds_read_b128 v[216:219], v165 offset:3072
	s_waitcnt vmcnt(0)
	s_barrier
	s_waitcnt lgkmcnt(0)
	s_setprio 1
	s_waitcnt lgkmcnt(0)
	v_mfma_f32_16x16x32_bf16 v[92:95], v[8:11], v[184:187], v[92:95]
	v_mfma_f32_16x16x32_bf16 v[8:11], v[8:11], v[212:215], v[88:91]
	v_mfma_f32_16x16x32_bf16 v[124:127], v[12:15], v[216:219], v[8:11]
	v_mfma_f32_16x16x32_bf16 v[8:11], v[32:35], v[184:187], v[84:87]
	v_mfma_f32_16x16x32_bf16 v[112:115], v[36:39], v[208:211], v[8:11]
	v_mfma_f32_16x16x32_bf16 v[8:11], v[32:35], v[212:215], v[80:83]
	v_mfma_f32_16x16x32_bf16 v[116:119], v[36:39], v[216:219], v[8:11]
	v_mfma_f32_16x16x32_bf16 v[8:11], v[40:43], v[184:187], v[166:169]
	v_mfma_f32_16x16x32_bf16 v[88:91], v[44:47], v[208:211], v[8:11]
	v_mfma_f32_16x16x32_bf16 v[8:11], v[40:43], v[212:215], v[172:175]
	v_mfma_f32_16x16x32_bf16 v[120:123], v[12:15], v[208:211], v[92:95]
	v_mfma_f32_16x16x32_bf16 v[92:95], v[44:47], v[216:219], v[8:11]
	v_mfma_f32_16x16x32_bf16 v[8:11], v[228:231], v[184:187], v[176:179]
	v_mfma_f32_16x16x32_bf16 v[80:83], v[232:235], v[208:211], v[8:11]
	v_mfma_f32_16x16x32_bf16 v[8:11], v[228:231], v[212:215], v[188:191]
	v_mfma_f32_16x16x32_bf16 v[84:87], v[232:235], v[216:219], v[8:11]
	s_setprio 0
	s_barrier
	ds_read_b128 v[166:169], v164 offset:49152
	ds_read_b128 v[170:173], v164 offset:50176
	ds_read_b128 v[174:177], v163 offset:49152
	ds_read_b128 v[178:181], v163 offset:50176
	ds_read_b128 v[188:191], v162 offset:49152
	ds_read_b128 v[162:165], v162 offset:50176
	ds_read_b128 v[228:231], v161 offset:49152
	ds_read_b128 v[232:235], v161 offset:50176
	s_barrier
	s_waitcnt lgkmcnt(0)
	s_setprio 1
	s_waitcnt lgkmcnt(0)
	v_mfma_f32_16x16x32_bf16 v[8:11], v[166:169], v[0:3], v[60:63]
	v_mfma_f32_16x16x32_bf16 v[40:43], v[170:173], v[4:7], v[8:11]
	v_mfma_f32_16x16x32_bf16 v[8:11], v[166:169], v[200:203], v[56:59]
	v_mfma_f32_16x16x32_bf16 v[44:47], v[170:173], v[204:207], v[8:11]
	v_mfma_f32_16x16x32_bf16 v[8:11], v[174:177], v[0:3], v[52:55]
	v_mfma_f32_16x16x32_bf16 v[32:35], v[178:181], v[4:7], v[8:11]
	v_mfma_f32_16x16x32_bf16 v[8:11], v[174:177], v[200:203], v[48:51]
	v_mfma_f32_16x16x32_bf16 v[36:39], v[178:181], v[204:207], v[8:11]
	v_mfma_f32_16x16x32_bf16 v[8:11], v[188:191], v[0:3], v[220:223]
	v_mfma_f32_16x16x32_bf16 v[0:3], v[228:231], v[0:3], v[138:141]
	v_mfma_f32_16x16x32_bf16 v[8:11], v[162:165], v[4:7], v[8:11]
	v_mfma_f32_16x16x32_bf16 v[12:15], v[188:191], v[200:203], v[224:227]
	v_mfma_f32_16x16x32_bf16 v[0:3], v[232:235], v[4:7], v[0:3]
	v_mfma_f32_16x16x32_bf16 v[4:7], v[228:231], v[200:203], v[146:149]
	v_mfma_f32_16x16x32_bf16 v[12:15], v[162:165], v[204:207], v[12:15]
	v_mfma_f32_16x16x32_bf16 v[4:7], v[232:235], v[204:207], v[4:7]
	s_setprio 0
	s_setprio 1
	v_mfma_f32_16x16x32_bf16 v[16:19], v[174:177], v[212:215], v[16:19]
	v_mfma_f32_16x16x32_bf16 v[24:27], v[166:169], v[212:215], v[24:27]
	v_mfma_f32_16x16x32_bf16 v[52:55], v[178:181], v[216:219], v[16:19]
	v_mfma_f32_16x16x32_bf16 v[16:19], v[188:191], v[184:187], v[150:153]
	v_mfma_f32_16x16x32_bf16 v[28:31], v[166:169], v[184:187], v[28:31]
	v_mfma_f32_16x16x32_bf16 v[60:63], v[170:173], v[216:219], v[24:27]
	v_mfma_f32_16x16x32_bf16 v[20:23], v[174:177], v[184:187], v[20:23]
	v_mfma_f32_16x16x32_bf16 v[24:27], v[162:165], v[208:211], v[16:19]
	v_mfma_f32_16x16x32_bf16 v[16:19], v[188:191], v[212:215], v[154:157]
	v_mfma_f32_16x16x32_bf16 v[56:59], v[170:173], v[208:211], v[28:31]
	v_mfma_f32_16x16x32_bf16 v[48:51], v[178:181], v[208:211], v[20:23]
	v_mfma_f32_16x16x32_bf16 v[28:31], v[162:165], v[216:219], v[16:19]
	v_mfma_f32_16x16x32_bf16 v[16:19], v[228:231], v[184:187], v[192:195]
	v_mfma_f32_16x16x32_bf16 v[20:23], v[228:231], v[212:215], v[196:199]
	v_mfma_f32_16x16x32_bf16 v[16:19], v[232:235], v[208:211], v[16:19]
	v_mfma_f32_16x16x32_bf16 v[20:23], v[232:235], v[216:219], v[20:23]
	s_setprio 0
	v_cmp_gt_u32_e32 vcc, s92, v132
	s_barrier
	s_and_saveexec_b64 s[10:11], vcc
	s_cbranch_execz .LBB0_902
	s_barrier
	s_branch .LBB0_902

.LBB0_994:
	s_or_b64 exec, exec, s[26:27]
	v_add_u32_e32 v152, s15, v3
	v_lshl_add_u64 v[6:7], s[24:25], 0, v[176:177]
	v_readfirstlane_b32 s9, v152
	v_add_u32_e32 v153, 0x2000, v152
	v_lshl_add_u64 v[8:9], v[6:7], 0, s[46:47]
	s_mov_b32 m0, s9
	v_readfirstlane_b32 s9, v153
	v_add_u32_e32 v154, 0x8000, v137
	s_waitcnt vmcnt(0)
	s_barrier
	global_load_lds_dwordx4 v[8:9], off
	v_lshl_add_u64 v[8:9], v[6:7], 0, s[48:49]
	s_mov_b32 m0, s9
	v_lshl_add_u64 v[128:129], s[22:23], 0, v[176:177]
	v_readfirstlane_b32 s9, v154
	v_add_u32_e32 v155, 0xa000, v137
	global_load_lds_dwordx4 v[8:9], off
	v_lshl_add_u64 v[8:9], v[128:129], 0, s[46:47]
	s_mov_b32 m0, s9
	v_readfirstlane_b32 s9, v155
	v_add_u32_e32 v156, s36, v3
	global_load_lds_dwordx4 v[8:9], off
	v_lshl_add_u64 v[8:9], v[128:129], 0, s[48:49]
	s_mov_b32 m0, s9
	s_mov_b64 s[22:23], 0x40080
	v_readfirstlane_b32 s9, v156
	v_add_u32_e32 v157, 0x2000, v156
	global_load_lds_dwordx4 v[8:9], off
	v_lshl_add_u64 v[8:9], v[6:7], 0, s[22:23]
	s_mov_b32 m0, s9
	v_readfirstlane_b32 s9, v157
	global_load_lds_dwordx4 v[8:9], off
	v_lshl_add_u64 v[6:7], v[6:7], 0, s[52:53]
	s_mov_b32 m0, s9
	v_and_b32_e32 v139, 15, v142
	global_load_lds_dwordx4 v[6:7], off
	v_bfe_u32 v134, v142, 4, 2
	v_lshlrev_b32_e32 v143, 2, v142
	v_lshlrev_b32_e32 v14, 8, v142
	v_ashrrev_i32_e32 v141, 6, v142
	v_lshlrev_b32_e32 v5, 4, v134
	v_lshlrev_b32_e32 v6, 6, v139
	v_and_b32_e32 v7, 32, v143
	v_lshlrev_b32_e32 v12, 6, v142
	v_and_b32_e32 v14, 0xffff8000, v14
	v_lshlrev_b32_e32 v0, 11, v0
	s_add_u32 s18, s10, s18
	v_and_b32_e32 v140, 3, v141
	s_waitcnt vmcnt(6)
	v_bitop3_b32 v6, v5, v7, v6 bitop3:0x36
	v_lshlrev_b32_e32 v144, 6, v4
	v_lshlrev_b32_e32 v4, 13, v4
	v_and_or_b32 v5, v12, s33, v5
	v_or3_b32 v0, v1, v14, v0
	s_addc_u32 s19, s11, s19
	v_lshlrev_b32_e32 v3, 12, v140
	v_add_u32_e32 v8, s35, v6
	v_add_u32_e32 v9, s14, v6
	v_add_u32_e32 v10, s15, v6
	v_add_u32_e32 v11, s36, v6
	v_add_u32_e32 v6, 16, v6
	v_xad_u32 v5, v5, v7, 16
	v_or_b32_e32 v7, 0x800, v4
	v_or_b32_e32 v12, 0x1000, v4
	v_or_b32_e32 v13, 0x1800, v4
	v_add_u32_e32 v130, v0, v2
	s_add_u32 s20, s10, s20
	v_mov_b32_e32 v0, 0
	v_mov_b32_e32 v131, v177
	s_addc_u32 s21, s11, s21
	s_mov_b32 s9, -2
	v_add_u32_e32 v161, v8, v3
	v_add_u32_e32 v149, v6, v4
	v_add_u32_e32 v148, v5, v7
	v_add_u32_e32 v147, v5, v12
	v_add_u32_e32 v146, v5, v13
	v_add_u32_e32 v160, 0xc000, v137
	v_add_u32_e32 v159, 0xe000, v137
	v_add_u32_e32 v158, v9, v3
	v_add_u32_e32 v145, 0x2000, v138
	v_add_u32_e32 v151, v10, v3
	v_add_u32_e32 v150, v11, v3
	v_mov_b32_e32 v1, v0
	v_mov_b32_e32 v2, v0
	v_mov_b32_e32 v3, v0
	v_mov_b32_e32 v4, v0
	v_mov_b32_e32 v5, v0
	v_mov_b32_e32 v6, v0
	v_mov_b32_e32 v7, v0
	v_mov_b32_e32 v8, v0
	v_mov_b32_e32 v9, v0
	v_mov_b32_e32 v10, v0
	v_mov_b32_e32 v11, v0
	v_mov_b32_e32 v12, v0
	v_mov_b32_e32 v13, v0
	v_mov_b32_e32 v14, v0
	v_mov_b32_e32 v15, v0
	v_mov_b32_e32 v16, v0
	v_mov_b32_e32 v17, v0
	v_mov_b32_e32 v18, v0
	v_mov_b32_e32 v19, v0
	v_mov_b32_e32 v20, v0
	v_mov_b32_e32 v21, v0
	v_mov_b32_e32 v22, v0
	v_mov_b32_e32 v23, v0
	v_mov_b32_e32 v24, v0
	v_mov_b32_e32 v25, v0
	v_mov_b32_e32 v26, v0
	v_mov_b32_e32 v27, v0
	v_mov_b32_e32 v28, v0
	v_mov_b32_e32 v29, v0
	v_mov_b32_e32 v30, v0
	v_mov_b32_e32 v31, v0
	v_mov_b32_e32 v32, v0
	v_mov_b32_e32 v33, v0
	v_mov_b32_e32 v34, v0
	v_mov_b32_e32 v35, v0
	v_mov_b32_e32 v36, v0
	v_mov_b32_e32 v37, v0
	v_mov_b32_e32 v38, v0
	v_mov_b32_e32 v39, v0
	v_mov_b32_e32 v40, v0
	v_mov_b32_e32 v41, v0
	v_mov_b32_e32 v42, v0
	v_mov_b32_e32 v43, v0
	v_mov_b32_e32 v44, v0
	v_mov_b32_e32 v45, v0
	v_mov_b32_e32 v46, v0
	v_mov_b32_e32 v47, v0
	v_mov_b32_e32 v48, v0
	v_mov_b32_e32 v49, v0
	v_mov_b32_e32 v50, v0
	v_mov_b32_e32 v51, v0
	v_mov_b32_e32 v52, v0
	v_mov_b32_e32 v53, v0
	v_mov_b32_e32 v54, v0
	v_mov_b32_e32 v55, v0
	v_mov_b32_e32 v56, v0
	v_mov_b32_e32 v57, v0
	v_mov_b32_e32 v58, v0
	v_mov_b32_e32 v59, v0
	v_mov_b32_e32 v60, v0
	v_mov_b32_e32 v61, v0
	v_mov_b32_e32 v62, v0
	v_mov_b32_e32 v63, v0
	v_mov_b32_e32 v64, v0
	v_mov_b32_e32 v65, v0
	v_mov_b32_e32 v66, v0
	v_mov_b32_e32 v67, v0
	v_mov_b32_e32 v68, v0
	v_mov_b32_e32 v69, v0
	v_mov_b32_e32 v70, v0
	v_mov_b32_e32 v71, v0
	v_mov_b32_e32 v72, v0
	v_mov_b32_e32 v73, v0
	v_mov_b32_e32 v74, v0
	v_mov_b32_e32 v75, v0
	v_mov_b32_e32 v76, v0
	v_mov_b32_e32 v77, v0
	v_mov_b32_e32 v78, v0
	v_mov_b32_e32 v79, v0
	v_mov_b32_e32 v80, v0
	v_mov_b32_e32 v81, v0
	v_mov_b32_e32 v82, v0
	v_mov_b32_e32 v83, v0
	v_mov_b32_e32 v84, v0
	v_mov_b32_e32 v85, v0
	v_mov_b32_e32 v86, v0
	v_mov_b32_e32 v87, v0
	v_mov_b32_e32 v88, v0
	v_mov_b32_e32 v89, v0
	v_mov_b32_e32 v90, v0
	v_mov_b32_e32 v91, v0
	v_mov_b32_e32 v92, v0
	v_mov_b32_e32 v93, v0
	v_mov_b32_e32 v94, v0
	v_mov_b32_e32 v95, v0
	v_mov_b32_e32 v96, v0
	v_mov_b32_e32 v97, v0
	v_mov_b32_e32 v98, v0
	v_mov_b32_e32 v99, v0
	v_mov_b32_e32 v100, v0
	v_mov_b32_e32 v101, v0
	v_mov_b32_e32 v102, v0
	v_mov_b32_e32 v103, v0
	v_mov_b32_e32 v104, v0
	v_mov_b32_e32 v105, v0
	v_mov_b32_e32 v106, v0
	v_mov_b32_e32 v107, v0
	v_mov_b32_e32 v108, v0
	v_mov_b32_e32 v109, v0
	v_mov_b32_e32 v110, v0
	v_mov_b32_e32 v111, v0
	v_mov_b32_e32 v112, v0
	v_mov_b32_e32 v113, v0
	v_mov_b32_e32 v114, v0
	v_mov_b32_e32 v115, v0
	v_mov_b32_e32 v116, v0
	v_mov_b32_e32 v117, v0
	v_mov_b32_e32 v118, v0
	v_mov_b32_e32 v119, v0
	v_mov_b32_e32 v120, v0
	v_mov_b32_e32 v121, v0
	v_mov_b32_e32 v122, v0
	v_mov_b32_e32 v123, v0
	v_mov_b32_e32 v124, v0
	v_mov_b32_e32 v125, v0
	v_mov_b32_e32 v126, v0
	v_mov_b32_e32 v127, v0
.Lkh_995:
	s_barrier
.LBB0_995:
	ds_read_b128 v[162:165], v161
	ds_read_b128 v[166:169], v161 offset:1024
	ds_read_b128 v[170:173], v161 offset:2048
	ds_read_b128 v[178:181], v161 offset:3072
	v_lshl_add_u64 v[240:241], s[20:21], 0, v[130:131]
	s_mov_b64 s[22:23], 0x37670180
	v_lshl_add_u64 v[174:175], v[240:241], 0, s[22:23]
	v_readfirstlane_b32 s22, v160
	s_mov_b32 m0, s22
	s_mov_b64 s[22:23], 0x37690180
	ds_read_b128 v[192:195], v149
	ds_read_b128 v[196:199], v149 offset:1024
	ds_read_b128 v[200:203], v148
	ds_read_b128 v[204:207], v148 offset:1024
	ds_read_b128 v[208:211], v147
	ds_read_b128 v[212:215], v147 offset:1024
	ds_read_b128 v[216:219], v146
	ds_read_b128 v[220:223], v146 offset:1024
	global_load_lds_dwordx4 v[174:175], off
	v_lshl_add_u64 v[174:175], v[240:241], 0, s[22:23]
	v_readfirstlane_b32 s22, v159
	s_mov_b32 m0, s22
	s_nop 0
	global_load_lds_dwordx4 v[174:175], off
	s_waitcnt lgkmcnt(8)
	s_barrier
	s_waitcnt lgkmcnt(0)
	s_setprio 1
	s_waitcnt lgkmcnt(0)
	v_mfma_f32_16x16x32_bf16 v[124:127], v[192:195], v[162:165], v[124:127]
	v_mfma_f32_16x16x32_bf16 v[120:123], v[192:195], v[170:173], v[120:123]
	v_mfma_f32_16x16x32_bf16 v[116:119], v[200:203], v[162:165], v[116:119]
	v_mfma_f32_16x16x32_bf16 v[112:115], v[200:203], v[170:173], v[112:115]
	v_mfma_f32_16x16x32_bf16 v[108:111], v[208:211], v[162:165], v[108:111]
	v_mfma_f32_16x16x32_bf16 v[104:107], v[208:211], v[170:173], v[104:107]
	v_mfma_f32_16x16x32_bf16 v[100:103], v[216:219], v[162:165], v[100:103]
	v_mfma_f32_16x16x32_bf16 v[96:99], v[216:219], v[170:173], v[96:99]
	v_mfma_f32_16x16x32_bf16 v[124:127], v[196:199], v[166:169], v[124:127]
	v_mfma_f32_16x16x32_bf16 v[120:123], v[196:199], v[178:181], v[120:123]
	v_mfma_f32_16x16x32_bf16 v[116:119], v[204:207], v[166:169], v[116:119]
	v_mfma_f32_16x16x32_bf16 v[112:115], v[204:207], v[178:181], v[112:115]
	v_mfma_f32_16x16x32_bf16 v[108:111], v[212:215], v[166:169], v[108:111]
	v_mfma_f32_16x16x32_bf16 v[104:107], v[212:215], v[178:181], v[104:107]
	v_mfma_f32_16x16x32_bf16 v[100:103], v[220:223], v[166:169], v[100:103]
	v_mfma_f32_16x16x32_bf16 v[96:99], v[220:223], v[178:181], v[96:99]
	s_setprio 0
	s_barrier
	v_lshl_add_u64 v[242:243], s[18:19], 0, v[130:131]
	s_mov_b64 s[22:23], 0x1000100
	v_lshl_add_u64 v[174:175], v[242:243], 0, s[22:23]
	v_readfirstlane_b32 s22, v138
	s_mov_b32 m0, s22
	s_mov_b64 s[22:23], 0x1020100
	ds_read_b128 v[224:227], v158
	ds_read_b128 v[228:231], v158 offset:1024
	ds_read_b128 v[232:235], v158 offset:2048
	ds_read_b128 v[236:239], v158 offset:3072
	global_load_lds_dwordx4 v[174:175], off
	v_lshl_add_u64 v[174:175], v[242:243], 0, s[22:23]
	v_readfirstlane_b32 s22, v145
	s_mov_b32 m0, s22
	s_nop 0
	global_load_lds_dwordx4 v[174:175], off
	s_barrier
	s_waitcnt lgkmcnt(0)
	s_setprio 1
	s_waitcnt lgkmcnt(0)
	v_mfma_f32_16x16x32_bf16 v[92:95], v[192:195], v[224:227], v[92:95]
	v_mfma_f32_16x16x32_bf16 v[88:91], v[192:195], v[232:235], v[88:91]
	v_mfma_f32_16x16x32_bf16 v[84:87], v[200:203], v[224:227], v[84:87]
	v_mfma_f32_16x16x32_bf16 v[80:83], v[200:203], v[232:235], v[80:83]
	v_mfma_f32_16x16x32_bf16 v[76:79], v[208:211], v[224:227], v[76:79]
	v_mfma_f32_16x16x32_bf16 v[72:75], v[208:211], v[232:235], v[72:75]
	v_mfma_f32_16x16x32_bf16 v[68:71], v[216:219], v[224:227], v[68:71]
	v_mfma_f32_16x16x32_bf16 v[64:67], v[216:219], v[232:235], v[64:67]
	v_mfma_f32_16x16x32_bf16 v[92:95], v[196:199], v[228:231], v[92:95]
	v_mfma_f32_16x16x32_bf16 v[88:91], v[196:199], v[236:239], v[88:91]
	v_mfma_f32_16x16x32_bf16 v[84:87], v[204:207], v[228:231], v[84:87]
	v_mfma_f32_16x16x32_bf16 v[80:83], v[204:207], v[236:239], v[80:83]
	v_mfma_f32_16x16x32_bf16 v[76:79], v[212:215], v[228:231], v[76:79]
	v_mfma_f32_16x16x32_bf16 v[72:75], v[212:215], v[236:239], v[72:75]
	v_mfma_f32_16x16x32_bf16 v[68:71], v[220:223], v[228:231], v[68:71]
	v_mfma_f32_16x16x32_bf16 v[64:67], v[220:223], v[236:239], v[64:67]
	s_setprio 0
	s_mov_b64 s[22:23], 0x37630200
	v_lshl_add_u64 v[174:175], v[240:241], 0, s[22:23]
	v_readfirstlane_b32 s22, v137
	s_mov_b32 m0, s22
	s_mov_b64 s[22:23], 0x37650200
	s_barrier
	ds_read_b128 v[192:195], v149 offset:16384
	ds_read_b128 v[196:199], v149 offset:17408
	ds_read_b128 v[200:203], v148 offset:16384
	ds_read_b128 v[204:207], v148 offset:17408
	ds_read_b128 v[208:211], v147 offset:16384
	ds_read_b128 v[212:215], v147 offset:17408
	ds_read_b128 v[216:219], v146 offset:16384
	ds_read_b128 v[220:223], v146 offset:17408
	global_load_lds_dwordx4 v[174:175], off
	v_lshl_add_u64 v[174:175], v[240:241], 0, s[22:23]
	v_readfirstlane_b32 s22, v136
	s_mov_b32 m0, s22
	s_nop 0
	global_load_lds_dwordx4 v[174:175], off
	s_barrier
	s_waitcnt lgkmcnt(0)
	s_setprio 1
	s_waitcnt lgkmcnt(0)
	v_mfma_f32_16x16x32_bf16 v[60:63], v[192:195], v[162:165], v[60:63]
	v_mfma_f32_16x16x32_bf16 v[56:59], v[192:195], v[170:173], v[56:59]
	v_mfma_f32_16x16x32_bf16 v[52:55], v[200:203], v[162:165], v[52:55]
	v_mfma_f32_16x16x32_bf16 v[48:51], v[200:203], v[170:173], v[48:51]
	v_mfma_f32_16x16x32_bf16 v[44:47], v[208:211], v[162:165], v[44:47]
	v_mfma_f32_16x16x32_bf16 v[40:43], v[208:211], v[170:173], v[40:43]
	v_mfma_f32_16x16x32_bf16 v[36:39], v[216:219], v[162:165], v[36:39]
	v_mfma_f32_16x16x32_bf16 v[32:35], v[216:219], v[170:173], v[32:35]
	v_mfma_f32_16x16x32_bf16 v[60:63], v[196:199], v[166:169], v[60:63]
	v_mfma_f32_16x16x32_bf16 v[56:59], v[196:199], v[178:181], v[56:59]
	v_mfma_f32_16x16x32_bf16 v[52:55], v[204:207], v[166:169], v[52:55]
	v_mfma_f32_16x16x32_bf16 v[48:51], v[204:207], v[178:181], v[48:51]
	v_mfma_f32_16x16x32_bf16 v[44:47], v[212:215], v[166:169], v[44:47]
	v_mfma_f32_16x16x32_bf16 v[40:43], v[212:215], v[178:181], v[40:43]
	v_mfma_f32_16x16x32_bf16 v[36:39], v[220:223], v[166:169], v[36:39]
	v_mfma_f32_16x16x32_bf16 v[32:35], v[220:223], v[178:181], v[32:35]
	s_setprio 0
	s_barrier
	s_mov_b64 s[22:23], 0x1040100
	v_lshl_add_u64 v[162:163], v[242:243], 0, s[22:23]
	v_readfirstlane_b32 s22, v135
	s_mov_b32 m0, s22
	s_mov_b64 s[22:23], 0x1060100
	global_load_lds_dwordx4 v[162:163], off
	v_add_u32_e32 v162, 0x2000, v135
	v_lshl_add_u64 v[164:165], v[242:243], 0, s[22:23]
	v_readfirstlane_b32 s22, v162
	s_mov_b32 m0, s22
	s_nop 0
	global_load_lds_dwordx4 v[164:165], off
	s_waitcnt vmcnt(6)
	s_barrier
	s_setprio 1
	v_mfma_f32_16x16x32_bf16 v[28:31], v[192:195], v[224:227], v[28:31]
	v_mfma_f32_16x16x32_bf16 v[24:27], v[192:195], v[232:235], v[24:27]
	v_mfma_f32_16x16x32_bf16 v[20:23], v[200:203], v[224:227], v[20:23]
	v_mfma_f32_16x16x32_bf16 v[16:19], v[200:203], v[232:235], v[16:19]
	v_mfma_f32_16x16x32_bf16 v[12:15], v[208:211], v[224:227], v[12:15]
	v_mfma_f32_16x16x32_bf16 v[8:11], v[208:211], v[232:235], v[8:11]
	v_mfma_f32_16x16x32_bf16 v[4:7], v[216:219], v[224:227], v[4:7]
	v_mfma_f32_16x16x32_bf16 v[0:3], v[216:219], v[232:235], v[0:3]
	v_mfma_f32_16x16x32_bf16 v[28:31], v[196:199], v[228:231], v[28:31]
	v_mfma_f32_16x16x32_bf16 v[24:27], v[196:199], v[236:239], v[24:27]
	v_mfma_f32_16x16x32_bf16 v[20:23], v[204:207], v[228:231], v[20:23]
	v_mfma_f32_16x16x32_bf16 v[16:19], v[204:207], v[236:239], v[16:19]
	v_mfma_f32_16x16x32_bf16 v[12:15], v[212:215], v[228:231], v[12:15]
	v_mfma_f32_16x16x32_bf16 v[8:11], v[212:215], v[236:239], v[8:11]
	v_mfma_f32_16x16x32_bf16 v[4:7], v[220:223], v[228:231], v[4:7]
	v_mfma_f32_16x16x32_bf16 v[0:3], v[220:223], v[236:239], v[0:3]
	s_setprio 0
	s_barrier
	ds_read_b128 v[164:167], v151
	ds_read_b128 v[168:171], v151 offset:1024
	ds_read_b128 v[172:175], v151 offset:2048
	ds_read_b128 v[178:181], v151 offset:3072
	s_mov_b64 s[22:23], 0x37670200
	v_lshl_add_u64 v[224:225], v[240:241], 0, s[22:23]
	v_readfirstlane_b32 s22, v133
	s_mov_b32 m0, s22
	s_mov_b64 s[22:23], 0x37690200
	ds_read_b128 v[192:195], v149 offset:32768
	ds_read_b128 v[196:199], v149 offset:33792
	ds_read_b128 v[200:203], v148 offset:32768
	ds_read_b128 v[204:207], v148 offset:33792
	ds_read_b128 v[208:211], v147 offset:32768
	ds_read_b128 v[212:215], v147 offset:33792
	ds_read_b128 v[216:219], v146 offset:32768
	ds_read_b128 v[220:223], v146 offset:33792
	global_load_lds_dwordx4 v[224:225], off
	v_lshl_add_u64 v[224:225], v[240:241], 0, s[22:23]
	v_readfirstlane_b32 s22, v132
	s_mov_b32 m0, s22
	s_nop 0
	global_load_lds_dwordx4 v[224:225], off
	s_waitcnt lgkmcnt(8)
	s_barrier
	s_waitcnt lgkmcnt(0)
	s_setprio 1
	s_waitcnt lgkmcnt(0)
	v_mfma_f32_16x16x32_bf16 v[124:127], v[192:195], v[164:167], v[124:127]
	v_mfma_f32_16x16x32_bf16 v[120:123], v[192:195], v[172:175], v[120:123]
	v_mfma_f32_16x16x32_bf16 v[116:119], v[200:203], v[164:167], v[116:119]
	v_mfma_f32_16x16x32_bf16 v[112:115], v[200:203], v[172:175], v[112:115]
	v_mfma_f32_16x16x32_bf16 v[108:111], v[208:211], v[164:167], v[108:111]
	v_mfma_f32_16x16x32_bf16 v[104:107], v[208:211], v[172:175], v[104:107]
	v_mfma_f32_16x16x32_bf16 v[100:103], v[216:219], v[164:167], v[100:103]
	v_mfma_f32_16x16x32_bf16 v[96:99], v[216:219], v[172:175], v[96:99]
	v_mfma_f32_16x16x32_bf16 v[124:127], v[196:199], v[168:171], v[124:127]
	v_mfma_f32_16x16x32_bf16 v[120:123], v[196:199], v[178:181], v[120:123]
	v_mfma_f32_16x16x32_bf16 v[116:119], v[204:207], v[168:171], v[116:119]
	v_mfma_f32_16x16x32_bf16 v[112:115], v[204:207], v[178:181], v[112:115]
	v_mfma_f32_16x16x32_bf16 v[108:111], v[212:215], v[168:171], v[108:111]
	v_mfma_f32_16x16x32_bf16 v[104:107], v[212:215], v[178:181], v[104:107]
	v_mfma_f32_16x16x32_bf16 v[100:103], v[220:223], v[168:171], v[100:103]
	v_mfma_f32_16x16x32_bf16 v[96:99], v[220:223], v[178:181], v[96:99]
	s_setprio 0
	s_barrier
	s_mov_b64 s[22:23], 0x1000180
	v_lshl_add_u64 v[244:245], v[242:243], 0, s[22:23]
	v_readfirstlane_b32 s22, v152
	s_mov_b32 m0, s22
	s_mov_b64 s[22:23], 0x1020180
	ds_read_b128 v[224:227], v150
	ds_read_b128 v[228:231], v150 offset:1024
	ds_read_b128 v[232:235], v150 offset:2048
	ds_read_b128 v[236:239], v150 offset:3072
	global_load_lds_dwordx4 v[244:245], off
	v_lshl_add_u64 v[244:245], v[242:243], 0, s[22:23]
	v_readfirstlane_b32 s22, v153
	s_mov_b32 m0, s22
	s_nop 0
	global_load_lds_dwordx4 v[244:245], off
	s_barrier
	s_waitcnt lgkmcnt(0)
	s_setprio 1
	s_waitcnt lgkmcnt(0)
	v_mfma_f32_16x16x32_bf16 v[92:95], v[192:195], v[224:227], v[92:95]
	v_mfma_f32_16x16x32_bf16 v[88:91], v[192:195], v[232:235], v[88:91]
	v_mfma_f32_16x16x32_bf16 v[84:87], v[200:203], v[224:227], v[84:87]
	v_mfma_f32_16x16x32_bf16 v[80:83], v[200:203], v[232:235], v[80:83]
	v_mfma_f32_16x16x32_bf16 v[76:79], v[208:211], v[224:227], v[76:79]
	v_mfma_f32_16x16x32_bf16 v[72:75], v[208:211], v[232:235], v[72:75]
	v_mfma_f32_16x16x32_bf16 v[68:71], v[216:219], v[224:227], v[68:71]
	v_mfma_f32_16x16x32_bf16 v[64:67], v[216:219], v[232:235], v[64:67]
	v_mfma_f32_16x16x32_bf16 v[92:95], v[196:199], v[228:231], v[92:95]
	v_mfma_f32_16x16x32_bf16 v[88:91], v[196:199], v[236:239], v[88:91]
	v_mfma_f32_16x16x32_bf16 v[84:87], v[204:207], v[228:231], v[84:87]
	v_mfma_f32_16x16x32_bf16 v[80:83], v[204:207], v[236:239], v[80:83]
	v_mfma_f32_16x16x32_bf16 v[76:79], v[212:215], v[228:231], v[76:79]
	v_mfma_f32_16x16x32_bf16 v[72:75], v[212:215], v[236:239], v[72:75]
	v_mfma_f32_16x16x32_bf16 v[68:71], v[220:223], v[228:231], v[68:71]
	v_mfma_f32_16x16x32_bf16 v[64:67], v[220:223], v[236:239], v[64:67]
	s_setprio 0
	s_mov_b64 s[22:23], 0x37630280
	v_lshl_add_u64 v[244:245], v[240:241], 0, s[22:23]
	v_readfirstlane_b32 s22, v154
	s_mov_b32 m0, s22
	s_mov_b64 s[22:23], 0x37650280
	v_lshl_add_u64 v[240:241], v[240:241], 0, s[22:23]
	v_readfirstlane_b32 s22, v155
	s_barrier
	ds_read_b128 v[192:195], v149 offset:49152
	ds_read_b128 v[196:199], v149 offset:50176
	ds_read_b128 v[200:203], v148 offset:49152
	ds_read_b128 v[204:207], v148 offset:50176
	ds_read_b128 v[208:211], v147 offset:49152
	ds_read_b128 v[212:215], v147 offset:50176
	ds_read_b128 v[216:219], v146 offset:49152
	ds_read_b128 v[220:223], v146 offset:50176
	global_load_lds_dwordx4 v[244:245], off
	s_mov_b32 m0, s22
	s_nop 0
	global_load_lds_dwordx4 v[240:241], off
	s_barrier
	s_waitcnt lgkmcnt(0)
	s_setprio 1
	s_waitcnt lgkmcnt(0)
	v_mfma_f32_16x16x32_bf16 v[60:63], v[192:195], v[164:167], v[60:63]
	v_mfma_f32_16x16x32_bf16 v[56:59], v[192:195], v[172:175], v[56:59]
	v_mfma_f32_16x16x32_bf16 v[52:55], v[200:203], v[164:167], v[52:55]
	v_mfma_f32_16x16x32_bf16 v[48:51], v[200:203], v[172:175], v[48:51]
	v_mfma_f32_16x16x32_bf16 v[44:47], v[208:211], v[164:167], v[44:47]
	v_mfma_f32_16x16x32_bf16 v[40:43], v[208:211], v[172:175], v[40:43]
	v_mfma_f32_16x16x32_bf16 v[36:39], v[216:219], v[164:167], v[36:39]
	v_mfma_f32_16x16x32_bf16 v[32:35], v[216:219], v[172:175], v[32:35]
	v_mfma_f32_16x16x32_bf16 v[60:63], v[196:199], v[168:171], v[60:63]
	v_mfma_f32_16x16x32_bf16 v[56:59], v[196:199], v[178:181], v[56:59]
	v_mfma_f32_16x16x32_bf16 v[52:55], v[204:207], v[168:171], v[52:55]
	v_mfma_f32_16x16x32_bf16 v[48:51], v[204:207], v[178:181], v[48:51]
	v_mfma_f32_16x16x32_bf16 v[44:47], v[212:215], v[168:171], v[44:47]
	v_mfma_f32_16x16x32_bf16 v[40:43], v[212:215], v[178:181], v[40:43]
	v_mfma_f32_16x16x32_bf16 v[36:39], v[220:223], v[168:171], v[36:39]
	v_mfma_f32_16x16x32_bf16 v[32:35], v[220:223], v[178:181], v[32:35]
	s_setprio 0
	s_barrier
	s_mov_b64 s[22:23], 0x1040180
	v_lshl_add_u64 v[164:165], v[242:243], 0, s[22:23]
	v_readfirstlane_b32 s22, v156
	s_mov_b32 m0, s22
	s_mov_b64 s[22:23], 0x1060180
	global_load_lds_dwordx4 v[164:165], off
	v_lshl_add_u64 v[164:165], v[242:243], 0, s[22:23]
	v_readfirstlane_b32 s22, v157
	s_mov_b32 m0, s22
	s_nop 0
	global_load_lds_dwordx4 v[164:165], off
	s_waitcnt vmcnt(6)
	s_barrier
	s_setprio 1
	v_mfma_f32_16x16x32_bf16 v[28:31], v[192:195], v[224:227], v[28:31]
	v_mfma_f32_16x16x32_bf16 v[24:27], v[192:195], v[232:235], v[24:27]
	v_mfma_f32_16x16x32_bf16 v[20:23], v[200:203], v[224:227], v[20:23]
	v_mfma_f32_16x16x32_bf16 v[16:19], v[200:203], v[232:235], v[16:19]
	v_mfma_f32_16x16x32_bf16 v[12:15], v[208:211], v[224:227], v[12:15]
	v_mfma_f32_16x16x32_bf16 v[8:11], v[208:211], v[232:235], v[8:11]
	v_mfma_f32_16x16x32_bf16 v[4:7], v[216:219], v[224:227], v[4:7]
	v_mfma_f32_16x16x32_bf16 v[0:3], v[216:219], v[232:235], v[0:3]
	v_mfma_f32_16x16x32_bf16 v[28:31], v[196:199], v[228:231], v[28:31]
	v_mfma_f32_16x16x32_bf16 v[24:27], v[196:199], v[236:239], v[24:27]
	v_mfma_f32_16x16x32_bf16 v[20:23], v[204:207], v[228:231], v[20:23]
	v_mfma_f32_16x16x32_bf16 v[16:19], v[204:207], v[236:239], v[16:19]
	v_mfma_f32_16x16x32_bf16 v[12:15], v[212:215], v[228:231], v[12:15]
	v_mfma_f32_16x16x32_bf16 v[8:11], v[212:215], v[236:239], v[8:11]
	v_mfma_f32_16x16x32_bf16 v[4:7], v[220:223], v[228:231], v[4:7]
	v_mfma_f32_16x16x32_bf16 v[0:3], v[220:223], v[236:239], v[0:3]
	s_setprio 0
	s_add_i32 s9, s9, 2
	s_add_u32 s18, s18, 0x100
	s_addc_u32 s19, s19, 0
	s_add_u32 s20, s20, 0x100
	s_addc_u32 s21, s21, 0
	s_cmp_lt_u32 s9, 12
	s_cbranch_scc1 .Lkh_995
	s_barrier
	v_readfirstlane_b32 s9, v160
	v_lshl_add_u64 v[130:131], v[128:129], 0, s[54:55]
	s_mov_b32 m0, s9
	v_readfirstlane_b32 s9, v159
	ds_read_b128 v[152:155], v161
	ds_read_b128 v[164:167], v161 offset:1024
	ds_read_b128 v[168:171], v161 offset:2048
	ds_read_b128 v[172:175], v161 offset:3072
	ds_read_b128 v[178:181], v149
	ds_read_b128 v[192:195], v149 offset:1024
	ds_read_b128 v[196:199], v148
	ds_read_b128 v[200:203], v148 offset:1024
	ds_read_b128 v[204:207], v147
	ds_read_b128 v[208:211], v147 offset:1024
	ds_read_b128 v[212:215], v146
	ds_read_b128 v[216:219], v146 offset:1024
	global_load_lds_dwordx4 v[130:131], off
	v_lshl_add_u64 v[128:129], v[128:129], 0, s[56:57]
	s_mov_b32 m0, s9
	s_nop 0
	global_load_lds_dwordx4 v[128:129], off
	s_barrier
	s_waitcnt lgkmcnt(0)
	s_setprio 1
	s_waitcnt lgkmcnt(0)
	v_mfma_f32_16x16x32_bf16 v[124:127], v[178:181], v[152:155], v[124:127]
	v_mfma_f32_16x16x32_bf16 v[120:123], v[178:181], v[168:171], v[120:123]
	v_mfma_f32_16x16x32_bf16 v[116:119], v[196:199], v[152:155], v[116:119]
	v_mfma_f32_16x16x32_bf16 v[112:115], v[196:199], v[168:171], v[112:115]
	v_mfma_f32_16x16x32_bf16 v[124:127], v[192:195], v[164:167], v[124:127]
	v_mfma_f32_16x16x32_bf16 v[120:123], v[192:195], v[172:175], v[120:123]
	v_mfma_f32_16x16x32_bf16 v[116:119], v[200:203], v[164:167], v[116:119]
	v_mfma_f32_16x16x32_bf16 v[112:115], v[200:203], v[172:175], v[112:115]
	v_mfma_f32_16x16x32_bf16 v[108:111], v[204:207], v[152:155], v[108:111]
	v_mfma_f32_16x16x32_bf16 v[104:107], v[204:207], v[168:171], v[104:107]
	v_mfma_f32_16x16x32_bf16 v[100:103], v[212:215], v[152:155], v[100:103]
	v_mfma_f32_16x16x32_bf16 v[96:99], v[212:215], v[168:171], v[96:99]
	v_mfma_f32_16x16x32_bf16 v[128:131], v[208:211], v[164:167], v[108:111]
	v_mfma_f32_16x16x32_bf16 v[220:223], v[208:211], v[172:175], v[104:107]
	v_mfma_f32_16x16x32_bf16 v[224:227], v[216:219], v[164:167], v[100:103]
	v_mfma_f32_16x16x32_bf16 v[228:231], v[216:219], v[172:175], v[96:99]
	s_setprio 0
	s_barrier
	s_nop 1
	ds_read_b128 v[96:99], v158
	ds_read_b128 v[100:103], v158 offset:1024
	ds_read_b128 v[104:107], v158 offset:2048
	ds_read_b128 v[108:111], v158 offset:3072
	s_barrier
	s_waitcnt lgkmcnt(0)
	s_setprio 1
	s_waitcnt lgkmcnt(0)
	v_mfma_f32_16x16x32_bf16 v[92:95], v[178:181], v[96:99], v[92:95]
	v_mfma_f32_16x16x32_bf16 v[88:91], v[178:181], v[104:107], v[88:91]
	v_mfma_f32_16x16x32_bf16 v[84:87], v[196:199], v[96:99], v[84:87]
	v_mfma_f32_16x16x32_bf16 v[80:83], v[196:199], v[104:107], v[80:83]
	v_mfma_f32_16x16x32_bf16 v[92:95], v[192:195], v[100:103], v[92:95]
	v_mfma_f32_16x16x32_bf16 v[88:91], v[192:195], v[108:111], v[88:91]
	v_mfma_f32_16x16x32_bf16 v[84:87], v[200:203], v[100:103], v[84:87]
	v_mfma_f32_16x16x32_bf16 v[80:83], v[200:203], v[108:111], v[80:83]
	v_mfma_f32_16x16x32_bf16 v[76:79], v[204:207], v[96:99], v[76:79]
	v_mfma_f32_16x16x32_bf16 v[72:75], v[204:207], v[104:107], v[72:75]
	v_mfma_f32_16x16x32_bf16 v[68:71], v[212:215], v[96:99], v[68:71]
	v_mfma_f32_16x16x32_bf16 v[64:67], v[212:215], v[104:107], v[64:67]
	v_mfma_f32_16x16x32_bf16 v[156:159], v[208:211], v[100:103], v[76:79]
	v_mfma_f32_16x16x32_bf16 v[178:181], v[208:211], v[108:111], v[72:75]
	v_mfma_f32_16x16x32_bf16 v[192:195], v[216:219], v[100:103], v[68:71]
	v_mfma_f32_16x16x32_bf16 v[196:199], v[216:219], v[108:111], v[64:67]
	s_setprio 0
	s_barrier
	s_nop 1
	ds_read_b128 v[64:67], v149 offset:16384
	ds_read_b128 v[68:71], v149 offset:17408
	ds_read_b128 v[72:75], v148 offset:16384
	ds_read_b128 v[76:79], v148 offset:17408
	ds_read_b128 v[200:203], v147 offset:16384
	ds_read_b128 v[204:207], v147 offset:17408
	ds_read_b128 v[208:211], v146 offset:16384
	ds_read_b128 v[212:215], v146 offset:17408
	s_waitcnt vmcnt(4)
	s_barrier
	s_waitcnt lgkmcnt(0)
	s_setprio 1
	s_waitcnt lgkmcnt(0)
	v_mfma_f32_16x16x32_bf16 v[60:63], v[64:67], v[152:155], v[60:63]
	v_mfma_f32_16x16x32_bf16 v[56:59], v[64:67], v[168:171], v[56:59]
	v_mfma_f32_16x16x32_bf16 v[52:55], v[72:75], v[152:155], v[52:55]
	v_mfma_f32_16x16x32_bf16 v[48:51], v[72:75], v[168:171], v[48:51]
	v_mfma_f32_16x16x32_bf16 v[60:63], v[68:71], v[164:167], v[60:63]
	v_mfma_f32_16x16x32_bf16 v[56:59], v[68:71], v[172:175], v[56:59]
	v_mfma_f32_16x16x32_bf16 v[52:55], v[76:79], v[164:167], v[52:55]
	v_mfma_f32_16x16x32_bf16 v[48:51], v[76:79], v[172:175], v[48:51]
	v_mfma_f32_16x16x32_bf16 v[44:47], v[200:203], v[152:155], v[44:47]
	v_mfma_f32_16x16x32_bf16 v[40:43], v[200:203], v[168:171], v[40:43]
	v_mfma_f32_16x16x32_bf16 v[36:39], v[208:211], v[152:155], v[36:39]
	v_mfma_f32_16x16x32_bf16 v[32:35], v[208:211], v[168:171], v[32:35]
	v_mfma_f32_16x16x32_bf16 v[216:219], v[204:207], v[164:167], v[44:47]
	v_mfma_f32_16x16x32_bf16 v[232:235], v[204:207], v[172:175], v[40:43]
	v_mfma_f32_16x16x32_bf16 v[152:155], v[212:215], v[164:167], v[36:39]
	v_mfma_f32_16x16x32_bf16 v[164:167], v[212:215], v[172:175], v[32:35]
	s_setprio 0
	s_setprio 1
	v_mfma_f32_16x16x32_bf16 v[28:31], v[64:67], v[96:99], v[28:31]
	v_mfma_f32_16x16x32_bf16 v[24:27], v[64:67], v[104:107], v[24:27]
	v_mfma_f32_16x16x32_bf16 v[20:23], v[72:75], v[96:99], v[20:23]
	v_mfma_f32_16x16x32_bf16 v[16:19], v[72:75], v[104:107], v[16:19]
	v_mfma_f32_16x16x32_bf16 v[28:31], v[68:71], v[100:103], v[28:31]
	v_mfma_f32_16x16x32_bf16 v[24:27], v[68:71], v[108:111], v[24:27]
	v_mfma_f32_16x16x32_bf16 v[20:23], v[76:79], v[100:103], v[20:23]
	v_mfma_f32_16x16x32_bf16 v[16:19], v[76:79], v[108:111], v[16:19]
	v_mfma_f32_16x16x32_bf16 v[12:15], v[200:203], v[96:99], v[12:15]
	v_mfma_f32_16x16x32_bf16 v[8:11], v[200:203], v[104:107], v[8:11]
	v_mfma_f32_16x16x32_bf16 v[4:7], v[208:211], v[96:99], v[4:7]
	v_mfma_f32_16x16x32_bf16 v[0:3], v[208:211], v[104:107], v[0:3]
	v_mfma_f32_16x16x32_bf16 v[168:171], v[204:207], v[100:103], v[12:15]
	v_mfma_f32_16x16x32_bf16 v[172:175], v[204:207], v[108:111], v[8:11]
	v_mfma_f32_16x16x32_bf16 v[200:203], v[212:215], v[100:103], v[4:7]
	v_mfma_f32_16x16x32_bf16 v[204:207], v[212:215], v[108:111], v[0:3]
	s_setprio 0
	s_barrier
	s_nop 1
	ds_read_b128 v[0:3], v151
	ds_read_b128 v[4:7], v151 offset:1024
	ds_read_b128 v[208:211], v151 offset:2048
	ds_read_b128 v[212:215], v151 offset:3072
	ds_read_b128 v[8:11], v149 offset:32768
	ds_read_b128 v[12:15], v149 offset:33792
	ds_read_b128 v[32:35], v148 offset:32768
	ds_read_b128 v[36:39], v148 offset:33792
	ds_read_b128 v[40:43], v147 offset:32768
	ds_read_b128 v[44:47], v147 offset:33792
	ds_read_b128 v[236:239], v146 offset:32768
	ds_read_b128 v[240:243], v146 offset:33792
	s_waitcnt vmcnt(2)
	s_barrier
	s_waitcnt lgkmcnt(0)
	s_setprio 1
	s_waitcnt lgkmcnt(0)
	v_mfma_f32_16x16x32_bf16 v[64:67], v[8:11], v[0:3], v[124:127]
	v_mfma_f32_16x16x32_bf16 v[104:107], v[12:15], v[4:7], v[64:67]
	v_mfma_f32_16x16x32_bf16 v[64:67], v[8:11], v[208:211], v[120:123]
	v_mfma_f32_16x16x32_bf16 v[108:111], v[12:15], v[212:215], v[64:67]
	v_mfma_f32_16x16x32_bf16 v[64:67], v[32:35], v[0:3], v[116:119]
	v_mfma_f32_16x16x32_bf16 v[96:99], v[36:39], v[4:7], v[64:67]
	v_mfma_f32_16x16x32_bf16 v[64:67], v[32:35], v[208:211], v[112:115]
	v_mfma_f32_16x16x32_bf16 v[100:103], v[36:39], v[212:215], v[64:67]
	v_mfma_f32_16x16x32_bf16 v[64:67], v[40:43], v[0:3], v[128:131]
	v_mfma_f32_16x16x32_bf16 v[72:75], v[44:47], v[4:7], v[64:67]
	v_mfma_f32_16x16x32_bf16 v[64:67], v[40:43], v[208:211], v[220:223]
	v_mfma_f32_16x16x32_bf16 v[76:79], v[44:47], v[212:215], v[64:67]
	v_mfma_f32_16x16x32_bf16 v[64:67], v[236:239], v[0:3], v[224:227]
	v_mfma_f32_16x16x32_bf16 v[68:71], v[236:239], v[208:211], v[228:231]
	v_mfma_f32_16x16x32_bf16 v[64:67], v[240:243], v[4:7], v[64:67]
	v_mfma_f32_16x16x32_bf16 v[68:71], v[240:243], v[212:215], v[68:71]
	s_setprio 0
	s_barrier
	ds_read_b128 v[128:131], v150
	ds_read_b128 v[220:223], v150 offset:1024
	ds_read_b128 v[224:227], v150 offset:2048
	ds_read_b128 v[228:231], v150 offset:3072
	s_waitcnt vmcnt(0)
	s_barrier
	s_waitcnt lgkmcnt(0)
	s_setprio 1
	s_waitcnt lgkmcnt(0)
	v_mfma_f32_16x16x32_bf16 v[92:95], v[8:11], v[128:131], v[92:95]
	v_mfma_f32_16x16x32_bf16 v[8:11], v[8:11], v[224:227], v[88:91]
	v_mfma_f32_16x16x32_bf16 v[124:127], v[12:15], v[228:231], v[8:11]
	v_mfma_f32_16x16x32_bf16 v[8:11], v[32:35], v[128:131], v[84:87]
	v_mfma_f32_16x16x32_bf16 v[112:115], v[36:39], v[220:223], v[8:11]
	v_mfma_f32_16x16x32_bf16 v[8:11], v[32:35], v[224:227], v[80:83]
	v_mfma_f32_16x16x32_bf16 v[116:119], v[36:39], v[228:231], v[8:11]
	v_mfma_f32_16x16x32_bf16 v[8:11], v[40:43], v[128:131], v[156:159]
	v_mfma_f32_16x16x32_bf16 v[88:91], v[44:47], v[220:223], v[8:11]
	v_mfma_f32_16x16x32_bf16 v[8:11], v[40:43], v[224:227], v[178:181]
	v_mfma_f32_16x16x32_bf16 v[120:123], v[12:15], v[220:223], v[92:95]
	v_mfma_f32_16x16x32_bf16 v[92:95], v[44:47], v[228:231], v[8:11]
	v_mfma_f32_16x16x32_bf16 v[8:11], v[236:239], v[128:131], v[192:195]
	v_mfma_f32_16x16x32_bf16 v[80:83], v[240:243], v[220:223], v[8:11]
	v_mfma_f32_16x16x32_bf16 v[8:11], v[236:239], v[224:227], v[196:199]
	v_mfma_f32_16x16x32_bf16 v[84:87], v[240:243], v[228:231], v[8:11]
	s_setprio 0
	s_barrier
	ds_read_b128 v[156:159], v149 offset:49152
	ds_read_b128 v[178:181], v149 offset:50176
	ds_read_b128 v[192:195], v148 offset:49152
	ds_read_b128 v[148:151], v148 offset:50176
	ds_read_b128 v[196:199], v147 offset:49152
	ds_read_b128 v[236:239], v147 offset:50176
	ds_read_b128 v[240:243], v146 offset:49152
	ds_read_b128 v[244:247], v146 offset:50176
	s_barrier
	s_waitcnt lgkmcnt(0)
	s_setprio 1
	s_waitcnt lgkmcnt(0)
	v_mfma_f32_16x16x32_bf16 v[8:11], v[156:159], v[0:3], v[60:63]
	v_mfma_f32_16x16x32_bf16 v[40:43], v[178:181], v[4:7], v[8:11]
	v_mfma_f32_16x16x32_bf16 v[8:11], v[156:159], v[208:211], v[56:59]
	v_mfma_f32_16x16x32_bf16 v[44:47], v[178:181], v[212:215], v[8:11]
	v_mfma_f32_16x16x32_bf16 v[8:11], v[192:195], v[0:3], v[52:55]
	v_mfma_f32_16x16x32_bf16 v[32:35], v[148:151], v[4:7], v[8:11]
	v_mfma_f32_16x16x32_bf16 v[8:11], v[192:195], v[208:211], v[48:51]
	v_mfma_f32_16x16x32_bf16 v[36:39], v[148:151], v[212:215], v[8:11]
	v_mfma_f32_16x16x32_bf16 v[8:11], v[196:199], v[0:3], v[216:219]
	v_mfma_f32_16x16x32_bf16 v[0:3], v[240:243], v[0:3], v[152:155]
	v_mfma_f32_16x16x32_bf16 v[8:11], v[236:239], v[4:7], v[8:11]
	v_mfma_f32_16x16x32_bf16 v[12:15], v[196:199], v[208:211], v[232:235]
	v_mfma_f32_16x16x32_bf16 v[0:3], v[244:247], v[4:7], v[0:3]
	v_mfma_f32_16x16x32_bf16 v[4:7], v[240:243], v[208:211], v[164:167]
	v_mfma_f32_16x16x32_bf16 v[12:15], v[236:239], v[212:215], v[12:15]
	v_mfma_f32_16x16x32_bf16 v[4:7], v[244:247], v[212:215], v[4:7]
	s_setprio 0
	s_setprio 1
	v_mfma_f32_16x16x32_bf16 v[16:19], v[192:195], v[224:227], v[16:19]
	v_mfma_f32_16x16x32_bf16 v[24:27], v[156:159], v[224:227], v[24:27]
	v_mfma_f32_16x16x32_bf16 v[52:55], v[148:151], v[228:231], v[16:19]
	v_mfma_f32_16x16x32_bf16 v[16:19], v[196:199], v[128:131], v[168:171]
	v_mfma_f32_16x16x32_bf16 v[28:31], v[156:159], v[128:131], v[28:31]
	v_mfma_f32_16x16x32_bf16 v[60:63], v[178:181], v[228:231], v[24:27]
	v_mfma_f32_16x16x32_bf16 v[20:23], v[192:195], v[128:131], v[20:23]
	v_mfma_f32_16x16x32_bf16 v[24:27], v[236:239], v[220:223], v[16:19]
	v_mfma_f32_16x16x32_bf16 v[16:19], v[196:199], v[224:227], v[172:175]
	v_mfma_f32_16x16x32_bf16 v[56:59], v[178:181], v[220:223], v[28:31]
	v_mfma_f32_16x16x32_bf16 v[48:51], v[148:151], v[220:223], v[20:23]
	v_mfma_f32_16x16x32_bf16 v[28:31], v[236:239], v[228:231], v[16:19]
	v_mfma_f32_16x16x32_bf16 v[16:19], v[240:243], v[128:131], v[200:203]
	v_mfma_f32_16x16x32_bf16 v[20:23], v[240:243], v[224:227], v[204:207]
	v_mfma_f32_16x16x32_bf16 v[16:19], v[244:247], v[220:223], v[16:19]
	v_mfma_f32_16x16x32_bf16 v[20:23], v[244:247], v[228:231], v[20:23]
	s_setprio 0
	v_cmp_gt_u32_e32 vcc, s2, v142
	s_barrier
	s_and_saveexec_b64 s[18:19], vcc
	s_cbranch_execz .LBB0_998
	s_barrier

.LBB0_1231:
	s_or_b64 exec, exec, s[18:19]
	v_add_u32_e32 v151, s15, v6
	v_add_u32_e32 v152, 0x2000, v151
	v_readfirstlane_b32 s18, v151
	v_lshl_add_u64 v[8:9], v[0:1], 0, s[46:47]
	s_mov_b32 m0, s18
	v_readfirstlane_b32 s18, v152
	v_add_u32_e32 v153, 0x8000, v144
	s_waitcnt vmcnt(0)
	s_barrier
	global_load_lds_dwordx4 v[8:9], off
	v_lshl_add_u64 v[8:9], v[0:1], 0, s[48:49]
	s_mov_b32 m0, s18
	v_readfirstlane_b32 s18, v153
	v_add_u32_e32 v154, 0xa000, v144
	global_load_lds_dwordx4 v[8:9], off
	v_lshl_add_u64 v[8:9], v[128:129], 0, s[46:47]
	s_mov_b32 m0, s18
	v_readfirstlane_b32 s18, v154
	global_load_lds_dwordx4 v[8:9], off
	v_lshl_add_u64 v[8:9], v[128:129], 0, s[48:49]
	s_mov_b32 m0, s18
	s_mov_b64 s[18:19], 0x40080
	v_add_u32_e32 v155, s36, v6
	global_load_lds_dwordx4 v[8:9], off
	v_lshl_add_u64 v[8:9], v[0:1], 0, s[18:19]
	v_readfirstlane_b32 s18, v155
	v_add_u32_e32 v156, 0x2000, v155
	s_mov_b32 m0, s18
	v_readfirstlane_b32 s18, v156
	global_load_lds_dwordx4 v[8:9], off
	v_lshl_add_u64 v[0:1], v[0:1], 0, s[52:53]
	s_mov_b32 m0, s18
	v_bfe_u32 v131, v130, 4, 2
	global_load_lds_dwordx4 v[0:1], off
	v_and_b32_e32 v132, 15, v130
	v_lshlrev_b32_e32 v135, 2, v130
	v_lshlrev_b32_e32 v0, 4, v131
	v_lshlrev_b32_e32 v6, 6, v132
	v_and_b32_e32 v7, 32, v135
	v_lshlrev_b32_e32 v12, 6, v130
	v_bitop3_b32 v6, v0, v7, v6 bitop3:0x36
	v_and_or_b32 v0, v12, s33, v0
	v_xad_u32 v7, v0, v7, 16
	v_lshlrev_b32_e32 v0, 8, v130
	v_ashrrev_i32_e32 v134, 6, v130
	v_and_b32_e32 v0, 0xffff8000, v0
	v_lshlrev_b32_e32 v2, 11, v2
	s_add_u32 s18, s8, s11
	v_and_b32_e32 v133, 3, v134
	s_waitcnt vmcnt(6)
	v_lshlrev_b32_e32 v136, 6, v5
	v_lshlrev_b32_e32 v5, 13, v5
	v_or3_b32 v0, v3, v0, v2
	s_addc_u32 s19, s9, 0
	v_lshlrev_b32_e32 v1, 12, v133
	v_add_u32_e32 v8, s35, v6
	v_add_u32_e32 v9, s14, v6
	v_add_u32_e32 v10, s15, v6
	v_add_u32_e32 v11, s36, v6
	v_add_u32_e32 v6, 16, v6
	v_or_b32_e32 v12, 0x800, v5
	v_or_b32_e32 v13, 0x1000, v5
	v_or_b32_e32 v14, 0x1800, v5
	v_add_u32_e32 v176, v0, v4
	s_add_u32 s20, s8, s12
	v_mov_b32_e32 v0, 0
	s_addc_u32 s21, s9, s13
	s_mov_b32 s11, -2
	v_add_u32_e32 v158, v8, v1
	v_add_u32_e32 v140, v6, v5
	v_add_u32_e32 v139, v7, v12
	v_add_u32_e32 v138, v7, v13
	v_add_u32_e32 v137, v7, v14
	v_add_u32_e32 v157, v9, v1
	v_add_u32_e32 v146, v10, v1
	v_add_u32_e32 v141, v11, v1
	v_mov_b32_e32 v1, v0
	v_mov_b32_e32 v2, v0
	v_mov_b32_e32 v3, v0
	v_mov_b32_e32 v4, v0
	v_mov_b32_e32 v5, v0
	v_mov_b32_e32 v6, v0
	v_mov_b32_e32 v7, v0
	v_mov_b32_e32 v8, v0
	v_mov_b32_e32 v9, v0
	v_mov_b32_e32 v10, v0
	v_mov_b32_e32 v11, v0
	v_mov_b32_e32 v12, v0
	v_mov_b32_e32 v13, v0
	v_mov_b32_e32 v14, v0
	v_mov_b32_e32 v15, v0
	v_mov_b32_e32 v16, v0
	v_mov_b32_e32 v17, v0
	v_mov_b32_e32 v18, v0
	v_mov_b32_e32 v19, v0
	v_mov_b32_e32 v20, v0
	v_mov_b32_e32 v21, v0
	v_mov_b32_e32 v22, v0
	v_mov_b32_e32 v23, v0
	v_mov_b32_e32 v24, v0
	v_mov_b32_e32 v25, v0
	v_mov_b32_e32 v26, v0
	v_mov_b32_e32 v27, v0
	v_mov_b32_e32 v28, v0
	v_mov_b32_e32 v29, v0
	v_mov_b32_e32 v30, v0
	v_mov_b32_e32 v31, v0
	v_mov_b32_e32 v32, v0
	v_mov_b32_e32 v33, v0
	v_mov_b32_e32 v34, v0
	v_mov_b32_e32 v35, v0
	v_mov_b32_e32 v36, v0
	v_mov_b32_e32 v37, v0
	v_mov_b32_e32 v38, v0
	v_mov_b32_e32 v39, v0
	v_mov_b32_e32 v40, v0
	v_mov_b32_e32 v41, v0
	v_mov_b32_e32 v42, v0
	v_mov_b32_e32 v43, v0
	v_mov_b32_e32 v44, v0
	v_mov_b32_e32 v45, v0
	v_mov_b32_e32 v46, v0
	v_mov_b32_e32 v47, v0
	v_mov_b32_e32 v48, v0
	v_mov_b32_e32 v49, v0
	v_mov_b32_e32 v50, v0
	v_mov_b32_e32 v51, v0
	v_mov_b32_e32 v52, v0
	v_mov_b32_e32 v53, v0
	v_mov_b32_e32 v54, v0
	v_mov_b32_e32 v55, v0
	v_mov_b32_e32 v56, v0
	v_mov_b32_e32 v57, v0
	v_mov_b32_e32 v58, v0
	v_mov_b32_e32 v59, v0
	v_mov_b32_e32 v60, v0
	v_mov_b32_e32 v61, v0
	v_mov_b32_e32 v62, v0
	v_mov_b32_e32 v63, v0
	v_mov_b32_e32 v64, v0
	v_mov_b32_e32 v65, v0
	v_mov_b32_e32 v66, v0
	v_mov_b32_e32 v67, v0
	v_mov_b32_e32 v68, v0
	v_mov_b32_e32 v69, v0
	v_mov_b32_e32 v70, v0
	v_mov_b32_e32 v71, v0
	v_mov_b32_e32 v72, v0
	v_mov_b32_e32 v73, v0
	v_mov_b32_e32 v74, v0
	v_mov_b32_e32 v75, v0
	v_mov_b32_e32 v76, v0
	v_mov_b32_e32 v77, v0
	v_mov_b32_e32 v78, v0
	v_mov_b32_e32 v79, v0
	v_mov_b32_e32 v80, v0
	v_mov_b32_e32 v81, v0
	v_mov_b32_e32 v82, v0
	v_mov_b32_e32 v83, v0
	v_mov_b32_e32 v84, v0
	v_mov_b32_e32 v85, v0
	v_mov_b32_e32 v86, v0
	v_mov_b32_e32 v87, v0
	v_mov_b32_e32 v88, v0
	v_mov_b32_e32 v89, v0
	v_mov_b32_e32 v90, v0
	v_mov_b32_e32 v91, v0
	v_mov_b32_e32 v92, v0
	v_mov_b32_e32 v93, v0
	v_mov_b32_e32 v94, v0
	v_mov_b32_e32 v95, v0
	v_mov_b32_e32 v96, v0
	v_mov_b32_e32 v97, v0
	v_mov_b32_e32 v98, v0
	v_mov_b32_e32 v99, v0
	v_mov_b32_e32 v100, v0
	v_mov_b32_e32 v101, v0
	v_mov_b32_e32 v102, v0
	v_mov_b32_e32 v103, v0
	v_mov_b32_e32 v104, v0
	v_mov_b32_e32 v105, v0
	v_mov_b32_e32 v106, v0
	v_mov_b32_e32 v107, v0
	v_mov_b32_e32 v108, v0
	v_mov_b32_e32 v109, v0
	v_mov_b32_e32 v110, v0
	v_mov_b32_e32 v111, v0
	v_mov_b32_e32 v112, v0
	v_mov_b32_e32 v113, v0
	v_mov_b32_e32 v114, v0
	v_mov_b32_e32 v115, v0
	v_mov_b32_e32 v116, v0
	v_mov_b32_e32 v117, v0
	v_mov_b32_e32 v118, v0
	v_mov_b32_e32 v119, v0
	v_mov_b32_e32 v120, v0
	v_mov_b32_e32 v121, v0
	v_mov_b32_e32 v122, v0
	v_mov_b32_e32 v123, v0
	v_mov_b32_e32 v124, v0
	v_mov_b32_e32 v125, v0
	v_mov_b32_e32 v126, v0
	v_mov_b32_e32 v127, v0
.Lkh_1232:
	s_barrier
.LBB0_1232:
	ds_read_b128 v[162:165], v158
	ds_read_b128 v[166:169], v158 offset:1024
	ds_read_b128 v[170:173], v158 offset:2048
	ds_read_b128 v[178:181], v158 offset:3072
	v_add_u32_e32 v159, 0xc000, v144
	v_lshl_add_u64 v[174:175], s[20:21], 0, v[176:177]
	s_mov_b64 s[70:71], 0xd66c180
	v_readfirstlane_b32 s61, v159
	v_lshl_add_u64 v[160:161], v[174:175], 0, s[70:71]
	s_mov_b32 m0, s61
	ds_read_b128 v[192:195], v140
	ds_read_b128 v[196:199], v140 offset:1024
	ds_read_b128 v[200:203], v139
	ds_read_b128 v[204:207], v139 offset:1024
	ds_read_b128 v[208:211], v138
	ds_read_b128 v[212:215], v138 offset:1024
	ds_read_b128 v[216:219], v137
	ds_read_b128 v[220:223], v137 offset:1024
	global_load_lds_dwordx4 v[160:161], off
	v_add_u32_e32 v160, 0xe000, v144
	s_mov_b64 s[70:71], 0xd68c180
	v_readfirstlane_b32 s61, v160
	v_lshl_add_u64 v[224:225], v[174:175], 0, s[70:71]
	s_mov_b32 m0, s61
	s_nop 0
	global_load_lds_dwordx4 v[224:225], off
	s_waitcnt lgkmcnt(8)
	s_barrier
	s_waitcnt lgkmcnt(0)
	s_setprio 1
	s_waitcnt lgkmcnt(0)
	v_mfma_f32_16x16x32_bf16 v[124:127], v[192:195], v[162:165], v[124:127]
	v_mfma_f32_16x16x32_bf16 v[120:123], v[192:195], v[170:173], v[120:123]
	v_mfma_f32_16x16x32_bf16 v[116:119], v[200:203], v[162:165], v[116:119]
	v_mfma_f32_16x16x32_bf16 v[112:115], v[200:203], v[170:173], v[112:115]
	v_mfma_f32_16x16x32_bf16 v[108:111], v[208:211], v[162:165], v[108:111]
	v_mfma_f32_16x16x32_bf16 v[104:107], v[208:211], v[170:173], v[104:107]
	v_mfma_f32_16x16x32_bf16 v[100:103], v[216:219], v[162:165], v[100:103]
	v_mfma_f32_16x16x32_bf16 v[96:99], v[216:219], v[170:173], v[96:99]
	v_mfma_f32_16x16x32_bf16 v[124:127], v[196:199], v[166:169], v[124:127]
	v_mfma_f32_16x16x32_bf16 v[120:123], v[196:199], v[178:181], v[120:123]
	v_mfma_f32_16x16x32_bf16 v[116:119], v[204:207], v[166:169], v[116:119]
	v_mfma_f32_16x16x32_bf16 v[112:115], v[204:207], v[178:181], v[112:115]
	v_mfma_f32_16x16x32_bf16 v[108:111], v[212:215], v[166:169], v[108:111]
	v_mfma_f32_16x16x32_bf16 v[104:107], v[212:215], v[178:181], v[104:107]
	v_mfma_f32_16x16x32_bf16 v[100:103], v[220:223], v[166:169], v[100:103]
	v_mfma_f32_16x16x32_bf16 v[96:99], v[220:223], v[178:181], v[96:99]
	s_setprio 0
	s_barrier
	v_lshl_add_u64 v[240:241], s[18:19], 0, v[176:177]
	s_mov_b64 s[70:71], 0x1300100
	v_readfirstlane_b32 s61, v142
	v_lshl_add_u64 v[242:243], v[240:241], 0, s[70:71]
	s_mov_b32 m0, s61
	s_mov_b64 s[70:71], 0x1320100
	v_readfirstlane_b32 s61, v143
	ds_read_b128 v[224:227], v157
	ds_read_b128 v[228:231], v157 offset:1024
	ds_read_b128 v[232:235], v157 offset:2048
	ds_read_b128 v[236:239], v157 offset:3072
	global_load_lds_dwordx4 v[242:243], off
	v_lshl_add_u64 v[242:243], v[240:241], 0, s[70:71]
	s_mov_b32 m0, s61
	s_nop 0
	global_load_lds_dwordx4 v[242:243], off
	s_barrier
	s_waitcnt lgkmcnt(0)
	s_setprio 1
	s_waitcnt lgkmcnt(0)
	v_mfma_f32_16x16x32_bf16 v[92:95], v[192:195], v[224:227], v[92:95]
	v_mfma_f32_16x16x32_bf16 v[88:91], v[192:195], v[232:235], v[88:91]
	v_mfma_f32_16x16x32_bf16 v[84:87], v[200:203], v[224:227], v[84:87]
	v_mfma_f32_16x16x32_bf16 v[80:83], v[200:203], v[232:235], v[80:83]
	v_mfma_f32_16x16x32_bf16 v[76:79], v[208:211], v[224:227], v[76:79]
	v_mfma_f32_16x16x32_bf16 v[72:75], v[208:211], v[232:235], v[72:75]
	v_mfma_f32_16x16x32_bf16 v[68:71], v[216:219], v[224:227], v[68:71]
	v_mfma_f32_16x16x32_bf16 v[64:67], v[216:219], v[232:235], v[64:67]
	v_mfma_f32_16x16x32_bf16 v[92:95], v[196:199], v[228:231], v[92:95]
	v_mfma_f32_16x16x32_bf16 v[88:91], v[196:199], v[236:239], v[88:91]
	v_mfma_f32_16x16x32_bf16 v[84:87], v[204:207], v[228:231], v[84:87]
	v_mfma_f32_16x16x32_bf16 v[80:83], v[204:207], v[236:239], v[80:83]
	v_mfma_f32_16x16x32_bf16 v[76:79], v[212:215], v[228:231], v[76:79]
	v_mfma_f32_16x16x32_bf16 v[72:75], v[212:215], v[236:239], v[72:75]
	v_mfma_f32_16x16x32_bf16 v[68:71], v[220:223], v[228:231], v[68:71]
	v_mfma_f32_16x16x32_bf16 v[64:67], v[220:223], v[236:239], v[64:67]
	s_setprio 0
	s_mov_b64 s[70:71], 0xd62c200
	v_readfirstlane_b32 s61, v144
	v_lshl_add_u64 v[242:243], v[174:175], 0, s[70:71]
	s_mov_b32 m0, s61
	s_mov_b64 s[70:71], 0xd64c200
	v_readfirstlane_b32 s61, v145
	s_barrier
	ds_read_b128 v[192:195], v140 offset:16384
	ds_read_b128 v[196:199], v140 offset:17408
	ds_read_b128 v[200:203], v139 offset:16384
	ds_read_b128 v[204:207], v139 offset:17408
	ds_read_b128 v[208:211], v138 offset:16384
	ds_read_b128 v[212:215], v138 offset:17408
	ds_read_b128 v[216:219], v137 offset:16384
	ds_read_b128 v[220:223], v137 offset:17408
	global_load_lds_dwordx4 v[242:243], off
	v_lshl_add_u64 v[242:243], v[174:175], 0, s[70:71]
	s_mov_b32 m0, s61
	s_nop 0
	global_load_lds_dwordx4 v[242:243], off
	s_barrier
	s_waitcnt lgkmcnt(0)
	s_setprio 1
	s_waitcnt lgkmcnt(0)
	v_mfma_f32_16x16x32_bf16 v[60:63], v[192:195], v[162:165], v[60:63]
	v_mfma_f32_16x16x32_bf16 v[56:59], v[192:195], v[170:173], v[56:59]
	v_mfma_f32_16x16x32_bf16 v[52:55], v[200:203], v[162:165], v[52:55]
	v_mfma_f32_16x16x32_bf16 v[48:51], v[200:203], v[170:173], v[48:51]
	v_mfma_f32_16x16x32_bf16 v[44:47], v[208:211], v[162:165], v[44:47]
	v_mfma_f32_16x16x32_bf16 v[40:43], v[208:211], v[170:173], v[40:43]
	v_mfma_f32_16x16x32_bf16 v[36:39], v[216:219], v[162:165], v[36:39]
	v_mfma_f32_16x16x32_bf16 v[32:35], v[216:219], v[170:173], v[32:35]
	v_mfma_f32_16x16x32_bf16 v[60:63], v[196:199], v[166:169], v[60:63]
	v_mfma_f32_16x16x32_bf16 v[56:59], v[196:199], v[178:181], v[56:59]
	v_mfma_f32_16x16x32_bf16 v[52:55], v[204:207], v[166:169], v[52:55]
	v_mfma_f32_16x16x32_bf16 v[48:51], v[204:207], v[178:181], v[48:51]
	v_mfma_f32_16x16x32_bf16 v[44:47], v[212:215], v[166:169], v[44:47]
	v_mfma_f32_16x16x32_bf16 v[40:43], v[212:215], v[178:181], v[40:43]
	v_mfma_f32_16x16x32_bf16 v[36:39], v[220:223], v[166:169], v[36:39]
	v_mfma_f32_16x16x32_bf16 v[32:35], v[220:223], v[178:181], v[32:35]
	s_setprio 0
	s_barrier
	s_mov_b64 s[70:71], 0x1340100
	v_readfirstlane_b32 s61, v147
	v_lshl_add_u64 v[162:163], v[240:241], 0, s[70:71]
	s_mov_b32 m0, s61
	s_mov_b64 s[70:71], 0x1360100
	v_readfirstlane_b32 s61, v148
	global_load_lds_dwordx4 v[162:163], off
	v_lshl_add_u64 v[162:163], v[240:241], 0, s[70:71]
	s_mov_b32 m0, s61
	s_nop 0
	global_load_lds_dwordx4 v[162:163], off
	s_waitcnt vmcnt(6)
	s_barrier
	s_setprio 1
	v_mfma_f32_16x16x32_bf16 v[28:31], v[192:195], v[224:227], v[28:31]
	v_mfma_f32_16x16x32_bf16 v[24:27], v[192:195], v[232:235], v[24:27]
	v_mfma_f32_16x16x32_bf16 v[20:23], v[200:203], v[224:227], v[20:23]
	v_mfma_f32_16x16x32_bf16 v[16:19], v[200:203], v[232:235], v[16:19]
	v_mfma_f32_16x16x32_bf16 v[12:15], v[208:211], v[224:227], v[12:15]
	v_mfma_f32_16x16x32_bf16 v[8:11], v[208:211], v[232:235], v[8:11]
	v_mfma_f32_16x16x32_bf16 v[4:7], v[216:219], v[224:227], v[4:7]
	v_mfma_f32_16x16x32_bf16 v[0:3], v[216:219], v[232:235], v[0:3]
	v_mfma_f32_16x16x32_bf16 v[28:31], v[196:199], v[228:231], v[28:31]
	v_mfma_f32_16x16x32_bf16 v[24:27], v[196:199], v[236:239], v[24:27]
	v_mfma_f32_16x16x32_bf16 v[20:23], v[204:207], v[228:231], v[20:23]
	v_mfma_f32_16x16x32_bf16 v[16:19], v[204:207], v[236:239], v[16:19]
	v_mfma_f32_16x16x32_bf16 v[12:15], v[212:215], v[228:231], v[12:15]
	v_mfma_f32_16x16x32_bf16 v[8:11], v[212:215], v[236:239], v[8:11]
	v_mfma_f32_16x16x32_bf16 v[4:7], v[220:223], v[228:231], v[4:7]
	v_mfma_f32_16x16x32_bf16 v[0:3], v[220:223], v[236:239], v[0:3]
	s_setprio 0
	s_barrier
	ds_read_b128 v[162:165], v146
	ds_read_b128 v[166:169], v146 offset:1024
	ds_read_b128 v[170:173], v146 offset:2048
	ds_read_b128 v[178:181], v146 offset:3072
	s_mov_b64 s[70:71], 0xd66c200
	v_readfirstlane_b32 s61, v149
	v_lshl_add_u64 v[224:225], v[174:175], 0, s[70:71]
	s_mov_b32 m0, s61
	s_mov_b64 s[70:71], 0xd68c200
	v_readfirstlane_b32 s61, v150
	ds_read_b128 v[192:195], v140 offset:32768
	ds_read_b128 v[196:199], v140 offset:33792
	ds_read_b128 v[200:203], v139 offset:32768
	ds_read_b128 v[204:207], v139 offset:33792
	ds_read_b128 v[208:211], v138 offset:32768
	ds_read_b128 v[212:215], v138 offset:33792
	ds_read_b128 v[216:219], v137 offset:32768
	ds_read_b128 v[220:223], v137 offset:33792
	global_load_lds_dwordx4 v[224:225], off
	v_lshl_add_u64 v[224:225], v[174:175], 0, s[70:71]
	s_mov_b32 m0, s61
	s_nop 0
	global_load_lds_dwordx4 v[224:225], off
	s_waitcnt lgkmcnt(8)
	s_barrier
	s_waitcnt lgkmcnt(0)
	s_setprio 1
	s_waitcnt lgkmcnt(0)
	v_mfma_f32_16x16x32_bf16 v[124:127], v[192:195], v[162:165], v[124:127]
	v_mfma_f32_16x16x32_bf16 v[120:123], v[192:195], v[170:173], v[120:123]
	v_mfma_f32_16x16x32_bf16 v[116:119], v[200:203], v[162:165], v[116:119]
	v_mfma_f32_16x16x32_bf16 v[112:115], v[200:203], v[170:173], v[112:115]
	v_mfma_f32_16x16x32_bf16 v[108:111], v[208:211], v[162:165], v[108:111]
	v_mfma_f32_16x16x32_bf16 v[104:107], v[208:211], v[170:173], v[104:107]
	v_mfma_f32_16x16x32_bf16 v[100:103], v[216:219], v[162:165], v[100:103]
	v_mfma_f32_16x16x32_bf16 v[96:99], v[216:219], v[170:173], v[96:99]
	v_mfma_f32_16x16x32_bf16 v[124:127], v[196:199], v[166:169], v[124:127]
	v_mfma_f32_16x16x32_bf16 v[120:123], v[196:199], v[178:181], v[120:123]
	v_mfma_f32_16x16x32_bf16 v[116:119], v[204:207], v[166:169], v[116:119]
	v_mfma_f32_16x16x32_bf16 v[112:115], v[204:207], v[178:181], v[112:115]
	v_mfma_f32_16x16x32_bf16 v[108:111], v[212:215], v[166:169], v[108:111]
	v_mfma_f32_16x16x32_bf16 v[104:107], v[212:215], v[178:181], v[104:107]
	v_mfma_f32_16x16x32_bf16 v[100:103], v[220:223], v[166:169], v[100:103]
	v_mfma_f32_16x16x32_bf16 v[96:99], v[220:223], v[178:181], v[96:99]
	s_setprio 0
	s_barrier
	s_mov_b64 s[70:71], 0x1300180
	v_readfirstlane_b32 s61, v151
	v_lshl_add_u64 v[242:243], v[240:241], 0, s[70:71]
	s_mov_b32 m0, s61
	s_mov_b64 s[70:71], 0x1320180
	v_readfirstlane_b32 s61, v152
	ds_read_b128 v[224:227], v141
	ds_read_b128 v[228:231], v141 offset:1024
	ds_read_b128 v[232:235], v141 offset:2048
	ds_read_b128 v[236:239], v141 offset:3072
	global_load_lds_dwordx4 v[242:243], off
	v_lshl_add_u64 v[242:243], v[240:241], 0, s[70:71]
	s_mov_b32 m0, s61
	s_nop 0
	global_load_lds_dwordx4 v[242:243], off
	s_barrier
	s_waitcnt lgkmcnt(0)
	s_setprio 1
	s_waitcnt lgkmcnt(0)
	v_mfma_f32_16x16x32_bf16 v[92:95], v[192:195], v[224:227], v[92:95]
	v_mfma_f32_16x16x32_bf16 v[88:91], v[192:195], v[232:235], v[88:91]
	v_mfma_f32_16x16x32_bf16 v[84:87], v[200:203], v[224:227], v[84:87]
	v_mfma_f32_16x16x32_bf16 v[80:83], v[200:203], v[232:235], v[80:83]
	v_mfma_f32_16x16x32_bf16 v[76:79], v[208:211], v[224:227], v[76:79]
	v_mfma_f32_16x16x32_bf16 v[72:75], v[208:211], v[232:235], v[72:75]
	v_mfma_f32_16x16x32_bf16 v[68:71], v[216:219], v[224:227], v[68:71]
	v_mfma_f32_16x16x32_bf16 v[64:67], v[216:219], v[232:235], v[64:67]
	v_mfma_f32_16x16x32_bf16 v[92:95], v[196:199], v[228:231], v[92:95]
	v_mfma_f32_16x16x32_bf16 v[88:91], v[196:199], v[236:239], v[88:91]
	v_mfma_f32_16x16x32_bf16 v[84:87], v[204:207], v[228:231], v[84:87]
	v_mfma_f32_16x16x32_bf16 v[80:83], v[204:207], v[236:239], v[80:83]
	v_mfma_f32_16x16x32_bf16 v[76:79], v[212:215], v[228:231], v[76:79]
	v_mfma_f32_16x16x32_bf16 v[72:75], v[212:215], v[236:239], v[72:75]
	v_mfma_f32_16x16x32_bf16 v[68:71], v[220:223], v[228:231], v[68:71]
	v_mfma_f32_16x16x32_bf16 v[64:67], v[220:223], v[236:239], v[64:67]
	s_setprio 0
	s_mov_b64 s[70:71], 0xd62c280
	v_readfirstlane_b32 s61, v153
	v_lshl_add_u64 v[242:243], v[174:175], 0, s[70:71]
	s_mov_b32 m0, s61
	s_mov_b64 s[70:71], 0xd64c280
	v_readfirstlane_b32 s61, v154
	s_barrier
	ds_read_b128 v[192:195], v140 offset:49152
	ds_read_b128 v[196:199], v140 offset:50176
	ds_read_b128 v[200:203], v139 offset:49152
	ds_read_b128 v[204:207], v139 offset:50176
	ds_read_b128 v[208:211], v138 offset:49152
	ds_read_b128 v[212:215], v138 offset:50176
	ds_read_b128 v[216:219], v137 offset:49152
	ds_read_b128 v[220:223], v137 offset:50176
	global_load_lds_dwordx4 v[242:243], off
	v_lshl_add_u64 v[174:175], v[174:175], 0, s[70:71]
	s_mov_b32 m0, s61
	s_nop 0
	global_load_lds_dwordx4 v[174:175], off
	s_barrier
	s_waitcnt lgkmcnt(0)
	s_setprio 1
	s_waitcnt lgkmcnt(0)
	v_mfma_f32_16x16x32_bf16 v[60:63], v[192:195], v[162:165], v[60:63]
	v_mfma_f32_16x16x32_bf16 v[56:59], v[192:195], v[170:173], v[56:59]
	v_mfma_f32_16x16x32_bf16 v[52:55], v[200:203], v[162:165], v[52:55]
	v_mfma_f32_16x16x32_bf16 v[48:51], v[200:203], v[170:173], v[48:51]
	v_mfma_f32_16x16x32_bf16 v[44:47], v[208:211], v[162:165], v[44:47]
	v_mfma_f32_16x16x32_bf16 v[40:43], v[208:211], v[170:173], v[40:43]
	v_mfma_f32_16x16x32_bf16 v[36:39], v[216:219], v[162:165], v[36:39]
	v_mfma_f32_16x16x32_bf16 v[32:35], v[216:219], v[170:173], v[32:35]
	v_mfma_f32_16x16x32_bf16 v[60:63], v[196:199], v[166:169], v[60:63]
	v_mfma_f32_16x16x32_bf16 v[56:59], v[196:199], v[178:181], v[56:59]
	v_mfma_f32_16x16x32_bf16 v[52:55], v[204:207], v[166:169], v[52:55]
	v_mfma_f32_16x16x32_bf16 v[48:51], v[204:207], v[178:181], v[48:51]
	v_mfma_f32_16x16x32_bf16 v[44:47], v[212:215], v[166:169], v[44:47]
	v_mfma_f32_16x16x32_bf16 v[40:43], v[212:215], v[178:181], v[40:43]
	v_mfma_f32_16x16x32_bf16 v[36:39], v[220:223], v[166:169], v[36:39]
	v_mfma_f32_16x16x32_bf16 v[32:35], v[220:223], v[178:181], v[32:35]
	s_setprio 0
	s_barrier
	s_mov_b64 s[70:71], 0x1340180
	v_readfirstlane_b32 s61, v155
	v_lshl_add_u64 v[162:163], v[240:241], 0, s[70:71]
	s_mov_b32 m0, s61
	s_mov_b64 s[70:71], 0x1360180
	v_readfirstlane_b32 s61, v156
	global_load_lds_dwordx4 v[162:163], off
	v_lshl_add_u64 v[162:163], v[240:241], 0, s[70:71]
	s_mov_b32 m0, s61
	s_nop 0
	global_load_lds_dwordx4 v[162:163], off
	s_waitcnt vmcnt(6)
	s_barrier
	s_setprio 1
	v_mfma_f32_16x16x32_bf16 v[28:31], v[192:195], v[224:227], v[28:31]
	v_mfma_f32_16x16x32_bf16 v[24:27], v[192:195], v[232:235], v[24:27]
	v_mfma_f32_16x16x32_bf16 v[20:23], v[200:203], v[224:227], v[20:23]
	v_mfma_f32_16x16x32_bf16 v[16:19], v[200:203], v[232:235], v[16:19]
	v_mfma_f32_16x16x32_bf16 v[12:15], v[208:211], v[224:227], v[12:15]
	v_mfma_f32_16x16x32_bf16 v[8:11], v[208:211], v[232:235], v[8:11]
	v_mfma_f32_16x16x32_bf16 v[4:7], v[216:219], v[224:227], v[4:7]
	v_mfma_f32_16x16x32_bf16 v[0:3], v[216:219], v[232:235], v[0:3]
	v_mfma_f32_16x16x32_bf16 v[28:31], v[196:199], v[228:231], v[28:31]
	v_mfma_f32_16x16x32_bf16 v[24:27], v[196:199], v[236:239], v[24:27]
	v_mfma_f32_16x16x32_bf16 v[20:23], v[204:207], v[228:231], v[20:23]
	v_mfma_f32_16x16x32_bf16 v[16:19], v[204:207], v[236:239], v[16:19]
	v_mfma_f32_16x16x32_bf16 v[12:15], v[212:215], v[228:231], v[12:15]
	v_mfma_f32_16x16x32_bf16 v[8:11], v[212:215], v[236:239], v[8:11]
	v_mfma_f32_16x16x32_bf16 v[4:7], v[220:223], v[228:231], v[4:7]
	v_mfma_f32_16x16x32_bf16 v[0:3], v[220:223], v[236:239], v[0:3]
	s_setprio 0
	s_add_i32 s11, s11, 2
	s_add_u32 s18, s18, 0x100
	s_addc_u32 s19, s19, 0
	s_add_u32 s20, s20, 0x100
	s_addc_u32 s21, s21, 0
	s_cmp_lt_u32 s11, 12
	s_cbranch_scc1 .Lkh_1232
	s_barrier
	v_readfirstlane_b32 s11, v159
	v_lshl_add_u64 v[174:175], v[128:129], 0, s[54:55]
	s_mov_b32 m0, s11
	v_readfirstlane_b32 s11, v160
	ds_read_b128 v[142:145], v158
	ds_read_b128 v[148:151], v158 offset:1024
	ds_read_b128 v[152:155], v158 offset:2048
	ds_read_b128 v[162:165], v158 offset:3072
	ds_read_b128 v[166:169], v140
	ds_read_b128 v[170:173], v140 offset:1024
	ds_read_b128 v[178:181], v139
	ds_read_b128 v[192:195], v139 offset:1024
	ds_read_b128 v[196:199], v138
	ds_read_b128 v[200:203], v138 offset:1024
	ds_read_b128 v[204:207], v137
	ds_read_b128 v[208:211], v137 offset:1024
	global_load_lds_dwordx4 v[174:175], off
	v_lshl_add_u64 v[128:129], v[128:129], 0, s[56:57]
	s_mov_b32 m0, s11
	s_nop 0
	global_load_lds_dwordx4 v[128:129], off
	s_barrier
	s_waitcnt lgkmcnt(0)
	s_setprio 1
	s_waitcnt lgkmcnt(0)
	v_mfma_f32_16x16x32_bf16 v[124:127], v[166:169], v[142:145], v[124:127]
	v_mfma_f32_16x16x32_bf16 v[120:123], v[166:169], v[152:155], v[120:123]
	v_mfma_f32_16x16x32_bf16 v[116:119], v[178:181], v[142:145], v[116:119]
	v_mfma_f32_16x16x32_bf16 v[112:115], v[178:181], v[152:155], v[112:115]
	v_mfma_f32_16x16x32_bf16 v[124:127], v[170:173], v[148:151], v[124:127]
	v_mfma_f32_16x16x32_bf16 v[120:123], v[170:173], v[162:165], v[120:123]
	v_mfma_f32_16x16x32_bf16 v[116:119], v[192:195], v[148:151], v[116:119]
	v_mfma_f32_16x16x32_bf16 v[112:115], v[192:195], v[162:165], v[112:115]
	v_mfma_f32_16x16x32_bf16 v[108:111], v[196:199], v[142:145], v[108:111]
	v_mfma_f32_16x16x32_bf16 v[104:107], v[196:199], v[152:155], v[104:107]
	v_mfma_f32_16x16x32_bf16 v[100:103], v[204:207], v[142:145], v[100:103]
	v_mfma_f32_16x16x32_bf16 v[96:99], v[204:207], v[152:155], v[96:99]
	v_mfma_f32_16x16x32_bf16 v[158:161], v[200:203], v[148:151], v[108:111]
	v_mfma_f32_16x16x32_bf16 v[212:215], v[200:203], v[162:165], v[104:107]
	v_mfma_f32_16x16x32_bf16 v[216:219], v[208:211], v[148:151], v[100:103]
	v_mfma_f32_16x16x32_bf16 v[220:223], v[208:211], v[162:165], v[96:99]
	s_setprio 0
	s_barrier
	s_nop 1
	ds_read_b128 v[96:99], v157
	ds_read_b128 v[100:103], v157 offset:1024
	ds_read_b128 v[104:107], v157 offset:2048
	ds_read_b128 v[108:111], v157 offset:3072
	s_barrier
	s_waitcnt lgkmcnt(0)
	s_setprio 1
	s_waitcnt lgkmcnt(0)
	v_mfma_f32_16x16x32_bf16 v[92:95], v[166:169], v[96:99], v[92:95]
	v_mfma_f32_16x16x32_bf16 v[88:91], v[166:169], v[104:107], v[88:91]
	v_mfma_f32_16x16x32_bf16 v[84:87], v[178:181], v[96:99], v[84:87]
	v_mfma_f32_16x16x32_bf16 v[80:83], v[178:181], v[104:107], v[80:83]
	v_mfma_f32_16x16x32_bf16 v[92:95], v[170:173], v[100:103], v[92:95]
	v_mfma_f32_16x16x32_bf16 v[88:91], v[170:173], v[108:111], v[88:91]
	v_mfma_f32_16x16x32_bf16 v[84:87], v[192:195], v[100:103], v[84:87]
	v_mfma_f32_16x16x32_bf16 v[80:83], v[192:195], v[108:111], v[80:83]
	v_mfma_f32_16x16x32_bf16 v[76:79], v[196:199], v[96:99], v[76:79]
	v_mfma_f32_16x16x32_bf16 v[72:75], v[196:199], v[104:107], v[72:75]
	v_mfma_f32_16x16x32_bf16 v[68:71], v[204:207], v[96:99], v[68:71]
	v_mfma_f32_16x16x32_bf16 v[64:67], v[204:207], v[104:107], v[64:67]
	v_mfma_f32_16x16x32_bf16 v[166:169], v[200:203], v[100:103], v[76:79]
	v_mfma_f32_16x16x32_bf16 v[170:173], v[200:203], v[108:111], v[72:75]
	v_mfma_f32_16x16x32_bf16 v[178:181], v[208:211], v[100:103], v[68:71]
	v_mfma_f32_16x16x32_bf16 v[192:195], v[208:211], v[108:111], v[64:67]
	s_setprio 0
	s_barrier
	s_nop 1
	ds_read_b128 v[64:67], v140 offset:16384
	ds_read_b128 v[68:71], v140 offset:17408
	ds_read_b128 v[72:75], v139 offset:16384
	ds_read_b128 v[76:79], v139 offset:17408
	ds_read_b128 v[196:199], v138 offset:16384
	ds_read_b128 v[200:203], v138 offset:17408
	ds_read_b128 v[204:207], v137 offset:16384
	ds_read_b128 v[208:211], v137 offset:17408
	s_waitcnt vmcnt(4)
	s_barrier
	s_waitcnt lgkmcnt(0)
	s_setprio 1
	s_waitcnt lgkmcnt(0)
	v_mfma_f32_16x16x32_bf16 v[60:63], v[64:67], v[142:145], v[60:63]
	v_mfma_f32_16x16x32_bf16 v[56:59], v[64:67], v[152:155], v[56:59]
	v_mfma_f32_16x16x32_bf16 v[52:55], v[72:75], v[142:145], v[52:55]
	v_mfma_f32_16x16x32_bf16 v[48:51], v[72:75], v[152:155], v[48:51]
	v_mfma_f32_16x16x32_bf16 v[60:63], v[68:71], v[148:151], v[60:63]
	v_mfma_f32_16x16x32_bf16 v[56:59], v[68:71], v[162:165], v[56:59]
	v_mfma_f32_16x16x32_bf16 v[52:55], v[76:79], v[148:151], v[52:55]
	v_mfma_f32_16x16x32_bf16 v[48:51], v[76:79], v[162:165], v[48:51]
	v_mfma_f32_16x16x32_bf16 v[44:47], v[196:199], v[142:145], v[44:47]
	v_mfma_f32_16x16x32_bf16 v[40:43], v[196:199], v[152:155], v[40:43]
	v_mfma_f32_16x16x32_bf16 v[36:39], v[204:207], v[142:145], v[36:39]
	v_mfma_f32_16x16x32_bf16 v[32:35], v[204:207], v[152:155], v[32:35]
	v_mfma_f32_16x16x32_bf16 v[224:227], v[200:203], v[148:151], v[44:47]
	v_mfma_f32_16x16x32_bf16 v[228:231], v[200:203], v[162:165], v[40:43]
	v_mfma_f32_16x16x32_bf16 v[142:145], v[208:211], v[148:151], v[36:39]
	v_mfma_f32_16x16x32_bf16 v[148:151], v[208:211], v[162:165], v[32:35]
	s_setprio 0
	s_setprio 1
	v_mfma_f32_16x16x32_bf16 v[28:31], v[64:67], v[96:99], v[28:31]
	v_mfma_f32_16x16x32_bf16 v[24:27], v[64:67], v[104:107], v[24:27]
	v_mfma_f32_16x16x32_bf16 v[20:23], v[72:75], v[96:99], v[20:23]
	v_mfma_f32_16x16x32_bf16 v[16:19], v[72:75], v[104:107], v[16:19]
	v_mfma_f32_16x16x32_bf16 v[28:31], v[68:71], v[100:103], v[28:31]
	v_mfma_f32_16x16x32_bf16 v[24:27], v[68:71], v[108:111], v[24:27]
	v_mfma_f32_16x16x32_bf16 v[20:23], v[76:79], v[100:103], v[20:23]
	v_mfma_f32_16x16x32_bf16 v[16:19], v[76:79], v[108:111], v[16:19]
	v_mfma_f32_16x16x32_bf16 v[12:15], v[196:199], v[96:99], v[12:15]
	v_mfma_f32_16x16x32_bf16 v[8:11], v[196:199], v[104:107], v[8:11]
	v_mfma_f32_16x16x32_bf16 v[4:7], v[204:207], v[96:99], v[4:7]
	v_mfma_f32_16x16x32_bf16 v[0:3], v[204:207], v[104:107], v[0:3]
	v_mfma_f32_16x16x32_bf16 v[152:155], v[200:203], v[100:103], v[12:15]
	v_mfma_f32_16x16x32_bf16 v[162:165], v[200:203], v[108:111], v[8:11]
	v_mfma_f32_16x16x32_bf16 v[196:199], v[208:211], v[100:103], v[4:7]
	v_mfma_f32_16x16x32_bf16 v[200:203], v[208:211], v[108:111], v[0:3]
	s_setprio 0
	s_barrier
	s_nop 1
	ds_read_b128 v[0:3], v146
	ds_read_b128 v[4:7], v146 offset:1024
	ds_read_b128 v[204:207], v146 offset:2048
	ds_read_b128 v[208:211], v146 offset:3072
	ds_read_b128 v[8:11], v140 offset:32768
	ds_read_b128 v[12:15], v140 offset:33792
	ds_read_b128 v[32:35], v139 offset:32768
	ds_read_b128 v[36:39], v139 offset:33792
	ds_read_b128 v[40:43], v138 offset:32768
	ds_read_b128 v[44:47], v138 offset:33792
	ds_read_b128 v[232:235], v137 offset:32768
	ds_read_b128 v[236:239], v137 offset:33792
	s_waitcnt vmcnt(2)
	s_barrier
	s_waitcnt lgkmcnt(0)
	s_setprio 1
	s_waitcnt lgkmcnt(0)
	v_mfma_f32_16x16x32_bf16 v[64:67], v[8:11], v[0:3], v[124:127]
	v_mfma_f32_16x16x32_bf16 v[104:107], v[12:15], v[4:7], v[64:67]
	v_mfma_f32_16x16x32_bf16 v[64:67], v[8:11], v[204:207], v[120:123]
	v_mfma_f32_16x16x32_bf16 v[108:111], v[12:15], v[208:211], v[64:67]
	v_mfma_f32_16x16x32_bf16 v[64:67], v[32:35], v[0:3], v[116:119]
	v_mfma_f32_16x16x32_bf16 v[96:99], v[36:39], v[4:7], v[64:67]
	v_mfma_f32_16x16x32_bf16 v[64:67], v[32:35], v[204:207], v[112:115]
	v_mfma_f32_16x16x32_bf16 v[100:103], v[36:39], v[208:211], v[64:67]
	v_mfma_f32_16x16x32_bf16 v[64:67], v[40:43], v[0:3], v[158:161]
	v_mfma_f32_16x16x32_bf16 v[72:75], v[44:47], v[4:7], v[64:67]
	v_mfma_f32_16x16x32_bf16 v[64:67], v[40:43], v[204:207], v[212:215]
	v_mfma_f32_16x16x32_bf16 v[76:79], v[44:47], v[208:211], v[64:67]
	v_mfma_f32_16x16x32_bf16 v[64:67], v[232:235], v[0:3], v[216:219]
	v_mfma_f32_16x16x32_bf16 v[68:71], v[232:235], v[204:207], v[220:223]
	v_mfma_f32_16x16x32_bf16 v[64:67], v[236:239], v[4:7], v[64:67]
	v_mfma_f32_16x16x32_bf16 v[68:71], v[236:239], v[208:211], v[68:71]
	s_setprio 0
	s_barrier
	ds_read_b128 v[156:159], v141
	ds_read_b128 v[212:215], v141 offset:1024
	ds_read_b128 v[216:219], v141 offset:2048
	ds_read_b128 v[220:223], v141 offset:3072
	s_waitcnt vmcnt(0)
	s_barrier
	s_waitcnt lgkmcnt(0)
	s_setprio 1
	s_waitcnt lgkmcnt(0)
	v_mfma_f32_16x16x32_bf16 v[92:95], v[8:11], v[156:159], v[92:95]
	v_mfma_f32_16x16x32_bf16 v[8:11], v[8:11], v[216:219], v[88:91]
	v_mfma_f32_16x16x32_bf16 v[124:127], v[12:15], v[220:223], v[8:11]
	v_mfma_f32_16x16x32_bf16 v[8:11], v[32:35], v[156:159], v[84:87]
	v_mfma_f32_16x16x32_bf16 v[112:115], v[36:39], v[212:215], v[8:11]
	v_mfma_f32_16x16x32_bf16 v[8:11], v[32:35], v[216:219], v[80:83]
	v_mfma_f32_16x16x32_bf16 v[116:119], v[36:39], v[220:223], v[8:11]
	v_mfma_f32_16x16x32_bf16 v[8:11], v[40:43], v[156:159], v[166:169]
	v_mfma_f32_16x16x32_bf16 v[88:91], v[44:47], v[212:215], v[8:11]
	v_mfma_f32_16x16x32_bf16 v[8:11], v[40:43], v[216:219], v[170:173]
	v_mfma_f32_16x16x32_bf16 v[120:123], v[12:15], v[212:215], v[92:95]
	v_mfma_f32_16x16x32_bf16 v[92:95], v[44:47], v[220:223], v[8:11]
	v_mfma_f32_16x16x32_bf16 v[8:11], v[232:235], v[156:159], v[178:181]
	v_mfma_f32_16x16x32_bf16 v[80:83], v[236:239], v[212:215], v[8:11]
	v_mfma_f32_16x16x32_bf16 v[8:11], v[232:235], v[216:219], v[192:195]
	v_mfma_f32_16x16x32_bf16 v[84:87], v[236:239], v[220:223], v[8:11]
	s_setprio 0
	s_barrier
	ds_read_b128 v[166:169], v140 offset:49152
	ds_read_b128 v[170:173], v140 offset:50176
	ds_read_b128 v[178:181], v139 offset:49152
	ds_read_b128 v[192:195], v139 offset:50176
	ds_read_b128 v[232:235], v138 offset:49152
	ds_read_b128 v[138:141], v138 offset:50176
	ds_read_b128 v[236:239], v137 offset:49152
	ds_read_b128 v[240:243], v137 offset:50176
	s_barrier
	s_waitcnt lgkmcnt(0)
	s_setprio 1
	s_waitcnt lgkmcnt(0)
	v_mfma_f32_16x16x32_bf16 v[8:11], v[166:169], v[0:3], v[60:63]
	v_mfma_f32_16x16x32_bf16 v[40:43], v[170:173], v[4:7], v[8:11]
	v_mfma_f32_16x16x32_bf16 v[8:11], v[166:169], v[204:207], v[56:59]
	v_mfma_f32_16x16x32_bf16 v[44:47], v[170:173], v[208:211], v[8:11]
	v_mfma_f32_16x16x32_bf16 v[8:11], v[178:181], v[0:3], v[52:55]
	v_mfma_f32_16x16x32_bf16 v[32:35], v[192:195], v[4:7], v[8:11]
	v_mfma_f32_16x16x32_bf16 v[8:11], v[178:181], v[204:207], v[48:51]
	v_mfma_f32_16x16x32_bf16 v[36:39], v[192:195], v[208:211], v[8:11]
	v_mfma_f32_16x16x32_bf16 v[8:11], v[232:235], v[0:3], v[224:227]
	v_mfma_f32_16x16x32_bf16 v[0:3], v[236:239], v[0:3], v[142:145]
	v_mfma_f32_16x16x32_bf16 v[8:11], v[138:141], v[4:7], v[8:11]
	v_mfma_f32_16x16x32_bf16 v[12:15], v[232:235], v[204:207], v[228:231]
	v_mfma_f32_16x16x32_bf16 v[0:3], v[240:243], v[4:7], v[0:3]
	v_mfma_f32_16x16x32_bf16 v[4:7], v[236:239], v[204:207], v[148:151]
	v_mfma_f32_16x16x32_bf16 v[12:15], v[138:141], v[208:211], v[12:15]
	v_mfma_f32_16x16x32_bf16 v[4:7], v[240:243], v[208:211], v[4:7]
	s_setprio 0
	s_setprio 1
	v_mfma_f32_16x16x32_bf16 v[16:19], v[178:181], v[216:219], v[16:19]
	v_mfma_f32_16x16x32_bf16 v[24:27], v[166:169], v[216:219], v[24:27]
	v_mfma_f32_16x16x32_bf16 v[52:55], v[192:195], v[220:223], v[16:19]
	v_mfma_f32_16x16x32_bf16 v[16:19], v[232:235], v[156:159], v[152:155]
	v_mfma_f32_16x16x32_bf16 v[28:31], v[166:169], v[156:159], v[28:31]
	v_mfma_f32_16x16x32_bf16 v[60:63], v[170:173], v[220:223], v[24:27]
	v_mfma_f32_16x16x32_bf16 v[20:23], v[178:181], v[156:159], v[20:23]
	v_mfma_f32_16x16x32_bf16 v[24:27], v[138:141], v[212:215], v[16:19]
	v_mfma_f32_16x16x32_bf16 v[16:19], v[232:235], v[216:219], v[162:165]
	v_mfma_f32_16x16x32_bf16 v[56:59], v[170:173], v[212:215], v[28:31]
	v_mfma_f32_16x16x32_bf16 v[48:51], v[192:195], v[212:215], v[20:23]
	v_mfma_f32_16x16x32_bf16 v[28:31], v[138:141], v[220:223], v[16:19]
	v_mfma_f32_16x16x32_bf16 v[16:19], v[236:239], v[156:159], v[196:199]
	v_mfma_f32_16x16x32_bf16 v[20:23], v[236:239], v[216:219], v[200:203]
	v_mfma_f32_16x16x32_bf16 v[16:19], v[240:243], v[212:215], v[16:19]
	v_mfma_f32_16x16x32_bf16 v[20:23], v[240:243], v[220:223], v[20:23]
	s_setprio 0
	v_cmp_gt_u32_e32 vcc, s2, v130
	s_barrier
	s_and_saveexec_b64 s[18:19], vcc
	s_cbranch_execz .LBB0_1228
	s_barrier
	s_branch .LBB0_1228

.LBB0_1407:
	s_or_b64 exec, exec, s[30:31]
	v_add_u32_e32 v151, s15, v3
	v_lshl_add_u64 v[6:7], s[28:29], 0, v[176:177]
	v_readfirstlane_b32 s12, v151
	v_add_u32_e32 v152, 0x2000, v151
	v_lshl_add_u64 v[8:9], v[6:7], 0, s[46:47]
	s_mov_b32 m0, s12
	v_readfirstlane_b32 s12, v152
	v_add_u32_e32 v153, 0x8000, v137
	s_waitcnt vmcnt(0)
	s_barrier
	global_load_lds_dwordx4 v[8:9], off
	v_lshl_add_u64 v[8:9], v[6:7], 0, s[48:49]
	s_mov_b32 m0, s12
	v_lshl_add_u64 v[128:129], s[26:27], 0, v[176:177]
	v_readfirstlane_b32 s12, v153
	v_add_u32_e32 v154, 0xa000, v137
	global_load_lds_dwordx4 v[8:9], off
	v_lshl_add_u64 v[8:9], v[128:129], 0, s[46:47]
	s_mov_b32 m0, s12
	v_readfirstlane_b32 s12, v154
	global_load_lds_dwordx4 v[8:9], off
	v_lshl_add_u64 v[8:9], v[128:129], 0, s[48:49]
	s_mov_b32 m0, s12
	s_mov_b64 s[12:13], 0x40080
	v_add_u32_e32 v155, s36, v3
	global_load_lds_dwordx4 v[8:9], off
	v_lshl_add_u64 v[8:9], v[6:7], 0, s[12:13]
	v_readfirstlane_b32 s12, v155
	v_add_u32_e32 v156, 0x2000, v155
	s_mov_b32 m0, s12
	v_readfirstlane_b32 s12, v156
	global_load_lds_dwordx4 v[8:9], off
	v_lshl_add_u64 v[6:7], v[6:7], 0, s[52:53]
	s_mov_b32 m0, s12
	v_and_b32_e32 v139, 15, v142
	global_load_lds_dwordx4 v[6:7], off
	v_bfe_u32 v134, v142, 4, 2
	v_lshlrev_b32_e32 v143, 2, v142
	v_lshlrev_b32_e32 v14, 8, v142
	v_ashrrev_i32_e32 v141, 6, v142
	v_lshlrev_b32_e32 v5, 4, v134
	v_lshlrev_b32_e32 v6, 6, v139
	v_and_b32_e32 v7, 32, v143
	v_lshlrev_b32_e32 v12, 6, v142
	v_and_b32_e32 v14, 0xffff8000, v14
	v_lshlrev_b32_e32 v0, 11, v0
	s_add_u32 s24, s22, s24
	v_and_b32_e32 v140, 3, v141
	s_waitcnt vmcnt(6)
	v_bitop3_b32 v6, v5, v7, v6 bitop3:0x36
	v_lshlrev_b32_e32 v144, 6, v4
	v_lshlrev_b32_e32 v4, 13, v4
	v_and_or_b32 v5, v12, s33, v5
	v_or3_b32 v0, v1, v14, v0
	s_addc_u32 s25, s23, s25
	v_lshlrev_b32_e32 v3, 12, v140
	v_add_u32_e32 v8, s35, v6
	v_add_u32_e32 v9, s14, v6
	v_add_u32_e32 v10, s15, v6
	v_add_u32_e32 v11, s36, v6
	v_add_u32_e32 v6, 16, v6
	v_xad_u32 v5, v5, v7, 16
	v_or_b32_e32 v7, 0x800, v4
	v_or_b32_e32 v12, 0x1000, v4
	v_or_b32_e32 v13, 0x1800, v4
	v_add_u32_e32 v130, v0, v2
	s_add_u32 s26, s22, s78
	v_mov_b32_e32 v0, 0
	v_mov_b32_e32 v131, v177
	s_addc_u32 s27, s23, 0
	s_mov_b32 s28, -2
	v_add_u32_e32 v158, v8, v3
	v_add_u32_e32 v148, v6, v4
	v_add_u32_e32 v147, v5, v7
	v_add_u32_e32 v146, v5, v12
	v_add_u32_e32 v145, v5, v13
	v_add_u32_e32 v157, v9, v3
	v_add_u32_e32 v150, v10, v3
	v_add_u32_e32 v149, v11, v3
	v_mov_b32_e32 v1, v0
	v_mov_b32_e32 v2, v0
	v_mov_b32_e32 v3, v0
	v_mov_b32_e32 v4, v0
	v_mov_b32_e32 v5, v0
	v_mov_b32_e32 v6, v0
	v_mov_b32_e32 v7, v0
	v_mov_b32_e32 v8, v0
	v_mov_b32_e32 v9, v0
	v_mov_b32_e32 v10, v0
	v_mov_b32_e32 v11, v0
	v_mov_b32_e32 v12, v0
	v_mov_b32_e32 v13, v0
	v_mov_b32_e32 v14, v0
	v_mov_b32_e32 v15, v0
	v_mov_b32_e32 v16, v0
	v_mov_b32_e32 v17, v0
	v_mov_b32_e32 v18, v0
	v_mov_b32_e32 v19, v0
	v_mov_b32_e32 v20, v0
	v_mov_b32_e32 v21, v0
	v_mov_b32_e32 v22, v0
	v_mov_b32_e32 v23, v0
	v_mov_b32_e32 v24, v0
	v_mov_b32_e32 v25, v0
	v_mov_b32_e32 v26, v0
	v_mov_b32_e32 v27, v0
	v_mov_b32_e32 v28, v0
	v_mov_b32_e32 v29, v0
	v_mov_b32_e32 v30, v0
	v_mov_b32_e32 v31, v0
	v_mov_b32_e32 v32, v0
	v_mov_b32_e32 v33, v0
	v_mov_b32_e32 v34, v0
	v_mov_b32_e32 v35, v0
	v_mov_b32_e32 v36, v0
	v_mov_b32_e32 v37, v0
	v_mov_b32_e32 v38, v0
	v_mov_b32_e32 v39, v0
	v_mov_b32_e32 v40, v0
	v_mov_b32_e32 v41, v0
	v_mov_b32_e32 v42, v0
	v_mov_b32_e32 v43, v0
	v_mov_b32_e32 v44, v0
	v_mov_b32_e32 v45, v0
	v_mov_b32_e32 v46, v0
	v_mov_b32_e32 v47, v0
	v_mov_b32_e32 v48, v0
	v_mov_b32_e32 v49, v0
	v_mov_b32_e32 v50, v0
	v_mov_b32_e32 v51, v0
	v_mov_b32_e32 v52, v0
	v_mov_b32_e32 v53, v0
	v_mov_b32_e32 v54, v0
	v_mov_b32_e32 v55, v0
	v_mov_b32_e32 v56, v0
	v_mov_b32_e32 v57, v0
	v_mov_b32_e32 v58, v0
	v_mov_b32_e32 v59, v0
	v_mov_b32_e32 v60, v0
	v_mov_b32_e32 v61, v0
	v_mov_b32_e32 v62, v0
	v_mov_b32_e32 v63, v0
	v_mov_b32_e32 v64, v0
	v_mov_b32_e32 v65, v0
	v_mov_b32_e32 v66, v0
	v_mov_b32_e32 v67, v0
	v_mov_b32_e32 v68, v0
	v_mov_b32_e32 v69, v0
	v_mov_b32_e32 v70, v0
	v_mov_b32_e32 v71, v0
	v_mov_b32_e32 v72, v0
	v_mov_b32_e32 v73, v0
	v_mov_b32_e32 v74, v0
	v_mov_b32_e32 v75, v0
	v_mov_b32_e32 v76, v0
	v_mov_b32_e32 v77, v0
	v_mov_b32_e32 v78, v0
	v_mov_b32_e32 v79, v0
	v_mov_b32_e32 v80, v0
	v_mov_b32_e32 v81, v0
	v_mov_b32_e32 v82, v0
	v_mov_b32_e32 v83, v0
	v_mov_b32_e32 v84, v0
	v_mov_b32_e32 v85, v0
	v_mov_b32_e32 v86, v0
	v_mov_b32_e32 v87, v0
	v_mov_b32_e32 v88, v0
	v_mov_b32_e32 v89, v0
	v_mov_b32_e32 v90, v0
	v_mov_b32_e32 v91, v0
	v_mov_b32_e32 v92, v0
	v_mov_b32_e32 v93, v0
	v_mov_b32_e32 v94, v0
	v_mov_b32_e32 v95, v0
	v_mov_b32_e32 v96, v0
	v_mov_b32_e32 v97, v0
	v_mov_b32_e32 v98, v0
	v_mov_b32_e32 v99, v0
	v_mov_b32_e32 v100, v0
	v_mov_b32_e32 v101, v0
	v_mov_b32_e32 v102, v0
	v_mov_b32_e32 v103, v0
	v_mov_b32_e32 v104, v0
	v_mov_b32_e32 v105, v0
	v_mov_b32_e32 v106, v0
	v_mov_b32_e32 v107, v0
	v_mov_b32_e32 v108, v0
	v_mov_b32_e32 v109, v0
	v_mov_b32_e32 v110, v0
	v_mov_b32_e32 v111, v0
	v_mov_b32_e32 v112, v0
	v_mov_b32_e32 v113, v0
	v_mov_b32_e32 v114, v0
	v_mov_b32_e32 v115, v0
	v_mov_b32_e32 v116, v0
	v_mov_b32_e32 v117, v0
	v_mov_b32_e32 v118, v0
	v_mov_b32_e32 v119, v0
	v_mov_b32_e32 v120, v0
	v_mov_b32_e32 v121, v0
	v_mov_b32_e32 v122, v0
	v_mov_b32_e32 v123, v0
	v_mov_b32_e32 v124, v0
	v_mov_b32_e32 v125, v0
	v_mov_b32_e32 v126, v0
	v_mov_b32_e32 v127, v0
.Lkh_1408:
	s_barrier
.LBB0_1408:
	ds_read_b128 v[164:167], v158
	ds_read_b128 v[168:171], v158 offset:1024
	ds_read_b128 v[172:175], v158 offset:2048
	ds_read_b128 v[178:181], v158 offset:3072
	v_lshl_add_u64 v[240:241], s[24:25], 0, v[130:131]
	s_mov_b64 s[12:13], 0x366c180
	v_add_u32_e32 v161, 0xc000, v137
	v_lshl_add_u64 v[162:163], v[240:241], 0, s[12:13]
	v_readfirstlane_b32 s12, v161
	s_mov_b32 m0, s12
	ds_read_b128 v[192:195], v148
	ds_read_b128 v[196:199], v148 offset:1024
	ds_read_b128 v[200:203], v147
	ds_read_b128 v[204:207], v147 offset:1024
	ds_read_b128 v[208:211], v146
	ds_read_b128 v[212:215], v146 offset:1024
	ds_read_b128 v[216:219], v145
	ds_read_b128 v[220:223], v145 offset:1024
	global_load_lds_dwordx4 v[162:163], off
	s_mov_b64 s[12:13], 0x368c180
	v_add_u32_e32 v162, 0xe000, v137
	v_lshl_add_u64 v[224:225], v[240:241], 0, s[12:13]
	v_readfirstlane_b32 s12, v162
	s_mov_b32 m0, s12
	s_nop 0
	global_load_lds_dwordx4 v[224:225], off
	s_waitcnt lgkmcnt(8)
	s_barrier
	s_waitcnt lgkmcnt(0)
	s_setprio 1
	s_waitcnt lgkmcnt(0)
	v_mfma_f32_16x16x32_bf16 v[124:127], v[192:195], v[164:167], v[124:127]
	v_mfma_f32_16x16x32_bf16 v[120:123], v[192:195], v[172:175], v[120:123]
	v_mfma_f32_16x16x32_bf16 v[116:119], v[200:203], v[164:167], v[116:119]
	v_mfma_f32_16x16x32_bf16 v[112:115], v[200:203], v[172:175], v[112:115]
	v_mfma_f32_16x16x32_bf16 v[108:111], v[208:211], v[164:167], v[108:111]
	v_mfma_f32_16x16x32_bf16 v[104:107], v[208:211], v[172:175], v[104:107]
	v_mfma_f32_16x16x32_bf16 v[100:103], v[216:219], v[164:167], v[100:103]
	v_mfma_f32_16x16x32_bf16 v[96:99], v[216:219], v[172:175], v[96:99]
	v_mfma_f32_16x16x32_bf16 v[124:127], v[196:199], v[168:171], v[124:127]
	v_mfma_f32_16x16x32_bf16 v[120:123], v[196:199], v[178:181], v[120:123]
	v_mfma_f32_16x16x32_bf16 v[116:119], v[204:207], v[168:171], v[116:119]
	v_mfma_f32_16x16x32_bf16 v[112:115], v[204:207], v[178:181], v[112:115]
	v_mfma_f32_16x16x32_bf16 v[108:111], v[212:215], v[168:171], v[108:111]
	v_mfma_f32_16x16x32_bf16 v[104:107], v[212:215], v[178:181], v[104:107]
	v_mfma_f32_16x16x32_bf16 v[100:103], v[220:223], v[168:171], v[100:103]
	v_mfma_f32_16x16x32_bf16 v[96:99], v[220:223], v[178:181], v[96:99]
	s_setprio 0
	s_barrier
	v_lshl_add_u64 v[242:243], s[26:27], 0, v[130:131]
	s_mov_b64 s[12:13], 0x1d00100
	v_lshl_add_u64 v[244:245], v[242:243], 0, s[12:13]
	v_readfirstlane_b32 s12, v138
	s_mov_b32 m0, s12
	s_mov_b64 s[12:13], 0x1d20100
	v_add_u32_e32 v159, 0x2000, v138
	ds_read_b128 v[224:227], v157
	ds_read_b128 v[228:231], v157 offset:1024
	ds_read_b128 v[232:235], v157 offset:2048
	ds_read_b128 v[236:239], v157 offset:3072
	global_load_lds_dwordx4 v[244:245], off
	v_lshl_add_u64 v[244:245], v[242:243], 0, s[12:13]
	v_readfirstlane_b32 s12, v159
	s_mov_b32 m0, s12
	s_nop 0
	global_load_lds_dwordx4 v[244:245], off
	s_barrier
	s_waitcnt lgkmcnt(0)
	s_setprio 1
	s_waitcnt lgkmcnt(0)
	v_mfma_f32_16x16x32_bf16 v[92:95], v[192:195], v[224:227], v[92:95]
	v_mfma_f32_16x16x32_bf16 v[88:91], v[192:195], v[232:235], v[88:91]
	v_mfma_f32_16x16x32_bf16 v[84:87], v[200:203], v[224:227], v[84:87]
	v_mfma_f32_16x16x32_bf16 v[80:83], v[200:203], v[232:235], v[80:83]
	v_mfma_f32_16x16x32_bf16 v[76:79], v[208:211], v[224:227], v[76:79]
	v_mfma_f32_16x16x32_bf16 v[72:75], v[208:211], v[232:235], v[72:75]
	v_mfma_f32_16x16x32_bf16 v[68:71], v[216:219], v[224:227], v[68:71]
	v_mfma_f32_16x16x32_bf16 v[64:67], v[216:219], v[232:235], v[64:67]
	v_mfma_f32_16x16x32_bf16 v[92:95], v[196:199], v[228:231], v[92:95]
	v_mfma_f32_16x16x32_bf16 v[88:91], v[196:199], v[236:239], v[88:91]
	v_mfma_f32_16x16x32_bf16 v[84:87], v[204:207], v[228:231], v[84:87]
	v_mfma_f32_16x16x32_bf16 v[80:83], v[204:207], v[236:239], v[80:83]
	v_mfma_f32_16x16x32_bf16 v[76:79], v[212:215], v[228:231], v[76:79]
	v_mfma_f32_16x16x32_bf16 v[72:75], v[212:215], v[236:239], v[72:75]
	v_mfma_f32_16x16x32_bf16 v[68:71], v[220:223], v[228:231], v[68:71]
	v_mfma_f32_16x16x32_bf16 v[64:67], v[220:223], v[236:239], v[64:67]
	s_setprio 0
	s_mov_b64 s[12:13], 0x362c200
	v_lshl_add_u64 v[244:245], v[240:241], 0, s[12:13]
	v_readfirstlane_b32 s12, v137
	s_mov_b32 m0, s12
	s_mov_b64 s[12:13], 0x364c200
	s_barrier
	ds_read_b128 v[192:195], v148 offset:16384
	ds_read_b128 v[196:199], v148 offset:17408
	ds_read_b128 v[200:203], v147 offset:16384
	ds_read_b128 v[204:207], v147 offset:17408
	ds_read_b128 v[208:211], v146 offset:16384
	ds_read_b128 v[212:215], v146 offset:17408
	ds_read_b128 v[216:219], v145 offset:16384
	ds_read_b128 v[220:223], v145 offset:17408
	global_load_lds_dwordx4 v[244:245], off
	v_lshl_add_u64 v[244:245], v[240:241], 0, s[12:13]
	v_readfirstlane_b32 s12, v136
	s_mov_b32 m0, s12
	s_nop 0
	global_load_lds_dwordx4 v[244:245], off
	s_barrier
	s_waitcnt lgkmcnt(0)
	s_setprio 1
	s_waitcnt lgkmcnt(0)
	v_mfma_f32_16x16x32_bf16 v[60:63], v[192:195], v[164:167], v[60:63]
	v_mfma_f32_16x16x32_bf16 v[56:59], v[192:195], v[172:175], v[56:59]
	v_mfma_f32_16x16x32_bf16 v[52:55], v[200:203], v[164:167], v[52:55]
	v_mfma_f32_16x16x32_bf16 v[48:51], v[200:203], v[172:175], v[48:51]
	v_mfma_f32_16x16x32_bf16 v[44:47], v[208:211], v[164:167], v[44:47]
	v_mfma_f32_16x16x32_bf16 v[40:43], v[208:211], v[172:175], v[40:43]
	v_mfma_f32_16x16x32_bf16 v[36:39], v[216:219], v[164:167], v[36:39]
	v_mfma_f32_16x16x32_bf16 v[32:35], v[216:219], v[172:175], v[32:35]
	v_mfma_f32_16x16x32_bf16 v[60:63], v[196:199], v[168:171], v[60:63]
	v_mfma_f32_16x16x32_bf16 v[56:59], v[196:199], v[178:181], v[56:59]
	v_mfma_f32_16x16x32_bf16 v[52:55], v[204:207], v[168:171], v[52:55]
	v_mfma_f32_16x16x32_bf16 v[48:51], v[204:207], v[178:181], v[48:51]
	v_mfma_f32_16x16x32_bf16 v[44:47], v[212:215], v[168:171], v[44:47]
	v_mfma_f32_16x16x32_bf16 v[40:43], v[212:215], v[178:181], v[40:43]
	v_mfma_f32_16x16x32_bf16 v[36:39], v[220:223], v[168:171], v[36:39]
	v_mfma_f32_16x16x32_bf16 v[32:35], v[220:223], v[178:181], v[32:35]
	s_setprio 0
	s_barrier
	s_mov_b64 s[12:13], 0x1d40100
	v_lshl_add_u64 v[164:165], v[242:243], 0, s[12:13]
	v_readfirstlane_b32 s12, v135
	s_mov_b32 m0, s12
	s_mov_b64 s[12:13], 0x1d60100
	v_add_u32_e32 v160, 0x2000, v135
	global_load_lds_dwordx4 v[164:165], off
	v_lshl_add_u64 v[164:165], v[242:243], 0, s[12:13]
	v_readfirstlane_b32 s12, v160
	s_mov_b32 m0, s12
	s_nop 0
	global_load_lds_dwordx4 v[164:165], off
	s_waitcnt vmcnt(6)
	s_barrier
	s_setprio 1
	v_mfma_f32_16x16x32_bf16 v[28:31], v[192:195], v[224:227], v[28:31]
	v_mfma_f32_16x16x32_bf16 v[24:27], v[192:195], v[232:235], v[24:27]
	v_mfma_f32_16x16x32_bf16 v[20:23], v[200:203], v[224:227], v[20:23]
	v_mfma_f32_16x16x32_bf16 v[16:19], v[200:203], v[232:235], v[16:19]
	v_mfma_f32_16x16x32_bf16 v[12:15], v[208:211], v[224:227], v[12:15]
	v_mfma_f32_16x16x32_bf16 v[8:11], v[208:211], v[232:235], v[8:11]
	v_mfma_f32_16x16x32_bf16 v[4:7], v[216:219], v[224:227], v[4:7]
	v_mfma_f32_16x16x32_bf16 v[0:3], v[216:219], v[232:235], v[0:3]
	v_mfma_f32_16x16x32_bf16 v[28:31], v[196:199], v[228:231], v[28:31]
	v_mfma_f32_16x16x32_bf16 v[24:27], v[196:199], v[236:239], v[24:27]
	v_mfma_f32_16x16x32_bf16 v[20:23], v[204:207], v[228:231], v[20:23]
	v_mfma_f32_16x16x32_bf16 v[16:19], v[204:207], v[236:239], v[16:19]
	v_mfma_f32_16x16x32_bf16 v[12:15], v[212:215], v[228:231], v[12:15]
	v_mfma_f32_16x16x32_bf16 v[8:11], v[212:215], v[236:239], v[8:11]
	v_mfma_f32_16x16x32_bf16 v[4:7], v[220:223], v[228:231], v[4:7]
	v_mfma_f32_16x16x32_bf16 v[0:3], v[220:223], v[236:239], v[0:3]
	s_setprio 0
	s_barrier
	ds_read_b128 v[164:167], v150
	ds_read_b128 v[168:171], v150 offset:1024
	ds_read_b128 v[172:175], v150 offset:2048
	ds_read_b128 v[178:181], v150 offset:3072
	s_mov_b64 s[12:13], 0x366c200
	v_lshl_add_u64 v[224:225], v[240:241], 0, s[12:13]
	v_readfirstlane_b32 s12, v133
	s_mov_b32 m0, s12
	s_mov_b64 s[12:13], 0x368c200
	ds_read_b128 v[192:195], v148 offset:32768
	ds_read_b128 v[196:199], v148 offset:33792
	ds_read_b128 v[200:203], v147 offset:32768
	ds_read_b128 v[204:207], v147 offset:33792
	ds_read_b128 v[208:211], v146 offset:32768
	ds_read_b128 v[212:215], v146 offset:33792
	ds_read_b128 v[216:219], v145 offset:32768
	ds_read_b128 v[220:223], v145 offset:33792
	global_load_lds_dwordx4 v[224:225], off
	v_lshl_add_u64 v[224:225], v[240:241], 0, s[12:13]
	v_readfirstlane_b32 s12, v132
	s_mov_b32 m0, s12
	s_nop 0
	global_load_lds_dwordx4 v[224:225], off
	s_waitcnt lgkmcnt(8)
	s_barrier
	s_waitcnt lgkmcnt(0)
	s_setprio 1
	s_waitcnt lgkmcnt(0)
	v_mfma_f32_16x16x32_bf16 v[124:127], v[192:195], v[164:167], v[124:127]
	v_mfma_f32_16x16x32_bf16 v[120:123], v[192:195], v[172:175], v[120:123]
	v_mfma_f32_16x16x32_bf16 v[116:119], v[200:203], v[164:167], v[116:119]
	v_mfma_f32_16x16x32_bf16 v[112:115], v[200:203], v[172:175], v[112:115]
	v_mfma_f32_16x16x32_bf16 v[108:111], v[208:211], v[164:167], v[108:111]
	v_mfma_f32_16x16x32_bf16 v[104:107], v[208:211], v[172:175], v[104:107]
	v_mfma_f32_16x16x32_bf16 v[100:103], v[216:219], v[164:167], v[100:103]
	v_mfma_f32_16x16x32_bf16 v[96:99], v[216:219], v[172:175], v[96:99]
	v_mfma_f32_16x16x32_bf16 v[124:127], v[196:199], v[168:171], v[124:127]
	v_mfma_f32_16x16x32_bf16 v[120:123], v[196:199], v[178:181], v[120:123]
	v_mfma_f32_16x16x32_bf16 v[116:119], v[204:207], v[168:171], v[116:119]
	v_mfma_f32_16x16x32_bf16 v[112:115], v[204:207], v[178:181], v[112:115]
	v_mfma_f32_16x16x32_bf16 v[108:111], v[212:215], v[168:171], v[108:111]
	v_mfma_f32_16x16x32_bf16 v[104:107], v[212:215], v[178:181], v[104:107]
	v_mfma_f32_16x16x32_bf16 v[100:103], v[220:223], v[168:171], v[100:103]
	v_mfma_f32_16x16x32_bf16 v[96:99], v[220:223], v[178:181], v[96:99]
	s_setprio 0
	s_barrier
	s_mov_b64 s[12:13], 0x1d00180
	v_lshl_add_u64 v[244:245], v[242:243], 0, s[12:13]
	v_readfirstlane_b32 s12, v151
	s_mov_b32 m0, s12
	s_mov_b64 s[12:13], 0x1d20180
	ds_read_b128 v[224:227], v149
	ds_read_b128 v[228:231], v149 offset:1024
	ds_read_b128 v[232:235], v149 offset:2048
	ds_read_b128 v[236:239], v149 offset:3072
	global_load_lds_dwordx4 v[244:245], off
	v_lshl_add_u64 v[244:245], v[242:243], 0, s[12:13]
	v_readfirstlane_b32 s12, v152
	s_mov_b32 m0, s12
	s_nop 0
	global_load_lds_dwordx4 v[244:245], off
	s_barrier
	s_waitcnt lgkmcnt(0)
	s_setprio 1
	s_waitcnt lgkmcnt(0)
	v_mfma_f32_16x16x32_bf16 v[92:95], v[192:195], v[224:227], v[92:95]
	v_mfma_f32_16x16x32_bf16 v[88:91], v[192:195], v[232:235], v[88:91]
	v_mfma_f32_16x16x32_bf16 v[84:87], v[200:203], v[224:227], v[84:87]
	v_mfma_f32_16x16x32_bf16 v[80:83], v[200:203], v[232:235], v[80:83]
	v_mfma_f32_16x16x32_bf16 v[76:79], v[208:211], v[224:227], v[76:79]
	v_mfma_f32_16x16x32_bf16 v[72:75], v[208:211], v[232:235], v[72:75]
	v_mfma_f32_16x16x32_bf16 v[68:71], v[216:219], v[224:227], v[68:71]
	v_mfma_f32_16x16x32_bf16 v[64:67], v[216:219], v[232:235], v[64:67]
	v_mfma_f32_16x16x32_bf16 v[92:95], v[196:199], v[228:231], v[92:95]
	v_mfma_f32_16x16x32_bf16 v[88:91], v[196:199], v[236:239], v[88:91]
	v_mfma_f32_16x16x32_bf16 v[84:87], v[204:207], v[228:231], v[84:87]
	v_mfma_f32_16x16x32_bf16 v[80:83], v[204:207], v[236:239], v[80:83]
	v_mfma_f32_16x16x32_bf16 v[76:79], v[212:215], v[228:231], v[76:79]
	v_mfma_f32_16x16x32_bf16 v[72:75], v[212:215], v[236:239], v[72:75]
	v_mfma_f32_16x16x32_bf16 v[68:71], v[220:223], v[228:231], v[68:71]
	v_mfma_f32_16x16x32_bf16 v[64:67], v[220:223], v[236:239], v[64:67]
	s_setprio 0
	s_mov_b64 s[12:13], 0x362c280
	v_lshl_add_u64 v[244:245], v[240:241], 0, s[12:13]
	v_readfirstlane_b32 s12, v153
	s_mov_b32 m0, s12
	s_mov_b64 s[12:13], 0x364c280
	v_lshl_add_u64 v[240:241], v[240:241], 0, s[12:13]
	v_readfirstlane_b32 s12, v154
	s_barrier
	ds_read_b128 v[192:195], v148 offset:49152
	ds_read_b128 v[196:199], v148 offset:50176
	ds_read_b128 v[200:203], v147 offset:49152
	ds_read_b128 v[204:207], v147 offset:50176
	ds_read_b128 v[208:211], v146 offset:49152
	ds_read_b128 v[212:215], v146 offset:50176
	ds_read_b128 v[216:219], v145 offset:49152
	ds_read_b128 v[220:223], v145 offset:50176
	global_load_lds_dwordx4 v[244:245], off
	s_mov_b32 m0, s12
	s_nop 0
	global_load_lds_dwordx4 v[240:241], off
	s_barrier
	s_waitcnt lgkmcnt(0)
	s_setprio 1
	s_waitcnt lgkmcnt(0)
	v_mfma_f32_16x16x32_bf16 v[60:63], v[192:195], v[164:167], v[60:63]
	v_mfma_f32_16x16x32_bf16 v[56:59], v[192:195], v[172:175], v[56:59]
	v_mfma_f32_16x16x32_bf16 v[52:55], v[200:203], v[164:167], v[52:55]
	v_mfma_f32_16x16x32_bf16 v[48:51], v[200:203], v[172:175], v[48:51]
	v_mfma_f32_16x16x32_bf16 v[44:47], v[208:211], v[164:167], v[44:47]
	v_mfma_f32_16x16x32_bf16 v[40:43], v[208:211], v[172:175], v[40:43]
	v_mfma_f32_16x16x32_bf16 v[36:39], v[216:219], v[164:167], v[36:39]
	v_mfma_f32_16x16x32_bf16 v[32:35], v[216:219], v[172:175], v[32:35]
	v_mfma_f32_16x16x32_bf16 v[60:63], v[196:199], v[168:171], v[60:63]
	v_mfma_f32_16x16x32_bf16 v[56:59], v[196:199], v[178:181], v[56:59]
	v_mfma_f32_16x16x32_bf16 v[52:55], v[204:207], v[168:171], v[52:55]
	v_mfma_f32_16x16x32_bf16 v[48:51], v[204:207], v[178:181], v[48:51]
	v_mfma_f32_16x16x32_bf16 v[44:47], v[212:215], v[168:171], v[44:47]
	v_mfma_f32_16x16x32_bf16 v[40:43], v[212:215], v[178:181], v[40:43]
	v_mfma_f32_16x16x32_bf16 v[36:39], v[220:223], v[168:171], v[36:39]
	v_mfma_f32_16x16x32_bf16 v[32:35], v[220:223], v[178:181], v[32:35]
	s_setprio 0
	s_barrier
	s_mov_b64 s[12:13], 0x1d40180
	v_lshl_add_u64 v[164:165], v[242:243], 0, s[12:13]
	v_readfirstlane_b32 s12, v155
	s_mov_b32 m0, s12
	s_mov_b64 s[12:13], 0x1d60180
	global_load_lds_dwordx4 v[164:165], off
	v_lshl_add_u64 v[164:165], v[242:243], 0, s[12:13]
	v_readfirstlane_b32 s12, v156
	s_mov_b32 m0, s12
	s_nop 0
	global_load_lds_dwordx4 v[164:165], off
	s_waitcnt vmcnt(6)
	s_barrier
	s_setprio 1
	v_mfma_f32_16x16x32_bf16 v[28:31], v[192:195], v[224:227], v[28:31]
	v_mfma_f32_16x16x32_bf16 v[24:27], v[192:195], v[232:235], v[24:27]
	v_mfma_f32_16x16x32_bf16 v[20:23], v[200:203], v[224:227], v[20:23]
	v_mfma_f32_16x16x32_bf16 v[16:19], v[200:203], v[232:235], v[16:19]
	v_mfma_f32_16x16x32_bf16 v[12:15], v[208:211], v[224:227], v[12:15]
	v_mfma_f32_16x16x32_bf16 v[8:11], v[208:211], v[232:235], v[8:11]
	v_mfma_f32_16x16x32_bf16 v[4:7], v[216:219], v[224:227], v[4:7]
	v_mfma_f32_16x16x32_bf16 v[0:3], v[216:219], v[232:235], v[0:3]
	v_mfma_f32_16x16x32_bf16 v[28:31], v[196:199], v[228:231], v[28:31]
	v_mfma_f32_16x16x32_bf16 v[24:27], v[196:199], v[236:239], v[24:27]
	v_mfma_f32_16x16x32_bf16 v[20:23], v[204:207], v[228:231], v[20:23]
	v_mfma_f32_16x16x32_bf16 v[16:19], v[204:207], v[236:239], v[16:19]
	v_mfma_f32_16x16x32_bf16 v[12:15], v[212:215], v[228:231], v[12:15]
	v_mfma_f32_16x16x32_bf16 v[8:11], v[212:215], v[236:239], v[8:11]
	v_mfma_f32_16x16x32_bf16 v[4:7], v[220:223], v[228:231], v[4:7]
	v_mfma_f32_16x16x32_bf16 v[0:3], v[220:223], v[236:239], v[0:3]
	s_setprio 0
	s_add_i32 s28, s28, 2
	s_add_u32 s24, s24, 0x100
	s_addc_u32 s25, s25, 0
	s_add_u32 s26, s26, 0x100
	s_addc_u32 s27, s27, 0
	s_cmp_lt_u32 s28, 12
	s_cbranch_scc1 .Lkh_1408
	s_barrier
	v_readfirstlane_b32 s12, v161
	v_lshl_add_u64 v[130:131], v[128:129], 0, s[54:55]
	s_mov_b32 m0, s12
	v_readfirstlane_b32 s12, v162
	ds_read_b128 v[152:155], v158
	ds_read_b128 v[164:167], v158 offset:1024
	ds_read_b128 v[168:171], v158 offset:2048
	ds_read_b128 v[172:175], v158 offset:3072
	ds_read_b128 v[178:181], v148
	ds_read_b128 v[192:195], v148 offset:1024
	ds_read_b128 v[196:199], v147
	ds_read_b128 v[200:203], v147 offset:1024
	ds_read_b128 v[204:207], v146
	ds_read_b128 v[208:211], v146 offset:1024
	ds_read_b128 v[212:215], v145
	ds_read_b128 v[216:219], v145 offset:1024
	global_load_lds_dwordx4 v[130:131], off
	v_lshl_add_u64 v[128:129], v[128:129], 0, s[56:57]
	s_mov_b32 m0, s12
	s_nop 0
	global_load_lds_dwordx4 v[128:129], off
	s_barrier
	s_waitcnt lgkmcnt(0)
	s_setprio 1
	s_waitcnt lgkmcnt(0)
	v_mfma_f32_16x16x32_bf16 v[124:127], v[178:181], v[152:155], v[124:127]
	v_mfma_f32_16x16x32_bf16 v[120:123], v[178:181], v[168:171], v[120:123]
	v_mfma_f32_16x16x32_bf16 v[116:119], v[196:199], v[152:155], v[116:119]
	v_mfma_f32_16x16x32_bf16 v[112:115], v[196:199], v[168:171], v[112:115]
	v_mfma_f32_16x16x32_bf16 v[124:127], v[192:195], v[164:167], v[124:127]
	v_mfma_f32_16x16x32_bf16 v[120:123], v[192:195], v[172:175], v[120:123]
	v_mfma_f32_16x16x32_bf16 v[116:119], v[200:203], v[164:167], v[116:119]
	v_mfma_f32_16x16x32_bf16 v[112:115], v[200:203], v[172:175], v[112:115]
	v_mfma_f32_16x16x32_bf16 v[108:111], v[204:207], v[152:155], v[108:111]
	v_mfma_f32_16x16x32_bf16 v[104:107], v[204:207], v[168:171], v[104:107]
	v_mfma_f32_16x16x32_bf16 v[100:103], v[212:215], v[152:155], v[100:103]
	v_mfma_f32_16x16x32_bf16 v[96:99], v[212:215], v[168:171], v[96:99]
	v_mfma_f32_16x16x32_bf16 v[128:131], v[208:211], v[164:167], v[108:111]
	v_mfma_f32_16x16x32_bf16 v[220:223], v[208:211], v[172:175], v[104:107]
	v_mfma_f32_16x16x32_bf16 v[224:227], v[216:219], v[164:167], v[100:103]
	v_mfma_f32_16x16x32_bf16 v[228:231], v[216:219], v[172:175], v[96:99]
	s_setprio 0
	s_barrier
	s_nop 1
	ds_read_b128 v[96:99], v157
	ds_read_b128 v[100:103], v157 offset:1024
	ds_read_b128 v[104:107], v157 offset:2048
	ds_read_b128 v[108:111], v157 offset:3072
	s_barrier
	s_waitcnt lgkmcnt(0)
	s_setprio 1
	s_waitcnt lgkmcnt(0)
	v_mfma_f32_16x16x32_bf16 v[92:95], v[178:181], v[96:99], v[92:95]
	v_mfma_f32_16x16x32_bf16 v[88:91], v[178:181], v[104:107], v[88:91]
	v_mfma_f32_16x16x32_bf16 v[84:87], v[196:199], v[96:99], v[84:87]
	v_mfma_f32_16x16x32_bf16 v[80:83], v[196:199], v[104:107], v[80:83]
	v_mfma_f32_16x16x32_bf16 v[92:95], v[192:195], v[100:103], v[92:95]
	v_mfma_f32_16x16x32_bf16 v[88:91], v[192:195], v[108:111], v[88:91]
	v_mfma_f32_16x16x32_bf16 v[84:87], v[200:203], v[100:103], v[84:87]
	v_mfma_f32_16x16x32_bf16 v[80:83], v[200:203], v[108:111], v[80:83]
	v_mfma_f32_16x16x32_bf16 v[76:79], v[204:207], v[96:99], v[76:79]
	v_mfma_f32_16x16x32_bf16 v[72:75], v[204:207], v[104:107], v[72:75]
	v_mfma_f32_16x16x32_bf16 v[68:71], v[212:215], v[96:99], v[68:71]
	v_mfma_f32_16x16x32_bf16 v[64:67], v[212:215], v[104:107], v[64:67]
	v_mfma_f32_16x16x32_bf16 v[178:181], v[208:211], v[100:103], v[76:79]
	v_mfma_f32_16x16x32_bf16 v[192:195], v[208:211], v[108:111], v[72:75]
	v_mfma_f32_16x16x32_bf16 v[196:199], v[216:219], v[100:103], v[68:71]
	v_mfma_f32_16x16x32_bf16 v[200:203], v[216:219], v[108:111], v[64:67]
	s_setprio 0
	s_barrier
	s_nop 1
	ds_read_b128 v[64:67], v148 offset:16384
	ds_read_b128 v[68:71], v148 offset:17408
	ds_read_b128 v[72:75], v147 offset:16384
	ds_read_b128 v[76:79], v147 offset:17408
	ds_read_b128 v[204:207], v146 offset:16384
	ds_read_b128 v[208:211], v146 offset:17408
	ds_read_b128 v[212:215], v145 offset:16384
	ds_read_b128 v[216:219], v145 offset:17408
	s_waitcnt vmcnt(4)
	s_barrier
	s_waitcnt lgkmcnt(0)
	s_setprio 1
	s_waitcnt lgkmcnt(0)
	v_mfma_f32_16x16x32_bf16 v[60:63], v[64:67], v[152:155], v[60:63]
	v_mfma_f32_16x16x32_bf16 v[56:59], v[64:67], v[168:171], v[56:59]
	v_mfma_f32_16x16x32_bf16 v[52:55], v[72:75], v[152:155], v[52:55]
	v_mfma_f32_16x16x32_bf16 v[48:51], v[72:75], v[168:171], v[48:51]
	v_mfma_f32_16x16x32_bf16 v[60:63], v[68:71], v[164:167], v[60:63]
	v_mfma_f32_16x16x32_bf16 v[56:59], v[68:71], v[172:175], v[56:59]
	v_mfma_f32_16x16x32_bf16 v[52:55], v[76:79], v[164:167], v[52:55]
	v_mfma_f32_16x16x32_bf16 v[48:51], v[76:79], v[172:175], v[48:51]
	v_mfma_f32_16x16x32_bf16 v[44:47], v[204:207], v[152:155], v[44:47]
	v_mfma_f32_16x16x32_bf16 v[40:43], v[204:207], v[168:171], v[40:43]
	v_mfma_f32_16x16x32_bf16 v[36:39], v[212:215], v[152:155], v[36:39]
	v_mfma_f32_16x16x32_bf16 v[32:35], v[212:215], v[168:171], v[32:35]
	v_mfma_f32_16x16x32_bf16 v[232:235], v[208:211], v[164:167], v[44:47]
	v_mfma_f32_16x16x32_bf16 v[236:239], v[208:211], v[172:175], v[40:43]
	v_mfma_f32_16x16x32_bf16 v[152:155], v[216:219], v[164:167], v[36:39]
	v_mfma_f32_16x16x32_bf16 v[162:165], v[216:219], v[172:175], v[32:35]
	s_setprio 0
	s_setprio 1
	v_mfma_f32_16x16x32_bf16 v[28:31], v[64:67], v[96:99], v[28:31]
	v_mfma_f32_16x16x32_bf16 v[24:27], v[64:67], v[104:107], v[24:27]
	v_mfma_f32_16x16x32_bf16 v[20:23], v[72:75], v[96:99], v[20:23]
	v_mfma_f32_16x16x32_bf16 v[16:19], v[72:75], v[104:107], v[16:19]
	v_mfma_f32_16x16x32_bf16 v[28:31], v[68:71], v[100:103], v[28:31]
	v_mfma_f32_16x16x32_bf16 v[24:27], v[68:71], v[108:111], v[24:27]
	v_mfma_f32_16x16x32_bf16 v[20:23], v[76:79], v[100:103], v[20:23]
	v_mfma_f32_16x16x32_bf16 v[16:19], v[76:79], v[108:111], v[16:19]
	v_mfma_f32_16x16x32_bf16 v[12:15], v[204:207], v[96:99], v[12:15]
	v_mfma_f32_16x16x32_bf16 v[8:11], v[204:207], v[104:107], v[8:11]
	v_mfma_f32_16x16x32_bf16 v[4:7], v[212:215], v[96:99], v[4:7]
	v_mfma_f32_16x16x32_bf16 v[0:3], v[212:215], v[104:107], v[0:3]
	v_mfma_f32_16x16x32_bf16 v[166:169], v[208:211], v[100:103], v[12:15]
	v_mfma_f32_16x16x32_bf16 v[170:173], v[208:211], v[108:111], v[8:11]
	v_mfma_f32_16x16x32_bf16 v[204:207], v[216:219], v[100:103], v[4:7]
	v_mfma_f32_16x16x32_bf16 v[208:211], v[216:219], v[108:111], v[0:3]
	s_setprio 0
	s_barrier
	s_nop 1
	ds_read_b128 v[0:3], v150
	ds_read_b128 v[4:7], v150 offset:1024
	ds_read_b128 v[212:215], v150 offset:2048
	ds_read_b128 v[216:219], v150 offset:3072
	ds_read_b128 v[8:11], v148 offset:32768
	ds_read_b128 v[12:15], v148 offset:33792
	ds_read_b128 v[32:35], v147 offset:32768
	ds_read_b128 v[36:39], v147 offset:33792
	ds_read_b128 v[40:43], v146 offset:32768
	ds_read_b128 v[44:47], v146 offset:33792
	ds_read_b128 v[240:243], v145 offset:32768
	ds_read_b128 v[244:247], v145 offset:33792
	s_waitcnt vmcnt(2)
	s_barrier
	s_waitcnt lgkmcnt(0)
	s_setprio 1
	s_waitcnt lgkmcnt(0)
	v_mfma_f32_16x16x32_bf16 v[64:67], v[8:11], v[0:3], v[124:127]
	v_mfma_f32_16x16x32_bf16 v[104:107], v[12:15], v[4:7], v[64:67]
	v_mfma_f32_16x16x32_bf16 v[64:67], v[8:11], v[212:215], v[120:123]
	v_mfma_f32_16x16x32_bf16 v[108:111], v[12:15], v[216:219], v[64:67]
	v_mfma_f32_16x16x32_bf16 v[64:67], v[32:35], v[0:3], v[116:119]
	v_mfma_f32_16x16x32_bf16 v[96:99], v[36:39], v[4:7], v[64:67]
	v_mfma_f32_16x16x32_bf16 v[64:67], v[32:35], v[212:215], v[112:115]
	v_mfma_f32_16x16x32_bf16 v[100:103], v[36:39], v[216:219], v[64:67]
	v_mfma_f32_16x16x32_bf16 v[64:67], v[40:43], v[0:3], v[128:131]
	v_mfma_f32_16x16x32_bf16 v[72:75], v[44:47], v[4:7], v[64:67]
	v_mfma_f32_16x16x32_bf16 v[64:67], v[40:43], v[212:215], v[220:223]
	v_mfma_f32_16x16x32_bf16 v[76:79], v[44:47], v[216:219], v[64:67]
	v_mfma_f32_16x16x32_bf16 v[64:67], v[240:243], v[0:3], v[224:227]
	v_mfma_f32_16x16x32_bf16 v[68:71], v[240:243], v[212:215], v[228:231]
	v_mfma_f32_16x16x32_bf16 v[64:67], v[244:247], v[4:7], v[64:67]
	v_mfma_f32_16x16x32_bf16 v[68:71], v[244:247], v[216:219], v[68:71]
	s_setprio 0
	s_barrier
	ds_read_b128 v[128:131], v149
	ds_read_b128 v[220:223], v149 offset:1024
	ds_read_b128 v[224:227], v149 offset:2048
	ds_read_b128 v[228:231], v149 offset:3072
	s_waitcnt vmcnt(0)
	s_barrier
	s_waitcnt lgkmcnt(0)
	s_setprio 1
	s_waitcnt lgkmcnt(0)
	v_mfma_f32_16x16x32_bf16 v[92:95], v[8:11], v[128:131], v[92:95]
	v_mfma_f32_16x16x32_bf16 v[8:11], v[8:11], v[224:227], v[88:91]
	v_mfma_f32_16x16x32_bf16 v[124:127], v[12:15], v[228:231], v[8:11]
	v_mfma_f32_16x16x32_bf16 v[8:11], v[32:35], v[128:131], v[84:87]
	v_mfma_f32_16x16x32_bf16 v[112:115], v[36:39], v[220:223], v[8:11]
	v_mfma_f32_16x16x32_bf16 v[8:11], v[32:35], v[224:227], v[80:83]
	v_mfma_f32_16x16x32_bf16 v[116:119], v[36:39], v[228:231], v[8:11]
	v_mfma_f32_16x16x32_bf16 v[8:11], v[40:43], v[128:131], v[178:181]
	v_mfma_f32_16x16x32_bf16 v[88:91], v[44:47], v[220:223], v[8:11]
	v_mfma_f32_16x16x32_bf16 v[8:11], v[40:43], v[224:227], v[192:195]
	v_mfma_f32_16x16x32_bf16 v[120:123], v[12:15], v[220:223], v[92:95]
	v_mfma_f32_16x16x32_bf16 v[92:95], v[44:47], v[228:231], v[8:11]
	v_mfma_f32_16x16x32_bf16 v[8:11], v[240:243], v[128:131], v[196:199]
	v_mfma_f32_16x16x32_bf16 v[80:83], v[244:247], v[220:223], v[8:11]
	v_mfma_f32_16x16x32_bf16 v[8:11], v[240:243], v[224:227], v[200:203]
	v_mfma_f32_16x16x32_bf16 v[84:87], v[244:247], v[228:231], v[8:11]
	s_setprio 0
	s_barrier
	ds_read_b128 v[178:181], v148 offset:49152
	ds_read_b128 v[148:151], v148 offset:50176
	ds_read_b128 v[192:195], v147 offset:49152
	ds_read_b128 v[196:199], v147 offset:50176
	ds_read_b128 v[200:203], v146 offset:49152
	ds_read_b128 v[240:243], v146 offset:50176
	ds_read_b128 v[244:247], v145 offset:49152
	ds_read_b128 v[248:251], v145 offset:50176
	s_barrier
	s_waitcnt lgkmcnt(0)
	s_setprio 1
	s_waitcnt lgkmcnt(0)
	v_mfma_f32_16x16x32_bf16 v[8:11], v[178:181], v[0:3], v[60:63]
	v_mfma_f32_16x16x32_bf16 v[40:43], v[148:151], v[4:7], v[8:11]
	v_mfma_f32_16x16x32_bf16 v[8:11], v[178:181], v[212:215], v[56:59]
	v_mfma_f32_16x16x32_bf16 v[44:47], v[148:151], v[216:219], v[8:11]
	v_mfma_f32_16x16x32_bf16 v[8:11], v[192:195], v[0:3], v[52:55]
	v_mfma_f32_16x16x32_bf16 v[32:35], v[196:199], v[4:7], v[8:11]
	v_mfma_f32_16x16x32_bf16 v[8:11], v[192:195], v[212:215], v[48:51]
	v_mfma_f32_16x16x32_bf16 v[36:39], v[196:199], v[216:219], v[8:11]
	v_mfma_f32_16x16x32_bf16 v[8:11], v[200:203], v[0:3], v[232:235]
	v_mfma_f32_16x16x32_bf16 v[0:3], v[244:247], v[0:3], v[152:155]
	v_mfma_f32_16x16x32_bf16 v[8:11], v[240:243], v[4:7], v[8:11]
	v_mfma_f32_16x16x32_bf16 v[12:15], v[200:203], v[212:215], v[236:239]
	v_mfma_f32_16x16x32_bf16 v[0:3], v[248:251], v[4:7], v[0:3]
	v_mfma_f32_16x16x32_bf16 v[4:7], v[244:247], v[212:215], v[162:165]
	v_mfma_f32_16x16x32_bf16 v[12:15], v[240:243], v[216:219], v[12:15]
	v_mfma_f32_16x16x32_bf16 v[4:7], v[248:251], v[216:219], v[4:7]
	s_setprio 0
	s_setprio 1
	v_mfma_f32_16x16x32_bf16 v[16:19], v[192:195], v[224:227], v[16:19]
	v_mfma_f32_16x16x32_bf16 v[24:27], v[178:181], v[224:227], v[24:27]
	v_mfma_f32_16x16x32_bf16 v[52:55], v[196:199], v[228:231], v[16:19]
	v_mfma_f32_16x16x32_bf16 v[16:19], v[200:203], v[128:131], v[166:169]
	v_mfma_f32_16x16x32_bf16 v[28:31], v[178:181], v[128:131], v[28:31]
	v_mfma_f32_16x16x32_bf16 v[60:63], v[148:151], v[228:231], v[24:27]
	v_mfma_f32_16x16x32_bf16 v[20:23], v[192:195], v[128:131], v[20:23]
	v_mfma_f32_16x16x32_bf16 v[24:27], v[240:243], v[220:223], v[16:19]
	v_mfma_f32_16x16x32_bf16 v[16:19], v[200:203], v[224:227], v[170:173]
	v_mfma_f32_16x16x32_bf16 v[56:59], v[148:151], v[220:223], v[28:31]
	v_mfma_f32_16x16x32_bf16 v[48:51], v[196:199], v[220:223], v[20:23]
	v_mfma_f32_16x16x32_bf16 v[28:31], v[240:243], v[228:231], v[16:19]
	v_mfma_f32_16x16x32_bf16 v[16:19], v[244:247], v[128:131], v[204:207]
	v_mfma_f32_16x16x32_bf16 v[20:23], v[244:247], v[224:227], v[208:211]
	v_mfma_f32_16x16x32_bf16 v[16:19], v[248:251], v[220:223], v[16:19]
	v_mfma_f32_16x16x32_bf16 v[20:23], v[248:251], v[228:231], v[20:23]
	s_setprio 0
	v_cmp_gt_u32_e32 vcc, s2, v142
	s_barrier
	s_and_saveexec_b64 s[24:25], vcc
	s_cbranch_execz .LBB0_1411
	s_barrier

.LBB0_1499:
	s_or_b64 exec, exec, s[20:21]
	v_add_u32_e32 v151, s15, v6
	v_add_u32_e32 v152, 0x2000, v151
	v_readfirstlane_b32 s12, v151
	v_lshl_add_u64 v[8:9], v[0:1], 0, s[46:47]
	s_mov_b32 m0, s12
	v_readfirstlane_b32 s12, v152
	v_add_u32_e32 v153, 0x8000, v144
	s_waitcnt vmcnt(0)
	s_barrier
	global_load_lds_dwordx4 v[8:9], off
	v_lshl_add_u64 v[8:9], v[0:1], 0, s[68:69]
	s_mov_b32 m0, s12
	v_readfirstlane_b32 s12, v153
	v_add_u32_e32 v154, 0xa000, v144
	global_load_lds_dwordx4 v[8:9], off
	v_lshl_add_u64 v[8:9], v[128:129], 0, s[46:47]
	s_mov_b32 m0, s12
	v_readfirstlane_b32 s12, v154
	global_load_lds_dwordx4 v[8:9], off
	v_lshl_add_u64 v[8:9], v[128:129], 0, s[68:69]
	s_mov_b32 m0, s12
	s_mov_b64 s[12:13], 0x100080
	v_add_u32_e32 v155, s36, v6
	global_load_lds_dwordx4 v[8:9], off
	v_lshl_add_u64 v[8:9], v[0:1], 0, s[12:13]
	v_readfirstlane_b32 s12, v155
	s_mov_b32 m0, s12
	s_mov_b64 s[12:13], 0x180080
	v_add_u32_e32 v157, 0x2000, v155
	v_lshl_add_u64 v[0:1], v[0:1], 0, s[12:13]
	v_readfirstlane_b32 s12, v157
	global_load_lds_dwordx4 v[8:9], off
	s_mov_b32 m0, s12
	v_bfe_u32 v131, v130, 4, 2
	global_load_lds_dwordx4 v[0:1], off
	v_and_b32_e32 v132, 15, v130
	v_lshlrev_b32_e32 v135, 2, v130
	v_lshlrev_b32_e32 v0, 4, v131
	v_lshlrev_b32_e32 v6, 6, v132
	v_and_b32_e32 v7, 32, v135
	v_lshlrev_b32_e32 v12, 6, v130
	v_bitop3_b32 v6, v0, v7, v6 bitop3:0x36
	v_and_or_b32 v0, v12, s33, v0
	v_xad_u32 v7, v0, v7, 16
	v_lshlrev_b32_e32 v0, 10, v130
	v_ashrrev_i32_e32 v134, 6, v130
	v_and_b32_e32 v0, 0xfffe0000, v0
	v_lshlrev_b32_e32 v2, 13, v2
	s_add_u32 s20, s8, s72
	v_and_b32_e32 v133, 3, v134
	s_waitcnt vmcnt(6)
	v_lshlrev_b32_e32 v136, 6, v5
	v_lshlrev_b32_e32 v5, 13, v5
	v_or3_b32 v0, v3, v0, v2
	s_addc_u32 s21, s9, 0
	v_lshlrev_b32_e32 v1, 12, v133
	v_add_u32_e32 v8, s35, v6
	v_add_u32_e32 v9, s14, v6
	v_add_u32_e32 v10, s15, v6
	v_add_u32_e32 v11, s36, v6
	v_add_u32_e32 v6, 16, v6
	v_or_b32_e32 v12, 0x800, v5
	v_or_b32_e32 v13, 0x1000, v5
	v_or_b32_e32 v14, 0x1800, v5
	v_add_u32_e32 v176, v0, v4
	s_add_u32 s24, s8, s24
	v_mov_b32_e32 v0, 0
	s_addc_u32 s25, s9, s25
	s_mov_b32 s72, -2
	v_add_u32_e32 v158, v8, v1
	v_add_u32_e32 v140, v6, v5
	v_add_u32_e32 v139, v7, v12
	v_add_u32_e32 v138, v7, v13
	v_add_u32_e32 v137, v7, v14
	v_add_u32_e32 v156, v9, v1
	v_add_u32_e32 v145, v10, v1
	v_add_u32_e32 v141, v11, v1
	v_mov_b32_e32 v1, v0
	v_mov_b32_e32 v2, v0
	v_mov_b32_e32 v3, v0
	v_mov_b32_e32 v4, v0
	v_mov_b32_e32 v5, v0
	v_mov_b32_e32 v6, v0
	v_mov_b32_e32 v7, v0
	v_mov_b32_e32 v8, v0
	v_mov_b32_e32 v9, v0
	v_mov_b32_e32 v10, v0
	v_mov_b32_e32 v11, v0
	v_mov_b32_e32 v12, v0
	v_mov_b32_e32 v13, v0
	v_mov_b32_e32 v14, v0
	v_mov_b32_e32 v15, v0
	v_mov_b32_e32 v16, v0
	v_mov_b32_e32 v17, v0
	v_mov_b32_e32 v18, v0
	v_mov_b32_e32 v19, v0
	v_mov_b32_e32 v20, v0
	v_mov_b32_e32 v21, v0
	v_mov_b32_e32 v22, v0
	v_mov_b32_e32 v23, v0
	v_mov_b32_e32 v24, v0
	v_mov_b32_e32 v25, v0
	v_mov_b32_e32 v26, v0
	v_mov_b32_e32 v27, v0
	v_mov_b32_e32 v28, v0
	v_mov_b32_e32 v29, v0
	v_mov_b32_e32 v30, v0
	v_mov_b32_e32 v31, v0
	v_mov_b32_e32 v32, v0
	v_mov_b32_e32 v33, v0
	v_mov_b32_e32 v34, v0
	v_mov_b32_e32 v35, v0
	v_mov_b32_e32 v36, v0
	v_mov_b32_e32 v37, v0
	v_mov_b32_e32 v38, v0
	v_mov_b32_e32 v39, v0
	v_mov_b32_e32 v40, v0
	v_mov_b32_e32 v41, v0
	v_mov_b32_e32 v42, v0
	v_mov_b32_e32 v43, v0
	v_mov_b32_e32 v44, v0
	v_mov_b32_e32 v45, v0
	v_mov_b32_e32 v46, v0
	v_mov_b32_e32 v47, v0
	v_mov_b32_e32 v48, v0
	v_mov_b32_e32 v49, v0
	v_mov_b32_e32 v50, v0
	v_mov_b32_e32 v51, v0
	v_mov_b32_e32 v52, v0
	v_mov_b32_e32 v53, v0
	v_mov_b32_e32 v54, v0
	v_mov_b32_e32 v55, v0
	v_mov_b32_e32 v56, v0
	v_mov_b32_e32 v57, v0
	v_mov_b32_e32 v58, v0
	v_mov_b32_e32 v59, v0
	v_mov_b32_e32 v60, v0
	v_mov_b32_e32 v61, v0
	v_mov_b32_e32 v62, v0
	v_mov_b32_e32 v63, v0
	v_mov_b32_e32 v64, v0
	v_mov_b32_e32 v65, v0
	v_mov_b32_e32 v66, v0
	v_mov_b32_e32 v67, v0
	v_mov_b32_e32 v68, v0
	v_mov_b32_e32 v69, v0
	v_mov_b32_e32 v70, v0
	v_mov_b32_e32 v71, v0
	v_mov_b32_e32 v72, v0
	v_mov_b32_e32 v73, v0
	v_mov_b32_e32 v74, v0
	v_mov_b32_e32 v75, v0
	v_mov_b32_e32 v76, v0
	v_mov_b32_e32 v77, v0
	v_mov_b32_e32 v78, v0
	v_mov_b32_e32 v79, v0
	v_mov_b32_e32 v80, v0
	v_mov_b32_e32 v81, v0
	v_mov_b32_e32 v82, v0
	v_mov_b32_e32 v83, v0
	v_mov_b32_e32 v84, v0
	v_mov_b32_e32 v85, v0
	v_mov_b32_e32 v86, v0
	v_mov_b32_e32 v87, v0
	v_mov_b32_e32 v88, v0
	v_mov_b32_e32 v89, v0
	v_mov_b32_e32 v90, v0
	v_mov_b32_e32 v91, v0
	v_mov_b32_e32 v92, v0
	v_mov_b32_e32 v93, v0
	v_mov_b32_e32 v94, v0
	v_mov_b32_e32 v95, v0
	v_mov_b32_e32 v96, v0
	v_mov_b32_e32 v97, v0
	v_mov_b32_e32 v98, v0
	v_mov_b32_e32 v99, v0
	v_mov_b32_e32 v100, v0
	v_mov_b32_e32 v101, v0
	v_mov_b32_e32 v102, v0
	v_mov_b32_e32 v103, v0
	v_mov_b32_e32 v104, v0
	v_mov_b32_e32 v105, v0
	v_mov_b32_e32 v106, v0
	v_mov_b32_e32 v107, v0
	v_mov_b32_e32 v108, v0
	v_mov_b32_e32 v109, v0
	v_mov_b32_e32 v110, v0
	v_mov_b32_e32 v111, v0
	v_mov_b32_e32 v112, v0
	v_mov_b32_e32 v113, v0
	v_mov_b32_e32 v114, v0
	v_mov_b32_e32 v115, v0
	v_mov_b32_e32 v116, v0
	v_mov_b32_e32 v117, v0
	v_mov_b32_e32 v118, v0
	v_mov_b32_e32 v119, v0
	v_mov_b32_e32 v120, v0
	v_mov_b32_e32 v121, v0
	v_mov_b32_e32 v122, v0
	v_mov_b32_e32 v123, v0
	v_mov_b32_e32 v124, v0
	v_mov_b32_e32 v125, v0
	v_mov_b32_e32 v126, v0
	v_mov_b32_e32 v127, v0
.Lkh_1500:
	s_barrier
.LBB0_1500:
	ds_read_b128 v[162:165], v158
	ds_read_b128 v[166:169], v158 offset:1024
	ds_read_b128 v[170:173], v158 offset:2048
	ds_read_b128 v[178:181], v158 offset:3072
	v_lshl_add_u64 v[174:175], s[24:25], 0, v[176:177]
	s_mov_b64 s[12:13], 0x572c180
	v_add_u32_e32 v159, 0xc000, v144
	v_lshl_add_u64 v[160:161], v[174:175], 0, s[12:13]
	v_readfirstlane_b32 s12, v159
	s_mov_b32 m0, s12
	ds_read_b128 v[192:195], v140
	ds_read_b128 v[196:199], v140 offset:1024
	ds_read_b128 v[200:203], v139
	ds_read_b128 v[204:207], v139 offset:1024
	ds_read_b128 v[208:211], v138
	ds_read_b128 v[212:215], v138 offset:1024
	ds_read_b128 v[216:219], v137
	ds_read_b128 v[220:223], v137 offset:1024
	global_load_lds_dwordx4 v[160:161], off
	s_mov_b64 s[12:13], 0x57ac180
	v_add_u32_e32 v160, 0xe000, v144
	v_lshl_add_u64 v[224:225], v[174:175], 0, s[12:13]
	v_readfirstlane_b32 s12, v160
	s_mov_b32 m0, s12
	s_nop 0
	global_load_lds_dwordx4 v[224:225], off
	s_waitcnt lgkmcnt(8)
	s_barrier
	s_waitcnt lgkmcnt(0)
	s_setprio 1
	s_waitcnt lgkmcnt(0)
	v_mfma_f32_16x16x32_bf16 v[124:127], v[192:195], v[162:165], v[124:127]
	v_mfma_f32_16x16x32_bf16 v[120:123], v[192:195], v[170:173], v[120:123]
	v_mfma_f32_16x16x32_bf16 v[116:119], v[200:203], v[162:165], v[116:119]
	v_mfma_f32_16x16x32_bf16 v[112:115], v[200:203], v[170:173], v[112:115]
	v_mfma_f32_16x16x32_bf16 v[108:111], v[208:211], v[162:165], v[108:111]
	v_mfma_f32_16x16x32_bf16 v[104:107], v[208:211], v[170:173], v[104:107]
	v_mfma_f32_16x16x32_bf16 v[100:103], v[216:219], v[162:165], v[100:103]
	v_mfma_f32_16x16x32_bf16 v[96:99], v[216:219], v[170:173], v[96:99]
	v_mfma_f32_16x16x32_bf16 v[124:127], v[196:199], v[166:169], v[124:127]
	v_mfma_f32_16x16x32_bf16 v[120:123], v[196:199], v[178:181], v[120:123]
	v_mfma_f32_16x16x32_bf16 v[116:119], v[204:207], v[166:169], v[116:119]
	v_mfma_f32_16x16x32_bf16 v[112:115], v[204:207], v[178:181], v[112:115]
	v_mfma_f32_16x16x32_bf16 v[108:111], v[212:215], v[166:169], v[108:111]
	v_mfma_f32_16x16x32_bf16 v[104:107], v[212:215], v[178:181], v[104:107]
	v_mfma_f32_16x16x32_bf16 v[100:103], v[220:223], v[166:169], v[100:103]
	v_mfma_f32_16x16x32_bf16 v[96:99], v[220:223], v[178:181], v[96:99]
	s_setprio 0
	s_barrier
	v_lshl_add_u64 v[240:241], s[20:21], 0, v[176:177]
	s_mov_b64 s[12:13], 0x2d00100
	v_lshl_add_u64 v[242:243], v[240:241], 0, s[12:13]
	v_readfirstlane_b32 s12, v142
	s_mov_b32 m0, s12
	s_mov_b64 s[12:13], 0x2d80100
	ds_read_b128 v[224:227], v156
	ds_read_b128 v[228:231], v156 offset:1024
	ds_read_b128 v[232:235], v156 offset:2048
	ds_read_b128 v[236:239], v156 offset:3072
	global_load_lds_dwordx4 v[242:243], off
	v_lshl_add_u64 v[242:243], v[240:241], 0, s[12:13]
	v_readfirstlane_b32 s12, v143
	s_mov_b32 m0, s12
	s_nop 0
	global_load_lds_dwordx4 v[242:243], off
	s_barrier
	s_waitcnt lgkmcnt(0)
	s_setprio 1
	s_waitcnt lgkmcnt(0)
	v_mfma_f32_16x16x32_bf16 v[92:95], v[192:195], v[224:227], v[92:95]
	v_mfma_f32_16x16x32_bf16 v[88:91], v[192:195], v[232:235], v[88:91]
	v_mfma_f32_16x16x32_bf16 v[84:87], v[200:203], v[224:227], v[84:87]
	v_mfma_f32_16x16x32_bf16 v[80:83], v[200:203], v[232:235], v[80:83]
	v_mfma_f32_16x16x32_bf16 v[76:79], v[208:211], v[224:227], v[76:79]
	v_mfma_f32_16x16x32_bf16 v[72:75], v[208:211], v[232:235], v[72:75]
	v_mfma_f32_16x16x32_bf16 v[68:71], v[216:219], v[224:227], v[68:71]
	v_mfma_f32_16x16x32_bf16 v[64:67], v[216:219], v[232:235], v[64:67]
	v_mfma_f32_16x16x32_bf16 v[92:95], v[196:199], v[228:231], v[92:95]
	v_mfma_f32_16x16x32_bf16 v[88:91], v[196:199], v[236:239], v[88:91]
	v_mfma_f32_16x16x32_bf16 v[84:87], v[204:207], v[228:231], v[84:87]
	v_mfma_f32_16x16x32_bf16 v[80:83], v[204:207], v[236:239], v[80:83]
	v_mfma_f32_16x16x32_bf16 v[76:79], v[212:215], v[228:231], v[76:79]
	v_mfma_f32_16x16x32_bf16 v[72:75], v[212:215], v[236:239], v[72:75]
	v_mfma_f32_16x16x32_bf16 v[68:71], v[220:223], v[228:231], v[68:71]
	v_mfma_f32_16x16x32_bf16 v[64:67], v[220:223], v[236:239], v[64:67]
	s_setprio 0
	s_mov_b64 s[12:13], 0x562c200
	v_lshl_add_u64 v[242:243], v[174:175], 0, s[12:13]
	v_readfirstlane_b32 s12, v144
	s_mov_b32 m0, s12
	s_mov_b64 s[12:13], 0x56ac200
	s_barrier
	ds_read_b128 v[192:195], v140 offset:16384
	ds_read_b128 v[196:199], v140 offset:17408
	ds_read_b128 v[200:203], v139 offset:16384
	ds_read_b128 v[204:207], v139 offset:17408
	ds_read_b128 v[208:211], v138 offset:16384
	ds_read_b128 v[212:215], v138 offset:17408
	ds_read_b128 v[216:219], v137 offset:16384
	ds_read_b128 v[220:223], v137 offset:17408
	global_load_lds_dwordx4 v[242:243], off
	v_lshl_add_u64 v[242:243], v[174:175], 0, s[12:13]
	v_readfirstlane_b32 s12, v146
	s_mov_b32 m0, s12
	s_nop 0
	global_load_lds_dwordx4 v[242:243], off
	s_barrier
	s_waitcnt lgkmcnt(0)
	s_setprio 1
	s_waitcnt lgkmcnt(0)
	v_mfma_f32_16x16x32_bf16 v[60:63], v[192:195], v[162:165], v[60:63]
	v_mfma_f32_16x16x32_bf16 v[56:59], v[192:195], v[170:173], v[56:59]
	v_mfma_f32_16x16x32_bf16 v[52:55], v[200:203], v[162:165], v[52:55]
	v_mfma_f32_16x16x32_bf16 v[48:51], v[200:203], v[170:173], v[48:51]
	v_mfma_f32_16x16x32_bf16 v[44:47], v[208:211], v[162:165], v[44:47]
	v_mfma_f32_16x16x32_bf16 v[40:43], v[208:211], v[170:173], v[40:43]
	v_mfma_f32_16x16x32_bf16 v[36:39], v[216:219], v[162:165], v[36:39]
	v_mfma_f32_16x16x32_bf16 v[32:35], v[216:219], v[170:173], v[32:35]
	v_mfma_f32_16x16x32_bf16 v[60:63], v[196:199], v[166:169], v[60:63]
	v_mfma_f32_16x16x32_bf16 v[56:59], v[196:199], v[178:181], v[56:59]
	v_mfma_f32_16x16x32_bf16 v[52:55], v[204:207], v[166:169], v[52:55]
	v_mfma_f32_16x16x32_bf16 v[48:51], v[204:207], v[178:181], v[48:51]
	v_mfma_f32_16x16x32_bf16 v[44:47], v[212:215], v[166:169], v[44:47]
	v_mfma_f32_16x16x32_bf16 v[40:43], v[212:215], v[178:181], v[40:43]
	v_mfma_f32_16x16x32_bf16 v[36:39], v[220:223], v[166:169], v[36:39]
	v_mfma_f32_16x16x32_bf16 v[32:35], v[220:223], v[178:181], v[32:35]
	s_setprio 0
	s_barrier
	s_mov_b64 s[12:13], 0x2e00100
	v_lshl_add_u64 v[162:163], v[240:241], 0, s[12:13]
	v_readfirstlane_b32 s12, v147
	s_mov_b32 m0, s12
	s_mov_b64 s[12:13], 0x2e80100
	global_load_lds_dwordx4 v[162:163], off
	v_lshl_add_u64 v[162:163], v[240:241], 0, s[12:13]
	v_readfirstlane_b32 s12, v148
	s_mov_b32 m0, s12
	s_nop 0
	global_load_lds_dwordx4 v[162:163], off
	s_waitcnt vmcnt(6)
	s_barrier
	s_setprio 1
	v_mfma_f32_16x16x32_bf16 v[28:31], v[192:195], v[224:227], v[28:31]
	v_mfma_f32_16x16x32_bf16 v[24:27], v[192:195], v[232:235], v[24:27]
	v_mfma_f32_16x16x32_bf16 v[20:23], v[200:203], v[224:227], v[20:23]
	v_mfma_f32_16x16x32_bf16 v[16:19], v[200:203], v[232:235], v[16:19]
	v_mfma_f32_16x16x32_bf16 v[12:15], v[208:211], v[224:227], v[12:15]
	v_mfma_f32_16x16x32_bf16 v[8:11], v[208:211], v[232:235], v[8:11]
	v_mfma_f32_16x16x32_bf16 v[4:7], v[216:219], v[224:227], v[4:7]
	v_mfma_f32_16x16x32_bf16 v[0:3], v[216:219], v[232:235], v[0:3]
	v_mfma_f32_16x16x32_bf16 v[28:31], v[196:199], v[228:231], v[28:31]
	v_mfma_f32_16x16x32_bf16 v[24:27], v[196:199], v[236:239], v[24:27]
	v_mfma_f32_16x16x32_bf16 v[20:23], v[204:207], v[228:231], v[20:23]
	v_mfma_f32_16x16x32_bf16 v[16:19], v[204:207], v[236:239], v[16:19]
	v_mfma_f32_16x16x32_bf16 v[12:15], v[212:215], v[228:231], v[12:15]
	v_mfma_f32_16x16x32_bf16 v[8:11], v[212:215], v[236:239], v[8:11]
	v_mfma_f32_16x16x32_bf16 v[4:7], v[220:223], v[228:231], v[4:7]
	v_mfma_f32_16x16x32_bf16 v[0:3], v[220:223], v[236:239], v[0:3]
	s_setprio 0
	s_barrier
	ds_read_b128 v[162:165], v145
	ds_read_b128 v[166:169], v145 offset:1024
	ds_read_b128 v[170:173], v145 offset:2048
	ds_read_b128 v[178:181], v145 offset:3072
	s_mov_b64 s[12:13], 0x572c200
	v_lshl_add_u64 v[224:225], v[174:175], 0, s[12:13]
	v_readfirstlane_b32 s12, v149
	s_mov_b32 m0, s12
	s_mov_b64 s[12:13], 0x57ac200
	ds_read_b128 v[192:195], v140 offset:32768
	ds_read_b128 v[196:199], v140 offset:33792
	ds_read_b128 v[200:203], v139 offset:32768
	ds_read_b128 v[204:207], v139 offset:33792
	ds_read_b128 v[208:211], v138 offset:32768
	ds_read_b128 v[212:215], v138 offset:33792
	ds_read_b128 v[216:219], v137 offset:32768
	ds_read_b128 v[220:223], v137 offset:33792
	global_load_lds_dwordx4 v[224:225], off
	v_lshl_add_u64 v[224:225], v[174:175], 0, s[12:13]
	v_readfirstlane_b32 s12, v150
	s_mov_b32 m0, s12
	s_nop 0
	global_load_lds_dwordx4 v[224:225], off
	s_waitcnt lgkmcnt(8)
	s_barrier
	s_waitcnt lgkmcnt(0)
	s_setprio 1
	s_waitcnt lgkmcnt(0)
	v_mfma_f32_16x16x32_bf16 v[124:127], v[192:195], v[162:165], v[124:127]
	v_mfma_f32_16x16x32_bf16 v[120:123], v[192:195], v[170:173], v[120:123]
	v_mfma_f32_16x16x32_bf16 v[116:119], v[200:203], v[162:165], v[116:119]
	v_mfma_f32_16x16x32_bf16 v[112:115], v[200:203], v[170:173], v[112:115]
	v_mfma_f32_16x16x32_bf16 v[108:111], v[208:211], v[162:165], v[108:111]
	v_mfma_f32_16x16x32_bf16 v[104:107], v[208:211], v[170:173], v[104:107]
	v_mfma_f32_16x16x32_bf16 v[100:103], v[216:219], v[162:165], v[100:103]
	v_mfma_f32_16x16x32_bf16 v[96:99], v[216:219], v[170:173], v[96:99]
	v_mfma_f32_16x16x32_bf16 v[124:127], v[196:199], v[166:169], v[124:127]
	v_mfma_f32_16x16x32_bf16 v[120:123], v[196:199], v[178:181], v[120:123]
	v_mfma_f32_16x16x32_bf16 v[116:119], v[204:207], v[166:169], v[116:119]
	v_mfma_f32_16x16x32_bf16 v[112:115], v[204:207], v[178:181], v[112:115]
	v_mfma_f32_16x16x32_bf16 v[108:111], v[212:215], v[166:169], v[108:111]
	v_mfma_f32_16x16x32_bf16 v[104:107], v[212:215], v[178:181], v[104:107]
	v_mfma_f32_16x16x32_bf16 v[100:103], v[220:223], v[166:169], v[100:103]
	v_mfma_f32_16x16x32_bf16 v[96:99], v[220:223], v[178:181], v[96:99]
	s_setprio 0
	s_barrier
	s_mov_b64 s[12:13], 0x2d00180
	v_lshl_add_u64 v[242:243], v[240:241], 0, s[12:13]
	v_readfirstlane_b32 s12, v151
	s_mov_b32 m0, s12
	s_mov_b64 s[12:13], 0x2d80180
	ds_read_b128 v[224:227], v141
	ds_read_b128 v[228:231], v141 offset:1024
	ds_read_b128 v[232:235], v141 offset:2048
	ds_read_b128 v[236:239], v141 offset:3072
	global_load_lds_dwordx4 v[242:243], off
	v_lshl_add_u64 v[242:243], v[240:241], 0, s[12:13]
	v_readfirstlane_b32 s12, v152
	s_mov_b32 m0, s12
	s_nop 0
	global_load_lds_dwordx4 v[242:243], off
	s_barrier
	s_waitcnt lgkmcnt(0)
	s_setprio 1
	s_waitcnt lgkmcnt(0)
	v_mfma_f32_16x16x32_bf16 v[92:95], v[192:195], v[224:227], v[92:95]
	v_mfma_f32_16x16x32_bf16 v[88:91], v[192:195], v[232:235], v[88:91]
	v_mfma_f32_16x16x32_bf16 v[84:87], v[200:203], v[224:227], v[84:87]
	v_mfma_f32_16x16x32_bf16 v[80:83], v[200:203], v[232:235], v[80:83]
	v_mfma_f32_16x16x32_bf16 v[76:79], v[208:211], v[224:227], v[76:79]
	v_mfma_f32_16x16x32_bf16 v[72:75], v[208:211], v[232:235], v[72:75]
	v_mfma_f32_16x16x32_bf16 v[68:71], v[216:219], v[224:227], v[68:71]
	v_mfma_f32_16x16x32_bf16 v[64:67], v[216:219], v[232:235], v[64:67]
	v_mfma_f32_16x16x32_bf16 v[92:95], v[196:199], v[228:231], v[92:95]
	v_mfma_f32_16x16x32_bf16 v[88:91], v[196:199], v[236:239], v[88:91]
	v_mfma_f32_16x16x32_bf16 v[84:87], v[204:207], v[228:231], v[84:87]
	v_mfma_f32_16x16x32_bf16 v[80:83], v[204:207], v[236:239], v[80:83]
	v_mfma_f32_16x16x32_bf16 v[76:79], v[212:215], v[228:231], v[76:79]
	v_mfma_f32_16x16x32_bf16 v[72:75], v[212:215], v[236:239], v[72:75]
	v_mfma_f32_16x16x32_bf16 v[68:71], v[220:223], v[228:231], v[68:71]
	v_mfma_f32_16x16x32_bf16 v[64:67], v[220:223], v[236:239], v[64:67]
	s_setprio 0
	s_mov_b64 s[12:13], 0x562c280
	v_lshl_add_u64 v[242:243], v[174:175], 0, s[12:13]
	v_readfirstlane_b32 s12, v153
	s_mov_b32 m0, s12
	s_mov_b64 s[12:13], 0x56ac280
	v_lshl_add_u64 v[174:175], v[174:175], 0, s[12:13]
	v_readfirstlane_b32 s12, v154
	s_barrier
	ds_read_b128 v[192:195], v140 offset:49152
	ds_read_b128 v[196:199], v140 offset:50176
	ds_read_b128 v[200:203], v139 offset:49152
	ds_read_b128 v[204:207], v139 offset:50176
	ds_read_b128 v[208:211], v138 offset:49152
	ds_read_b128 v[212:215], v138 offset:50176
	ds_read_b128 v[216:219], v137 offset:49152
	ds_read_b128 v[220:223], v137 offset:50176
	global_load_lds_dwordx4 v[242:243], off
	s_mov_b32 m0, s12
	s_nop 0
	global_load_lds_dwordx4 v[174:175], off
	s_barrier
	s_waitcnt lgkmcnt(0)
	s_setprio 1
	s_waitcnt lgkmcnt(0)
	v_mfma_f32_16x16x32_bf16 v[60:63], v[192:195], v[162:165], v[60:63]
	v_mfma_f32_16x16x32_bf16 v[56:59], v[192:195], v[170:173], v[56:59]
	v_mfma_f32_16x16x32_bf16 v[52:55], v[200:203], v[162:165], v[52:55]
	v_mfma_f32_16x16x32_bf16 v[48:51], v[200:203], v[170:173], v[48:51]
	v_mfma_f32_16x16x32_bf16 v[44:47], v[208:211], v[162:165], v[44:47]
	v_mfma_f32_16x16x32_bf16 v[40:43], v[208:211], v[170:173], v[40:43]
	v_mfma_f32_16x16x32_bf16 v[36:39], v[216:219], v[162:165], v[36:39]
	v_mfma_f32_16x16x32_bf16 v[32:35], v[216:219], v[170:173], v[32:35]
	v_mfma_f32_16x16x32_bf16 v[60:63], v[196:199], v[166:169], v[60:63]
	v_mfma_f32_16x16x32_bf16 v[56:59], v[196:199], v[178:181], v[56:59]
	v_mfma_f32_16x16x32_bf16 v[52:55], v[204:207], v[166:169], v[52:55]
	v_mfma_f32_16x16x32_bf16 v[48:51], v[204:207], v[178:181], v[48:51]
	v_mfma_f32_16x16x32_bf16 v[44:47], v[212:215], v[166:169], v[44:47]
	v_mfma_f32_16x16x32_bf16 v[40:43], v[212:215], v[178:181], v[40:43]
	v_mfma_f32_16x16x32_bf16 v[36:39], v[220:223], v[166:169], v[36:39]
	v_mfma_f32_16x16x32_bf16 v[32:35], v[220:223], v[178:181], v[32:35]
	s_setprio 0
	s_barrier
	s_mov_b64 s[12:13], 0x2e00180
	v_lshl_add_u64 v[162:163], v[240:241], 0, s[12:13]
	v_readfirstlane_b32 s12, v155
	s_mov_b32 m0, s12
	s_mov_b64 s[12:13], 0x2e80180
	global_load_lds_dwordx4 v[162:163], off
	v_lshl_add_u64 v[162:163], v[240:241], 0, s[12:13]
	v_readfirstlane_b32 s12, v157
	s_mov_b32 m0, s12
	s_nop 0
	global_load_lds_dwordx4 v[162:163], off
	s_waitcnt vmcnt(6)
	s_barrier
	s_setprio 1
	v_mfma_f32_16x16x32_bf16 v[28:31], v[192:195], v[224:227], v[28:31]
	v_mfma_f32_16x16x32_bf16 v[24:27], v[192:195], v[232:235], v[24:27]
	v_mfma_f32_16x16x32_bf16 v[20:23], v[200:203], v[224:227], v[20:23]
	v_mfma_f32_16x16x32_bf16 v[16:19], v[200:203], v[232:235], v[16:19]
	v_mfma_f32_16x16x32_bf16 v[12:15], v[208:211], v[224:227], v[12:15]
	v_mfma_f32_16x16x32_bf16 v[8:11], v[208:211], v[232:235], v[8:11]
	v_mfma_f32_16x16x32_bf16 v[4:7], v[216:219], v[224:227], v[4:7]
	v_mfma_f32_16x16x32_bf16 v[0:3], v[216:219], v[232:235], v[0:3]
	v_mfma_f32_16x16x32_bf16 v[28:31], v[196:199], v[228:231], v[28:31]
	v_mfma_f32_16x16x32_bf16 v[24:27], v[196:199], v[236:239], v[24:27]
	v_mfma_f32_16x16x32_bf16 v[20:23], v[204:207], v[228:231], v[20:23]
	v_mfma_f32_16x16x32_bf16 v[16:19], v[204:207], v[236:239], v[16:19]
	v_mfma_f32_16x16x32_bf16 v[12:15], v[212:215], v[228:231], v[12:15]
	v_mfma_f32_16x16x32_bf16 v[8:11], v[212:215], v[236:239], v[8:11]
	v_mfma_f32_16x16x32_bf16 v[4:7], v[220:223], v[228:231], v[4:7]
	v_mfma_f32_16x16x32_bf16 v[0:3], v[220:223], v[236:239], v[0:3]
	s_setprio 0
	s_add_i32 s72, s72, 2
	s_add_u32 s20, s20, 0x100
	s_addc_u32 s21, s21, 0
	s_add_u32 s24, s24, 0x100
	s_addc_u32 s25, s25, 0
	s_cmp_lt_u32 s72, 60
	s_cbranch_scc1 .Lkh_1500
	s_barrier
	s_mov_b64 s[12:13], 0x101f80
	v_lshl_add_u64 v[142:143], v[128:129], 0, s[12:13]
	v_readfirstlane_b32 s12, v159
	s_mov_b32 m0, s12
	s_mov_b64 s[12:13], 0x181f80
	v_lshl_add_u64 v[128:129], v[128:129], 0, s[12:13]
	v_readfirstlane_b32 s12, v160
	ds_read_b128 v[146:149], v158
	ds_read_b128 v[150:153], v158 offset:1024
	ds_read_b128 v[162:165], v158 offset:2048
	ds_read_b128 v[166:169], v158 offset:3072
	ds_read_b128 v[170:173], v140
	ds_read_b128 v[178:181], v140 offset:1024
	ds_read_b128 v[192:195], v139
	ds_read_b128 v[196:199], v139 offset:1024
	ds_read_b128 v[200:203], v138
	ds_read_b128 v[204:207], v138 offset:1024
	ds_read_b128 v[208:211], v137
	ds_read_b128 v[212:215], v137 offset:1024
	global_load_lds_dwordx4 v[142:143], off
	s_mov_b32 m0, s12
	s_nop 0
	global_load_lds_dwordx4 v[128:129], off
	s_barrier
	s_waitcnt lgkmcnt(0)
	s_setprio 1
	s_waitcnt lgkmcnt(0)
	v_mfma_f32_16x16x32_bf16 v[124:127], v[170:173], v[146:149], v[124:127]
	v_mfma_f32_16x16x32_bf16 v[120:123], v[170:173], v[162:165], v[120:123]
	v_mfma_f32_16x16x32_bf16 v[116:119], v[192:195], v[146:149], v[116:119]
	v_mfma_f32_16x16x32_bf16 v[112:115], v[192:195], v[162:165], v[112:115]
	v_mfma_f32_16x16x32_bf16 v[124:127], v[178:181], v[150:153], v[124:127]
	v_mfma_f32_16x16x32_bf16 v[120:123], v[178:181], v[166:169], v[120:123]
	v_mfma_f32_16x16x32_bf16 v[116:119], v[196:199], v[150:153], v[116:119]
	v_mfma_f32_16x16x32_bf16 v[112:115], v[196:199], v[166:169], v[112:115]
	v_mfma_f32_16x16x32_bf16 v[108:111], v[200:203], v[146:149], v[108:111]
	v_mfma_f32_16x16x32_bf16 v[104:107], v[200:203], v[162:165], v[104:107]
	v_mfma_f32_16x16x32_bf16 v[100:103], v[208:211], v[146:149], v[100:103]
	v_mfma_f32_16x16x32_bf16 v[96:99], v[208:211], v[162:165], v[96:99]
	v_mfma_f32_16x16x32_bf16 v[158:161], v[204:207], v[150:153], v[108:111]
	v_mfma_f32_16x16x32_bf16 v[216:219], v[204:207], v[166:169], v[104:107]
	v_mfma_f32_16x16x32_bf16 v[220:223], v[212:215], v[150:153], v[100:103]
	v_mfma_f32_16x16x32_bf16 v[224:227], v[212:215], v[166:169], v[96:99]
	s_setprio 0
	s_barrier
	s_nop 1
	ds_read_b128 v[96:99], v156
	ds_read_b128 v[100:103], v156 offset:1024
	ds_read_b128 v[104:107], v156 offset:2048
	ds_read_b128 v[108:111], v156 offset:3072
	s_barrier
	s_waitcnt lgkmcnt(0)
	s_setprio 1
	s_waitcnt lgkmcnt(0)
	v_mfma_f32_16x16x32_bf16 v[92:95], v[170:173], v[96:99], v[92:95]
	v_mfma_f32_16x16x32_bf16 v[88:91], v[170:173], v[104:107], v[88:91]
	v_mfma_f32_16x16x32_bf16 v[84:87], v[192:195], v[96:99], v[84:87]
	v_mfma_f32_16x16x32_bf16 v[80:83], v[192:195], v[104:107], v[80:83]
	v_mfma_f32_16x16x32_bf16 v[92:95], v[178:181], v[100:103], v[92:95]
	v_mfma_f32_16x16x32_bf16 v[88:91], v[178:181], v[108:111], v[88:91]
	v_mfma_f32_16x16x32_bf16 v[84:87], v[196:199], v[100:103], v[84:87]
	v_mfma_f32_16x16x32_bf16 v[80:83], v[196:199], v[108:111], v[80:83]
	v_mfma_f32_16x16x32_bf16 v[76:79], v[200:203], v[96:99], v[76:79]
	v_mfma_f32_16x16x32_bf16 v[72:75], v[200:203], v[104:107], v[72:75]
	v_mfma_f32_16x16x32_bf16 v[68:71], v[208:211], v[96:99], v[68:71]
	v_mfma_f32_16x16x32_bf16 v[64:67], v[208:211], v[104:107], v[64:67]
	v_mfma_f32_16x16x32_bf16 v[154:157], v[204:207], v[100:103], v[76:79]
	v_mfma_f32_16x16x32_bf16 v[170:173], v[204:207], v[108:111], v[72:75]
	v_mfma_f32_16x16x32_bf16 v[178:181], v[212:215], v[100:103], v[68:71]
	v_mfma_f32_16x16x32_bf16 v[192:195], v[212:215], v[108:111], v[64:67]
	s_setprio 0
	s_barrier
	s_nop 1
	ds_read_b128 v[64:67], v140 offset:16384
	ds_read_b128 v[68:71], v140 offset:17408
	ds_read_b128 v[72:75], v139 offset:16384
	ds_read_b128 v[76:79], v139 offset:17408
	ds_read_b128 v[196:199], v138 offset:16384
	ds_read_b128 v[200:203], v138 offset:17408
	ds_read_b128 v[204:207], v137 offset:16384
	ds_read_b128 v[208:211], v137 offset:17408
	s_waitcnt vmcnt(4)
	s_barrier
	s_waitcnt lgkmcnt(0)
	s_setprio 1
	s_waitcnt lgkmcnt(0)
	v_mfma_f32_16x16x32_bf16 v[60:63], v[64:67], v[146:149], v[60:63]
	v_mfma_f32_16x16x32_bf16 v[56:59], v[64:67], v[162:165], v[56:59]
	v_mfma_f32_16x16x32_bf16 v[52:55], v[72:75], v[146:149], v[52:55]
	v_mfma_f32_16x16x32_bf16 v[48:51], v[72:75], v[162:165], v[48:51]
	v_mfma_f32_16x16x32_bf16 v[60:63], v[68:71], v[150:153], v[60:63]
	v_mfma_f32_16x16x32_bf16 v[56:59], v[68:71], v[166:169], v[56:59]
	v_mfma_f32_16x16x32_bf16 v[52:55], v[76:79], v[150:153], v[52:55]
	v_mfma_f32_16x16x32_bf16 v[48:51], v[76:79], v[166:169], v[48:51]
	v_mfma_f32_16x16x32_bf16 v[44:47], v[196:199], v[146:149], v[44:47]
	v_mfma_f32_16x16x32_bf16 v[40:43], v[196:199], v[162:165], v[40:43]
	v_mfma_f32_16x16x32_bf16 v[36:39], v[204:207], v[146:149], v[36:39]
	v_mfma_f32_16x16x32_bf16 v[32:35], v[204:207], v[162:165], v[32:35]
	v_mfma_f32_16x16x32_bf16 v[212:215], v[200:203], v[150:153], v[44:47]
	v_mfma_f32_16x16x32_bf16 v[228:231], v[200:203], v[166:169], v[40:43]
	v_mfma_f32_16x16x32_bf16 v[146:149], v[208:211], v[150:153], v[36:39]
	v_mfma_f32_16x16x32_bf16 v[150:153], v[208:211], v[166:169], v[32:35]
	s_setprio 0
	s_setprio 1
	v_mfma_f32_16x16x32_bf16 v[28:31], v[64:67], v[96:99], v[28:31]
	v_mfma_f32_16x16x32_bf16 v[24:27], v[64:67], v[104:107], v[24:27]
	v_mfma_f32_16x16x32_bf16 v[20:23], v[72:75], v[96:99], v[20:23]
	v_mfma_f32_16x16x32_bf16 v[16:19], v[72:75], v[104:107], v[16:19]
	v_mfma_f32_16x16x32_bf16 v[28:31], v[68:71], v[100:103], v[28:31]
	v_mfma_f32_16x16x32_bf16 v[24:27], v[68:71], v[108:111], v[24:27]
	v_mfma_f32_16x16x32_bf16 v[20:23], v[76:79], v[100:103], v[20:23]
	v_mfma_f32_16x16x32_bf16 v[16:19], v[76:79], v[108:111], v[16:19]
	v_mfma_f32_16x16x32_bf16 v[12:15], v[196:199], v[96:99], v[12:15]
	v_mfma_f32_16x16x32_bf16 v[8:11], v[196:199], v[104:107], v[8:11]
	v_mfma_f32_16x16x32_bf16 v[4:7], v[204:207], v[96:99], v[4:7]
	v_mfma_f32_16x16x32_bf16 v[0:3], v[204:207], v[104:107], v[0:3]
	v_mfma_f32_16x16x32_bf16 v[162:165], v[200:203], v[100:103], v[12:15]
	v_mfma_f32_16x16x32_bf16 v[166:169], v[200:203], v[108:111], v[8:11]
	v_mfma_f32_16x16x32_bf16 v[196:199], v[208:211], v[100:103], v[4:7]
	v_mfma_f32_16x16x32_bf16 v[200:203], v[208:211], v[108:111], v[0:3]
	s_setprio 0
	s_barrier
	s_nop 1
	ds_read_b128 v[0:3], v145
	ds_read_b128 v[4:7], v145 offset:1024
	ds_read_b128 v[204:207], v145 offset:2048
	ds_read_b128 v[142:145], v145 offset:3072
	ds_read_b128 v[8:11], v140 offset:32768
	ds_read_b128 v[12:15], v140 offset:33792
	ds_read_b128 v[32:35], v139 offset:32768
	ds_read_b128 v[36:39], v139 offset:33792
	ds_read_b128 v[40:43], v138 offset:32768
	ds_read_b128 v[44:47], v138 offset:33792
	ds_read_b128 v[208:211], v137 offset:32768
	ds_read_b128 v[232:235], v137 offset:33792
	s_waitcnt vmcnt(2)
	s_barrier
	s_waitcnt lgkmcnt(0)
	s_setprio 1
	s_waitcnt lgkmcnt(0)
	v_mfma_f32_16x16x32_bf16 v[64:67], v[8:11], v[0:3], v[124:127]
	v_mfma_f32_16x16x32_bf16 v[104:107], v[12:15], v[4:7], v[64:67]
	v_mfma_f32_16x16x32_bf16 v[64:67], v[8:11], v[204:207], v[120:123]
	v_mfma_f32_16x16x32_bf16 v[108:111], v[12:15], v[142:145], v[64:67]
	v_mfma_f32_16x16x32_bf16 v[64:67], v[32:35], v[0:3], v[116:119]
	v_mfma_f32_16x16x32_bf16 v[96:99], v[36:39], v[4:7], v[64:67]
	v_mfma_f32_16x16x32_bf16 v[64:67], v[32:35], v[204:207], v[112:115]
	v_mfma_f32_16x16x32_bf16 v[100:103], v[36:39], v[142:145], v[64:67]
	v_mfma_f32_16x16x32_bf16 v[64:67], v[40:43], v[0:3], v[158:161]
	v_mfma_f32_16x16x32_bf16 v[72:75], v[44:47], v[4:7], v[64:67]
	v_mfma_f32_16x16x32_bf16 v[64:67], v[40:43], v[204:207], v[216:219]
	v_mfma_f32_16x16x32_bf16 v[76:79], v[44:47], v[142:145], v[64:67]
	v_mfma_f32_16x16x32_bf16 v[64:67], v[208:211], v[0:3], v[220:223]
	v_mfma_f32_16x16x32_bf16 v[68:71], v[208:211], v[204:207], v[224:227]
	v_mfma_f32_16x16x32_bf16 v[64:67], v[232:235], v[4:7], v[64:67]
	v_mfma_f32_16x16x32_bf16 v[68:71], v[232:235], v[142:145], v[68:71]
	s_setprio 0
	s_barrier
	ds_read_b128 v[158:161], v141
	ds_read_b128 v[216:219], v141 offset:1024
	ds_read_b128 v[220:223], v141 offset:2048
	ds_read_b128 v[224:227], v141 offset:3072
	s_waitcnt vmcnt(0)
	s_barrier
	s_waitcnt lgkmcnt(0)
	s_setprio 1
	s_waitcnt lgkmcnt(0)
	v_mfma_f32_16x16x32_bf16 v[92:95], v[8:11], v[158:161], v[92:95]
	v_mfma_f32_16x16x32_bf16 v[8:11], v[8:11], v[220:223], v[88:91]
	v_mfma_f32_16x16x32_bf16 v[124:127], v[12:15], v[224:227], v[8:11]
	v_mfma_f32_16x16x32_bf16 v[8:11], v[32:35], v[158:161], v[84:87]
	v_mfma_f32_16x16x32_bf16 v[112:115], v[36:39], v[216:219], v[8:11]
	v_mfma_f32_16x16x32_bf16 v[8:11], v[32:35], v[220:223], v[80:83]
	v_mfma_f32_16x16x32_bf16 v[116:119], v[36:39], v[224:227], v[8:11]
	v_mfma_f32_16x16x32_bf16 v[8:11], v[40:43], v[158:161], v[154:157]
	v_mfma_f32_16x16x32_bf16 v[88:91], v[44:47], v[216:219], v[8:11]
	v_mfma_f32_16x16x32_bf16 v[8:11], v[40:43], v[220:223], v[170:173]
	v_mfma_f32_16x16x32_bf16 v[120:123], v[12:15], v[216:219], v[92:95]
	v_mfma_f32_16x16x32_bf16 v[92:95], v[44:47], v[224:227], v[8:11]
	v_mfma_f32_16x16x32_bf16 v[8:11], v[208:211], v[158:161], v[178:181]
	v_mfma_f32_16x16x32_bf16 v[80:83], v[232:235], v[216:219], v[8:11]
	v_mfma_f32_16x16x32_bf16 v[8:11], v[208:211], v[220:223], v[192:195]
	v_mfma_f32_16x16x32_bf16 v[84:87], v[232:235], v[224:227], v[8:11]
	s_setprio 0
	s_barrier
	ds_read_b128 v[154:157], v140 offset:49152
	ds_read_b128 v[170:173], v140 offset:50176
	ds_read_b128 v[178:181], v139 offset:49152
	ds_read_b128 v[192:195], v139 offset:50176
	ds_read_b128 v[208:211], v138 offset:49152
	ds_read_b128 v[138:141], v138 offset:50176
	ds_read_b128 v[232:235], v137 offset:49152
	ds_read_b128 v[236:239], v137 offset:50176
	s_barrier
	s_waitcnt lgkmcnt(0)
	s_setprio 1
	s_waitcnt lgkmcnt(0)
	v_mfma_f32_16x16x32_bf16 v[8:11], v[154:157], v[0:3], v[60:63]
	v_mfma_f32_16x16x32_bf16 v[40:43], v[170:173], v[4:7], v[8:11]
	v_mfma_f32_16x16x32_bf16 v[8:11], v[154:157], v[204:207], v[56:59]
	v_mfma_f32_16x16x32_bf16 v[44:47], v[170:173], v[142:145], v[8:11]
	v_mfma_f32_16x16x32_bf16 v[8:11], v[178:181], v[0:3], v[52:55]
	v_mfma_f32_16x16x32_bf16 v[32:35], v[192:195], v[4:7], v[8:11]
	v_mfma_f32_16x16x32_bf16 v[8:11], v[178:181], v[204:207], v[48:51]
	v_mfma_f32_16x16x32_bf16 v[36:39], v[192:195], v[142:145], v[8:11]
	v_mfma_f32_16x16x32_bf16 v[8:11], v[208:211], v[0:3], v[212:215]
	v_mfma_f32_16x16x32_bf16 v[0:3], v[232:235], v[0:3], v[146:149]
	v_mfma_f32_16x16x32_bf16 v[8:11], v[138:141], v[4:7], v[8:11]
	v_mfma_f32_16x16x32_bf16 v[12:15], v[208:211], v[204:207], v[228:231]
	v_mfma_f32_16x16x32_bf16 v[0:3], v[236:239], v[4:7], v[0:3]
	v_mfma_f32_16x16x32_bf16 v[4:7], v[232:235], v[204:207], v[150:153]
	v_mfma_f32_16x16x32_bf16 v[12:15], v[138:141], v[142:145], v[12:15]
	v_mfma_f32_16x16x32_bf16 v[4:7], v[236:239], v[142:145], v[4:7]
	s_setprio 0
	s_setprio 1
	v_mfma_f32_16x16x32_bf16 v[16:19], v[178:181], v[220:223], v[16:19]
	v_mfma_f32_16x16x32_bf16 v[24:27], v[154:157], v[220:223], v[24:27]
	v_mfma_f32_16x16x32_bf16 v[52:55], v[192:195], v[224:227], v[16:19]
	v_mfma_f32_16x16x32_bf16 v[16:19], v[208:211], v[158:161], v[162:165]
	v_mfma_f32_16x16x32_bf16 v[28:31], v[154:157], v[158:161], v[28:31]
	v_mfma_f32_16x16x32_bf16 v[60:63], v[170:173], v[224:227], v[24:27]
	v_mfma_f32_16x16x32_bf16 v[20:23], v[178:181], v[158:161], v[20:23]
	v_mfma_f32_16x16x32_bf16 v[24:27], v[138:141], v[216:219], v[16:19]
	v_mfma_f32_16x16x32_bf16 v[16:19], v[208:211], v[220:223], v[166:169]
	v_mfma_f32_16x16x32_bf16 v[56:59], v[170:173], v[216:219], v[28:31]
	v_mfma_f32_16x16x32_bf16 v[48:51], v[192:195], v[216:219], v[20:23]
	v_mfma_f32_16x16x32_bf16 v[28:31], v[138:141], v[224:227], v[16:19]
	v_mfma_f32_16x16x32_bf16 v[16:19], v[232:235], v[158:161], v[196:199]
	v_mfma_f32_16x16x32_bf16 v[20:23], v[232:235], v[220:223], v[200:203]
	v_mfma_f32_16x16x32_bf16 v[16:19], v[236:239], v[216:219], v[16:19]
	v_mfma_f32_16x16x32_bf16 v[20:23], v[236:239], v[224:227], v[20:23]
	s_setprio 0
	v_cmp_gt_u32_e32 vcc, s2, v130
	s_barrier
	s_and_saveexec_b64 s[20:21], vcc
	s_cbranch_execz .LBB0_1496
	s_barrier
	s_branch .LBB0_1496
